# row phases: packed f32 adds / multiplies / fmas for the element-wise LayerNorm and modulation math
# baseline (speedup 1.0000x reference)
; DI void ln_row_v(const Frame& F, f32x4 (&v)[4], float* xout, const float* g, const float* b, const float* sh, const float* sc, bf16_t* hout, const float* slab, const float* gres, float* stat = nullptr) {
;     ...
;     if (g) {
;         float s = 0.f, s2 = 0.f;
; #pragma unroll
;         for (int j = 0; j < 4; ++j) { s += (v[j][0] + v[j][1]) + (v[j][2] + v[j][3]); s2 += (v[j][0] * v[j][0] + v[j][1] * v[j][1]) + (v[j][2] * v[j][2] + v[j][3] * v[j][3]); }
;         wave_sum2(s, s2, F.lane);
;         const float mean = s * (1.f / D); const float rstd = 1.f / sqrtf(fmaxf(s2 * (1.f / D) - mean * mean, 0.f) + EPS);
;         if (stat && F.lane == 0) { f32x2 sv = {mean, rstd}; *(f32x2*)stat = sv; }
; #pragma unroll
;         for (int j = 0; j < 4; ++j) { const f32x4 gg = ((const f32x4*)g)[F.lane + 64 * j], bb = ((const f32x4*)b)[F.lane + 64 * j];
;             v[j] = (v[j] - mean) * rstd * gg + bb; if (xout) ((f32x4*)xout)[F.lane + 64 * j] = v[j]; }
;     }
; DI void ln_phase(const Frame& F, int which) {
;     const int gw = F.vcu * 8 + F.wave, NGW = F.G * 8; const int l = F.l;
;     const int nrows = (l == NL - 1) ? ML : MT;
;     bf16_t* H = (bf16_t*)(F.ws + WS_HB);
;     const float* g = pin(F, which == 0 ? I_LN1G : I_LN2G) + l * 1024; const float* b = pin(F, which == 0 ? I_LN1B : I_LN2B) + l * 1024;
;     const bool wh = !(which == 1 && l == NL - 1);
;     f32x4 vc[4], vn[4];
;     if (gw < nrows) ln_load(F, xrow_ptr(F, gw), vc);
;     for (int row = gw; row < nrows; row += NGW) {
;         if (row + NGW < nrows) ln_load(F, xrow_ptr(F, row + NGW), vn);
;         const int mr = row < ML ? (row >> 11) : 8;
;         const float* sh = which == 0 ? modp(F, l, mr, 3) : modp(F, l + 1 < NL ? l + 1 : l, mr, 0);
;         const float* sc = which == 0 ? modp(F, l, mr, 4) : modp(F, l + 1 < NL ? l + 1 : l, mr, 1);
;         const bool sl = (which == 1 && row >= ML);
;         const bool st_only = row < ML && !(which == 1 && l == NL - 1);
;         float* stp = st_only ? (float*)(F.ws + (which == 0 ? WS_ST1 : WS_ST2)) + 2 * (size_t)row : nullptr;
;         ln_row_v(F, vc, st_only ? nullptr : xrow_ptr(F, row), g, b, sh, sc, wh ? H + (size_t)row * D : nullptr, sl ? (const float*)(F.ws + WS_KN) + (size_t)(row - ML) * 1024 : nullptr, modp(F, l, mr, 5), stp);
; #pragma unroll
;         for (int j = 0; j < 4; ++j) vc[j] = vn[j];
;     }
; }
.LBB0_107:
	s_cmp_gt_i32 s28, 4
	s_mov_b64 s[2:3], -1
	s_cbranch_scc0 .LBB0_125
	v_readlane_b32 s2, v255, 29
	s_lshl_b32 s2, s2, 3
	v_readlane_b32 s3, v255, 31
	s_add_i32 s16, s3, s2
	v_lshlrev_b32_e32 v0, 4, v186
	v_lshlrev_b32_e32 v1, 3, v186
	v_lshlrev_b32_e32 v96, 2, v186
	v_xor_b32_e32 v3, 4, v96
	v_xor_b32_e32 v4, 8, v96
	v_xor_b32_e32 v5, 16, v96
	v_xor_b32_e32 v6, 32, v96
	v_xor_b32_e32 v7, 64, v96
	v_xor_b32_e32 v8, 128, v96
	s_load_dwordx4 s[4:7], s[62:63], 0x98
	v_readlane_b32 s22, v255, 35
	v_readlane_b32 s8, v255, 17
	v_readlane_b32 s9, v255, 18
	s_add_u32 s20, s94, 0x3600000
	s_addc_u32 s21, s95, 0
	s_lshl_b32 s2, s16, 12
	s_lshl_b32 s3, s16, 15
	s_add_u32 s8, s8, s3
	s_addc_u32 s9, s9, 0
	s_add_u32 s20, s20, s2
	s_addc_u32 s21, s21, 0
	s_lshl_b32 s2, s16, 14
	s_add_u32 s10, s94, s2
	s_addc_u32 s11, s95, 0
	s_add_u32 s10, s10, 0x3e00000
	s_addc_u32 s11, s11, 0
	s_lshl_b32 s2, s16, 6
	s_add_u32 s12, s94, s2
	s_addc_u32 s13, s95, 0
	s_add_u32 s12, s12, 0x480000
	s_addc_u32 s13, s13, 0
	s_mov_b32 s3, s22
	s_mul_i32 s3, s3, 0x36000
	s_add_u32 s14, s94, s3
	s_addc_u32 s15, s95, 0
	s_add_u32 s14, s14, 0x103000
	s_addc_u32 s15, s15, 0
	s_add_u32 s18, s14, 0x1000
	s_addc_u32 s19, s15, 0
	s_lshl_b32 s2, s22, 12
	s_waitcnt lgkmcnt(0)
	s_add_u32 s4, s4, s2
	s_addc_u32 s5, s5, 0
	s_add_u32 s6, s6, s2
	s_addc_u32 s7, s7, 0
	global_load_dwordx4 v[10:13], v0, s[4:5]
	global_load_dwordx4 v[14:17], v0, s[4:5] offset:1024
	global_load_dwordx4 v[18:21], v0, s[4:5] offset:2048
	global_load_dwordx4 v[22:25], v0, s[4:5] offset:3072
	global_load_dwordx4 v[26:29], v0, s[6:7]
	global_load_dwordx4 v[30:33], v0, s[6:7] offset:1024
	global_load_dwordx4 v[34:37], v0, s[6:7] offset:2048
	global_load_dwordx4 v[38:41], v0, s[6:7] offset:3072
	s_add_u32 s2, s8, 0x0
	s_addc_u32 s3, s9, 0
	global_load_dwordx4 v[42:45], v0, s[2:3]
	global_load_dwordx4 v[46:49], v0, s[2:3] offset:1024
	global_load_dwordx4 v[50:53], v0, s[2:3] offset:2048
	global_load_dwordx4 v[54:57], v0, s[2:3] offset:3072
	s_lshr_b32 s23, s16, 8
	s_mul_i32 s23, s23, 0x6000
	s_add_u32 s2, s14, s23
	s_addc_u32 s3, s15, 0
	global_load_dwordx4 v[114:117], v0, s[2:3]
	global_load_dwordx4 v[118:121], v0, s[2:3] offset:1024
	global_load_dwordx4 v[122:125], v0, s[2:3] offset:2048
	global_load_dwordx4 v[126:129], v0, s[2:3] offset:3072
	s_add_u32 s2, s18, s23
	s_addc_u32 s3, s19, 0
	global_load_dwordx4 v[130:133], v0, s[2:3]
	global_load_dwordx4 v[134:137], v0, s[2:3] offset:1024
	global_load_dwordx4 v[138:141], v0, s[2:3] offset:2048
	global_load_dwordx4 v[142:145], v0, s[2:3] offset:3072
	s_add_u32 s2, s8, 0x1000
	s_addc_u32 s3, s9, 0
	global_load_dwordx4 v[58:61], v0, s[2:3]
	global_load_dwordx4 v[62:65], v0, s[2:3] offset:1024
	global_load_dwordx4 v[66:69], v0, s[2:3] offset:2048
	global_load_dwordx4 v[70:73], v0, s[2:3] offset:3072
	s_mov_b32 s23, 0x30000
	s_add_u32 s2, s14, s23
	s_addc_u32 s3, s15, 0
	global_load_dwordx4 v[146:149], v0, s[2:3]
	global_load_dwordx4 v[150:153], v0, s[2:3] offset:1024
	global_load_dwordx4 v[154:157], v0, s[2:3] offset:2048
	global_load_dwordx4 v[158:161], v0, s[2:3] offset:3072
	s_add_u32 s2, s18, s23
	s_addc_u32 s3, s19, 0
	global_load_dwordx4 v[162:165], v0, s[2:3]
	global_load_dwordx4 v[166:169], v0, s[2:3] offset:1024
	global_load_dwordx4 v[170:173], v0, s[2:3] offset:2048
	global_load_dwordx4 v[174:177], v0, s[2:3] offset:3072
	s_add_u32 s2, s8, 0x2000
	s_addc_u32 s3, s9, 0
	global_load_dwordx4 v[74:77], v0, s[2:3]
	global_load_dwordx4 v[78:81], v0, s[2:3] offset:1024
	global_load_dwordx4 v[82:85], v0, s[2:3] offset:2048
	global_load_dwordx4 v[86:89], v0, s[2:3] offset:3072
	s_add_u32 s2, s8, 0x3000
	s_addc_u32 s3, s9, 0
	global_load_dwordx4 v[98:101], v0, s[2:3]
	global_load_dwordx4 v[102:105], v0, s[2:3] offset:1024
	global_load_dwordx4 v[106:109], v0, s[2:3] offset:2048
	global_load_dwordx4 v[110:113], v0, s[2:3] offset:3072
	s_waitcnt vmcnt(28)
	v_pk_add_f32 v[198:199], v[42:43], v[44:45]
	v_pk_mul_f32 v[200:201], v[42:43], v[42:43]
	v_pk_fma_f32 v[200:201], v[44:45], v[44:45], v[200:201]
	v_pk_add_f32 v[198:199], v[198:199], v[46:47]
	v_pk_fma_f32 v[200:201], v[46:47], v[46:47], v[200:201]
	v_pk_add_f32 v[198:199], v[198:199], v[48:49]
	v_pk_fma_f32 v[200:201], v[48:49], v[48:49], v[200:201]
	v_pk_add_f32 v[198:199], v[198:199], v[50:51]
	v_pk_fma_f32 v[200:201], v[50:51], v[50:51], v[200:201]
	v_pk_add_f32 v[198:199], v[198:199], v[52:53]
	v_pk_fma_f32 v[200:201], v[52:53], v[52:53], v[200:201]
	v_pk_add_f32 v[198:199], v[198:199], v[54:55]
	v_pk_fma_f32 v[200:201], v[54:55], v[54:55], v[200:201]
	v_pk_add_f32 v[198:199], v[198:199], v[56:57]
	v_pk_fma_f32 v[200:201], v[56:57], v[56:57], v[200:201]
	v_add_f32_e32 v9, v198, v199
	v_add_f32_e32 v90, v200, v201
	s_nop 1
	v_add_f32_dpp v9, v9, v9 quad_perm:[1,0,3,2] row_mask:0xf bank_mask:0xf
	v_add_f32_dpp v90, v90, v90 quad_perm:[1,0,3,2] row_mask:0xf bank_mask:0xf
	s_nop 0
	v_add_f32_dpp v9, v9, v9 quad_perm:[2,3,0,1] row_mask:0xf bank_mask:0xf
	v_add_f32_dpp v90, v90, v90 quad_perm:[2,3,0,1] row_mask:0xf bank_mask:0xf
	s_nop 0
	v_add_f32_dpp v9, v9, v9 row_half_mirror row_mask:0xf bank_mask:0xf
	v_add_f32_dpp v90, v90, v90 row_half_mirror row_mask:0xf bank_mask:0xf
	s_nop 0
	v_add_f32_dpp v9, v9, v9 row_mirror row_mask:0xf bank_mask:0xf
	v_add_f32_dpp v90, v90, v90 row_mirror row_mask:0xf bank_mask:0xf
	s_nop 0
	v_add_f32_dpp v9, v9, v9 row_bcast:15 row_mask:0xa bank_mask:0xf
	v_add_f32_dpp v90, v90, v90 row_bcast:15 row_mask:0xa bank_mask:0xf
	s_nop 0
	v_add_f32_dpp v9, v9, v9 row_bcast:31 row_mask:0xc bank_mask:0xf
	v_add_f32_dpp v90, v90, v90 row_bcast:31 row_mask:0xc bank_mask:0xf
	s_nop 0
; DI unsigned pk2(float lo, float hi) { f32x2 v = {lo, hi}; bf16x2_t b = __builtin_convertvector(v, bf16x2_t); return __builtin_bit_cast(unsigned, b); }
; DI void ln_row_v(const Frame& F, f32x4 (&v)[4], float* xout, const float* g, const float* b, const float* sh, const float* sc, bf16_t* hout, const float* slab, const float* gres, float* stat = nullptr) {
;     ...
;     if (g) {
;         float s = 0.f, s2 = 0.f;
; #pragma unroll
;         for (int j = 0; j < 4; ++j) { s += (v[j][0] + v[j][1]) + (v[j][2] + v[j][3]); s2 += (v[j][0] * v[j][0] + v[j][1] * v[j][1]) + (v[j][2] * v[j][2] + v[j][3] * v[j][3]); }
;         wave_sum2(s, s2, F.lane);
;         const float mean = s * (1.f / D); const float rstd = 1.f / sqrtf(fmaxf(s2 * (1.f / D) - mean * mean, 0.f) + EPS);
;         if (stat && F.lane == 0) { f32x2 sv = {mean, rstd}; *(f32x2*)stat = sv; }
; #pragma unroll
;         for (int j = 0; j < 4; ++j) { const f32x4 gg = ((const f32x4*)g)[F.lane + 64 * j], bb = ((const f32x4*)b)[F.lane + 64 * j];
;             v[j] = (v[j] - mean) * rstd * gg + bb; if (xout) ((f32x4*)xout)[F.lane + 64 * j] = v[j]; }
;     }
;     if (hout) {
;         float s = 0.f, s2 = 0.f;
; #pragma unroll
;         for (int j = 0; j < 4; ++j) { s += (v[j][0] + v[j][1]) + (v[j][2] + v[j][3]); s2 += (v[j][0] * v[j][0] + v[j][1] * v[j][1]) + (v[j][2] * v[j][2] + v[j][3] * v[j][3]); }
;         wave_sum2(s, s2, F.lane);
;         const float mean = s * (1.f / D); const float rstd = 1.f / sqrtf(fmaxf(s2 * (1.f / D) - mean * mean, 0.f) + EPS);
; #pragma unroll
;         for (int j = 0; j < 4; ++j) { const f32x4 hh = ((const f32x4*)sh)[F.lane + 64 * j], cc = ((const f32x4*)sc)[F.lane + 64 * j];
;             const f32x4 o = (v[j] - mean) * rstd * (cc + 1.f) + hh; u32x2 wv; wv.x = pk2(o[0], o[1]); wv.y = pk2(o[2], o[3]);
;             ((u32x2*)hout)[F.lane + 64 * j] = wv; }
;     }
	v_readlane_b32 s2, v9, 63
	v_readlane_b32 s3, v90, 63
	s_nop 1
	v_mov_b32_e32 v9, s2
	v_mov_b32_e32 v90, s3
	v_mul_f32_e32 v93, 0x3a800000, v9
	v_mul_f32_e32 v91, 0x3a800000, v90
	v_fma_f32 v91, -v93, v93, v91
	v_max_f32_e32 v91, 0, v91
	v_add_f32_e32 v91, 0x358637bd, v91
	v_rsq_f32_e32 v94, v91
	v_mul_f32_e32 v91, 0.5, v91
	v_mul_f32_e32 v92, v94, v94
	v_fma_f32 v92, -v91, v92, 0.5
	v_fma_f32 v94, v94, v92, v94
	s_add_u32 s2, s12, 0x0
	s_addc_u32 s3, s13, 0
	v_mov_b32_e32 v188, v93
	v_mov_b32_e32 v189, v94
	s_mov_b64 exec, 1
	global_store_dwordx2 v97, v[188:189], s[2:3]
	s_mov_b64 exec, -1
	v_pk_add_f32 v[42:43], v[42:43], v[92:93] op_sel:[0,1] op_sel_hi:[1,1] neg_lo:[0,1] neg_hi:[0,1]
	v_pk_add_f32 v[44:45], v[44:45], v[92:93] op_sel:[0,1] op_sel_hi:[1,1] neg_lo:[0,1] neg_hi:[0,1]
	v_pk_add_f32 v[46:47], v[46:47], v[92:93] op_sel:[0,1] op_sel_hi:[1,1] neg_lo:[0,1] neg_hi:[0,1]
	v_pk_add_f32 v[48:49], v[48:49], v[92:93] op_sel:[0,1] op_sel_hi:[1,1] neg_lo:[0,1] neg_hi:[0,1]
	v_pk_add_f32 v[50:51], v[50:51], v[92:93] op_sel:[0,1] op_sel_hi:[1,1] neg_lo:[0,1] neg_hi:[0,1]
	v_pk_add_f32 v[52:53], v[52:53], v[92:93] op_sel:[0,1] op_sel_hi:[1,1] neg_lo:[0,1] neg_hi:[0,1]
	v_pk_add_f32 v[54:55], v[54:55], v[92:93] op_sel:[0,1] op_sel_hi:[1,1] neg_lo:[0,1] neg_hi:[0,1]
	v_pk_add_f32 v[56:57], v[56:57], v[92:93] op_sel:[0,1] op_sel_hi:[1,1] neg_lo:[0,1] neg_hi:[0,1]
	v_pk_mul_f32 v[42:43], v[42:43], v[94:95] op_sel_hi:[1,0]
	v_pk_mul_f32 v[44:45], v[44:45], v[94:95] op_sel_hi:[1,0]
	v_pk_mul_f32 v[46:47], v[46:47], v[94:95] op_sel_hi:[1,0]
	v_pk_mul_f32 v[48:49], v[48:49], v[94:95] op_sel_hi:[1,0]
	v_pk_mul_f32 v[50:51], v[50:51], v[94:95] op_sel_hi:[1,0]
	v_pk_mul_f32 v[52:53], v[52:53], v[94:95] op_sel_hi:[1,0]
	v_pk_mul_f32 v[54:55], v[54:55], v[94:95] op_sel_hi:[1,0]
	v_pk_mul_f32 v[56:57], v[56:57], v[94:95] op_sel_hi:[1,0]
	v_pk_fma_f32 v[42:43], v[42:43], v[10:11], v[26:27]
	v_pk_fma_f32 v[44:45], v[44:45], v[12:13], v[28:29]
	v_pk_fma_f32 v[46:47], v[46:47], v[14:15], v[30:31]
	v_pk_fma_f32 v[48:49], v[48:49], v[16:17], v[32:33]
	v_pk_fma_f32 v[50:51], v[50:51], v[18:19], v[34:35]
	v_pk_fma_f32 v[52:53], v[52:53], v[20:21], v[36:37]
	v_pk_fma_f32 v[54:55], v[54:55], v[22:23], v[38:39]
	v_pk_fma_f32 v[56:57], v[56:57], v[24:25], v[40:41]
	v_pk_add_f32 v[198:199], v[42:43], v[44:45]
	v_pk_mul_f32 v[200:201], v[42:43], v[42:43]
	v_pk_fma_f32 v[200:201], v[44:45], v[44:45], v[200:201]
	v_pk_add_f32 v[198:199], v[198:199], v[46:47]
	v_pk_fma_f32 v[200:201], v[46:47], v[46:47], v[200:201]
	v_pk_add_f32 v[198:199], v[198:199], v[48:49]
	v_pk_fma_f32 v[200:201], v[48:49], v[48:49], v[200:201]
	v_pk_add_f32 v[198:199], v[198:199], v[50:51]
	v_pk_fma_f32 v[200:201], v[50:51], v[50:51], v[200:201]
	v_pk_add_f32 v[198:199], v[198:199], v[52:53]
	v_pk_fma_f32 v[200:201], v[52:53], v[52:53], v[200:201]
	v_pk_add_f32 v[198:199], v[198:199], v[54:55]
	v_pk_fma_f32 v[200:201], v[54:55], v[54:55], v[200:201]
	v_pk_add_f32 v[198:199], v[198:199], v[56:57]
	v_pk_fma_f32 v[200:201], v[56:57], v[56:57], v[200:201]
	v_add_f32_e32 v9, v198, v199
	v_add_f32_e32 v90, v200, v201
	s_nop 1
	v_add_f32_dpp v9, v9, v9 quad_perm:[1,0,3,2] row_mask:0xf bank_mask:0xf
	v_add_f32_dpp v90, v90, v90 quad_perm:[1,0,3,2] row_mask:0xf bank_mask:0xf
	s_nop 0
	v_add_f32_dpp v9, v9, v9 quad_perm:[2,3,0,1] row_mask:0xf bank_mask:0xf
	v_add_f32_dpp v90, v90, v90 quad_perm:[2,3,0,1] row_mask:0xf bank_mask:0xf
	s_nop 0
	v_add_f32_dpp v9, v9, v9 row_half_mirror row_mask:0xf bank_mask:0xf
	v_add_f32_dpp v90, v90, v90 row_half_mirror row_mask:0xf bank_mask:0xf
	s_nop 0
	v_add_f32_dpp v9, v9, v9 row_mirror row_mask:0xf bank_mask:0xf
	v_add_f32_dpp v90, v90, v90 row_mirror row_mask:0xf bank_mask:0xf
	s_nop 0
	v_add_f32_dpp v9, v9, v9 row_bcast:15 row_mask:0xa bank_mask:0xf
	v_add_f32_dpp v90, v90, v90 row_bcast:15 row_mask:0xa bank_mask:0xf
	s_nop 0
	v_add_f32_dpp v9, v9, v9 row_bcast:31 row_mask:0xc bank_mask:0xf
	v_add_f32_dpp v90, v90, v90 row_bcast:31 row_mask:0xc bank_mask:0xf
	s_nop 0
	v_readlane_b32 s2, v9, 63
	v_readlane_b32 s3, v90, 63
	s_nop 1
	v_mov_b32_e32 v9, s2
	v_mov_b32_e32 v90, s3
	v_mul_f32_e32 v93, 0x3a800000, v9
	v_mul_f32_e32 v91, 0x3a800000, v90
	v_fma_f32 v91, -v93, v93, v91
	v_max_f32_e32 v91, 0, v91
	v_add_f32_e32 v91, 0x358637bd, v91
	v_rsq_f32_e32 v94, v91
	v_mul_f32_e32 v91, 0.5, v91
	v_mul_f32_e32 v92, v94, v94
	v_fma_f32 v92, -v91, v92, 0.5
	v_fma_f32 v94, v94, v92, v94
	s_waitcnt vmcnt(21)
; DI unsigned pk2(float lo, float hi) { f32x2 v = {lo, hi}; bf16x2_t b = __builtin_convertvector(v, bf16x2_t); return __builtin_bit_cast(unsigned, b); }
; DI void ln_row_v(const Frame& F, f32x4 (&v)[4], float* xout, const float* g, const float* b, const float* sh, const float* sc, bf16_t* hout, const float* slab, const float* gres, float* stat = nullptr) {
;     ...
;     if (g) {
;         float s = 0.f, s2 = 0.f;
; #pragma unroll
;         for (int j = 0; j < 4; ++j) { s += (v[j][0] + v[j][1]) + (v[j][2] + v[j][3]); s2 += (v[j][0] * v[j][0] + v[j][1] * v[j][1]) + (v[j][2] * v[j][2] + v[j][3] * v[j][3]); }
;         wave_sum2(s, s2, F.lane);
;         const float mean = s * (1.f / D); const float rstd = 1.f / sqrtf(fmaxf(s2 * (1.f / D) - mean * mean, 0.f) + EPS);
;         if (stat && F.lane == 0) { f32x2 sv = {mean, rstd}; *(f32x2*)stat = sv; }
; #pragma unroll
;         for (int j = 0; j < 4; ++j) { const f32x4 gg = ((const f32x4*)g)[F.lane + 64 * j], bb = ((const f32x4*)b)[F.lane + 64 * j];
;             v[j] = (v[j] - mean) * rstd * gg + bb; if (xout) ((f32x4*)xout)[F.lane + 64 * j] = v[j]; }
;     }
;     if (hout) {
;         float s = 0.f, s2 = 0.f;
; #pragma unroll
;         for (int j = 0; j < 4; ++j) { s += (v[j][0] + v[j][1]) + (v[j][2] + v[j][3]); s2 += (v[j][0] * v[j][0] + v[j][1] * v[j][1]) + (v[j][2] * v[j][2] + v[j][3] * v[j][3]); }
;         wave_sum2(s, s2, F.lane);
;         const float mean = s * (1.f / D); const float rstd = 1.f / sqrtf(fmaxf(s2 * (1.f / D) - mean * mean, 0.f) + EPS);
; #pragma unroll
;         for (int j = 0; j < 4; ++j) { const f32x4 hh = ((const f32x4*)sh)[F.lane + 64 * j], cc = ((const f32x4*)sc)[F.lane + 64 * j];
;             const f32x4 o = (v[j] - mean) * rstd * (cc + 1.f) + hh; u32x2 wv; wv.x = pk2(o[0], o[1]); wv.y = pk2(o[2], o[3]);
;             ((u32x2*)hout)[F.lane + 64 * j] = wv; }
;     }
	v_pk_add_f32 v[42:43], v[42:43], v[92:93] op_sel:[0,1] op_sel_hi:[1,1] neg_lo:[0,1] neg_hi:[0,1]
	v_pk_add_f32 v[44:45], v[44:45], v[92:93] op_sel:[0,1] op_sel_hi:[1,1] neg_lo:[0,1] neg_hi:[0,1]
	v_pk_add_f32 v[46:47], v[46:47], v[92:93] op_sel:[0,1] op_sel_hi:[1,1] neg_lo:[0,1] neg_hi:[0,1]
	v_pk_add_f32 v[48:49], v[48:49], v[92:93] op_sel:[0,1] op_sel_hi:[1,1] neg_lo:[0,1] neg_hi:[0,1]
	v_pk_add_f32 v[50:51], v[50:51], v[92:93] op_sel:[0,1] op_sel_hi:[1,1] neg_lo:[0,1] neg_hi:[0,1]
	v_pk_add_f32 v[52:53], v[52:53], v[92:93] op_sel:[0,1] op_sel_hi:[1,1] neg_lo:[0,1] neg_hi:[0,1]
	v_pk_add_f32 v[54:55], v[54:55], v[92:93] op_sel:[0,1] op_sel_hi:[1,1] neg_lo:[0,1] neg_hi:[0,1]
	v_pk_add_f32 v[56:57], v[56:57], v[92:93] op_sel:[0,1] op_sel_hi:[1,1] neg_lo:[0,1] neg_hi:[0,1]
	v_add_f32_e32 v130, 1.0, v130
	v_add_f32_e32 v131, 1.0, v131
	v_add_f32_e32 v132, 1.0, v132
	v_add_f32_e32 v133, 1.0, v133
	v_add_f32_e32 v134, 1.0, v134
	v_add_f32_e32 v135, 1.0, v135
	v_add_f32_e32 v136, 1.0, v136
	v_add_f32_e32 v137, 1.0, v137
	v_add_f32_e32 v138, 1.0, v138
	v_add_f32_e32 v139, 1.0, v139
	v_add_f32_e32 v140, 1.0, v140
	v_add_f32_e32 v141, 1.0, v141
	v_add_f32_e32 v142, 1.0, v142
	v_add_f32_e32 v143, 1.0, v143
	v_add_f32_e32 v144, 1.0, v144
	v_add_f32_e32 v145, 1.0, v145
	v_pk_mul_f32 v[42:43], v[42:43], v[94:95] op_sel_hi:[1,0]
	v_pk_mul_f32 v[44:45], v[44:45], v[94:95] op_sel_hi:[1,0]
	v_pk_mul_f32 v[46:47], v[46:47], v[94:95] op_sel_hi:[1,0]
	v_pk_mul_f32 v[48:49], v[48:49], v[94:95] op_sel_hi:[1,0]
	v_pk_mul_f32 v[50:51], v[50:51], v[94:95] op_sel_hi:[1,0]
	v_pk_mul_f32 v[52:53], v[52:53], v[94:95] op_sel_hi:[1,0]
	v_pk_mul_f32 v[54:55], v[54:55], v[94:95] op_sel_hi:[1,0]
	v_pk_mul_f32 v[56:57], v[56:57], v[94:95] op_sel_hi:[1,0]
	v_pk_fma_f32 v[42:43], v[42:43], v[130:131], v[114:115]
	v_pk_fma_f32 v[44:45], v[44:45], v[132:133], v[116:117]
	v_pk_fma_f32 v[46:47], v[46:47], v[134:135], v[118:119]
	v_pk_fma_f32 v[48:49], v[48:49], v[136:137], v[120:121]
	v_pk_fma_f32 v[50:51], v[50:51], v[138:139], v[122:123]
	v_pk_fma_f32 v[52:53], v[52:53], v[140:141], v[124:125]
	v_pk_fma_f32 v[54:55], v[54:55], v[142:143], v[126:127]
	v_pk_fma_f32 v[56:57], v[56:57], v[144:145], v[128:129]
	v_cvt_pk_bf16_f32 v190, v42, v43
	v_cvt_pk_bf16_f32 v191, v44, v45
	v_cvt_pk_bf16_f32 v192, v46, v47
	v_cvt_pk_bf16_f32 v193, v48, v49
	v_cvt_pk_bf16_f32 v194, v50, v51
	v_cvt_pk_bf16_f32 v195, v52, v53
	v_cvt_pk_bf16_f32 v196, v54, v55
	v_cvt_pk_bf16_f32 v197, v56, v57
	s_add_u32 s2, s10, 0x0
	s_addc_u32 s3, s11, 0
	global_store_dwordx2 v1, v[190:191], s[2:3]
	global_store_dwordx2 v1, v[192:193], s[2:3] offset:512
	global_store_dwordx2 v1, v[194:195], s[2:3] offset:1024
	global_store_dwordx2 v1, v[196:197], s[2:3] offset:1536
	s_add_u32 s2, s8, 0x4000
	s_addc_u32 s3, s9, 0
	global_load_dwordx4 v[42:45], v0, s[2:3]
	global_load_dwordx4 v[46:49], v0, s[2:3] offset:1024
	global_load_dwordx4 v[50:53], v0, s[2:3] offset:2048
	global_load_dwordx4 v[54:57], v0, s[2:3] offset:3072
	s_waitcnt vmcnt(25)
	v_pk_add_f32 v[198:199], v[58:59], v[60:61]
	v_pk_mul_f32 v[200:201], v[58:59], v[58:59]
	v_pk_fma_f32 v[200:201], v[60:61], v[60:61], v[200:201]
	v_pk_add_f32 v[198:199], v[198:199], v[62:63]
	v_pk_fma_f32 v[200:201], v[62:63], v[62:63], v[200:201]
	v_pk_add_f32 v[198:199], v[198:199], v[64:65]
	v_pk_fma_f32 v[200:201], v[64:65], v[64:65], v[200:201]
	v_pk_add_f32 v[198:199], v[198:199], v[66:67]
	v_pk_fma_f32 v[200:201], v[66:67], v[66:67], v[200:201]
	v_pk_add_f32 v[198:199], v[198:199], v[68:69]
	v_pk_fma_f32 v[200:201], v[68:69], v[68:69], v[200:201]
	v_pk_add_f32 v[198:199], v[198:199], v[70:71]
	v_pk_fma_f32 v[200:201], v[70:71], v[70:71], v[200:201]
	v_pk_add_f32 v[198:199], v[198:199], v[72:73]
	v_pk_fma_f32 v[200:201], v[72:73], v[72:73], v[200:201]
	v_add_f32_e32 v9, v198, v199
	v_add_f32_e32 v90, v200, v201
	s_nop 1
	v_add_f32_dpp v9, v9, v9 quad_perm:[1,0,3,2] row_mask:0xf bank_mask:0xf
	v_add_f32_dpp v90, v90, v90 quad_perm:[1,0,3,2] row_mask:0xf bank_mask:0xf
	s_nop 0
	v_add_f32_dpp v9, v9, v9 quad_perm:[2,3,0,1] row_mask:0xf bank_mask:0xf
	v_add_f32_dpp v90, v90, v90 quad_perm:[2,3,0,1] row_mask:0xf bank_mask:0xf
	s_nop 0
	v_add_f32_dpp v9, v9, v9 row_half_mirror row_mask:0xf bank_mask:0xf
	v_add_f32_dpp v90, v90, v90 row_half_mirror row_mask:0xf bank_mask:0xf
	s_nop 0
	v_add_f32_dpp v9, v9, v9 row_mirror row_mask:0xf bank_mask:0xf
	v_add_f32_dpp v90, v90, v90 row_mirror row_mask:0xf bank_mask:0xf
	s_nop 0
	v_add_f32_dpp v9, v9, v9 row_bcast:15 row_mask:0xa bank_mask:0xf
	v_add_f32_dpp v90, v90, v90 row_bcast:15 row_mask:0xa bank_mask:0xf
	s_nop 0
	v_add_f32_dpp v9, v9, v9 row_bcast:31 row_mask:0xc bank_mask:0xf
	v_add_f32_dpp v90, v90, v90 row_bcast:31 row_mask:0xc bank_mask:0xf
	s_nop 0
	v_readlane_b32 s2, v9, 63
	v_readlane_b32 s3, v90, 63
	s_nop 1
	v_mov_b32_e32 v9, s2
	v_mov_b32_e32 v90, s3
	v_mul_f32_e32 v93, 0x3a800000, v9
	v_mul_f32_e32 v91, 0x3a800000, v90
	v_fma_f32 v91, -v93, v93, v91
	v_max_f32_e32 v91, 0, v91
	v_add_f32_e32 v91, 0x358637bd, v91
	v_rsq_f32_e32 v94, v91
	v_mul_f32_e32 v91, 0.5, v91
	v_mul_f32_e32 v92, v94, v94
	v_fma_f32 v92, -v91, v92, 0.5
	v_fma_f32 v94, v94, v92, v94
	s_add_u32 s2, s12, 0x8
	s_addc_u32 s3, s13, 0
	v_mov_b32_e32 v188, v93
	v_mov_b32_e32 v189, v94
	s_mov_b64 exec, 1
	global_store_dwordx2 v97, v[188:189], s[2:3]
	s_mov_b64 exec, -1
	v_pk_add_f32 v[58:59], v[58:59], v[92:93] op_sel:[0,1] op_sel_hi:[1,1] neg_lo:[0,1] neg_hi:[0,1]
	v_pk_add_f32 v[60:61], v[60:61], v[92:93] op_sel:[0,1] op_sel_hi:[1,1] neg_lo:[0,1] neg_hi:[0,1]
	v_pk_add_f32 v[62:63], v[62:63], v[92:93] op_sel:[0,1] op_sel_hi:[1,1] neg_lo:[0,1] neg_hi:[0,1]
; DI unsigned pk2(float lo, float hi) { f32x2 v = {lo, hi}; bf16x2_t b = __builtin_convertvector(v, bf16x2_t); return __builtin_bit_cast(unsigned, b); }
; DI void ln_row_v(const Frame& F, f32x4 (&v)[4], float* xout, const float* g, const float* b, const float* sh, const float* sc, bf16_t* hout, const float* slab, const float* gres, float* stat = nullptr) {
;     ...
;     if (g) {
;         float s = 0.f, s2 = 0.f;
; #pragma unroll
;         for (int j = 0; j < 4; ++j) { s += (v[j][0] + v[j][1]) + (v[j][2] + v[j][3]); s2 += (v[j][0] * v[j][0] + v[j][1] * v[j][1]) + (v[j][2] * v[j][2] + v[j][3] * v[j][3]); }
;         wave_sum2(s, s2, F.lane);
;         const float mean = s * (1.f / D); const float rstd = 1.f / sqrtf(fmaxf(s2 * (1.f / D) - mean * mean, 0.f) + EPS);
;         if (stat && F.lane == 0) { f32x2 sv = {mean, rstd}; *(f32x2*)stat = sv; }
; #pragma unroll
;         for (int j = 0; j < 4; ++j) { const f32x4 gg = ((const f32x4*)g)[F.lane + 64 * j], bb = ((const f32x4*)b)[F.lane + 64 * j];
;             v[j] = (v[j] - mean) * rstd * gg + bb; if (xout) ((f32x4*)xout)[F.lane + 64 * j] = v[j]; }
;     }
;     if (hout) {
;         float s = 0.f, s2 = 0.f;
; #pragma unroll
;         for (int j = 0; j < 4; ++j) { s += (v[j][0] + v[j][1]) + (v[j][2] + v[j][3]); s2 += (v[j][0] * v[j][0] + v[j][1] * v[j][1]) + (v[j][2] * v[j][2] + v[j][3] * v[j][3]); }
;         wave_sum2(s, s2, F.lane);
;         const float mean = s * (1.f / D); const float rstd = 1.f / sqrtf(fmaxf(s2 * (1.f / D) - mean * mean, 0.f) + EPS);
; #pragma unroll
;         for (int j = 0; j < 4; ++j) { const f32x4 hh = ((const f32x4*)sh)[F.lane + 64 * j], cc = ((const f32x4*)sc)[F.lane + 64 * j];
;             const f32x4 o = (v[j] - mean) * rstd * (cc + 1.f) + hh; u32x2 wv; wv.x = pk2(o[0], o[1]); wv.y = pk2(o[2], o[3]);
;             ((u32x2*)hout)[F.lane + 64 * j] = wv; }
;     }
	v_pk_add_f32 v[64:65], v[64:65], v[92:93] op_sel:[0,1] op_sel_hi:[1,1] neg_lo:[0,1] neg_hi:[0,1]
	v_pk_add_f32 v[66:67], v[66:67], v[92:93] op_sel:[0,1] op_sel_hi:[1,1] neg_lo:[0,1] neg_hi:[0,1]
	v_pk_add_f32 v[68:69], v[68:69], v[92:93] op_sel:[0,1] op_sel_hi:[1,1] neg_lo:[0,1] neg_hi:[0,1]
	v_pk_add_f32 v[70:71], v[70:71], v[92:93] op_sel:[0,1] op_sel_hi:[1,1] neg_lo:[0,1] neg_hi:[0,1]
	v_pk_add_f32 v[72:73], v[72:73], v[92:93] op_sel:[0,1] op_sel_hi:[1,1] neg_lo:[0,1] neg_hi:[0,1]
	v_pk_mul_f32 v[58:59], v[58:59], v[94:95] op_sel_hi:[1,0]
	v_pk_mul_f32 v[60:61], v[60:61], v[94:95] op_sel_hi:[1,0]
	v_pk_mul_f32 v[62:63], v[62:63], v[94:95] op_sel_hi:[1,0]
	v_pk_mul_f32 v[64:65], v[64:65], v[94:95] op_sel_hi:[1,0]
	v_pk_mul_f32 v[66:67], v[66:67], v[94:95] op_sel_hi:[1,0]
	v_pk_mul_f32 v[68:69], v[68:69], v[94:95] op_sel_hi:[1,0]
	v_pk_mul_f32 v[70:71], v[70:71], v[94:95] op_sel_hi:[1,0]
	v_pk_mul_f32 v[72:73], v[72:73], v[94:95] op_sel_hi:[1,0]
	v_pk_fma_f32 v[58:59], v[58:59], v[10:11], v[26:27]
	v_pk_fma_f32 v[60:61], v[60:61], v[12:13], v[28:29]
	v_pk_fma_f32 v[62:63], v[62:63], v[14:15], v[30:31]
	v_pk_fma_f32 v[64:65], v[64:65], v[16:17], v[32:33]
	v_pk_fma_f32 v[66:67], v[66:67], v[18:19], v[34:35]
	v_pk_fma_f32 v[68:69], v[68:69], v[20:21], v[36:37]
	v_pk_fma_f32 v[70:71], v[70:71], v[22:23], v[38:39]
	v_pk_fma_f32 v[72:73], v[72:73], v[24:25], v[40:41]
	v_pk_add_f32 v[198:199], v[58:59], v[60:61]
	v_pk_mul_f32 v[200:201], v[58:59], v[58:59]
	v_pk_fma_f32 v[200:201], v[60:61], v[60:61], v[200:201]
	v_pk_add_f32 v[198:199], v[198:199], v[62:63]
	v_pk_fma_f32 v[200:201], v[62:63], v[62:63], v[200:201]
	v_pk_add_f32 v[198:199], v[198:199], v[64:65]
	v_pk_fma_f32 v[200:201], v[64:65], v[64:65], v[200:201]
	v_pk_add_f32 v[198:199], v[198:199], v[66:67]
	v_pk_fma_f32 v[200:201], v[66:67], v[66:67], v[200:201]
	v_pk_add_f32 v[198:199], v[198:199], v[68:69]
	v_pk_fma_f32 v[200:201], v[68:69], v[68:69], v[200:201]
	v_pk_add_f32 v[198:199], v[198:199], v[70:71]
	v_pk_fma_f32 v[200:201], v[70:71], v[70:71], v[200:201]
	v_pk_add_f32 v[198:199], v[198:199], v[72:73]
	v_pk_fma_f32 v[200:201], v[72:73], v[72:73], v[200:201]
	v_add_f32_e32 v9, v198, v199
	v_add_f32_e32 v90, v200, v201
	s_nop 1
	v_add_f32_dpp v9, v9, v9 quad_perm:[1,0,3,2] row_mask:0xf bank_mask:0xf
	v_add_f32_dpp v90, v90, v90 quad_perm:[1,0,3,2] row_mask:0xf bank_mask:0xf
	s_nop 0
	v_add_f32_dpp v9, v9, v9 quad_perm:[2,3,0,1] row_mask:0xf bank_mask:0xf
	v_add_f32_dpp v90, v90, v90 quad_perm:[2,3,0,1] row_mask:0xf bank_mask:0xf
	s_nop 0
	v_add_f32_dpp v9, v9, v9 row_half_mirror row_mask:0xf bank_mask:0xf
	v_add_f32_dpp v90, v90, v90 row_half_mirror row_mask:0xf bank_mask:0xf
	s_nop 0
	v_add_f32_dpp v9, v9, v9 row_mirror row_mask:0xf bank_mask:0xf
	v_add_f32_dpp v90, v90, v90 row_mirror row_mask:0xf bank_mask:0xf
	s_nop 0
	v_add_f32_dpp v9, v9, v9 row_bcast:15 row_mask:0xa bank_mask:0xf
	v_add_f32_dpp v90, v90, v90 row_bcast:15 row_mask:0xa bank_mask:0xf
	s_nop 0
	v_add_f32_dpp v9, v9, v9 row_bcast:31 row_mask:0xc bank_mask:0xf
	v_add_f32_dpp v90, v90, v90 row_bcast:31 row_mask:0xc bank_mask:0xf
	s_nop 0
	v_readlane_b32 s2, v9, 63
	v_readlane_b32 s3, v90, 63
	s_nop 1
	v_mov_b32_e32 v9, s2
	v_mov_b32_e32 v90, s3
	v_mul_f32_e32 v93, 0x3a800000, v9
	v_mul_f32_e32 v91, 0x3a800000, v90
	v_fma_f32 v91, -v93, v93, v91
	v_max_f32_e32 v91, 0, v91
	v_add_f32_e32 v91, 0x358637bd, v91
	v_rsq_f32_e32 v94, v91
	v_mul_f32_e32 v91, 0.5, v91
	v_mul_f32_e32 v92, v94, v94
	v_fma_f32 v92, -v91, v92, 0.5
	v_fma_f32 v94, v94, v92, v94
	v_pk_add_f32 v[58:59], v[58:59], v[92:93] op_sel:[0,1] op_sel_hi:[1,1] neg_lo:[0,1] neg_hi:[0,1]
	v_pk_add_f32 v[60:61], v[60:61], v[92:93] op_sel:[0,1] op_sel_hi:[1,1] neg_lo:[0,1] neg_hi:[0,1]
	v_pk_add_f32 v[62:63], v[62:63], v[92:93] op_sel:[0,1] op_sel_hi:[1,1] neg_lo:[0,1] neg_hi:[0,1]
	v_pk_add_f32 v[64:65], v[64:65], v[92:93] op_sel:[0,1] op_sel_hi:[1,1] neg_lo:[0,1] neg_hi:[0,1]
	v_pk_add_f32 v[66:67], v[66:67], v[92:93] op_sel:[0,1] op_sel_hi:[1,1] neg_lo:[0,1] neg_hi:[0,1]
	v_pk_add_f32 v[68:69], v[68:69], v[92:93] op_sel:[0,1] op_sel_hi:[1,1] neg_lo:[0,1] neg_hi:[0,1]
	v_pk_add_f32 v[70:71], v[70:71], v[92:93] op_sel:[0,1] op_sel_hi:[1,1] neg_lo:[0,1] neg_hi:[0,1]
	v_pk_add_f32 v[72:73], v[72:73], v[92:93] op_sel:[0,1] op_sel_hi:[1,1] neg_lo:[0,1] neg_hi:[0,1]
	v_pk_mul_f32 v[58:59], v[58:59], v[94:95] op_sel_hi:[1,0]
	v_pk_mul_f32 v[60:61], v[60:61], v[94:95] op_sel_hi:[1,0]
	v_pk_mul_f32 v[62:63], v[62:63], v[94:95] op_sel_hi:[1,0]
	v_pk_mul_f32 v[64:65], v[64:65], v[94:95] op_sel_hi:[1,0]
	v_pk_mul_f32 v[66:67], v[66:67], v[94:95] op_sel_hi:[1,0]
	v_pk_mul_f32 v[68:69], v[68:69], v[94:95] op_sel_hi:[1,0]
	v_pk_mul_f32 v[70:71], v[70:71], v[94:95] op_sel_hi:[1,0]
	v_pk_mul_f32 v[72:73], v[72:73], v[94:95] op_sel_hi:[1,0]
	v_pk_fma_f32 v[58:59], v[58:59], v[130:131], v[114:115]
	v_pk_fma_f32 v[60:61], v[60:61], v[132:133], v[116:117]
	v_pk_fma_f32 v[62:63], v[62:63], v[134:135], v[118:119]
	v_pk_fma_f32 v[64:65], v[64:65], v[136:137], v[120:121]
	v_pk_fma_f32 v[66:67], v[66:67], v[138:139], v[122:123]
	v_pk_fma_f32 v[68:69], v[68:69], v[140:141], v[124:125]
	v_pk_fma_f32 v[70:71], v[70:71], v[142:143], v[126:127]
	v_pk_fma_f32 v[72:73], v[72:73], v[144:145], v[128:129]
	v_cvt_pk_bf16_f32 v190, v58, v59
	v_cvt_pk_bf16_f32 v191, v60, v61
	v_cvt_pk_bf16_f32 v192, v62, v63
	v_cvt_pk_bf16_f32 v193, v64, v65
	v_cvt_pk_bf16_f32 v194, v66, v67
	v_cvt_pk_bf16_f32 v195, v68, v69
	v_cvt_pk_bf16_f32 v196, v70, v71
	v_cvt_pk_bf16_f32 v197, v72, v73
	s_add_u32 s2, s10, 0x800
	s_addc_u32 s3, s11, 0
	global_store_dwordx2 v1, v[190:191], s[2:3]
	global_store_dwordx2 v1, v[192:193], s[2:3] offset:512
	global_store_dwordx2 v1, v[194:195], s[2:3] offset:1024
	global_store_dwordx2 v1, v[196:197], s[2:3] offset:1536
	s_add_u32 s2, s8, 0x5000
	s_addc_u32 s3, s9, 0
	global_load_dwordx4 v[58:61], v0, s[2:3]
	global_load_dwordx4 v[62:65], v0, s[2:3] offset:1024
	global_load_dwordx4 v[66:69], v0, s[2:3] offset:2048
	global_load_dwordx4 v[70:73], v0, s[2:3] offset:3072
	s_waitcnt vmcnt(22)
; DI void ln_row_v(const Frame& F, f32x4 (&v)[4], float* xout, const float* g, const float* b, const float* sh, const float* sc, bf16_t* hout, const float* slab, const float* gres, float* stat = nullptr) {
;     ...
;         float s = 0.f, s2 = 0.f;
; #pragma unroll
;         for (int j = 0; j < 4; ++j) { s += (v[j][0] + v[j][1]) + (v[j][2] + v[j][3]); s2 += (v[j][0] * v[j][0] + v[j][1] * v[j][1]) + (v[j][2] * v[j][2] + v[j][3] * v[j][3]); }
;         wave_sum2(s, s2, F.lane);
;         const float mean = s * (1.f / D); const float rstd = 1.f / sqrtf(fmaxf(s2 * (1.f / D) - mean * mean, 0.f) + EPS);
;         if (stat && F.lane == 0) { f32x2 sv = {mean, rstd}; *(f32x2*)stat = sv; }
; #pragma unroll
;         for (int j = 0; j < 4; ++j) { const f32x4 gg = ((const f32x4*)g)[F.lane + 64 * j], bb = ((const f32x4*)b)[F.lane + 64 * j];
;             v[j] = (v[j] - mean) * rstd * gg + bb; if (xout) ((f32x4*)xout)[F.lane + 64 * j] = v[j]; }
;     }
;     if (hout) {
;         float s = 0.f, s2 = 0.f;
; #pragma unroll
;         for (int j = 0; j < 4; ++j) { s += (v[j][0] + v[j][1]) + (v[j][2] + v[j][3]); s2 += (v[j][0] * v[j][0] + v[j][1] * v[j][1]) + (v[j][2] * v[j][2] + v[j][3] * v[j][3]); }
;         wave_sum2(s, s2, F.lane);
;         const float mean = s * (1.f / D); const float rstd = 1.f / sqrtf(fmaxf(s2 * (1.f / D) - mean * mean, 0.f) + EPS);
	v_pk_add_f32 v[198:199], v[74:75], v[76:77]
	v_pk_mul_f32 v[200:201], v[74:75], v[74:75]
	v_pk_fma_f32 v[200:201], v[76:77], v[76:77], v[200:201]
	v_pk_add_f32 v[198:199], v[198:199], v[78:79]
	v_pk_fma_f32 v[200:201], v[78:79], v[78:79], v[200:201]
	v_pk_add_f32 v[198:199], v[198:199], v[80:81]
	v_pk_fma_f32 v[200:201], v[80:81], v[80:81], v[200:201]
	v_pk_add_f32 v[198:199], v[198:199], v[82:83]
	v_pk_fma_f32 v[200:201], v[82:83], v[82:83], v[200:201]
	v_pk_add_f32 v[198:199], v[198:199], v[84:85]
	v_pk_fma_f32 v[200:201], v[84:85], v[84:85], v[200:201]
	v_pk_add_f32 v[198:199], v[198:199], v[86:87]
	v_pk_fma_f32 v[200:201], v[86:87], v[86:87], v[200:201]
	v_pk_add_f32 v[198:199], v[198:199], v[88:89]
	v_pk_fma_f32 v[200:201], v[88:89], v[88:89], v[200:201]
	v_add_f32_e32 v9, v198, v199
	v_add_f32_e32 v90, v200, v201
	s_nop 1
	v_add_f32_dpp v9, v9, v9 quad_perm:[1,0,3,2] row_mask:0xf bank_mask:0xf
	v_add_f32_dpp v90, v90, v90 quad_perm:[1,0,3,2] row_mask:0xf bank_mask:0xf
	s_nop 0
	v_add_f32_dpp v9, v9, v9 quad_perm:[2,3,0,1] row_mask:0xf bank_mask:0xf
	v_add_f32_dpp v90, v90, v90 quad_perm:[2,3,0,1] row_mask:0xf bank_mask:0xf
	s_nop 0
	v_add_f32_dpp v9, v9, v9 row_half_mirror row_mask:0xf bank_mask:0xf
	v_add_f32_dpp v90, v90, v90 row_half_mirror row_mask:0xf bank_mask:0xf
	s_nop 0
	v_add_f32_dpp v9, v9, v9 row_mirror row_mask:0xf bank_mask:0xf
	v_add_f32_dpp v90, v90, v90 row_mirror row_mask:0xf bank_mask:0xf
	s_nop 0
	v_add_f32_dpp v9, v9, v9 row_bcast:15 row_mask:0xa bank_mask:0xf
	v_add_f32_dpp v90, v90, v90 row_bcast:15 row_mask:0xa bank_mask:0xf
	s_nop 0
	v_add_f32_dpp v9, v9, v9 row_bcast:31 row_mask:0xc bank_mask:0xf
	v_add_f32_dpp v90, v90, v90 row_bcast:31 row_mask:0xc bank_mask:0xf
	s_nop 0
	v_readlane_b32 s2, v9, 63
	v_readlane_b32 s3, v90, 63
	s_nop 1
	v_mov_b32_e32 v9, s2
	v_mov_b32_e32 v90, s3
	v_mul_f32_e32 v93, 0x3a800000, v9
	v_mul_f32_e32 v91, 0x3a800000, v90
	v_fma_f32 v91, -v93, v93, v91
	v_max_f32_e32 v91, 0, v91
	v_add_f32_e32 v91, 0x358637bd, v91
	v_rsq_f32_e32 v94, v91
	v_mul_f32_e32 v91, 0.5, v91
	v_mul_f32_e32 v92, v94, v94
	v_fma_f32 v92, -v91, v92, 0.5
	v_fma_f32 v94, v94, v92, v94
	s_add_u32 s2, s12, 0x10
	s_addc_u32 s3, s13, 0
	v_mov_b32_e32 v188, v93
	v_mov_b32_e32 v189, v94
	s_mov_b64 exec, 1
	global_store_dwordx2 v97, v[188:189], s[2:3]
	s_mov_b64 exec, -1
	v_pk_add_f32 v[74:75], v[74:75], v[92:93] op_sel:[0,1] op_sel_hi:[1,1] neg_lo:[0,1] neg_hi:[0,1]
	v_pk_add_f32 v[76:77], v[76:77], v[92:93] op_sel:[0,1] op_sel_hi:[1,1] neg_lo:[0,1] neg_hi:[0,1]
	v_pk_add_f32 v[78:79], v[78:79], v[92:93] op_sel:[0,1] op_sel_hi:[1,1] neg_lo:[0,1] neg_hi:[0,1]
	v_pk_add_f32 v[80:81], v[80:81], v[92:93] op_sel:[0,1] op_sel_hi:[1,1] neg_lo:[0,1] neg_hi:[0,1]
	v_pk_add_f32 v[82:83], v[82:83], v[92:93] op_sel:[0,1] op_sel_hi:[1,1] neg_lo:[0,1] neg_hi:[0,1]
	v_pk_add_f32 v[84:85], v[84:85], v[92:93] op_sel:[0,1] op_sel_hi:[1,1] neg_lo:[0,1] neg_hi:[0,1]
	v_pk_add_f32 v[86:87], v[86:87], v[92:93] op_sel:[0,1] op_sel_hi:[1,1] neg_lo:[0,1] neg_hi:[0,1]
	v_pk_add_f32 v[88:89], v[88:89], v[92:93] op_sel:[0,1] op_sel_hi:[1,1] neg_lo:[0,1] neg_hi:[0,1]
	v_pk_mul_f32 v[74:75], v[74:75], v[94:95] op_sel_hi:[1,0]
	v_pk_mul_f32 v[76:77], v[76:77], v[94:95] op_sel_hi:[1,0]
	v_pk_mul_f32 v[78:79], v[78:79], v[94:95] op_sel_hi:[1,0]
	v_pk_mul_f32 v[80:81], v[80:81], v[94:95] op_sel_hi:[1,0]
	v_pk_mul_f32 v[82:83], v[82:83], v[94:95] op_sel_hi:[1,0]
	v_pk_mul_f32 v[84:85], v[84:85], v[94:95] op_sel_hi:[1,0]
	v_pk_mul_f32 v[86:87], v[86:87], v[94:95] op_sel_hi:[1,0]
	v_pk_mul_f32 v[88:89], v[88:89], v[94:95] op_sel_hi:[1,0]
	v_pk_fma_f32 v[74:75], v[74:75], v[10:11], v[26:27]
	v_pk_fma_f32 v[76:77], v[76:77], v[12:13], v[28:29]
	v_pk_fma_f32 v[78:79], v[78:79], v[14:15], v[30:31]
	v_pk_fma_f32 v[80:81], v[80:81], v[16:17], v[32:33]
	v_pk_fma_f32 v[82:83], v[82:83], v[18:19], v[34:35]
	v_pk_fma_f32 v[84:85], v[84:85], v[20:21], v[36:37]
	v_pk_fma_f32 v[86:87], v[86:87], v[22:23], v[38:39]
	v_pk_fma_f32 v[88:89], v[88:89], v[24:25], v[40:41]
	v_pk_add_f32 v[198:199], v[74:75], v[76:77]
	v_pk_mul_f32 v[200:201], v[74:75], v[74:75]
	v_pk_fma_f32 v[200:201], v[76:77], v[76:77], v[200:201]
	v_pk_add_f32 v[198:199], v[198:199], v[78:79]
	v_pk_fma_f32 v[200:201], v[78:79], v[78:79], v[200:201]
	v_pk_add_f32 v[198:199], v[198:199], v[80:81]
	v_pk_fma_f32 v[200:201], v[80:81], v[80:81], v[200:201]
	v_pk_add_f32 v[198:199], v[198:199], v[82:83]
	v_pk_fma_f32 v[200:201], v[82:83], v[82:83], v[200:201]
	v_pk_add_f32 v[198:199], v[198:199], v[84:85]
	v_pk_fma_f32 v[200:201], v[84:85], v[84:85], v[200:201]
	v_pk_add_f32 v[198:199], v[198:199], v[86:87]
	v_pk_fma_f32 v[200:201], v[86:87], v[86:87], v[200:201]
	v_pk_add_f32 v[198:199], v[198:199], v[88:89]
	v_pk_fma_f32 v[200:201], v[88:89], v[88:89], v[200:201]
	v_add_f32_e32 v9, v198, v199
	v_add_f32_e32 v90, v200, v201
	s_nop 1
	v_add_f32_dpp v9, v9, v9 quad_perm:[1,0,3,2] row_mask:0xf bank_mask:0xf
	v_add_f32_dpp v90, v90, v90 quad_perm:[1,0,3,2] row_mask:0xf bank_mask:0xf
	s_nop 0
	v_add_f32_dpp v9, v9, v9 quad_perm:[2,3,0,1] row_mask:0xf bank_mask:0xf
	v_add_f32_dpp v90, v90, v90 quad_perm:[2,3,0,1] row_mask:0xf bank_mask:0xf
	s_nop 0
	v_add_f32_dpp v9, v9, v9 row_half_mirror row_mask:0xf bank_mask:0xf
	v_add_f32_dpp v90, v90, v90 row_half_mirror row_mask:0xf bank_mask:0xf
	s_nop 0
	v_add_f32_dpp v9, v9, v9 row_mirror row_mask:0xf bank_mask:0xf
	v_add_f32_dpp v90, v90, v90 row_mirror row_mask:0xf bank_mask:0xf
	s_nop 0
	v_add_f32_dpp v9, v9, v9 row_bcast:15 row_mask:0xa bank_mask:0xf
	v_add_f32_dpp v90, v90, v90 row_bcast:15 row_mask:0xa bank_mask:0xf
	s_nop 0
	v_add_f32_dpp v9, v9, v9 row_bcast:31 row_mask:0xc bank_mask:0xf
; DI unsigned pk2(float lo, float hi) { f32x2 v = {lo, hi}; bf16x2_t b = __builtin_convertvector(v, bf16x2_t); return __builtin_bit_cast(unsigned, b); }
; DI void ln_row_v(const Frame& F, f32x4 (&v)[4], float* xout, const float* g, const float* b, const float* sh, const float* sc, bf16_t* hout, const float* slab, const float* gres, float* stat = nullptr) {
;     ...
;         float s = 0.f, s2 = 0.f;
; #pragma unroll
;         for (int j = 0; j < 4; ++j) { s += (v[j][0] + v[j][1]) + (v[j][2] + v[j][3]); s2 += (v[j][0] * v[j][0] + v[j][1] * v[j][1]) + (v[j][2] * v[j][2] + v[j][3] * v[j][3]); }
;         wave_sum2(s, s2, F.lane);
;         const float mean = s * (1.f / D); const float rstd = 1.f / sqrtf(fmaxf(s2 * (1.f / D) - mean * mean, 0.f) + EPS);
;         if (stat && F.lane == 0) { f32x2 sv = {mean, rstd}; *(f32x2*)stat = sv; }
; #pragma unroll
;         for (int j = 0; j < 4; ++j) { const f32x4 gg = ((const f32x4*)g)[F.lane + 64 * j], bb = ((const f32x4*)b)[F.lane + 64 * j];
;             v[j] = (v[j] - mean) * rstd * gg + bb; if (xout) ((f32x4*)xout)[F.lane + 64 * j] = v[j]; }
;     ...
;         const float mean = s * (1.f / D); const float rstd = 1.f / sqrtf(fmaxf(s2 * (1.f / D) - mean * mean, 0.f) + EPS);
; #pragma unroll
;         for (int j = 0; j < 4; ++j) { const f32x4 hh = ((const f32x4*)sh)[F.lane + 64 * j], cc = ((const f32x4*)sc)[F.lane + 64 * j];
;             const f32x4 o = (v[j] - mean) * rstd * (cc + 1.f) + hh; u32x2 wv; wv.x = pk2(o[0], o[1]); wv.y = pk2(o[2], o[3]);
;             ((u32x2*)hout)[F.lane + 64 * j] = wv; }
	v_add_f32_dpp v90, v90, v90 row_bcast:31 row_mask:0xc bank_mask:0xf
	s_nop 0
	v_readlane_b32 s2, v9, 63
	v_readlane_b32 s3, v90, 63
	s_nop 1
	v_mov_b32_e32 v9, s2
	v_mov_b32_e32 v90, s3
	v_mul_f32_e32 v93, 0x3a800000, v9
	v_mul_f32_e32 v91, 0x3a800000, v90
	v_fma_f32 v91, -v93, v93, v91
	v_max_f32_e32 v91, 0, v91
	v_add_f32_e32 v91, 0x358637bd, v91
	v_rsq_f32_e32 v94, v91
	v_mul_f32_e32 v91, 0.5, v91
	v_mul_f32_e32 v92, v94, v94
	v_fma_f32 v92, -v91, v92, 0.5
	v_fma_f32 v94, v94, v92, v94
	v_pk_add_f32 v[74:75], v[74:75], v[92:93] op_sel:[0,1] op_sel_hi:[1,1] neg_lo:[0,1] neg_hi:[0,1]
	v_pk_add_f32 v[76:77], v[76:77], v[92:93] op_sel:[0,1] op_sel_hi:[1,1] neg_lo:[0,1] neg_hi:[0,1]
	v_pk_add_f32 v[78:79], v[78:79], v[92:93] op_sel:[0,1] op_sel_hi:[1,1] neg_lo:[0,1] neg_hi:[0,1]
	v_pk_add_f32 v[80:81], v[80:81], v[92:93] op_sel:[0,1] op_sel_hi:[1,1] neg_lo:[0,1] neg_hi:[0,1]
	v_pk_add_f32 v[82:83], v[82:83], v[92:93] op_sel:[0,1] op_sel_hi:[1,1] neg_lo:[0,1] neg_hi:[0,1]
	v_pk_add_f32 v[84:85], v[84:85], v[92:93] op_sel:[0,1] op_sel_hi:[1,1] neg_lo:[0,1] neg_hi:[0,1]
	v_pk_add_f32 v[86:87], v[86:87], v[92:93] op_sel:[0,1] op_sel_hi:[1,1] neg_lo:[0,1] neg_hi:[0,1]
	v_pk_add_f32 v[88:89], v[88:89], v[92:93] op_sel:[0,1] op_sel_hi:[1,1] neg_lo:[0,1] neg_hi:[0,1]
	v_pk_mul_f32 v[74:75], v[74:75], v[94:95] op_sel_hi:[1,0]
	v_pk_mul_f32 v[76:77], v[76:77], v[94:95] op_sel_hi:[1,0]
	v_pk_mul_f32 v[78:79], v[78:79], v[94:95] op_sel_hi:[1,0]
	v_pk_mul_f32 v[80:81], v[80:81], v[94:95] op_sel_hi:[1,0]
	v_pk_mul_f32 v[82:83], v[82:83], v[94:95] op_sel_hi:[1,0]
	v_pk_mul_f32 v[84:85], v[84:85], v[94:95] op_sel_hi:[1,0]
	v_pk_mul_f32 v[86:87], v[86:87], v[94:95] op_sel_hi:[1,0]
	v_pk_mul_f32 v[88:89], v[88:89], v[94:95] op_sel_hi:[1,0]
	v_pk_fma_f32 v[74:75], v[74:75], v[130:131], v[114:115]
	v_pk_fma_f32 v[76:77], v[76:77], v[132:133], v[116:117]
	v_pk_fma_f32 v[78:79], v[78:79], v[134:135], v[118:119]
	v_pk_fma_f32 v[80:81], v[80:81], v[136:137], v[120:121]
	v_pk_fma_f32 v[82:83], v[82:83], v[138:139], v[122:123]
	v_pk_fma_f32 v[84:85], v[84:85], v[140:141], v[124:125]
	v_pk_fma_f32 v[86:87], v[86:87], v[142:143], v[126:127]
	v_pk_fma_f32 v[88:89], v[88:89], v[144:145], v[128:129]
	v_cvt_pk_bf16_f32 v190, v74, v75
	v_cvt_pk_bf16_f32 v191, v76, v77
	v_cvt_pk_bf16_f32 v192, v78, v79
	v_cvt_pk_bf16_f32 v193, v80, v81
	v_cvt_pk_bf16_f32 v194, v82, v83
	v_cvt_pk_bf16_f32 v195, v84, v85
	v_cvt_pk_bf16_f32 v196, v86, v87
	v_cvt_pk_bf16_f32 v197, v88, v89
	s_add_u32 s2, s10, 0x1000
	s_addc_u32 s3, s11, 0
	global_store_dwordx2 v1, v[190:191], s[2:3]
	global_store_dwordx2 v1, v[192:193], s[2:3] offset:512
	global_store_dwordx2 v1, v[194:195], s[2:3] offset:1024
	global_store_dwordx2 v1, v[196:197], s[2:3] offset:1536
	s_add_u32 s2, s8, 0x6000
	s_addc_u32 s3, s9, 0
	global_load_dwordx4 v[74:77], v0, s[2:3]
	global_load_dwordx4 v[78:81], v0, s[2:3] offset:1024
	global_load_dwordx4 v[82:85], v0, s[2:3] offset:2048
	global_load_dwordx4 v[86:89], v0, s[2:3] offset:3072
	s_waitcnt vmcnt(27)
	v_pk_add_f32 v[198:199], v[98:99], v[100:101]
	v_pk_mul_f32 v[200:201], v[98:99], v[98:99]
	v_pk_fma_f32 v[200:201], v[100:101], v[100:101], v[200:201]
	v_pk_add_f32 v[198:199], v[198:199], v[102:103]
	v_pk_fma_f32 v[200:201], v[102:103], v[102:103], v[200:201]
	v_pk_add_f32 v[198:199], v[198:199], v[104:105]
	v_pk_fma_f32 v[200:201], v[104:105], v[104:105], v[200:201]
	v_pk_add_f32 v[198:199], v[198:199], v[106:107]
	v_pk_fma_f32 v[200:201], v[106:107], v[106:107], v[200:201]
	v_pk_add_f32 v[198:199], v[198:199], v[108:109]
	v_pk_fma_f32 v[200:201], v[108:109], v[108:109], v[200:201]
	v_pk_add_f32 v[198:199], v[198:199], v[110:111]
	v_pk_fma_f32 v[200:201], v[110:111], v[110:111], v[200:201]
	v_pk_add_f32 v[198:199], v[198:199], v[112:113]
	v_pk_fma_f32 v[200:201], v[112:113], v[112:113], v[200:201]
	v_add_f32_e32 v9, v198, v199
	v_add_f32_e32 v90, v200, v201
	s_nop 1
	v_add_f32_dpp v9, v9, v9 quad_perm:[1,0,3,2] row_mask:0xf bank_mask:0xf
	v_add_f32_dpp v90, v90, v90 quad_perm:[1,0,3,2] row_mask:0xf bank_mask:0xf
	s_nop 0
	v_add_f32_dpp v9, v9, v9 quad_perm:[2,3,0,1] row_mask:0xf bank_mask:0xf
	v_add_f32_dpp v90, v90, v90 quad_perm:[2,3,0,1] row_mask:0xf bank_mask:0xf
	s_nop 0
	v_add_f32_dpp v9, v9, v9 row_half_mirror row_mask:0xf bank_mask:0xf
	v_add_f32_dpp v90, v90, v90 row_half_mirror row_mask:0xf bank_mask:0xf
	s_nop 0
	v_add_f32_dpp v9, v9, v9 row_mirror row_mask:0xf bank_mask:0xf
	v_add_f32_dpp v90, v90, v90 row_mirror row_mask:0xf bank_mask:0xf
	s_nop 0
	v_add_f32_dpp v9, v9, v9 row_bcast:15 row_mask:0xa bank_mask:0xf
	v_add_f32_dpp v90, v90, v90 row_bcast:15 row_mask:0xa bank_mask:0xf
	s_nop 0
	v_add_f32_dpp v9, v9, v9 row_bcast:31 row_mask:0xc bank_mask:0xf
	v_add_f32_dpp v90, v90, v90 row_bcast:31 row_mask:0xc bank_mask:0xf
	s_nop 0
	v_readlane_b32 s2, v9, 63
	v_readlane_b32 s3, v90, 63
	s_nop 1
	v_mov_b32_e32 v9, s2
	v_mov_b32_e32 v90, s3
	v_mul_f32_e32 v93, 0x3a800000, v9
	v_mul_f32_e32 v91, 0x3a800000, v90
	v_fma_f32 v91, -v93, v93, v91
	v_max_f32_e32 v91, 0, v91
	v_add_f32_e32 v91, 0x358637bd, v91
	v_rsq_f32_e32 v94, v91
	v_mul_f32_e32 v91, 0.5, v91
	v_mul_f32_e32 v92, v94, v94
	v_fma_f32 v92, -v91, v92, 0.5
	v_fma_f32 v94, v94, v92, v94
	s_add_u32 s2, s12, 0x18
	s_addc_u32 s3, s13, 0
	v_mov_b32_e32 v188, v93
	v_mov_b32_e32 v189, v94
	s_mov_b64 exec, 1
	global_store_dwordx2 v97, v[188:189], s[2:3]
	s_mov_b64 exec, -1
	v_pk_add_f32 v[98:99], v[98:99], v[92:93] op_sel:[0,1] op_sel_hi:[1,1] neg_lo:[0,1] neg_hi:[0,1]
	v_pk_add_f32 v[100:101], v[100:101], v[92:93] op_sel:[0,1] op_sel_hi:[1,1] neg_lo:[0,1] neg_hi:[0,1]
; DI unsigned pk2(float lo, float hi) { f32x2 v = {lo, hi}; bf16x2_t b = __builtin_convertvector(v, bf16x2_t); return __builtin_bit_cast(unsigned, b); }
; DI void ln_row_v(const Frame& F, f32x4 (&v)[4], float* xout, const float* g, const float* b, const float* sh, const float* sc, bf16_t* hout, const float* slab, const float* gres, float* stat = nullptr) {
;     ...
;         float s = 0.f, s2 = 0.f;
; #pragma unroll
;         for (int j = 0; j < 4; ++j) { s += (v[j][0] + v[j][1]) + (v[j][2] + v[j][3]); s2 += (v[j][0] * v[j][0] + v[j][1] * v[j][1]) + (v[j][2] * v[j][2] + v[j][3] * v[j][3]); }
;         wave_sum2(s, s2, F.lane);
;         const float mean = s * (1.f / D); const float rstd = 1.f / sqrtf(fmaxf(s2 * (1.f / D) - mean * mean, 0.f) + EPS);
;         if (stat && F.lane == 0) { f32x2 sv = {mean, rstd}; *(f32x2*)stat = sv; }
; #pragma unroll
;         for (int j = 0; j < 4; ++j) { const f32x4 gg = ((const f32x4*)g)[F.lane + 64 * j], bb = ((const f32x4*)b)[F.lane + 64 * j];
;             v[j] = (v[j] - mean) * rstd * gg + bb; if (xout) ((f32x4*)xout)[F.lane + 64 * j] = v[j]; }
;     }
;     if (hout) {
;         float s = 0.f, s2 = 0.f;
; #pragma unroll
;         for (int j = 0; j < 4; ++j) { s += (v[j][0] + v[j][1]) + (v[j][2] + v[j][3]); s2 += (v[j][0] * v[j][0] + v[j][1] * v[j][1]) + (v[j][2] * v[j][2] + v[j][3] * v[j][3]); }
;         wave_sum2(s, s2, F.lane);
;         const float mean = s * (1.f / D); const float rstd = 1.f / sqrtf(fmaxf(s2 * (1.f / D) - mean * mean, 0.f) + EPS);
; #pragma unroll
;         for (int j = 0; j < 4; ++j) { const f32x4 hh = ((const f32x4*)sh)[F.lane + 64 * j], cc = ((const f32x4*)sc)[F.lane + 64 * j];
;             const f32x4 o = (v[j] - mean) * rstd * (cc + 1.f) + hh; u32x2 wv; wv.x = pk2(o[0], o[1]); wv.y = pk2(o[2], o[3]);
;             ((u32x2*)hout)[F.lane + 64 * j] = wv; }
	v_pk_add_f32 v[102:103], v[102:103], v[92:93] op_sel:[0,1] op_sel_hi:[1,1] neg_lo:[0,1] neg_hi:[0,1]
	v_pk_add_f32 v[104:105], v[104:105], v[92:93] op_sel:[0,1] op_sel_hi:[1,1] neg_lo:[0,1] neg_hi:[0,1]
	v_pk_add_f32 v[106:107], v[106:107], v[92:93] op_sel:[0,1] op_sel_hi:[1,1] neg_lo:[0,1] neg_hi:[0,1]
	v_pk_add_f32 v[108:109], v[108:109], v[92:93] op_sel:[0,1] op_sel_hi:[1,1] neg_lo:[0,1] neg_hi:[0,1]
	v_pk_add_f32 v[110:111], v[110:111], v[92:93] op_sel:[0,1] op_sel_hi:[1,1] neg_lo:[0,1] neg_hi:[0,1]
	v_pk_add_f32 v[112:113], v[112:113], v[92:93] op_sel:[0,1] op_sel_hi:[1,1] neg_lo:[0,1] neg_hi:[0,1]
	v_pk_mul_f32 v[98:99], v[98:99], v[94:95] op_sel_hi:[1,0]
	v_pk_mul_f32 v[100:101], v[100:101], v[94:95] op_sel_hi:[1,0]
	v_pk_mul_f32 v[102:103], v[102:103], v[94:95] op_sel_hi:[1,0]
	v_pk_mul_f32 v[104:105], v[104:105], v[94:95] op_sel_hi:[1,0]
	v_pk_mul_f32 v[106:107], v[106:107], v[94:95] op_sel_hi:[1,0]
	v_pk_mul_f32 v[108:109], v[108:109], v[94:95] op_sel_hi:[1,0]
	v_pk_mul_f32 v[110:111], v[110:111], v[94:95] op_sel_hi:[1,0]
	v_pk_mul_f32 v[112:113], v[112:113], v[94:95] op_sel_hi:[1,0]
	v_pk_fma_f32 v[98:99], v[98:99], v[10:11], v[26:27]
	v_pk_fma_f32 v[100:101], v[100:101], v[12:13], v[28:29]
	v_pk_fma_f32 v[102:103], v[102:103], v[14:15], v[30:31]
	v_pk_fma_f32 v[104:105], v[104:105], v[16:17], v[32:33]
	v_pk_fma_f32 v[106:107], v[106:107], v[18:19], v[34:35]
	v_pk_fma_f32 v[108:109], v[108:109], v[20:21], v[36:37]
	v_pk_fma_f32 v[110:111], v[110:111], v[22:23], v[38:39]
	v_pk_fma_f32 v[112:113], v[112:113], v[24:25], v[40:41]
	v_pk_add_f32 v[198:199], v[98:99], v[100:101]
	v_pk_mul_f32 v[200:201], v[98:99], v[98:99]
	v_pk_fma_f32 v[200:201], v[100:101], v[100:101], v[200:201]
	v_pk_add_f32 v[198:199], v[198:199], v[102:103]
	v_pk_fma_f32 v[200:201], v[102:103], v[102:103], v[200:201]
	v_pk_add_f32 v[198:199], v[198:199], v[104:105]
	v_pk_fma_f32 v[200:201], v[104:105], v[104:105], v[200:201]
	v_pk_add_f32 v[198:199], v[198:199], v[106:107]
	v_pk_fma_f32 v[200:201], v[106:107], v[106:107], v[200:201]
	v_pk_add_f32 v[198:199], v[198:199], v[108:109]
	v_pk_fma_f32 v[200:201], v[108:109], v[108:109], v[200:201]
	v_pk_add_f32 v[198:199], v[198:199], v[110:111]
	v_pk_fma_f32 v[200:201], v[110:111], v[110:111], v[200:201]
	v_pk_add_f32 v[198:199], v[198:199], v[112:113]
	v_pk_fma_f32 v[200:201], v[112:113], v[112:113], v[200:201]
	v_add_f32_e32 v9, v198, v199
	v_add_f32_e32 v90, v200, v201
	s_nop 1
	v_add_f32_dpp v9, v9, v9 quad_perm:[1,0,3,2] row_mask:0xf bank_mask:0xf
	v_add_f32_dpp v90, v90, v90 quad_perm:[1,0,3,2] row_mask:0xf bank_mask:0xf
	s_nop 0
	v_add_f32_dpp v9, v9, v9 quad_perm:[2,3,0,1] row_mask:0xf bank_mask:0xf
	v_add_f32_dpp v90, v90, v90 quad_perm:[2,3,0,1] row_mask:0xf bank_mask:0xf
	s_nop 0
	v_add_f32_dpp v9, v9, v9 row_half_mirror row_mask:0xf bank_mask:0xf
	v_add_f32_dpp v90, v90, v90 row_half_mirror row_mask:0xf bank_mask:0xf
	s_nop 0
	v_add_f32_dpp v9, v9, v9 row_mirror row_mask:0xf bank_mask:0xf
	v_add_f32_dpp v90, v90, v90 row_mirror row_mask:0xf bank_mask:0xf
	s_nop 0
	v_add_f32_dpp v9, v9, v9 row_bcast:15 row_mask:0xa bank_mask:0xf
	v_add_f32_dpp v90, v90, v90 row_bcast:15 row_mask:0xa bank_mask:0xf
	s_nop 0
	v_add_f32_dpp v9, v9, v9 row_bcast:31 row_mask:0xc bank_mask:0xf
	v_add_f32_dpp v90, v90, v90 row_bcast:31 row_mask:0xc bank_mask:0xf
	s_nop 0
	v_readlane_b32 s2, v9, 63
	v_readlane_b32 s3, v90, 63
	s_nop 1
	v_mov_b32_e32 v9, s2
	v_mov_b32_e32 v90, s3
	v_mul_f32_e32 v93, 0x3a800000, v9
	v_mul_f32_e32 v91, 0x3a800000, v90
	v_fma_f32 v91, -v93, v93, v91
	v_max_f32_e32 v91, 0, v91
	v_add_f32_e32 v91, 0x358637bd, v91
	v_rsq_f32_e32 v94, v91
	v_mul_f32_e32 v91, 0.5, v91
	v_mul_f32_e32 v92, v94, v94
	v_fma_f32 v92, -v91, v92, 0.5
	v_fma_f32 v94, v94, v92, v94
	v_pk_add_f32 v[98:99], v[98:99], v[92:93] op_sel:[0,1] op_sel_hi:[1,1] neg_lo:[0,1] neg_hi:[0,1]
	v_pk_add_f32 v[100:101], v[100:101], v[92:93] op_sel:[0,1] op_sel_hi:[1,1] neg_lo:[0,1] neg_hi:[0,1]
	v_pk_add_f32 v[102:103], v[102:103], v[92:93] op_sel:[0,1] op_sel_hi:[1,1] neg_lo:[0,1] neg_hi:[0,1]
	v_pk_add_f32 v[104:105], v[104:105], v[92:93] op_sel:[0,1] op_sel_hi:[1,1] neg_lo:[0,1] neg_hi:[0,1]
	v_pk_add_f32 v[106:107], v[106:107], v[92:93] op_sel:[0,1] op_sel_hi:[1,1] neg_lo:[0,1] neg_hi:[0,1]
	v_pk_add_f32 v[108:109], v[108:109], v[92:93] op_sel:[0,1] op_sel_hi:[1,1] neg_lo:[0,1] neg_hi:[0,1]
	v_pk_add_f32 v[110:111], v[110:111], v[92:93] op_sel:[0,1] op_sel_hi:[1,1] neg_lo:[0,1] neg_hi:[0,1]
	v_pk_add_f32 v[112:113], v[112:113], v[92:93] op_sel:[0,1] op_sel_hi:[1,1] neg_lo:[0,1] neg_hi:[0,1]
	v_pk_mul_f32 v[98:99], v[98:99], v[94:95] op_sel_hi:[1,0]
	v_pk_mul_f32 v[100:101], v[100:101], v[94:95] op_sel_hi:[1,0]
	v_pk_mul_f32 v[102:103], v[102:103], v[94:95] op_sel_hi:[1,0]
	v_pk_mul_f32 v[104:105], v[104:105], v[94:95] op_sel_hi:[1,0]
	v_pk_mul_f32 v[106:107], v[106:107], v[94:95] op_sel_hi:[1,0]
	v_pk_mul_f32 v[108:109], v[108:109], v[94:95] op_sel_hi:[1,0]
	v_pk_mul_f32 v[110:111], v[110:111], v[94:95] op_sel_hi:[1,0]
	v_pk_mul_f32 v[112:113], v[112:113], v[94:95] op_sel_hi:[1,0]
	v_pk_fma_f32 v[98:99], v[98:99], v[130:131], v[114:115]
	v_pk_fma_f32 v[100:101], v[100:101], v[132:133], v[116:117]
	v_pk_fma_f32 v[102:103], v[102:103], v[134:135], v[118:119]
	v_pk_fma_f32 v[104:105], v[104:105], v[136:137], v[120:121]
	v_pk_fma_f32 v[106:107], v[106:107], v[138:139], v[122:123]
	v_pk_fma_f32 v[108:109], v[108:109], v[140:141], v[124:125]
	v_pk_fma_f32 v[110:111], v[110:111], v[142:143], v[126:127]
	v_pk_fma_f32 v[112:113], v[112:113], v[144:145], v[128:129]
	v_cvt_pk_bf16_f32 v190, v98, v99
	v_cvt_pk_bf16_f32 v191, v100, v101
	v_cvt_pk_bf16_f32 v192, v102, v103
	v_cvt_pk_bf16_f32 v193, v104, v105
	v_cvt_pk_bf16_f32 v194, v106, v107
	v_cvt_pk_bf16_f32 v195, v108, v109
	v_cvt_pk_bf16_f32 v196, v110, v111
	v_cvt_pk_bf16_f32 v197, v112, v113
	s_add_u32 s2, s10, 0x1800
	s_addc_u32 s3, s11, 0
	global_store_dwordx2 v1, v[190:191], s[2:3]
	global_store_dwordx2 v1, v[192:193], s[2:3] offset:512
	global_store_dwordx2 v1, v[194:195], s[2:3] offset:1024
	global_store_dwordx2 v1, v[196:197], s[2:3] offset:1536
	s_add_u32 s2, s8, 0x7000
	s_addc_u32 s3, s9, 0
	global_load_dwordx4 v[98:101], v0, s[2:3]
	global_load_dwordx4 v[102:105], v0, s[2:3] offset:1024
	global_load_dwordx4 v[106:109], v0, s[2:3] offset:2048
	global_load_dwordx4 v[110:113], v0, s[2:3] offset:3072
	s_waitcnt vmcnt(27)
; DI void ln_row_v(const Frame& F, f32x4 (&v)[4], float* xout, const float* g, const float* b, const float* sh, const float* sc, bf16_t* hout, const float* slab, const float* gres, float* stat = nullptr) {
;     ...
;         float s = 0.f, s2 = 0.f;
; #pragma unroll
;         for (int j = 0; j < 4; ++j) { s += (v[j][0] + v[j][1]) + (v[j][2] + v[j][3]); s2 += (v[j][0] * v[j][0] + v[j][1] * v[j][1]) + (v[j][2] * v[j][2] + v[j][3] * v[j][3]); }
;         wave_sum2(s, s2, F.lane);
;         const float mean = s * (1.f / D); const float rstd = 1.f / sqrtf(fmaxf(s2 * (1.f / D) - mean * mean, 0.f) + EPS);
;         if (stat && F.lane == 0) { f32x2 sv = {mean, rstd}; *(f32x2*)stat = sv; }
; #pragma unroll
;         for (int j = 0; j < 4; ++j) { const f32x4 gg = ((const f32x4*)g)[F.lane + 64 * j], bb = ((const f32x4*)b)[F.lane + 64 * j];
;             v[j] = (v[j] - mean) * rstd * gg + bb; if (xout) ((f32x4*)xout)[F.lane + 64 * j] = v[j]; }
;     }
;     if (hout) {
;         float s = 0.f, s2 = 0.f;
; #pragma unroll
;         for (int j = 0; j < 4; ++j) { s += (v[j][0] + v[j][1]) + (v[j][2] + v[j][3]); s2 += (v[j][0] * v[j][0] + v[j][1] * v[j][1]) + (v[j][2] * v[j][2] + v[j][3] * v[j][3]); }
;         wave_sum2(s, s2, F.lane);
;         const float mean = s * (1.f / D); const float rstd = 1.f / sqrtf(fmaxf(s2 * (1.f / D) - mean * mean, 0.f) + EPS);
	v_pk_add_f32 v[198:199], v[42:43], v[44:45]
	v_pk_mul_f32 v[200:201], v[42:43], v[42:43]
	v_pk_fma_f32 v[200:201], v[44:45], v[44:45], v[200:201]
	v_pk_add_f32 v[198:199], v[198:199], v[46:47]
	v_pk_fma_f32 v[200:201], v[46:47], v[46:47], v[200:201]
	v_pk_add_f32 v[198:199], v[198:199], v[48:49]
	v_pk_fma_f32 v[200:201], v[48:49], v[48:49], v[200:201]
	v_pk_add_f32 v[198:199], v[198:199], v[50:51]
	v_pk_fma_f32 v[200:201], v[50:51], v[50:51], v[200:201]
	v_pk_add_f32 v[198:199], v[198:199], v[52:53]
	v_pk_fma_f32 v[200:201], v[52:53], v[52:53], v[200:201]
	v_pk_add_f32 v[198:199], v[198:199], v[54:55]
	v_pk_fma_f32 v[200:201], v[54:55], v[54:55], v[200:201]
	v_pk_add_f32 v[198:199], v[198:199], v[56:57]
	v_pk_fma_f32 v[200:201], v[56:57], v[56:57], v[200:201]
	v_add_f32_e32 v9, v198, v199
	v_add_f32_e32 v90, v200, v201
	s_nop 1
	v_add_f32_dpp v9, v9, v9 quad_perm:[1,0,3,2] row_mask:0xf bank_mask:0xf
	v_add_f32_dpp v90, v90, v90 quad_perm:[1,0,3,2] row_mask:0xf bank_mask:0xf
	s_nop 0
	v_add_f32_dpp v9, v9, v9 quad_perm:[2,3,0,1] row_mask:0xf bank_mask:0xf
	v_add_f32_dpp v90, v90, v90 quad_perm:[2,3,0,1] row_mask:0xf bank_mask:0xf
	s_nop 0
	v_add_f32_dpp v9, v9, v9 row_half_mirror row_mask:0xf bank_mask:0xf
	v_add_f32_dpp v90, v90, v90 row_half_mirror row_mask:0xf bank_mask:0xf
	s_nop 0
	v_add_f32_dpp v9, v9, v9 row_mirror row_mask:0xf bank_mask:0xf
	v_add_f32_dpp v90, v90, v90 row_mirror row_mask:0xf bank_mask:0xf
	s_nop 0
	v_add_f32_dpp v9, v9, v9 row_bcast:15 row_mask:0xa bank_mask:0xf
	v_add_f32_dpp v90, v90, v90 row_bcast:15 row_mask:0xa bank_mask:0xf
	s_nop 0
	v_add_f32_dpp v9, v9, v9 row_bcast:31 row_mask:0xc bank_mask:0xf
	v_add_f32_dpp v90, v90, v90 row_bcast:31 row_mask:0xc bank_mask:0xf
	s_nop 0
	v_readlane_b32 s2, v9, 63
	v_readlane_b32 s3, v90, 63
	s_nop 1
	v_mov_b32_e32 v9, s2
	v_mov_b32_e32 v90, s3
	v_mul_f32_e32 v93, 0x3a800000, v9
	v_mul_f32_e32 v91, 0x3a800000, v90
	v_fma_f32 v91, -v93, v93, v91
	v_max_f32_e32 v91, 0, v91
	v_add_f32_e32 v91, 0x358637bd, v91
	v_rsq_f32_e32 v94, v91
	v_mul_f32_e32 v91, 0.5, v91
	v_mul_f32_e32 v92, v94, v94
	v_fma_f32 v92, -v91, v92, 0.5
	v_fma_f32 v94, v94, v92, v94
	s_add_u32 s2, s12, 0x20
	s_addc_u32 s3, s13, 0
	v_mov_b32_e32 v188, v93
	v_mov_b32_e32 v189, v94
	s_mov_b64 exec, 1
	global_store_dwordx2 v97, v[188:189], s[2:3]
	s_mov_b64 exec, -1
	v_pk_add_f32 v[42:43], v[42:43], v[92:93] op_sel:[0,1] op_sel_hi:[1,1] neg_lo:[0,1] neg_hi:[0,1]
	v_pk_add_f32 v[44:45], v[44:45], v[92:93] op_sel:[0,1] op_sel_hi:[1,1] neg_lo:[0,1] neg_hi:[0,1]
	v_pk_add_f32 v[46:47], v[46:47], v[92:93] op_sel:[0,1] op_sel_hi:[1,1] neg_lo:[0,1] neg_hi:[0,1]
	v_pk_add_f32 v[48:49], v[48:49], v[92:93] op_sel:[0,1] op_sel_hi:[1,1] neg_lo:[0,1] neg_hi:[0,1]
	v_pk_add_f32 v[50:51], v[50:51], v[92:93] op_sel:[0,1] op_sel_hi:[1,1] neg_lo:[0,1] neg_hi:[0,1]
	v_pk_add_f32 v[52:53], v[52:53], v[92:93] op_sel:[0,1] op_sel_hi:[1,1] neg_lo:[0,1] neg_hi:[0,1]
	v_pk_add_f32 v[54:55], v[54:55], v[92:93] op_sel:[0,1] op_sel_hi:[1,1] neg_lo:[0,1] neg_hi:[0,1]
	v_pk_add_f32 v[56:57], v[56:57], v[92:93] op_sel:[0,1] op_sel_hi:[1,1] neg_lo:[0,1] neg_hi:[0,1]
	v_pk_mul_f32 v[42:43], v[42:43], v[94:95] op_sel_hi:[1,0]
	v_pk_mul_f32 v[44:45], v[44:45], v[94:95] op_sel_hi:[1,0]
	v_pk_mul_f32 v[46:47], v[46:47], v[94:95] op_sel_hi:[1,0]
	v_pk_mul_f32 v[48:49], v[48:49], v[94:95] op_sel_hi:[1,0]
	v_pk_mul_f32 v[50:51], v[50:51], v[94:95] op_sel_hi:[1,0]
	v_pk_mul_f32 v[52:53], v[52:53], v[94:95] op_sel_hi:[1,0]
	v_pk_mul_f32 v[54:55], v[54:55], v[94:95] op_sel_hi:[1,0]
	v_pk_mul_f32 v[56:57], v[56:57], v[94:95] op_sel_hi:[1,0]
	v_pk_fma_f32 v[42:43], v[42:43], v[10:11], v[26:27]
	v_pk_fma_f32 v[44:45], v[44:45], v[12:13], v[28:29]
	v_pk_fma_f32 v[46:47], v[46:47], v[14:15], v[30:31]
	v_pk_fma_f32 v[48:49], v[48:49], v[16:17], v[32:33]
	v_pk_fma_f32 v[50:51], v[50:51], v[18:19], v[34:35]
	v_pk_fma_f32 v[52:53], v[52:53], v[20:21], v[36:37]
	v_pk_fma_f32 v[54:55], v[54:55], v[22:23], v[38:39]
	v_pk_fma_f32 v[56:57], v[56:57], v[24:25], v[40:41]
	v_pk_add_f32 v[198:199], v[42:43], v[44:45]
	v_pk_mul_f32 v[200:201], v[42:43], v[42:43]
	v_pk_fma_f32 v[200:201], v[44:45], v[44:45], v[200:201]
	v_pk_add_f32 v[198:199], v[198:199], v[46:47]
	v_pk_fma_f32 v[200:201], v[46:47], v[46:47], v[200:201]
	v_pk_add_f32 v[198:199], v[198:199], v[48:49]
	v_pk_fma_f32 v[200:201], v[48:49], v[48:49], v[200:201]
	v_pk_add_f32 v[198:199], v[198:199], v[50:51]
	v_pk_fma_f32 v[200:201], v[50:51], v[50:51], v[200:201]
	v_pk_add_f32 v[198:199], v[198:199], v[52:53]
	v_pk_fma_f32 v[200:201], v[52:53], v[52:53], v[200:201]
	v_pk_add_f32 v[198:199], v[198:199], v[54:55]
	v_pk_fma_f32 v[200:201], v[54:55], v[54:55], v[200:201]
	v_pk_add_f32 v[198:199], v[198:199], v[56:57]
	v_pk_fma_f32 v[200:201], v[56:57], v[56:57], v[200:201]
	v_add_f32_e32 v9, v198, v199
	v_add_f32_e32 v90, v200, v201
	s_nop 1
	v_add_f32_dpp v9, v9, v9 quad_perm:[1,0,3,2] row_mask:0xf bank_mask:0xf
	v_add_f32_dpp v90, v90, v90 quad_perm:[1,0,3,2] row_mask:0xf bank_mask:0xf
	s_nop 0
	v_add_f32_dpp v9, v9, v9 quad_perm:[2,3,0,1] row_mask:0xf bank_mask:0xf
	v_add_f32_dpp v90, v90, v90 quad_perm:[2,3,0,1] row_mask:0xf bank_mask:0xf
	s_nop 0
	v_add_f32_dpp v9, v9, v9 row_half_mirror row_mask:0xf bank_mask:0xf
	v_add_f32_dpp v90, v90, v90 row_half_mirror row_mask:0xf bank_mask:0xf
	s_nop 0
	v_add_f32_dpp v9, v9, v9 row_mirror row_mask:0xf bank_mask:0xf
	v_add_f32_dpp v90, v90, v90 row_mirror row_mask:0xf bank_mask:0xf
	s_nop 0
	v_add_f32_dpp v9, v9, v9 row_bcast:15 row_mask:0xa bank_mask:0xf
	v_add_f32_dpp v90, v90, v90 row_bcast:15 row_mask:0xa bank_mask:0xf
	s_nop 0
	v_add_f32_dpp v9, v9, v9 row_bcast:31 row_mask:0xc bank_mask:0xf
; DI unsigned pk2(float lo, float hi) { f32x2 v = {lo, hi}; bf16x2_t b = __builtin_convertvector(v, bf16x2_t); return __builtin_bit_cast(unsigned, b); }
; DI void ln_row_v(const Frame& F, f32x4 (&v)[4], float* xout, const float* g, const float* b, const float* sh, const float* sc, bf16_t* hout, const float* slab, const float* gres, float* stat = nullptr) {
;     ...
;         float s = 0.f, s2 = 0.f;
; #pragma unroll
;         for (int j = 0; j < 4; ++j) { s += (v[j][0] + v[j][1]) + (v[j][2] + v[j][3]); s2 += (v[j][0] * v[j][0] + v[j][1] * v[j][1]) + (v[j][2] * v[j][2] + v[j][3] * v[j][3]); }
;         wave_sum2(s, s2, F.lane);
;         const float mean = s * (1.f / D); const float rstd = 1.f / sqrtf(fmaxf(s2 * (1.f / D) - mean * mean, 0.f) + EPS);
;         if (stat && F.lane == 0) { f32x2 sv = {mean, rstd}; *(f32x2*)stat = sv; }
; #pragma unroll
;         for (int j = 0; j < 4; ++j) { const f32x4 gg = ((const f32x4*)g)[F.lane + 64 * j], bb = ((const f32x4*)b)[F.lane + 64 * j];
;             v[j] = (v[j] - mean) * rstd * gg + bb; if (xout) ((f32x4*)xout)[F.lane + 64 * j] = v[j]; }
;     ...
;         const float mean = s * (1.f / D); const float rstd = 1.f / sqrtf(fmaxf(s2 * (1.f / D) - mean * mean, 0.f) + EPS);
; #pragma unroll
;         for (int j = 0; j < 4; ++j) { const f32x4 hh = ((const f32x4*)sh)[F.lane + 64 * j], cc = ((const f32x4*)sc)[F.lane + 64 * j];
;             const f32x4 o = (v[j] - mean) * rstd * (cc + 1.f) + hh; u32x2 wv; wv.x = pk2(o[0], o[1]); wv.y = pk2(o[2], o[3]);
;             ((u32x2*)hout)[F.lane + 64 * j] = wv; }
	v_add_f32_dpp v90, v90, v90 row_bcast:31 row_mask:0xc bank_mask:0xf
	s_nop 0
	v_readlane_b32 s2, v9, 63
	v_readlane_b32 s3, v90, 63
	s_nop 1
	v_mov_b32_e32 v9, s2
	v_mov_b32_e32 v90, s3
	v_mul_f32_e32 v93, 0x3a800000, v9
	v_mul_f32_e32 v91, 0x3a800000, v90
	v_fma_f32 v91, -v93, v93, v91
	v_max_f32_e32 v91, 0, v91
	v_add_f32_e32 v91, 0x358637bd, v91
	v_rsq_f32_e32 v94, v91
	v_mul_f32_e32 v91, 0.5, v91
	v_mul_f32_e32 v92, v94, v94
	v_fma_f32 v92, -v91, v92, 0.5
	v_fma_f32 v94, v94, v92, v94
	v_pk_add_f32 v[42:43], v[42:43], v[92:93] op_sel:[0,1] op_sel_hi:[1,1] neg_lo:[0,1] neg_hi:[0,1]
	v_pk_add_f32 v[44:45], v[44:45], v[92:93] op_sel:[0,1] op_sel_hi:[1,1] neg_lo:[0,1] neg_hi:[0,1]
	v_pk_add_f32 v[46:47], v[46:47], v[92:93] op_sel:[0,1] op_sel_hi:[1,1] neg_lo:[0,1] neg_hi:[0,1]
	v_pk_add_f32 v[48:49], v[48:49], v[92:93] op_sel:[0,1] op_sel_hi:[1,1] neg_lo:[0,1] neg_hi:[0,1]
	v_pk_add_f32 v[50:51], v[50:51], v[92:93] op_sel:[0,1] op_sel_hi:[1,1] neg_lo:[0,1] neg_hi:[0,1]
	v_pk_add_f32 v[52:53], v[52:53], v[92:93] op_sel:[0,1] op_sel_hi:[1,1] neg_lo:[0,1] neg_hi:[0,1]
	v_pk_add_f32 v[54:55], v[54:55], v[92:93] op_sel:[0,1] op_sel_hi:[1,1] neg_lo:[0,1] neg_hi:[0,1]
	v_pk_add_f32 v[56:57], v[56:57], v[92:93] op_sel:[0,1] op_sel_hi:[1,1] neg_lo:[0,1] neg_hi:[0,1]
	v_pk_mul_f32 v[42:43], v[42:43], v[94:95] op_sel_hi:[1,0]
	v_pk_mul_f32 v[44:45], v[44:45], v[94:95] op_sel_hi:[1,0]
	v_pk_mul_f32 v[46:47], v[46:47], v[94:95] op_sel_hi:[1,0]
	v_pk_mul_f32 v[48:49], v[48:49], v[94:95] op_sel_hi:[1,0]
	v_pk_mul_f32 v[50:51], v[50:51], v[94:95] op_sel_hi:[1,0]
	v_pk_mul_f32 v[52:53], v[52:53], v[94:95] op_sel_hi:[1,0]
	v_pk_mul_f32 v[54:55], v[54:55], v[94:95] op_sel_hi:[1,0]
	v_pk_mul_f32 v[56:57], v[56:57], v[94:95] op_sel_hi:[1,0]
	v_pk_fma_f32 v[42:43], v[42:43], v[130:131], v[114:115]
	v_pk_fma_f32 v[44:45], v[44:45], v[132:133], v[116:117]
	v_pk_fma_f32 v[46:47], v[46:47], v[134:135], v[118:119]
	v_pk_fma_f32 v[48:49], v[48:49], v[136:137], v[120:121]
	v_pk_fma_f32 v[50:51], v[50:51], v[138:139], v[122:123]
	v_pk_fma_f32 v[52:53], v[52:53], v[140:141], v[124:125]
	v_pk_fma_f32 v[54:55], v[54:55], v[142:143], v[126:127]
	v_pk_fma_f32 v[56:57], v[56:57], v[144:145], v[128:129]
	v_cvt_pk_bf16_f32 v190, v42, v43
	v_cvt_pk_bf16_f32 v191, v44, v45
	v_cvt_pk_bf16_f32 v192, v46, v47
	v_cvt_pk_bf16_f32 v193, v48, v49
	v_cvt_pk_bf16_f32 v194, v50, v51
	v_cvt_pk_bf16_f32 v195, v52, v53
	v_cvt_pk_bf16_f32 v196, v54, v55
	v_cvt_pk_bf16_f32 v197, v56, v57
	s_add_u32 s2, s10, 0x2000
	s_addc_u32 s3, s11, 0
	global_store_dwordx2 v1, v[190:191], s[2:3]
	global_store_dwordx2 v1, v[192:193], s[2:3] offset:512
	global_store_dwordx2 v1, v[194:195], s[2:3] offset:1024
	global_store_dwordx2 v1, v[196:197], s[2:3] offset:1536
	s_mov_b64 s[2:3], s[20:21]
	global_load_dwordx4 v[42:45], v0, s[2:3]
	global_load_dwordx4 v[46:49], v0, s[2:3] offset:1024
	global_load_dwordx4 v[50:53], v0, s[2:3] offset:2048
	global_load_dwordx4 v[54:57], v0, s[2:3] offset:3072
	s_waitcnt vmcnt(27)
	v_pk_add_f32 v[198:199], v[58:59], v[60:61]
	v_pk_mul_f32 v[200:201], v[58:59], v[58:59]
	v_pk_fma_f32 v[200:201], v[60:61], v[60:61], v[200:201]
	v_pk_add_f32 v[198:199], v[198:199], v[62:63]
	v_pk_fma_f32 v[200:201], v[62:63], v[62:63], v[200:201]
	v_pk_add_f32 v[198:199], v[198:199], v[64:65]
	v_pk_fma_f32 v[200:201], v[64:65], v[64:65], v[200:201]
	v_pk_add_f32 v[198:199], v[198:199], v[66:67]
	v_pk_fma_f32 v[200:201], v[66:67], v[66:67], v[200:201]
	v_pk_add_f32 v[198:199], v[198:199], v[68:69]
	v_pk_fma_f32 v[200:201], v[68:69], v[68:69], v[200:201]
	v_pk_add_f32 v[198:199], v[198:199], v[70:71]
	v_pk_fma_f32 v[200:201], v[70:71], v[70:71], v[200:201]
	v_pk_add_f32 v[198:199], v[198:199], v[72:73]
	v_pk_fma_f32 v[200:201], v[72:73], v[72:73], v[200:201]
	v_add_f32_e32 v9, v198, v199
	v_add_f32_e32 v90, v200, v201
	s_nop 1
	v_add_f32_dpp v9, v9, v9 quad_perm:[1,0,3,2] row_mask:0xf bank_mask:0xf
	v_add_f32_dpp v90, v90, v90 quad_perm:[1,0,3,2] row_mask:0xf bank_mask:0xf
	s_nop 0
	v_add_f32_dpp v9, v9, v9 quad_perm:[2,3,0,1] row_mask:0xf bank_mask:0xf
	v_add_f32_dpp v90, v90, v90 quad_perm:[2,3,0,1] row_mask:0xf bank_mask:0xf
	s_nop 0
	v_add_f32_dpp v9, v9, v9 row_half_mirror row_mask:0xf bank_mask:0xf
	v_add_f32_dpp v90, v90, v90 row_half_mirror row_mask:0xf bank_mask:0xf
	s_nop 0
	v_add_f32_dpp v9, v9, v9 row_mirror row_mask:0xf bank_mask:0xf
	v_add_f32_dpp v90, v90, v90 row_mirror row_mask:0xf bank_mask:0xf
	s_nop 0
	v_add_f32_dpp v9, v9, v9 row_bcast:15 row_mask:0xa bank_mask:0xf
	v_add_f32_dpp v90, v90, v90 row_bcast:15 row_mask:0xa bank_mask:0xf
	s_nop 0
	v_add_f32_dpp v9, v9, v9 row_bcast:31 row_mask:0xc bank_mask:0xf
	v_add_f32_dpp v90, v90, v90 row_bcast:31 row_mask:0xc bank_mask:0xf
	s_nop 0
	v_readlane_b32 s2, v9, 63
	v_readlane_b32 s3, v90, 63
	s_nop 1
	v_mov_b32_e32 v9, s2
	v_mov_b32_e32 v90, s3
	v_mul_f32_e32 v93, 0x3a800000, v9
	v_mul_f32_e32 v91, 0x3a800000, v90
	v_fma_f32 v91, -v93, v93, v91
	v_max_f32_e32 v91, 0, v91
	v_add_f32_e32 v91, 0x358637bd, v91
	v_rsq_f32_e32 v94, v91
	v_mul_f32_e32 v91, 0.5, v91
	v_mul_f32_e32 v92, v94, v94
	v_fma_f32 v92, -v91, v92, 0.5
	v_fma_f32 v94, v94, v92, v94
	s_add_u32 s2, s12, 0x28
	s_addc_u32 s3, s13, 0
	v_mov_b32_e32 v188, v93
	v_mov_b32_e32 v189, v94
	s_mov_b64 exec, 1
	global_store_dwordx2 v97, v[188:189], s[2:3]
	s_mov_b64 exec, -1
	v_pk_add_f32 v[58:59], v[58:59], v[92:93] op_sel:[0,1] op_sel_hi:[1,1] neg_lo:[0,1] neg_hi:[0,1]
	v_pk_add_f32 v[60:61], v[60:61], v[92:93] op_sel:[0,1] op_sel_hi:[1,1] neg_lo:[0,1] neg_hi:[0,1]
	v_pk_add_f32 v[62:63], v[62:63], v[92:93] op_sel:[0,1] op_sel_hi:[1,1] neg_lo:[0,1] neg_hi:[0,1]
; DI unsigned pk2(float lo, float hi) { f32x2 v = {lo, hi}; bf16x2_t b = __builtin_convertvector(v, bf16x2_t); return __builtin_bit_cast(unsigned, b); }
; DI void ln_row_v(const Frame& F, f32x4 (&v)[4], float* xout, const float* g, const float* b, const float* sh, const float* sc, bf16_t* hout, const float* slab, const float* gres, float* stat = nullptr) {
;     ...
;         float s = 0.f, s2 = 0.f;
; #pragma unroll
;         for (int j = 0; j < 4; ++j) { s += (v[j][0] + v[j][1]) + (v[j][2] + v[j][3]); s2 += (v[j][0] * v[j][0] + v[j][1] * v[j][1]) + (v[j][2] * v[j][2] + v[j][3] * v[j][3]); }
;         wave_sum2(s, s2, F.lane);
;         const float mean = s * (1.f / D); const float rstd = 1.f / sqrtf(fmaxf(s2 * (1.f / D) - mean * mean, 0.f) + EPS);
;         if (stat && F.lane == 0) { f32x2 sv = {mean, rstd}; *(f32x2*)stat = sv; }
; #pragma unroll
;         for (int j = 0; j < 4; ++j) { const f32x4 gg = ((const f32x4*)g)[F.lane + 64 * j], bb = ((const f32x4*)b)[F.lane + 64 * j];
;             v[j] = (v[j] - mean) * rstd * gg + bb; if (xout) ((f32x4*)xout)[F.lane + 64 * j] = v[j]; }
;     }
;     if (hout) {
;         float s = 0.f, s2 = 0.f;
; #pragma unroll
;         for (int j = 0; j < 4; ++j) { s += (v[j][0] + v[j][1]) + (v[j][2] + v[j][3]); s2 += (v[j][0] * v[j][0] + v[j][1] * v[j][1]) + (v[j][2] * v[j][2] + v[j][3] * v[j][3]); }
;         wave_sum2(s, s2, F.lane);
;         const float mean = s * (1.f / D); const float rstd = 1.f / sqrtf(fmaxf(s2 * (1.f / D) - mean * mean, 0.f) + EPS);
; #pragma unroll
;         for (int j = 0; j < 4; ++j) { const f32x4 hh = ((const f32x4*)sh)[F.lane + 64 * j], cc = ((const f32x4*)sc)[F.lane + 64 * j];
;             const f32x4 o = (v[j] - mean) * rstd * (cc + 1.f) + hh; u32x2 wv; wv.x = pk2(o[0], o[1]); wv.y = pk2(o[2], o[3]);
;             ((u32x2*)hout)[F.lane + 64 * j] = wv; }
	v_pk_add_f32 v[64:65], v[64:65], v[92:93] op_sel:[0,1] op_sel_hi:[1,1] neg_lo:[0,1] neg_hi:[0,1]
	v_pk_add_f32 v[66:67], v[66:67], v[92:93] op_sel:[0,1] op_sel_hi:[1,1] neg_lo:[0,1] neg_hi:[0,1]
	v_pk_add_f32 v[68:69], v[68:69], v[92:93] op_sel:[0,1] op_sel_hi:[1,1] neg_lo:[0,1] neg_hi:[0,1]
	v_pk_add_f32 v[70:71], v[70:71], v[92:93] op_sel:[0,1] op_sel_hi:[1,1] neg_lo:[0,1] neg_hi:[0,1]
	v_pk_add_f32 v[72:73], v[72:73], v[92:93] op_sel:[0,1] op_sel_hi:[1,1] neg_lo:[0,1] neg_hi:[0,1]
	v_pk_mul_f32 v[58:59], v[58:59], v[94:95] op_sel_hi:[1,0]
	v_pk_mul_f32 v[60:61], v[60:61], v[94:95] op_sel_hi:[1,0]
	v_pk_mul_f32 v[62:63], v[62:63], v[94:95] op_sel_hi:[1,0]
	v_pk_mul_f32 v[64:65], v[64:65], v[94:95] op_sel_hi:[1,0]
	v_pk_mul_f32 v[66:67], v[66:67], v[94:95] op_sel_hi:[1,0]
	v_pk_mul_f32 v[68:69], v[68:69], v[94:95] op_sel_hi:[1,0]
	v_pk_mul_f32 v[70:71], v[70:71], v[94:95] op_sel_hi:[1,0]
	v_pk_mul_f32 v[72:73], v[72:73], v[94:95] op_sel_hi:[1,0]
	v_pk_fma_f32 v[58:59], v[58:59], v[10:11], v[26:27]
	v_pk_fma_f32 v[60:61], v[60:61], v[12:13], v[28:29]
	v_pk_fma_f32 v[62:63], v[62:63], v[14:15], v[30:31]
	v_pk_fma_f32 v[64:65], v[64:65], v[16:17], v[32:33]
	v_pk_fma_f32 v[66:67], v[66:67], v[18:19], v[34:35]
	v_pk_fma_f32 v[68:69], v[68:69], v[20:21], v[36:37]
	v_pk_fma_f32 v[70:71], v[70:71], v[22:23], v[38:39]
	v_pk_fma_f32 v[72:73], v[72:73], v[24:25], v[40:41]
	v_pk_add_f32 v[198:199], v[58:59], v[60:61]
	v_pk_mul_f32 v[200:201], v[58:59], v[58:59]
	v_pk_fma_f32 v[200:201], v[60:61], v[60:61], v[200:201]
	v_pk_add_f32 v[198:199], v[198:199], v[62:63]
	v_pk_fma_f32 v[200:201], v[62:63], v[62:63], v[200:201]
	v_pk_add_f32 v[198:199], v[198:199], v[64:65]
	v_pk_fma_f32 v[200:201], v[64:65], v[64:65], v[200:201]
	v_pk_add_f32 v[198:199], v[198:199], v[66:67]
	v_pk_fma_f32 v[200:201], v[66:67], v[66:67], v[200:201]
	v_pk_add_f32 v[198:199], v[198:199], v[68:69]
	v_pk_fma_f32 v[200:201], v[68:69], v[68:69], v[200:201]
	v_pk_add_f32 v[198:199], v[198:199], v[70:71]
	v_pk_fma_f32 v[200:201], v[70:71], v[70:71], v[200:201]
	v_pk_add_f32 v[198:199], v[198:199], v[72:73]
	v_pk_fma_f32 v[200:201], v[72:73], v[72:73], v[200:201]
	v_add_f32_e32 v9, v198, v199
	v_add_f32_e32 v90, v200, v201
	s_nop 1
	v_add_f32_dpp v9, v9, v9 quad_perm:[1,0,3,2] row_mask:0xf bank_mask:0xf
	v_add_f32_dpp v90, v90, v90 quad_perm:[1,0,3,2] row_mask:0xf bank_mask:0xf
	s_nop 0
	v_add_f32_dpp v9, v9, v9 quad_perm:[2,3,0,1] row_mask:0xf bank_mask:0xf
	v_add_f32_dpp v90, v90, v90 quad_perm:[2,3,0,1] row_mask:0xf bank_mask:0xf
	s_nop 0
	v_add_f32_dpp v9, v9, v9 row_half_mirror row_mask:0xf bank_mask:0xf
	v_add_f32_dpp v90, v90, v90 row_half_mirror row_mask:0xf bank_mask:0xf
	s_nop 0
	v_add_f32_dpp v9, v9, v9 row_mirror row_mask:0xf bank_mask:0xf
	v_add_f32_dpp v90, v90, v90 row_mirror row_mask:0xf bank_mask:0xf
	s_nop 0
	v_add_f32_dpp v9, v9, v9 row_bcast:15 row_mask:0xa bank_mask:0xf
	v_add_f32_dpp v90, v90, v90 row_bcast:15 row_mask:0xa bank_mask:0xf
	s_nop 0
	v_add_f32_dpp v9, v9, v9 row_bcast:31 row_mask:0xc bank_mask:0xf
	v_add_f32_dpp v90, v90, v90 row_bcast:31 row_mask:0xc bank_mask:0xf
	s_nop 0
	v_readlane_b32 s2, v9, 63
	v_readlane_b32 s3, v90, 63
	s_nop 1
	v_mov_b32_e32 v9, s2
	v_mov_b32_e32 v90, s3
	v_mul_f32_e32 v93, 0x3a800000, v9
	v_mul_f32_e32 v91, 0x3a800000, v90
	v_fma_f32 v91, -v93, v93, v91
	v_max_f32_e32 v91, 0, v91
	v_add_f32_e32 v91, 0x358637bd, v91
	v_rsq_f32_e32 v94, v91
	v_mul_f32_e32 v91, 0.5, v91
	v_mul_f32_e32 v92, v94, v94
	v_fma_f32 v92, -v91, v92, 0.5
	v_fma_f32 v94, v94, v92, v94
	v_pk_add_f32 v[58:59], v[58:59], v[92:93] op_sel:[0,1] op_sel_hi:[1,1] neg_lo:[0,1] neg_hi:[0,1]
	v_pk_add_f32 v[60:61], v[60:61], v[92:93] op_sel:[0,1] op_sel_hi:[1,1] neg_lo:[0,1] neg_hi:[0,1]
	v_pk_add_f32 v[62:63], v[62:63], v[92:93] op_sel:[0,1] op_sel_hi:[1,1] neg_lo:[0,1] neg_hi:[0,1]
	v_pk_add_f32 v[64:65], v[64:65], v[92:93] op_sel:[0,1] op_sel_hi:[1,1] neg_lo:[0,1] neg_hi:[0,1]
	v_pk_add_f32 v[66:67], v[66:67], v[92:93] op_sel:[0,1] op_sel_hi:[1,1] neg_lo:[0,1] neg_hi:[0,1]
	v_pk_add_f32 v[68:69], v[68:69], v[92:93] op_sel:[0,1] op_sel_hi:[1,1] neg_lo:[0,1] neg_hi:[0,1]
	v_pk_add_f32 v[70:71], v[70:71], v[92:93] op_sel:[0,1] op_sel_hi:[1,1] neg_lo:[0,1] neg_hi:[0,1]
	v_pk_add_f32 v[72:73], v[72:73], v[92:93] op_sel:[0,1] op_sel_hi:[1,1] neg_lo:[0,1] neg_hi:[0,1]
	v_pk_mul_f32 v[58:59], v[58:59], v[94:95] op_sel_hi:[1,0]
	v_pk_mul_f32 v[60:61], v[60:61], v[94:95] op_sel_hi:[1,0]
	v_pk_mul_f32 v[62:63], v[62:63], v[94:95] op_sel_hi:[1,0]
	v_pk_mul_f32 v[64:65], v[64:65], v[94:95] op_sel_hi:[1,0]
	v_pk_mul_f32 v[66:67], v[66:67], v[94:95] op_sel_hi:[1,0]
	v_pk_mul_f32 v[68:69], v[68:69], v[94:95] op_sel_hi:[1,0]
	v_pk_mul_f32 v[70:71], v[70:71], v[94:95] op_sel_hi:[1,0]
	v_pk_mul_f32 v[72:73], v[72:73], v[94:95] op_sel_hi:[1,0]
	v_pk_fma_f32 v[58:59], v[58:59], v[130:131], v[114:115]
	v_pk_fma_f32 v[60:61], v[60:61], v[132:133], v[116:117]
	v_pk_fma_f32 v[62:63], v[62:63], v[134:135], v[118:119]
	v_pk_fma_f32 v[64:65], v[64:65], v[136:137], v[120:121]
	v_pk_fma_f32 v[66:67], v[66:67], v[138:139], v[122:123]
	v_pk_fma_f32 v[68:69], v[68:69], v[140:141], v[124:125]
	v_pk_fma_f32 v[70:71], v[70:71], v[142:143], v[126:127]
	v_pk_fma_f32 v[72:73], v[72:73], v[144:145], v[128:129]
	v_cvt_pk_bf16_f32 v190, v58, v59
	v_cvt_pk_bf16_f32 v191, v60, v61
	v_cvt_pk_bf16_f32 v192, v62, v63
	v_cvt_pk_bf16_f32 v193, v64, v65
	v_cvt_pk_bf16_f32 v194, v66, v67
	v_cvt_pk_bf16_f32 v195, v68, v69
	v_cvt_pk_bf16_f32 v196, v70, v71
	v_cvt_pk_bf16_f32 v197, v72, v73
	s_add_u32 s2, s10, 0x2800
	s_addc_u32 s3, s11, 0
	global_store_dwordx2 v1, v[190:191], s[2:3]
	global_store_dwordx2 v1, v[192:193], s[2:3] offset:512
	global_store_dwordx2 v1, v[194:195], s[2:3] offset:1024
	global_store_dwordx2 v1, v[196:197], s[2:3] offset:1536
	s_waitcnt vmcnt(23)
; DI void ln_row_v(const Frame& F, f32x4 (&v)[4], float* xout, const float* g, const float* b, const float* sh, const float* sc, bf16_t* hout, const float* slab, const float* gres, float* stat = nullptr) {
;     ...
;         float s = 0.f, s2 = 0.f;
; #pragma unroll
;         for (int j = 0; j < 4; ++j) { s += (v[j][0] + v[j][1]) + (v[j][2] + v[j][3]); s2 += (v[j][0] * v[j][0] + v[j][1] * v[j][1]) + (v[j][2] * v[j][2] + v[j][3] * v[j][3]); }
;         wave_sum2(s, s2, F.lane);
;         const float mean = s * (1.f / D); const float rstd = 1.f / sqrtf(fmaxf(s2 * (1.f / D) - mean * mean, 0.f) + EPS);
;         if (stat && F.lane == 0) { f32x2 sv = {mean, rstd}; *(f32x2*)stat = sv; }
; #pragma unroll
;         for (int j = 0; j < 4; ++j) { const f32x4 gg = ((const f32x4*)g)[F.lane + 64 * j], bb = ((const f32x4*)b)[F.lane + 64 * j];
;             v[j] = (v[j] - mean) * rstd * gg + bb; if (xout) ((f32x4*)xout)[F.lane + 64 * j] = v[j]; }
;     }
;     if (hout) {
;         float s = 0.f, s2 = 0.f;
; #pragma unroll
;         for (int j = 0; j < 4; ++j) { s += (v[j][0] + v[j][1]) + (v[j][2] + v[j][3]); s2 += (v[j][0] * v[j][0] + v[j][1] * v[j][1]) + (v[j][2] * v[j][2] + v[j][3] * v[j][3]); }
;         wave_sum2(s, s2, F.lane);
;         const float mean = s * (1.f / D); const float rstd = 1.f / sqrtf(fmaxf(s2 * (1.f / D) - mean * mean, 0.f) + EPS);
	v_pk_add_f32 v[198:199], v[74:75], v[76:77]
	v_pk_mul_f32 v[200:201], v[74:75], v[74:75]
	v_pk_fma_f32 v[200:201], v[76:77], v[76:77], v[200:201]
	v_pk_add_f32 v[198:199], v[198:199], v[78:79]
	v_pk_fma_f32 v[200:201], v[78:79], v[78:79], v[200:201]
	v_pk_add_f32 v[198:199], v[198:199], v[80:81]
	v_pk_fma_f32 v[200:201], v[80:81], v[80:81], v[200:201]
	v_pk_add_f32 v[198:199], v[198:199], v[82:83]
	v_pk_fma_f32 v[200:201], v[82:83], v[82:83], v[200:201]
	v_pk_add_f32 v[198:199], v[198:199], v[84:85]
	v_pk_fma_f32 v[200:201], v[84:85], v[84:85], v[200:201]
	v_pk_add_f32 v[198:199], v[198:199], v[86:87]
	v_pk_fma_f32 v[200:201], v[86:87], v[86:87], v[200:201]
	v_pk_add_f32 v[198:199], v[198:199], v[88:89]
	v_pk_fma_f32 v[200:201], v[88:89], v[88:89], v[200:201]
	v_add_f32_e32 v9, v198, v199
	v_add_f32_e32 v90, v200, v201
	s_nop 1
	v_add_f32_dpp v9, v9, v9 quad_perm:[1,0,3,2] row_mask:0xf bank_mask:0xf
	v_add_f32_dpp v90, v90, v90 quad_perm:[1,0,3,2] row_mask:0xf bank_mask:0xf
	s_nop 0
	v_add_f32_dpp v9, v9, v9 quad_perm:[2,3,0,1] row_mask:0xf bank_mask:0xf
	v_add_f32_dpp v90, v90, v90 quad_perm:[2,3,0,1] row_mask:0xf bank_mask:0xf
	s_nop 0
	v_add_f32_dpp v9, v9, v9 row_half_mirror row_mask:0xf bank_mask:0xf
	v_add_f32_dpp v90, v90, v90 row_half_mirror row_mask:0xf bank_mask:0xf
	s_nop 0
	v_add_f32_dpp v9, v9, v9 row_mirror row_mask:0xf bank_mask:0xf
	v_add_f32_dpp v90, v90, v90 row_mirror row_mask:0xf bank_mask:0xf
	s_nop 0
	v_add_f32_dpp v9, v9, v9 row_bcast:15 row_mask:0xa bank_mask:0xf
	v_add_f32_dpp v90, v90, v90 row_bcast:15 row_mask:0xa bank_mask:0xf
	s_nop 0
	v_add_f32_dpp v9, v9, v9 row_bcast:31 row_mask:0xc bank_mask:0xf
	v_add_f32_dpp v90, v90, v90 row_bcast:31 row_mask:0xc bank_mask:0xf
	s_nop 0
	v_readlane_b32 s2, v9, 63
	v_readlane_b32 s3, v90, 63
	s_nop 1
	v_mov_b32_e32 v9, s2
	v_mov_b32_e32 v90, s3
	v_mul_f32_e32 v93, 0x3a800000, v9
	v_mul_f32_e32 v91, 0x3a800000, v90
	v_fma_f32 v91, -v93, v93, v91
	v_max_f32_e32 v91, 0, v91
	v_add_f32_e32 v91, 0x358637bd, v91
	v_rsq_f32_e32 v94, v91
	v_mul_f32_e32 v91, 0.5, v91
	v_mul_f32_e32 v92, v94, v94
	v_fma_f32 v92, -v91, v92, 0.5
	v_fma_f32 v94, v94, v92, v94
	s_add_u32 s2, s12, 0x30
	s_addc_u32 s3, s13, 0
	v_mov_b32_e32 v188, v93
	v_mov_b32_e32 v189, v94
	s_mov_b64 exec, 1
	global_store_dwordx2 v97, v[188:189], s[2:3]
	s_mov_b64 exec, -1
	v_pk_add_f32 v[74:75], v[74:75], v[92:93] op_sel:[0,1] op_sel_hi:[1,1] neg_lo:[0,1] neg_hi:[0,1]
	v_pk_add_f32 v[76:77], v[76:77], v[92:93] op_sel:[0,1] op_sel_hi:[1,1] neg_lo:[0,1] neg_hi:[0,1]
	v_pk_add_f32 v[78:79], v[78:79], v[92:93] op_sel:[0,1] op_sel_hi:[1,1] neg_lo:[0,1] neg_hi:[0,1]
	v_pk_add_f32 v[80:81], v[80:81], v[92:93] op_sel:[0,1] op_sel_hi:[1,1] neg_lo:[0,1] neg_hi:[0,1]
	v_pk_add_f32 v[82:83], v[82:83], v[92:93] op_sel:[0,1] op_sel_hi:[1,1] neg_lo:[0,1] neg_hi:[0,1]
	v_pk_add_f32 v[84:85], v[84:85], v[92:93] op_sel:[0,1] op_sel_hi:[1,1] neg_lo:[0,1] neg_hi:[0,1]
	v_pk_add_f32 v[86:87], v[86:87], v[92:93] op_sel:[0,1] op_sel_hi:[1,1] neg_lo:[0,1] neg_hi:[0,1]
	v_pk_add_f32 v[88:89], v[88:89], v[92:93] op_sel:[0,1] op_sel_hi:[1,1] neg_lo:[0,1] neg_hi:[0,1]
	v_pk_mul_f32 v[74:75], v[74:75], v[94:95] op_sel_hi:[1,0]
	v_pk_mul_f32 v[76:77], v[76:77], v[94:95] op_sel_hi:[1,0]
	v_pk_mul_f32 v[78:79], v[78:79], v[94:95] op_sel_hi:[1,0]
	v_pk_mul_f32 v[80:81], v[80:81], v[94:95] op_sel_hi:[1,0]
	v_pk_mul_f32 v[82:83], v[82:83], v[94:95] op_sel_hi:[1,0]
	v_pk_mul_f32 v[84:85], v[84:85], v[94:95] op_sel_hi:[1,0]
	v_pk_mul_f32 v[86:87], v[86:87], v[94:95] op_sel_hi:[1,0]
	v_pk_mul_f32 v[88:89], v[88:89], v[94:95] op_sel_hi:[1,0]
	v_pk_fma_f32 v[74:75], v[74:75], v[10:11], v[26:27]
	v_pk_fma_f32 v[76:77], v[76:77], v[12:13], v[28:29]
	v_pk_fma_f32 v[78:79], v[78:79], v[14:15], v[30:31]
	v_pk_fma_f32 v[80:81], v[80:81], v[16:17], v[32:33]
	v_pk_fma_f32 v[82:83], v[82:83], v[18:19], v[34:35]
	v_pk_fma_f32 v[84:85], v[84:85], v[20:21], v[36:37]
	v_pk_fma_f32 v[86:87], v[86:87], v[22:23], v[38:39]
	v_pk_fma_f32 v[88:89], v[88:89], v[24:25], v[40:41]
	v_pk_add_f32 v[198:199], v[74:75], v[76:77]
	v_pk_mul_f32 v[200:201], v[74:75], v[74:75]
	v_pk_fma_f32 v[200:201], v[76:77], v[76:77], v[200:201]
	v_pk_add_f32 v[198:199], v[198:199], v[78:79]
	v_pk_fma_f32 v[200:201], v[78:79], v[78:79], v[200:201]
	v_pk_add_f32 v[198:199], v[198:199], v[80:81]
	v_pk_fma_f32 v[200:201], v[80:81], v[80:81], v[200:201]
	v_pk_add_f32 v[198:199], v[198:199], v[82:83]
	v_pk_fma_f32 v[200:201], v[82:83], v[82:83], v[200:201]
	v_pk_add_f32 v[198:199], v[198:199], v[84:85]
	v_pk_fma_f32 v[200:201], v[84:85], v[84:85], v[200:201]
	v_pk_add_f32 v[198:199], v[198:199], v[86:87]
	v_pk_fma_f32 v[200:201], v[86:87], v[86:87], v[200:201]
	v_pk_add_f32 v[198:199], v[198:199], v[88:89]
	v_pk_fma_f32 v[200:201], v[88:89], v[88:89], v[200:201]
	v_add_f32_e32 v9, v198, v199
	v_add_f32_e32 v90, v200, v201
	s_nop 1
	v_add_f32_dpp v9, v9, v9 quad_perm:[1,0,3,2] row_mask:0xf bank_mask:0xf
	v_add_f32_dpp v90, v90, v90 quad_perm:[1,0,3,2] row_mask:0xf bank_mask:0xf
	s_nop 0
	v_add_f32_dpp v9, v9, v9 quad_perm:[2,3,0,1] row_mask:0xf bank_mask:0xf
	v_add_f32_dpp v90, v90, v90 quad_perm:[2,3,0,1] row_mask:0xf bank_mask:0xf
	s_nop 0
	v_add_f32_dpp v9, v9, v9 row_half_mirror row_mask:0xf bank_mask:0xf
	v_add_f32_dpp v90, v90, v90 row_half_mirror row_mask:0xf bank_mask:0xf
	s_nop 0
	v_add_f32_dpp v9, v9, v9 row_mirror row_mask:0xf bank_mask:0xf
	v_add_f32_dpp v90, v90, v90 row_mirror row_mask:0xf bank_mask:0xf
	s_nop 0
	v_add_f32_dpp v9, v9, v9 row_bcast:15 row_mask:0xa bank_mask:0xf
	v_add_f32_dpp v90, v90, v90 row_bcast:15 row_mask:0xa bank_mask:0xf
	s_nop 0
	v_add_f32_dpp v9, v9, v9 row_bcast:31 row_mask:0xc bank_mask:0xf
; DI unsigned pk2(float lo, float hi) { f32x2 v = {lo, hi}; bf16x2_t b = __builtin_convertvector(v, bf16x2_t); return __builtin_bit_cast(unsigned, b); }
; DI void ln_row_v(const Frame& F, f32x4 (&v)[4], float* xout, const float* g, const float* b, const float* sh, const float* sc, bf16_t* hout, const float* slab, const float* gres, float* stat = nullptr) {
;     ...
;         float s = 0.f, s2 = 0.f;
; #pragma unroll
;         for (int j = 0; j < 4; ++j) { s += (v[j][0] + v[j][1]) + (v[j][2] + v[j][3]); s2 += (v[j][0] * v[j][0] + v[j][1] * v[j][1]) + (v[j][2] * v[j][2] + v[j][3] * v[j][3]); }
;         wave_sum2(s, s2, F.lane);
;         const float mean = s * (1.f / D); const float rstd = 1.f / sqrtf(fmaxf(s2 * (1.f / D) - mean * mean, 0.f) + EPS);
;         if (stat && F.lane == 0) { f32x2 sv = {mean, rstd}; *(f32x2*)stat = sv; }
; #pragma unroll
;         for (int j = 0; j < 4; ++j) { const f32x4 gg = ((const f32x4*)g)[F.lane + 64 * j], bb = ((const f32x4*)b)[F.lane + 64 * j];
;             v[j] = (v[j] - mean) * rstd * gg + bb; if (xout) ((f32x4*)xout)[F.lane + 64 * j] = v[j]; }
;     ...
;         const float mean = s * (1.f / D); const float rstd = 1.f / sqrtf(fmaxf(s2 * (1.f / D) - mean * mean, 0.f) + EPS);
; #pragma unroll
;         for (int j = 0; j < 4; ++j) { const f32x4 hh = ((const f32x4*)sh)[F.lane + 64 * j], cc = ((const f32x4*)sc)[F.lane + 64 * j];
;             const f32x4 o = (v[j] - mean) * rstd * (cc + 1.f) + hh; u32x2 wv; wv.x = pk2(o[0], o[1]); wv.y = pk2(o[2], o[3]);
;             ((u32x2*)hout)[F.lane + 64 * j] = wv; }
	v_add_f32_dpp v90, v90, v90 row_bcast:31 row_mask:0xc bank_mask:0xf
	s_nop 0
	v_readlane_b32 s2, v9, 63
	v_readlane_b32 s3, v90, 63
	s_nop 1
	v_mov_b32_e32 v9, s2
	v_mov_b32_e32 v90, s3
	v_mul_f32_e32 v93, 0x3a800000, v9
	v_mul_f32_e32 v91, 0x3a800000, v90
	v_fma_f32 v91, -v93, v93, v91
	v_max_f32_e32 v91, 0, v91
	v_add_f32_e32 v91, 0x358637bd, v91
	v_rsq_f32_e32 v94, v91
	v_mul_f32_e32 v91, 0.5, v91
	v_mul_f32_e32 v92, v94, v94
	v_fma_f32 v92, -v91, v92, 0.5
	v_fma_f32 v94, v94, v92, v94
	v_pk_add_f32 v[74:75], v[74:75], v[92:93] op_sel:[0,1] op_sel_hi:[1,1] neg_lo:[0,1] neg_hi:[0,1]
	v_pk_add_f32 v[76:77], v[76:77], v[92:93] op_sel:[0,1] op_sel_hi:[1,1] neg_lo:[0,1] neg_hi:[0,1]
	v_pk_add_f32 v[78:79], v[78:79], v[92:93] op_sel:[0,1] op_sel_hi:[1,1] neg_lo:[0,1] neg_hi:[0,1]
	v_pk_add_f32 v[80:81], v[80:81], v[92:93] op_sel:[0,1] op_sel_hi:[1,1] neg_lo:[0,1] neg_hi:[0,1]
	v_pk_add_f32 v[82:83], v[82:83], v[92:93] op_sel:[0,1] op_sel_hi:[1,1] neg_lo:[0,1] neg_hi:[0,1]
	v_pk_add_f32 v[84:85], v[84:85], v[92:93] op_sel:[0,1] op_sel_hi:[1,1] neg_lo:[0,1] neg_hi:[0,1]
	v_pk_add_f32 v[86:87], v[86:87], v[92:93] op_sel:[0,1] op_sel_hi:[1,1] neg_lo:[0,1] neg_hi:[0,1]
	v_pk_add_f32 v[88:89], v[88:89], v[92:93] op_sel:[0,1] op_sel_hi:[1,1] neg_lo:[0,1] neg_hi:[0,1]
	v_pk_mul_f32 v[74:75], v[74:75], v[94:95] op_sel_hi:[1,0]
	v_pk_mul_f32 v[76:77], v[76:77], v[94:95] op_sel_hi:[1,0]
	v_pk_mul_f32 v[78:79], v[78:79], v[94:95] op_sel_hi:[1,0]
	v_pk_mul_f32 v[80:81], v[80:81], v[94:95] op_sel_hi:[1,0]
	v_pk_mul_f32 v[82:83], v[82:83], v[94:95] op_sel_hi:[1,0]
	v_pk_mul_f32 v[84:85], v[84:85], v[94:95] op_sel_hi:[1,0]
	v_pk_mul_f32 v[86:87], v[86:87], v[94:95] op_sel_hi:[1,0]
	v_pk_mul_f32 v[88:89], v[88:89], v[94:95] op_sel_hi:[1,0]
	v_pk_fma_f32 v[74:75], v[74:75], v[130:131], v[114:115]
	v_pk_fma_f32 v[76:77], v[76:77], v[132:133], v[116:117]
	v_pk_fma_f32 v[78:79], v[78:79], v[134:135], v[118:119]
	v_pk_fma_f32 v[80:81], v[80:81], v[136:137], v[120:121]
	v_pk_fma_f32 v[82:83], v[82:83], v[138:139], v[122:123]
	v_pk_fma_f32 v[84:85], v[84:85], v[140:141], v[124:125]
	v_pk_fma_f32 v[86:87], v[86:87], v[142:143], v[126:127]
	v_pk_fma_f32 v[88:89], v[88:89], v[144:145], v[128:129]
	v_cvt_pk_bf16_f32 v190, v74, v75
	v_cvt_pk_bf16_f32 v191, v76, v77
	v_cvt_pk_bf16_f32 v192, v78, v79
	v_cvt_pk_bf16_f32 v193, v80, v81
	v_cvt_pk_bf16_f32 v194, v82, v83
	v_cvt_pk_bf16_f32 v195, v84, v85
	v_cvt_pk_bf16_f32 v196, v86, v87
	v_cvt_pk_bf16_f32 v197, v88, v89
	s_add_u32 s2, s10, 0x3000
	s_addc_u32 s3, s11, 0
	global_store_dwordx2 v1, v[190:191], s[2:3]
	global_store_dwordx2 v1, v[192:193], s[2:3] offset:512
	global_store_dwordx2 v1, v[194:195], s[2:3] offset:1024
	global_store_dwordx2 v1, v[196:197], s[2:3] offset:1536
	s_waitcnt vmcnt(19)
	v_pk_add_f32 v[198:199], v[98:99], v[100:101]
	v_pk_mul_f32 v[200:201], v[98:99], v[98:99]
	v_pk_fma_f32 v[200:201], v[100:101], v[100:101], v[200:201]
	v_pk_add_f32 v[198:199], v[198:199], v[102:103]
	v_pk_fma_f32 v[200:201], v[102:103], v[102:103], v[200:201]
	v_pk_add_f32 v[198:199], v[198:199], v[104:105]
	v_pk_fma_f32 v[200:201], v[104:105], v[104:105], v[200:201]
	v_pk_add_f32 v[198:199], v[198:199], v[106:107]
	v_pk_fma_f32 v[200:201], v[106:107], v[106:107], v[200:201]
	v_pk_add_f32 v[198:199], v[198:199], v[108:109]
	v_pk_fma_f32 v[200:201], v[108:109], v[108:109], v[200:201]
	v_pk_add_f32 v[198:199], v[198:199], v[110:111]
	v_pk_fma_f32 v[200:201], v[110:111], v[110:111], v[200:201]
	v_pk_add_f32 v[198:199], v[198:199], v[112:113]
	v_pk_fma_f32 v[200:201], v[112:113], v[112:113], v[200:201]
	v_add_f32_e32 v9, v198, v199
	v_add_f32_e32 v90, v200, v201
	s_nop 1
	v_add_f32_dpp v9, v9, v9 quad_perm:[1,0,3,2] row_mask:0xf bank_mask:0xf
	v_add_f32_dpp v90, v90, v90 quad_perm:[1,0,3,2] row_mask:0xf bank_mask:0xf
	s_nop 0
	v_add_f32_dpp v9, v9, v9 quad_perm:[2,3,0,1] row_mask:0xf bank_mask:0xf
	v_add_f32_dpp v90, v90, v90 quad_perm:[2,3,0,1] row_mask:0xf bank_mask:0xf
	s_nop 0
	v_add_f32_dpp v9, v9, v9 row_half_mirror row_mask:0xf bank_mask:0xf
	v_add_f32_dpp v90, v90, v90 row_half_mirror row_mask:0xf bank_mask:0xf
	s_nop 0
	v_add_f32_dpp v9, v9, v9 row_mirror row_mask:0xf bank_mask:0xf
	v_add_f32_dpp v90, v90, v90 row_mirror row_mask:0xf bank_mask:0xf
	s_nop 0
	v_add_f32_dpp v9, v9, v9 row_bcast:15 row_mask:0xa bank_mask:0xf
	v_add_f32_dpp v90, v90, v90 row_bcast:15 row_mask:0xa bank_mask:0xf
	s_nop 0
	v_add_f32_dpp v9, v9, v9 row_bcast:31 row_mask:0xc bank_mask:0xf
	v_add_f32_dpp v90, v90, v90 row_bcast:31 row_mask:0xc bank_mask:0xf
	s_nop 0
	v_readlane_b32 s2, v9, 63
	v_readlane_b32 s3, v90, 63
	s_nop 1
	v_mov_b32_e32 v9, s2
	v_mov_b32_e32 v90, s3
	v_mul_f32_e32 v93, 0x3a800000, v9
	v_mul_f32_e32 v91, 0x3a800000, v90
	v_fma_f32 v91, -v93, v93, v91
	v_max_f32_e32 v91, 0, v91
	v_add_f32_e32 v91, 0x358637bd, v91
	v_rsq_f32_e32 v94, v91
	v_mul_f32_e32 v91, 0.5, v91
	v_mul_f32_e32 v92, v94, v94
	v_fma_f32 v92, -v91, v92, 0.5
	v_fma_f32 v94, v94, v92, v94
	s_add_u32 s2, s12, 0x38
	s_addc_u32 s3, s13, 0
	v_mov_b32_e32 v188, v93
	v_mov_b32_e32 v189, v94
	s_mov_b64 exec, 1
	global_store_dwordx2 v97, v[188:189], s[2:3]
	s_mov_b64 exec, -1
	v_pk_add_f32 v[98:99], v[98:99], v[92:93] op_sel:[0,1] op_sel_hi:[1,1] neg_lo:[0,1] neg_hi:[0,1]
	v_pk_add_f32 v[100:101], v[100:101], v[92:93] op_sel:[0,1] op_sel_hi:[1,1] neg_lo:[0,1] neg_hi:[0,1]
	v_pk_add_f32 v[102:103], v[102:103], v[92:93] op_sel:[0,1] op_sel_hi:[1,1] neg_lo:[0,1] neg_hi:[0,1]
	v_pk_add_f32 v[104:105], v[104:105], v[92:93] op_sel:[0,1] op_sel_hi:[1,1] neg_lo:[0,1] neg_hi:[0,1]
	v_pk_add_f32 v[106:107], v[106:107], v[92:93] op_sel:[0,1] op_sel_hi:[1,1] neg_lo:[0,1] neg_hi:[0,1]
; DI unsigned pk2(float lo, float hi) { f32x2 v = {lo, hi}; bf16x2_t b = __builtin_convertvector(v, bf16x2_t); return __builtin_bit_cast(unsigned, b); }
; DI void ln_row_v(const Frame& F, f32x4 (&v)[4], float* xout, const float* g, const float* b, const float* sh, const float* sc, bf16_t* hout, const float* slab, const float* gres, float* stat = nullptr) {
;     ...
;         float s = 0.f, s2 = 0.f;
; #pragma unroll
;         for (int j = 0; j < 4; ++j) { s += (v[j][0] + v[j][1]) + (v[j][2] + v[j][3]); s2 += (v[j][0] * v[j][0] + v[j][1] * v[j][1]) + (v[j][2] * v[j][2] + v[j][3] * v[j][3]); }
;         wave_sum2(s, s2, F.lane);
;         const float mean = s * (1.f / D); const float rstd = 1.f / sqrtf(fmaxf(s2 * (1.f / D) - mean * mean, 0.f) + EPS);
;         if (stat && F.lane == 0) { f32x2 sv = {mean, rstd}; *(f32x2*)stat = sv; }
; #pragma unroll
;         for (int j = 0; j < 4; ++j) { const f32x4 gg = ((const f32x4*)g)[F.lane + 64 * j], bb = ((const f32x4*)b)[F.lane + 64 * j];
;             v[j] = (v[j] - mean) * rstd * gg + bb; if (xout) ((f32x4*)xout)[F.lane + 64 * j] = v[j]; }
;     }
;     if (hout) {
;         float s = 0.f, s2 = 0.f;
; #pragma unroll
;         for (int j = 0; j < 4; ++j) { s += (v[j][0] + v[j][1]) + (v[j][2] + v[j][3]); s2 += (v[j][0] * v[j][0] + v[j][1] * v[j][1]) + (v[j][2] * v[j][2] + v[j][3] * v[j][3]); }
;         wave_sum2(s, s2, F.lane);
;         const float mean = s * (1.f / D); const float rstd = 1.f / sqrtf(fmaxf(s2 * (1.f / D) - mean * mean, 0.f) + EPS);
; #pragma unroll
;         for (int j = 0; j < 4; ++j) { const f32x4 hh = ((const f32x4*)sh)[F.lane + 64 * j], cc = ((const f32x4*)sc)[F.lane + 64 * j];
;             const f32x4 o = (v[j] - mean) * rstd * (cc + 1.f) + hh; u32x2 wv; wv.x = pk2(o[0], o[1]); wv.y = pk2(o[2], o[3]);
;             ((u32x2*)hout)[F.lane + 64 * j] = wv; }
; DI void ln_phase(const Frame& F, int which) {
;     const int gw = F.vcu * 8 + F.wave, NGW = F.G * 8; const int l = F.l;
;     const int nrows = (l == NL - 1) ? ML : MT;
;     bf16_t* H = (bf16_t*)(F.ws + WS_HB);
;     const float* g = pin(F, which == 0 ? I_LN1G : I_LN2G) + l * 1024; const float* b = pin(F, which == 0 ? I_LN1B : I_LN2B) + l * 1024;
;     const bool wh = !(which == 1 && l == NL - 1);
;     f32x4 vc[4], vn[4];
;     if (gw < nrows) ln_load(F, xrow_ptr(F, gw), vc);
;     for (int row = gw; row < nrows; row += NGW) {
	v_pk_add_f32 v[108:109], v[108:109], v[92:93] op_sel:[0,1] op_sel_hi:[1,1] neg_lo:[0,1] neg_hi:[0,1]
	v_pk_add_f32 v[110:111], v[110:111], v[92:93] op_sel:[0,1] op_sel_hi:[1,1] neg_lo:[0,1] neg_hi:[0,1]
	v_pk_add_f32 v[112:113], v[112:113], v[92:93] op_sel:[0,1] op_sel_hi:[1,1] neg_lo:[0,1] neg_hi:[0,1]
	v_pk_mul_f32 v[98:99], v[98:99], v[94:95] op_sel_hi:[1,0]
	v_pk_mul_f32 v[100:101], v[100:101], v[94:95] op_sel_hi:[1,0]
	v_pk_mul_f32 v[102:103], v[102:103], v[94:95] op_sel_hi:[1,0]
	v_pk_mul_f32 v[104:105], v[104:105], v[94:95] op_sel_hi:[1,0]
	v_pk_mul_f32 v[106:107], v[106:107], v[94:95] op_sel_hi:[1,0]
	v_pk_mul_f32 v[108:109], v[108:109], v[94:95] op_sel_hi:[1,0]
	v_pk_mul_f32 v[110:111], v[110:111], v[94:95] op_sel_hi:[1,0]
	v_pk_mul_f32 v[112:113], v[112:113], v[94:95] op_sel_hi:[1,0]
	v_pk_fma_f32 v[98:99], v[98:99], v[10:11], v[26:27]
	v_pk_fma_f32 v[100:101], v[100:101], v[12:13], v[28:29]
	v_pk_fma_f32 v[102:103], v[102:103], v[14:15], v[30:31]
	v_pk_fma_f32 v[104:105], v[104:105], v[16:17], v[32:33]
	v_pk_fma_f32 v[106:107], v[106:107], v[18:19], v[34:35]
	v_pk_fma_f32 v[108:109], v[108:109], v[20:21], v[36:37]
	v_pk_fma_f32 v[110:111], v[110:111], v[22:23], v[38:39]
	v_pk_fma_f32 v[112:113], v[112:113], v[24:25], v[40:41]
	v_pk_add_f32 v[198:199], v[98:99], v[100:101]
	v_pk_mul_f32 v[200:201], v[98:99], v[98:99]
	v_pk_fma_f32 v[200:201], v[100:101], v[100:101], v[200:201]
	v_pk_add_f32 v[198:199], v[198:199], v[102:103]
	v_pk_fma_f32 v[200:201], v[102:103], v[102:103], v[200:201]
	v_pk_add_f32 v[198:199], v[198:199], v[104:105]
	v_pk_fma_f32 v[200:201], v[104:105], v[104:105], v[200:201]
	v_pk_add_f32 v[198:199], v[198:199], v[106:107]
	v_pk_fma_f32 v[200:201], v[106:107], v[106:107], v[200:201]
	v_pk_add_f32 v[198:199], v[198:199], v[108:109]
	v_pk_fma_f32 v[200:201], v[108:109], v[108:109], v[200:201]
	v_pk_add_f32 v[198:199], v[198:199], v[110:111]
	v_pk_fma_f32 v[200:201], v[110:111], v[110:111], v[200:201]
	v_pk_add_f32 v[198:199], v[198:199], v[112:113]
	v_pk_fma_f32 v[200:201], v[112:113], v[112:113], v[200:201]
	v_add_f32_e32 v9, v198, v199
	v_add_f32_e32 v90, v200, v201
	s_nop 1
	v_add_f32_dpp v9, v9, v9 quad_perm:[1,0,3,2] row_mask:0xf bank_mask:0xf
	v_add_f32_dpp v90, v90, v90 quad_perm:[1,0,3,2] row_mask:0xf bank_mask:0xf
	s_nop 0
	v_add_f32_dpp v9, v9, v9 quad_perm:[2,3,0,1] row_mask:0xf bank_mask:0xf
	v_add_f32_dpp v90, v90, v90 quad_perm:[2,3,0,1] row_mask:0xf bank_mask:0xf
	s_nop 0
	v_add_f32_dpp v9, v9, v9 row_half_mirror row_mask:0xf bank_mask:0xf
	v_add_f32_dpp v90, v90, v90 row_half_mirror row_mask:0xf bank_mask:0xf
	s_nop 0
	v_add_f32_dpp v9, v9, v9 row_mirror row_mask:0xf bank_mask:0xf
	v_add_f32_dpp v90, v90, v90 row_mirror row_mask:0xf bank_mask:0xf
	s_nop 0
	v_add_f32_dpp v9, v9, v9 row_bcast:15 row_mask:0xa bank_mask:0xf
	v_add_f32_dpp v90, v90, v90 row_bcast:15 row_mask:0xa bank_mask:0xf
	s_nop 0
	v_add_f32_dpp v9, v9, v9 row_bcast:31 row_mask:0xc bank_mask:0xf
	v_add_f32_dpp v90, v90, v90 row_bcast:31 row_mask:0xc bank_mask:0xf
	s_nop 0
	v_readlane_b32 s2, v9, 63
	v_readlane_b32 s3, v90, 63
	s_nop 1
	v_mov_b32_e32 v9, s2
	v_mov_b32_e32 v90, s3
	v_mul_f32_e32 v93, 0x3a800000, v9
	v_mul_f32_e32 v91, 0x3a800000, v90
	v_fma_f32 v91, -v93, v93, v91
	v_max_f32_e32 v91, 0, v91
	v_add_f32_e32 v91, 0x358637bd, v91
	v_rsq_f32_e32 v94, v91
	v_mul_f32_e32 v91, 0.5, v91
	v_mul_f32_e32 v92, v94, v94
	v_fma_f32 v92, -v91, v92, 0.5
	v_fma_f32 v94, v94, v92, v94
	v_pk_add_f32 v[98:99], v[98:99], v[92:93] op_sel:[0,1] op_sel_hi:[1,1] neg_lo:[0,1] neg_hi:[0,1]
	v_pk_add_f32 v[100:101], v[100:101], v[92:93] op_sel:[0,1] op_sel_hi:[1,1] neg_lo:[0,1] neg_hi:[0,1]
	v_pk_add_f32 v[102:103], v[102:103], v[92:93] op_sel:[0,1] op_sel_hi:[1,1] neg_lo:[0,1] neg_hi:[0,1]
	v_pk_add_f32 v[104:105], v[104:105], v[92:93] op_sel:[0,1] op_sel_hi:[1,1] neg_lo:[0,1] neg_hi:[0,1]
	v_pk_add_f32 v[106:107], v[106:107], v[92:93] op_sel:[0,1] op_sel_hi:[1,1] neg_lo:[0,1] neg_hi:[0,1]
	v_pk_add_f32 v[108:109], v[108:109], v[92:93] op_sel:[0,1] op_sel_hi:[1,1] neg_lo:[0,1] neg_hi:[0,1]
	v_pk_add_f32 v[110:111], v[110:111], v[92:93] op_sel:[0,1] op_sel_hi:[1,1] neg_lo:[0,1] neg_hi:[0,1]
	v_pk_add_f32 v[112:113], v[112:113], v[92:93] op_sel:[0,1] op_sel_hi:[1,1] neg_lo:[0,1] neg_hi:[0,1]
	v_pk_mul_f32 v[98:99], v[98:99], v[94:95] op_sel_hi:[1,0]
	v_pk_mul_f32 v[100:101], v[100:101], v[94:95] op_sel_hi:[1,0]
	v_pk_mul_f32 v[102:103], v[102:103], v[94:95] op_sel_hi:[1,0]
	v_pk_mul_f32 v[104:105], v[104:105], v[94:95] op_sel_hi:[1,0]
	v_pk_mul_f32 v[106:107], v[106:107], v[94:95] op_sel_hi:[1,0]
	v_pk_mul_f32 v[108:109], v[108:109], v[94:95] op_sel_hi:[1,0]
	v_pk_mul_f32 v[110:111], v[110:111], v[94:95] op_sel_hi:[1,0]
	v_pk_mul_f32 v[112:113], v[112:113], v[94:95] op_sel_hi:[1,0]
	v_pk_fma_f32 v[98:99], v[98:99], v[130:131], v[114:115]
	v_pk_fma_f32 v[100:101], v[100:101], v[132:133], v[116:117]
	v_pk_fma_f32 v[102:103], v[102:103], v[134:135], v[118:119]
	v_pk_fma_f32 v[104:105], v[104:105], v[136:137], v[120:121]
	v_pk_fma_f32 v[106:107], v[106:107], v[138:139], v[122:123]
	v_pk_fma_f32 v[108:109], v[108:109], v[140:141], v[124:125]
	v_pk_fma_f32 v[110:111], v[110:111], v[142:143], v[126:127]
	v_pk_fma_f32 v[112:113], v[112:113], v[144:145], v[128:129]
	v_cvt_pk_bf16_f32 v190, v98, v99
	v_cvt_pk_bf16_f32 v191, v100, v101
	v_cvt_pk_bf16_f32 v192, v102, v103
	v_cvt_pk_bf16_f32 v193, v104, v105
	v_cvt_pk_bf16_f32 v194, v106, v107
	v_cvt_pk_bf16_f32 v195, v108, v109
	v_cvt_pk_bf16_f32 v196, v110, v111
	v_cvt_pk_bf16_f32 v197, v112, v113
	s_add_u32 s2, s10, 0x3800
	s_addc_u32 s3, s11, 0
	global_store_dwordx2 v1, v[190:191], s[2:3]
	global_store_dwordx2 v1, v[192:193], s[2:3] offset:512
	global_store_dwordx2 v1, v[194:195], s[2:3] offset:1024
	global_store_dwordx2 v1, v[196:197], s[2:3] offset:1536
	s_cmp_eq_u32 s22, 3
	s_cbranch_scc1 .Lln_a_noctx
; DI unsigned pk2(float lo, float hi) { f32x2 v = {lo, hi}; bf16x2_t b = __builtin_convertvector(v, bf16x2_t); return __builtin_bit_cast(unsigned, b); }
; DI void ln_row_v(const Frame& F, f32x4 (&v)[4], float* xout, const float* g, const float* b, const float* sh, const float* sc, bf16_t* hout, const float* slab, const float* gres, float* stat = nullptr) {
;     ...
;         float s = 0.f, s2 = 0.f;
; #pragma unroll
;         for (int j = 0; j < 4; ++j) { s += (v[j][0] + v[j][1]) + (v[j][2] + v[j][3]); s2 += (v[j][0] * v[j][0] + v[j][1] * v[j][1]) + (v[j][2] * v[j][2] + v[j][3] * v[j][3]); }
;         wave_sum2(s, s2, F.lane);
;         const float mean = s * (1.f / D); const float rstd = 1.f / sqrtf(fmaxf(s2 * (1.f / D) - mean * mean, 0.f) + EPS);
;         if (stat && F.lane == 0) { f32x2 sv = {mean, rstd}; *(f32x2*)stat = sv; }
; #pragma unroll
;         for (int j = 0; j < 4; ++j) { const f32x4 gg = ((const f32x4*)g)[F.lane + 64 * j], bb = ((const f32x4*)b)[F.lane + 64 * j];
;             v[j] = (v[j] - mean) * rstd * gg + bb; if (xout) ((f32x4*)xout)[F.lane + 64 * j] = v[j]; }
;     }
;     if (hout) {
;         float s = 0.f, s2 = 0.f;
; #pragma unroll
;         for (int j = 0; j < 4; ++j) { s += (v[j][0] + v[j][1]) + (v[j][2] + v[j][3]); s2 += (v[j][0] * v[j][0] + v[j][1] * v[j][1]) + (v[j][2] * v[j][2] + v[j][3] * v[j][3]); }
;         wave_sum2(s, s2, F.lane);
;         const float mean = s * (1.f / D); const float rstd = 1.f / sqrtf(fmaxf(s2 * (1.f / D) - mean * mean, 0.f) + EPS);
; #pragma unroll
;         for (int j = 0; j < 4; ++j) { const f32x4 hh = ((const f32x4*)sh)[F.lane + 64 * j], cc = ((const f32x4*)sc)[F.lane + 64 * j];
;             const f32x4 o = (v[j] - mean) * rstd * (cc + 1.f) + hh; u32x2 wv; wv.x = pk2(o[0], o[1]); wv.y = pk2(o[2], o[3]);
;             ((u32x2*)hout)[F.lane + 64 * j] = wv; }
	s_waitcnt vmcnt(15)
	v_pk_add_f32 v[198:199], v[42:43], v[44:45]
	v_pk_mul_f32 v[200:201], v[42:43], v[42:43]
	v_pk_fma_f32 v[200:201], v[44:45], v[44:45], v[200:201]
	v_pk_add_f32 v[198:199], v[198:199], v[46:47]
	v_pk_fma_f32 v[200:201], v[46:47], v[46:47], v[200:201]
	v_pk_add_f32 v[198:199], v[198:199], v[48:49]
	v_pk_fma_f32 v[200:201], v[48:49], v[48:49], v[200:201]
	v_pk_add_f32 v[198:199], v[198:199], v[50:51]
	v_pk_fma_f32 v[200:201], v[50:51], v[50:51], v[200:201]
	v_pk_add_f32 v[198:199], v[198:199], v[52:53]
	v_pk_fma_f32 v[200:201], v[52:53], v[52:53], v[200:201]
	v_pk_add_f32 v[198:199], v[198:199], v[54:55]
	v_pk_fma_f32 v[200:201], v[54:55], v[54:55], v[200:201]
	v_pk_add_f32 v[198:199], v[198:199], v[56:57]
	v_pk_fma_f32 v[200:201], v[56:57], v[56:57], v[200:201]
	v_add_f32_e32 v9, v198, v199
	v_add_f32_e32 v90, v200, v201
	s_nop 1
	v_add_f32_dpp v9, v9, v9 quad_perm:[1,0,3,2] row_mask:0xf bank_mask:0xf
	v_add_f32_dpp v90, v90, v90 quad_perm:[1,0,3,2] row_mask:0xf bank_mask:0xf
	s_nop 0
	v_add_f32_dpp v9, v9, v9 quad_perm:[2,3,0,1] row_mask:0xf bank_mask:0xf
	v_add_f32_dpp v90, v90, v90 quad_perm:[2,3,0,1] row_mask:0xf bank_mask:0xf
	s_nop 0
	v_add_f32_dpp v9, v9, v9 row_half_mirror row_mask:0xf bank_mask:0xf
	v_add_f32_dpp v90, v90, v90 row_half_mirror row_mask:0xf bank_mask:0xf
	s_nop 0
	v_add_f32_dpp v9, v9, v9 row_mirror row_mask:0xf bank_mask:0xf
	v_add_f32_dpp v90, v90, v90 row_mirror row_mask:0xf bank_mask:0xf
	s_nop 0
	v_add_f32_dpp v9, v9, v9 row_bcast:15 row_mask:0xa bank_mask:0xf
	v_add_f32_dpp v90, v90, v90 row_bcast:15 row_mask:0xa bank_mask:0xf
	s_nop 0
	v_add_f32_dpp v9, v9, v9 row_bcast:31 row_mask:0xc bank_mask:0xf
	v_add_f32_dpp v90, v90, v90 row_bcast:31 row_mask:0xc bank_mask:0xf
	s_nop 0
	v_readlane_b32 s2, v9, 63
	v_readlane_b32 s3, v90, 63
	s_nop 1
	v_mov_b32_e32 v9, s2
	v_mov_b32_e32 v90, s3
	v_mul_f32_e32 v93, 0x3a800000, v9
	v_mul_f32_e32 v91, 0x3a800000, v90
	v_fma_f32 v91, -v93, v93, v91
	v_max_f32_e32 v91, 0, v91
	v_add_f32_e32 v91, 0x358637bd, v91
	v_rsq_f32_e32 v94, v91
	v_mul_f32_e32 v91, 0.5, v91
	v_mul_f32_e32 v92, v94, v94
	v_fma_f32 v92, -v91, v92, 0.5
	v_fma_f32 v94, v94, v92, v94
	v_pk_add_f32 v[42:43], v[42:43], v[92:93] op_sel:[0,1] op_sel_hi:[1,1] neg_lo:[0,1] neg_hi:[0,1]
	v_pk_add_f32 v[44:45], v[44:45], v[92:93] op_sel:[0,1] op_sel_hi:[1,1] neg_lo:[0,1] neg_hi:[0,1]
	v_pk_add_f32 v[46:47], v[46:47], v[92:93] op_sel:[0,1] op_sel_hi:[1,1] neg_lo:[0,1] neg_hi:[0,1]
	v_pk_add_f32 v[48:49], v[48:49], v[92:93] op_sel:[0,1] op_sel_hi:[1,1] neg_lo:[0,1] neg_hi:[0,1]
	v_pk_add_f32 v[50:51], v[50:51], v[92:93] op_sel:[0,1] op_sel_hi:[1,1] neg_lo:[0,1] neg_hi:[0,1]
	v_pk_add_f32 v[52:53], v[52:53], v[92:93] op_sel:[0,1] op_sel_hi:[1,1] neg_lo:[0,1] neg_hi:[0,1]
	v_pk_add_f32 v[54:55], v[54:55], v[92:93] op_sel:[0,1] op_sel_hi:[1,1] neg_lo:[0,1] neg_hi:[0,1]
	v_pk_add_f32 v[56:57], v[56:57], v[92:93] op_sel:[0,1] op_sel_hi:[1,1] neg_lo:[0,1] neg_hi:[0,1]
	v_pk_mul_f32 v[42:43], v[42:43], v[94:95] op_sel_hi:[1,0]
	v_pk_mul_f32 v[44:45], v[44:45], v[94:95] op_sel_hi:[1,0]
	v_pk_mul_f32 v[46:47], v[46:47], v[94:95] op_sel_hi:[1,0]
	v_pk_mul_f32 v[48:49], v[48:49], v[94:95] op_sel_hi:[1,0]
	v_pk_mul_f32 v[50:51], v[50:51], v[94:95] op_sel_hi:[1,0]
	v_pk_mul_f32 v[52:53], v[52:53], v[94:95] op_sel_hi:[1,0]
	v_pk_mul_f32 v[54:55], v[54:55], v[94:95] op_sel_hi:[1,0]
	v_pk_mul_f32 v[56:57], v[56:57], v[94:95] op_sel_hi:[1,0]
	v_pk_fma_f32 v[42:43], v[42:43], v[10:11], v[26:27]
	v_pk_fma_f32 v[44:45], v[44:45], v[12:13], v[28:29]
	v_pk_fma_f32 v[46:47], v[46:47], v[14:15], v[30:31]
	v_pk_fma_f32 v[48:49], v[48:49], v[16:17], v[32:33]
	v_pk_fma_f32 v[50:51], v[50:51], v[18:19], v[34:35]
	v_pk_fma_f32 v[52:53], v[52:53], v[20:21], v[36:37]
	v_pk_fma_f32 v[54:55], v[54:55], v[22:23], v[38:39]
	v_pk_fma_f32 v[56:57], v[56:57], v[24:25], v[40:41]
	s_mov_b64 s[2:3], s[20:21]
	global_store_dwordx4 v0, v[42:45], s[2:3]
	global_store_dwordx4 v0, v[46:49], s[2:3] offset:1024
	global_store_dwordx4 v0, v[50:53], s[2:3] offset:2048
	global_store_dwordx4 v0, v[54:57], s[2:3] offset:3072
	v_pk_add_f32 v[198:199], v[42:43], v[44:45]
	v_pk_mul_f32 v[200:201], v[42:43], v[42:43]
	v_pk_fma_f32 v[200:201], v[44:45], v[44:45], v[200:201]
	v_pk_add_f32 v[198:199], v[198:199], v[46:47]
	v_pk_fma_f32 v[200:201], v[46:47], v[46:47], v[200:201]
	v_pk_add_f32 v[198:199], v[198:199], v[48:49]
	v_pk_fma_f32 v[200:201], v[48:49], v[48:49], v[200:201]
	v_pk_add_f32 v[198:199], v[198:199], v[50:51]
	v_pk_fma_f32 v[200:201], v[50:51], v[50:51], v[200:201]
; DI unsigned pk2(float lo, float hi) { f32x2 v = {lo, hi}; bf16x2_t b = __builtin_convertvector(v, bf16x2_t); return __builtin_bit_cast(unsigned, b); }
; DI void ln_row_v(const Frame& F, f32x4 (&v)[4], float* xout, const float* g, const float* b, const float* sh, const float* sc, bf16_t* hout, const float* slab, const float* gres, float* stat = nullptr) {
;     ...
;         const float mean = s * (1.f / D); const float rstd = 1.f / sqrtf(fmaxf(s2 * (1.f / D) - mean * mean, 0.f) + EPS);
; #pragma unroll
;         for (int j = 0; j < 4; ++j) { const f32x4 hh = ((const f32x4*)sh)[F.lane + 64 * j], cc = ((const f32x4*)sc)[F.lane + 64 * j];
;             const f32x4 o = (v[j] - mean) * rstd * (cc + 1.f) + hh; u32x2 wv; wv.x = pk2(o[0], o[1]); wv.y = pk2(o[2], o[3]);
;             ((u32x2*)hout)[F.lane + 64 * j] = wv; }
	v_pk_add_f32 v[198:199], v[198:199], v[52:53]
	v_pk_fma_f32 v[200:201], v[52:53], v[52:53], v[200:201]
	v_pk_add_f32 v[198:199], v[198:199], v[54:55]
	v_pk_fma_f32 v[200:201], v[54:55], v[54:55], v[200:201]
	v_pk_add_f32 v[198:199], v[198:199], v[56:57]
	v_pk_fma_f32 v[200:201], v[56:57], v[56:57], v[200:201]
	v_add_f32_e32 v9, v198, v199
	v_add_f32_e32 v90, v200, v201
	s_nop 1
	v_add_f32_dpp v9, v9, v9 quad_perm:[1,0,3,2] row_mask:0xf bank_mask:0xf
	v_add_f32_dpp v90, v90, v90 quad_perm:[1,0,3,2] row_mask:0xf bank_mask:0xf
	s_nop 0
	v_add_f32_dpp v9, v9, v9 quad_perm:[2,3,0,1] row_mask:0xf bank_mask:0xf
	v_add_f32_dpp v90, v90, v90 quad_perm:[2,3,0,1] row_mask:0xf bank_mask:0xf
	s_nop 0
	v_add_f32_dpp v9, v9, v9 row_half_mirror row_mask:0xf bank_mask:0xf
	v_add_f32_dpp v90, v90, v90 row_half_mirror row_mask:0xf bank_mask:0xf
	s_nop 0
	v_add_f32_dpp v9, v9, v9 row_mirror row_mask:0xf bank_mask:0xf
	v_add_f32_dpp v90, v90, v90 row_mirror row_mask:0xf bank_mask:0xf
	s_nop 0
	v_add_f32_dpp v9, v9, v9 row_bcast:15 row_mask:0xa bank_mask:0xf
	v_add_f32_dpp v90, v90, v90 row_bcast:15 row_mask:0xa bank_mask:0xf
	s_nop 0
	v_add_f32_dpp v9, v9, v9 row_bcast:31 row_mask:0xc bank_mask:0xf
	v_add_f32_dpp v90, v90, v90 row_bcast:31 row_mask:0xc bank_mask:0xf
	s_nop 0
	v_readlane_b32 s2, v9, 63
	v_readlane_b32 s3, v90, 63
	s_nop 1
	v_mov_b32_e32 v9, s2
	v_mov_b32_e32 v90, s3
	v_mul_f32_e32 v93, 0x3a800000, v9
	v_mul_f32_e32 v91, 0x3a800000, v90
	v_fma_f32 v91, -v93, v93, v91
	v_max_f32_e32 v91, 0, v91
	v_add_f32_e32 v91, 0x358637bd, v91
	v_rsq_f32_e32 v94, v91
	v_mul_f32_e32 v91, 0.5, v91
	v_mul_f32_e32 v92, v94, v94
	v_fma_f32 v92, -v91, v92, 0.5
	v_fma_f32 v94, v94, v92, v94
	v_pk_add_f32 v[42:43], v[42:43], v[92:93] op_sel:[0,1] op_sel_hi:[1,1] neg_lo:[0,1] neg_hi:[0,1]
	v_pk_add_f32 v[44:45], v[44:45], v[92:93] op_sel:[0,1] op_sel_hi:[1,1] neg_lo:[0,1] neg_hi:[0,1]
	v_pk_add_f32 v[46:47], v[46:47], v[92:93] op_sel:[0,1] op_sel_hi:[1,1] neg_lo:[0,1] neg_hi:[0,1]
	v_pk_add_f32 v[48:49], v[48:49], v[92:93] op_sel:[0,1] op_sel_hi:[1,1] neg_lo:[0,1] neg_hi:[0,1]
	v_pk_add_f32 v[50:51], v[50:51], v[92:93] op_sel:[0,1] op_sel_hi:[1,1] neg_lo:[0,1] neg_hi:[0,1]
	v_pk_add_f32 v[52:53], v[52:53], v[92:93] op_sel:[0,1] op_sel_hi:[1,1] neg_lo:[0,1] neg_hi:[0,1]
	v_pk_add_f32 v[54:55], v[54:55], v[92:93] op_sel:[0,1] op_sel_hi:[1,1] neg_lo:[0,1] neg_hi:[0,1]
	v_pk_add_f32 v[56:57], v[56:57], v[92:93] op_sel:[0,1] op_sel_hi:[1,1] neg_lo:[0,1] neg_hi:[0,1]
	v_add_f32_e32 v162, 1.0, v162
	v_add_f32_e32 v163, 1.0, v163
	v_add_f32_e32 v164, 1.0, v164
	v_add_f32_e32 v165, 1.0, v165
	v_add_f32_e32 v166, 1.0, v166
	v_add_f32_e32 v167, 1.0, v167
	v_add_f32_e32 v168, 1.0, v168
	v_add_f32_e32 v169, 1.0, v169
	v_add_f32_e32 v170, 1.0, v170
	v_add_f32_e32 v171, 1.0, v171
	v_add_f32_e32 v172, 1.0, v172
	v_add_f32_e32 v173, 1.0, v173
	v_add_f32_e32 v174, 1.0, v174
	v_add_f32_e32 v175, 1.0, v175
	v_add_f32_e32 v176, 1.0, v176
	v_add_f32_e32 v177, 1.0, v177
	v_pk_mul_f32 v[42:43], v[42:43], v[94:95] op_sel_hi:[1,0]
	v_pk_mul_f32 v[44:45], v[44:45], v[94:95] op_sel_hi:[1,0]
	v_pk_mul_f32 v[46:47], v[46:47], v[94:95] op_sel_hi:[1,0]
	v_pk_mul_f32 v[48:49], v[48:49], v[94:95] op_sel_hi:[1,0]
	v_pk_mul_f32 v[50:51], v[50:51], v[94:95] op_sel_hi:[1,0]
	v_pk_mul_f32 v[52:53], v[52:53], v[94:95] op_sel_hi:[1,0]
	v_pk_mul_f32 v[54:55], v[54:55], v[94:95] op_sel_hi:[1,0]
	v_pk_mul_f32 v[56:57], v[56:57], v[94:95] op_sel_hi:[1,0]
	v_pk_fma_f32 v[42:43], v[42:43], v[162:163], v[146:147]
	v_pk_fma_f32 v[44:45], v[44:45], v[164:165], v[148:149]
	v_pk_fma_f32 v[46:47], v[46:47], v[166:167], v[150:151]
	v_pk_fma_f32 v[48:49], v[48:49], v[168:169], v[152:153]
	v_pk_fma_f32 v[50:51], v[50:51], v[170:171], v[154:155]
	v_pk_fma_f32 v[52:53], v[52:53], v[172:173], v[156:157]
	v_pk_fma_f32 v[54:55], v[54:55], v[174:175], v[158:159]
	v_pk_fma_f32 v[56:57], v[56:57], v[176:177], v[160:161]
	v_cvt_pk_bf16_f32 v190, v42, v43
	v_cvt_pk_bf16_f32 v191, v44, v45
	v_cvt_pk_bf16_f32 v192, v46, v47
	v_cvt_pk_bf16_f32 v193, v48, v49
	v_cvt_pk_bf16_f32 v194, v50, v51
	v_cvt_pk_bf16_f32 v195, v52, v53
	v_cvt_pk_bf16_f32 v196, v54, v55
	v_cvt_pk_bf16_f32 v197, v56, v57
	s_lshl_b32 s2, s16, 11
	s_add_u32 s2, s94, s2
	s_addc_u32 s3, s95, 0
	s_add_u32 s2, s2, 0x5e00000
	s_addc_u32 s3, s3, 0
	global_store_dwordx2 v1, v[190:191], s[2:3]
	global_store_dwordx2 v1, v[192:193], s[2:3] offset:512
	global_store_dwordx2 v1, v[194:195], s[2:3] offset:1024
	global_store_dwordx2 v1, v[196:197], s[2:3] offset:1536

; DI const float* modp(const Frame& F, int l, int mr, int which) { return (const float*)(F.ws + WS_MOD) + ((size_t)(l * 9 + mr) * 6 + which) * 1024; }
; DI void ln_row_v(const Frame& F, f32x4 (&v)[4], float* xout, const float* g, const float* b, const float* sh, const float* sc, bf16_t* hout, const float* slab, const float* gres, float* stat = nullptr) {
;     ...
;         float s = 0.f, s2 = 0.f;
; #pragma unroll
;         for (int j = 0; j < 4; ++j) { s += (v[j][0] + v[j][1]) + (v[j][2] + v[j][3]); s2 += (v[j][0] * v[j][0] + v[j][1] * v[j][1]) + (v[j][2] * v[j][2] + v[j][3] * v[j][3]); }
;         wave_sum2(s, s2, F.lane);
;         const float mean = s * (1.f / D); const float rstd = 1.f / sqrtf(fmaxf(s2 * (1.f / D) - mean * mean, 0.f) + EPS);
; DI void ln_phase(const Frame& F, int which) {
;     const int gw = F.vcu * 8 + F.wave, NGW = F.G * 8; const int l = F.l;
;     const int nrows = (l == NL - 1) ? ML : MT;
;     bf16_t* H = (bf16_t*)(F.ws + WS_HB);
;     const float* g = pin(F, which == 0 ? I_LN1G : I_LN2G) + l * 1024; const float* b = pin(F, which == 0 ? I_LN1B : I_LN2B) + l * 1024;
;     const bool wh = !(which == 1 && l == NL - 1);
;     f32x4 vc[4], vn[4];
;     if (gw < nrows) ln_load(F, xrow_ptr(F, gw), vc);
;     for (int row = gw; row < nrows; row += NGW) {
;         if (row + NGW < nrows) ln_load(F, xrow_ptr(F, row + NGW), vn);
;         const int mr = row < ML ? (row >> 11) : 8;
;         const float* sh = which == 0 ? modp(F, l, mr, 3) : modp(F, l + 1 < NL ? l + 1 : l, mr, 0);
;         const float* sc = which == 0 ? modp(F, l, mr, 4) : modp(F, l + 1 < NL ? l + 1 : l, mr, 1);
;         const bool sl = (which == 1 && row >= ML);
;         const bool st_only = row < ML && !(which == 1 && l == NL - 1);
;         float* stp = st_only ? (float*)(F.ws + (which == 0 ? WS_ST1 : WS_ST2)) + 2 * (size_t)row : nullptr;
;         ln_row_v(F, vc, st_only ? nullptr : xrow_ptr(F, row), g, b, sh, sc, wh ? H + (size_t)row * D : nullptr, sl ? (const float*)(F.ws + WS_KN) + (size_t)(row - ML) * 1024 : nullptr, modp(F, l, mr, 5), stp);
.LBB0_513:
	s_and_b64 vcc, exec, s[2:3]
	s_cbranch_vccz .LBB0_537
	v_readlane_b32 s2, v255, 29
	s_lshl_b32 s2, s2, 3
	v_readlane_b32 s3, v255, 31
	s_add_i32 s16, s3, s2
	v_lshlrev_b32_e32 v0, 4, v186
	v_lshlrev_b32_e32 v1, 3, v186
	v_lshlrev_b32_e32 v96, 2, v186
	v_xor_b32_e32 v3, 4, v96
	v_xor_b32_e32 v4, 8, v96
	v_xor_b32_e32 v5, 16, v96
	v_xor_b32_e32 v6, 32, v96
	v_xor_b32_e32 v7, 64, v96
	v_xor_b32_e32 v8, 128, v96
	s_load_dwordx4 s[4:7], s[62:63], 0xb8
	v_readlane_b32 s22, v255, 35
	v_readlane_b32 s8, v255, 17
	v_readlane_b32 s9, v255, 18
	s_add_u32 s20, s94, 0x3600000
	s_addc_u32 s21, s95, 0
	s_lshl_b32 s2, s16, 12
	s_lshl_b32 s3, s16, 15
	s_add_u32 s8, s8, s3
	s_addc_u32 s9, s9, 0
	s_add_u32 s20, s20, s2
	s_addc_u32 s21, s21, 0
	s_lshl_b32 s2, s16, 14
	s_add_u32 s10, s94, s2
	s_addc_u32 s11, s95, 0
	s_add_u32 s10, s10, 0x3e00000
	s_addc_u32 s11, s11, 0
	s_lshl_b32 s2, s16, 6
	s_add_u32 s12, s94, s2
	s_addc_u32 s13, s95, 0
	s_add_u32 s12, s12, 0x4c0000
	s_addc_u32 s13, s13, 0
	s_add_i32 s3, s22, 1
	s_min_u32 s3, s3, 3
	s_mul_i32 s3, s3, 0x36000
	s_add_u32 s14, s94, s3
	s_addc_u32 s15, s95, 0
	s_add_u32 s14, s14, 0x100000
	s_addc_u32 s15, s15, 0
	s_add_u32 s18, s14, 0x1000
	s_addc_u32 s19, s15, 0
	s_lshl_b32 s2, s22, 12
	s_waitcnt lgkmcnt(0)
	s_add_u32 s4, s4, s2
	s_addc_u32 s5, s5, 0
	s_add_u32 s6, s6, s2
	s_addc_u32 s7, s7, 0
	s_lshl_b32 s2, s16, 12
	s_add_u32 s24, s94, s2
	s_addc_u32 s25, s95, 0
	s_add_u32 s24, s24, 0x9100000
	s_addc_u32 s25, s25, 0
	s_mul_i32 s2, s22, 0x36000
	s_add_u32 s26, s94, s2
	s_addc_u32 s27, s95, 0
	s_add_u32 s26, s26, 0x135000
	s_addc_u32 s27, s27, 0
	s_cmp_eq_u32 s22, 3
	s_cbranch_scc1 .Lln_b_final
	global_load_dwordx4 v[10:13], v0, s[4:5]
	global_load_dwordx4 v[14:17], v0, s[4:5] offset:1024
	global_load_dwordx4 v[18:21], v0, s[4:5] offset:2048
	global_load_dwordx4 v[22:25], v0, s[4:5] offset:3072
	global_load_dwordx4 v[26:29], v0, s[6:7]
	global_load_dwordx4 v[30:33], v0, s[6:7] offset:1024
	global_load_dwordx4 v[34:37], v0, s[6:7] offset:2048
	global_load_dwordx4 v[38:41], v0, s[6:7] offset:3072
	s_add_u32 s2, s8, 0x0
	s_addc_u32 s3, s9, 0
	global_load_dwordx4 v[42:45], v0, s[2:3]
	global_load_dwordx4 v[46:49], v0, s[2:3] offset:1024
	global_load_dwordx4 v[50:53], v0, s[2:3] offset:2048
	global_load_dwordx4 v[54:57], v0, s[2:3] offset:3072
	s_lshr_b32 s23, s16, 8
	s_mul_i32 s23, s23, 0x6000
	s_add_u32 s2, s14, s23
	s_addc_u32 s3, s15, 0
	global_load_dwordx4 v[114:117], v0, s[2:3]
	global_load_dwordx4 v[118:121], v0, s[2:3] offset:1024
	global_load_dwordx4 v[122:125], v0, s[2:3] offset:2048
	global_load_dwordx4 v[126:129], v0, s[2:3] offset:3072
	s_add_u32 s2, s18, s23
	s_addc_u32 s3, s19, 0
	global_load_dwordx4 v[130:133], v0, s[2:3]
	global_load_dwordx4 v[134:137], v0, s[2:3] offset:1024
	global_load_dwordx4 v[138:141], v0, s[2:3] offset:2048
	global_load_dwordx4 v[142:145], v0, s[2:3] offset:3072
	s_add_u32 s2, s8, 0x1000
	s_addc_u32 s3, s9, 0
	global_load_dwordx4 v[58:61], v0, s[2:3]
	global_load_dwordx4 v[62:65], v0, s[2:3] offset:1024
	global_load_dwordx4 v[66:69], v0, s[2:3] offset:2048
	global_load_dwordx4 v[70:73], v0, s[2:3] offset:3072
	s_add_u32 s2, s8, 0x2000
	s_addc_u32 s3, s9, 0
	global_load_dwordx4 v[74:77], v0, s[2:3]
	global_load_dwordx4 v[78:81], v0, s[2:3] offset:1024
	global_load_dwordx4 v[82:85], v0, s[2:3] offset:2048
	global_load_dwordx4 v[86:89], v0, s[2:3] offset:3072
	s_add_u32 s2, s8, 0x3000
	s_addc_u32 s3, s9, 0
	global_load_dwordx4 v[98:101], v0, s[2:3]
	global_load_dwordx4 v[102:105], v0, s[2:3] offset:1024
	global_load_dwordx4 v[106:109], v0, s[2:3] offset:2048
	global_load_dwordx4 v[110:113], v0, s[2:3] offset:3072
	s_waitcnt vmcnt(20)
	v_pk_add_f32 v[198:199], v[42:43], v[44:45]
	v_pk_mul_f32 v[200:201], v[42:43], v[42:43]
	v_pk_fma_f32 v[200:201], v[44:45], v[44:45], v[200:201]
	v_pk_add_f32 v[198:199], v[198:199], v[46:47]
	v_pk_fma_f32 v[200:201], v[46:47], v[46:47], v[200:201]
	v_pk_add_f32 v[198:199], v[198:199], v[48:49]
	v_pk_fma_f32 v[200:201], v[48:49], v[48:49], v[200:201]
	v_pk_add_f32 v[198:199], v[198:199], v[50:51]
	v_pk_fma_f32 v[200:201], v[50:51], v[50:51], v[200:201]
	v_pk_add_f32 v[198:199], v[198:199], v[52:53]
	v_pk_fma_f32 v[200:201], v[52:53], v[52:53], v[200:201]
	v_pk_add_f32 v[198:199], v[198:199], v[54:55]
	v_pk_fma_f32 v[200:201], v[54:55], v[54:55], v[200:201]
	v_pk_add_f32 v[198:199], v[198:199], v[56:57]
	v_pk_fma_f32 v[200:201], v[56:57], v[56:57], v[200:201]
	v_add_f32_e32 v9, v198, v199
	v_add_f32_e32 v90, v200, v201
	s_nop 1
	v_add_f32_dpp v9, v9, v9 quad_perm:[1,0,3,2] row_mask:0xf bank_mask:0xf
	v_add_f32_dpp v90, v90, v90 quad_perm:[1,0,3,2] row_mask:0xf bank_mask:0xf
	s_nop 0
	v_add_f32_dpp v9, v9, v9 quad_perm:[2,3,0,1] row_mask:0xf bank_mask:0xf
	v_add_f32_dpp v90, v90, v90 quad_perm:[2,3,0,1] row_mask:0xf bank_mask:0xf
	s_nop 0
	v_add_f32_dpp v9, v9, v9 row_half_mirror row_mask:0xf bank_mask:0xf
	v_add_f32_dpp v90, v90, v90 row_half_mirror row_mask:0xf bank_mask:0xf
	s_nop 0
	v_add_f32_dpp v9, v9, v9 row_mirror row_mask:0xf bank_mask:0xf
	v_add_f32_dpp v90, v90, v90 row_mirror row_mask:0xf bank_mask:0xf
	s_nop 0
	v_add_f32_dpp v9, v9, v9 row_bcast:15 row_mask:0xa bank_mask:0xf
	v_add_f32_dpp v90, v90, v90 row_bcast:15 row_mask:0xa bank_mask:0xf
	s_nop 0
	v_add_f32_dpp v9, v9, v9 row_bcast:31 row_mask:0xc bank_mask:0xf
	v_add_f32_dpp v90, v90, v90 row_bcast:31 row_mask:0xc bank_mask:0xf
	s_nop 0
	v_readlane_b32 s2, v9, 63
	v_readlane_b32 s3, v90, 63
	s_nop 1
	v_mov_b32_e32 v9, s2
	v_mov_b32_e32 v90, s3
	v_mul_f32_e32 v93, 0x3a800000, v9
	v_mul_f32_e32 v91, 0x3a800000, v90
	v_fma_f32 v91, -v93, v93, v91
	v_max_f32_e32 v91, 0, v91
; DI unsigned pk2(float lo, float hi) { f32x2 v = {lo, hi}; bf16x2_t b = __builtin_convertvector(v, bf16x2_t); return __builtin_bit_cast(unsigned, b); }
; DI void ln_row_v(const Frame& F, f32x4 (&v)[4], float* xout, const float* g, const float* b, const float* sh, const float* sc, bf16_t* hout, const float* slab, const float* gres, float* stat = nullptr) {
;     ...
;         float s = 0.f, s2 = 0.f;
; #pragma unroll
;         for (int j = 0; j < 4; ++j) { s += (v[j][0] + v[j][1]) + (v[j][2] + v[j][3]); s2 += (v[j][0] * v[j][0] + v[j][1] * v[j][1]) + (v[j][2] * v[j][2] + v[j][3] * v[j][3]); }
;         wave_sum2(s, s2, F.lane);
;         const float mean = s * (1.f / D); const float rstd = 1.f / sqrtf(fmaxf(s2 * (1.f / D) - mean * mean, 0.f) + EPS);
;         if (stat && F.lane == 0) { f32x2 sv = {mean, rstd}; *(f32x2*)stat = sv; }
; #pragma unroll
;         for (int j = 0; j < 4; ++j) { const f32x4 gg = ((const f32x4*)g)[F.lane + 64 * j], bb = ((const f32x4*)b)[F.lane + 64 * j];
;             v[j] = (v[j] - mean) * rstd * gg + bb; if (xout) ((f32x4*)xout)[F.lane + 64 * j] = v[j]; }
;     }
;     if (hout) {
;         float s = 0.f, s2 = 0.f;
; #pragma unroll
;         for (int j = 0; j < 4; ++j) { s += (v[j][0] + v[j][1]) + (v[j][2] + v[j][3]); s2 += (v[j][0] * v[j][0] + v[j][1] * v[j][1]) + (v[j][2] * v[j][2] + v[j][3] * v[j][3]); }
;         wave_sum2(s, s2, F.lane);
;         const float mean = s * (1.f / D); const float rstd = 1.f / sqrtf(fmaxf(s2 * (1.f / D) - mean * mean, 0.f) + EPS);
; #pragma unroll
;         for (int j = 0; j < 4; ++j) { const f32x4 hh = ((const f32x4*)sh)[F.lane + 64 * j], cc = ((const f32x4*)sc)[F.lane + 64 * j];
;             const f32x4 o = (v[j] - mean) * rstd * (cc + 1.f) + hh; u32x2 wv; wv.x = pk2(o[0], o[1]); wv.y = pk2(o[2], o[3]);
;             ((u32x2*)hout)[F.lane + 64 * j] = wv; }
	v_add_f32_e32 v91, 0x358637bd, v91
	v_rsq_f32_e32 v94, v91
	v_mul_f32_e32 v91, 0.5, v91
	v_mul_f32_e32 v92, v94, v94
	v_fma_f32 v92, -v91, v92, 0.5
	v_fma_f32 v94, v94, v92, v94
	s_add_u32 s2, s12, 0x0
	s_addc_u32 s3, s13, 0
	v_mov_b32_e32 v188, v93
	v_mov_b32_e32 v189, v94
	s_mov_b64 exec, 1
	global_store_dwordx2 v97, v[188:189], s[2:3]
	s_mov_b64 exec, -1
	v_pk_add_f32 v[42:43], v[42:43], v[92:93] op_sel:[0,1] op_sel_hi:[1,1] neg_lo:[0,1] neg_hi:[0,1]
	v_pk_add_f32 v[44:45], v[44:45], v[92:93] op_sel:[0,1] op_sel_hi:[1,1] neg_lo:[0,1] neg_hi:[0,1]
	v_pk_add_f32 v[46:47], v[46:47], v[92:93] op_sel:[0,1] op_sel_hi:[1,1] neg_lo:[0,1] neg_hi:[0,1]
	v_pk_add_f32 v[48:49], v[48:49], v[92:93] op_sel:[0,1] op_sel_hi:[1,1] neg_lo:[0,1] neg_hi:[0,1]
	v_pk_add_f32 v[50:51], v[50:51], v[92:93] op_sel:[0,1] op_sel_hi:[1,1] neg_lo:[0,1] neg_hi:[0,1]
	v_pk_add_f32 v[52:53], v[52:53], v[92:93] op_sel:[0,1] op_sel_hi:[1,1] neg_lo:[0,1] neg_hi:[0,1]
	v_pk_add_f32 v[54:55], v[54:55], v[92:93] op_sel:[0,1] op_sel_hi:[1,1] neg_lo:[0,1] neg_hi:[0,1]
	v_pk_add_f32 v[56:57], v[56:57], v[92:93] op_sel:[0,1] op_sel_hi:[1,1] neg_lo:[0,1] neg_hi:[0,1]
	v_pk_mul_f32 v[42:43], v[42:43], v[94:95] op_sel_hi:[1,0]
	v_pk_mul_f32 v[44:45], v[44:45], v[94:95] op_sel_hi:[1,0]
	v_pk_mul_f32 v[46:47], v[46:47], v[94:95] op_sel_hi:[1,0]
	v_pk_mul_f32 v[48:49], v[48:49], v[94:95] op_sel_hi:[1,0]
	v_pk_mul_f32 v[50:51], v[50:51], v[94:95] op_sel_hi:[1,0]
	v_pk_mul_f32 v[52:53], v[52:53], v[94:95] op_sel_hi:[1,0]
	v_pk_mul_f32 v[54:55], v[54:55], v[94:95] op_sel_hi:[1,0]
	v_pk_mul_f32 v[56:57], v[56:57], v[94:95] op_sel_hi:[1,0]
	v_pk_fma_f32 v[42:43], v[42:43], v[10:11], v[26:27]
	v_pk_fma_f32 v[44:45], v[44:45], v[12:13], v[28:29]
	v_pk_fma_f32 v[46:47], v[46:47], v[14:15], v[30:31]
	v_pk_fma_f32 v[48:49], v[48:49], v[16:17], v[32:33]
	v_pk_fma_f32 v[50:51], v[50:51], v[18:19], v[34:35]
	v_pk_fma_f32 v[52:53], v[52:53], v[20:21], v[36:37]
	v_pk_fma_f32 v[54:55], v[54:55], v[22:23], v[38:39]
	v_pk_fma_f32 v[56:57], v[56:57], v[24:25], v[40:41]
	v_pk_add_f32 v[198:199], v[42:43], v[44:45]
	v_pk_mul_f32 v[200:201], v[42:43], v[42:43]
	v_pk_fma_f32 v[200:201], v[44:45], v[44:45], v[200:201]
	v_pk_add_f32 v[198:199], v[198:199], v[46:47]
	v_pk_fma_f32 v[200:201], v[46:47], v[46:47], v[200:201]
	v_pk_add_f32 v[198:199], v[198:199], v[48:49]
	v_pk_fma_f32 v[200:201], v[48:49], v[48:49], v[200:201]
	v_pk_add_f32 v[198:199], v[198:199], v[50:51]
	v_pk_fma_f32 v[200:201], v[50:51], v[50:51], v[200:201]
	v_pk_add_f32 v[198:199], v[198:199], v[52:53]
	v_pk_fma_f32 v[200:201], v[52:53], v[52:53], v[200:201]
	v_pk_add_f32 v[198:199], v[198:199], v[54:55]
	v_pk_fma_f32 v[200:201], v[54:55], v[54:55], v[200:201]
	v_pk_add_f32 v[198:199], v[198:199], v[56:57]
	v_pk_fma_f32 v[200:201], v[56:57], v[56:57], v[200:201]
	v_add_f32_e32 v9, v198, v199
	v_add_f32_e32 v90, v200, v201
	s_nop 1
	v_add_f32_dpp v9, v9, v9 quad_perm:[1,0,3,2] row_mask:0xf bank_mask:0xf
	v_add_f32_dpp v90, v90, v90 quad_perm:[1,0,3,2] row_mask:0xf bank_mask:0xf
	s_nop 0
	v_add_f32_dpp v9, v9, v9 quad_perm:[2,3,0,1] row_mask:0xf bank_mask:0xf
	v_add_f32_dpp v90, v90, v90 quad_perm:[2,3,0,1] row_mask:0xf bank_mask:0xf
	s_nop 0
	v_add_f32_dpp v9, v9, v9 row_half_mirror row_mask:0xf bank_mask:0xf
	v_add_f32_dpp v90, v90, v90 row_half_mirror row_mask:0xf bank_mask:0xf
	s_nop 0
	v_add_f32_dpp v9, v9, v9 row_mirror row_mask:0xf bank_mask:0xf
	v_add_f32_dpp v90, v90, v90 row_mirror row_mask:0xf bank_mask:0xf
	s_nop 0
	v_add_f32_dpp v9, v9, v9 row_bcast:15 row_mask:0xa bank_mask:0xf
	v_add_f32_dpp v90, v90, v90 row_bcast:15 row_mask:0xa bank_mask:0xf
	s_nop 0
	v_add_f32_dpp v9, v9, v9 row_bcast:31 row_mask:0xc bank_mask:0xf
	v_add_f32_dpp v90, v90, v90 row_bcast:31 row_mask:0xc bank_mask:0xf
	s_nop 0
	v_readlane_b32 s2, v9, 63
	v_readlane_b32 s3, v90, 63
	s_nop 1
	v_mov_b32_e32 v9, s2
	v_mov_b32_e32 v90, s3
	v_mul_f32_e32 v93, 0x3a800000, v9
	v_mul_f32_e32 v91, 0x3a800000, v90
	v_fma_f32 v91, -v93, v93, v91
	v_max_f32_e32 v91, 0, v91
	v_add_f32_e32 v91, 0x358637bd, v91
	v_rsq_f32_e32 v94, v91
	v_mul_f32_e32 v91, 0.5, v91
	v_mul_f32_e32 v92, v94, v94
	v_fma_f32 v92, -v91, v92, 0.5
	v_fma_f32 v94, v94, v92, v94
	s_waitcnt vmcnt(13)
	v_pk_add_f32 v[42:43], v[42:43], v[92:93] op_sel:[0,1] op_sel_hi:[1,1] neg_lo:[0,1] neg_hi:[0,1]
	v_pk_add_f32 v[44:45], v[44:45], v[92:93] op_sel:[0,1] op_sel_hi:[1,1] neg_lo:[0,1] neg_hi:[0,1]
	v_pk_add_f32 v[46:47], v[46:47], v[92:93] op_sel:[0,1] op_sel_hi:[1,1] neg_lo:[0,1] neg_hi:[0,1]
	v_pk_add_f32 v[48:49], v[48:49], v[92:93] op_sel:[0,1] op_sel_hi:[1,1] neg_lo:[0,1] neg_hi:[0,1]
	v_pk_add_f32 v[50:51], v[50:51], v[92:93] op_sel:[0,1] op_sel_hi:[1,1] neg_lo:[0,1] neg_hi:[0,1]
	v_pk_add_f32 v[52:53], v[52:53], v[92:93] op_sel:[0,1] op_sel_hi:[1,1] neg_lo:[0,1] neg_hi:[0,1]
	v_pk_add_f32 v[54:55], v[54:55], v[92:93] op_sel:[0,1] op_sel_hi:[1,1] neg_lo:[0,1] neg_hi:[0,1]
	v_pk_add_f32 v[56:57], v[56:57], v[92:93] op_sel:[0,1] op_sel_hi:[1,1] neg_lo:[0,1] neg_hi:[0,1]
	v_add_f32_e32 v130, 1.0, v130
	v_add_f32_e32 v131, 1.0, v131
	v_add_f32_e32 v132, 1.0, v132
	v_add_f32_e32 v133, 1.0, v133
	v_add_f32_e32 v134, 1.0, v134
	v_add_f32_e32 v135, 1.0, v135
	v_add_f32_e32 v136, 1.0, v136
	v_add_f32_e32 v137, 1.0, v137
	v_add_f32_e32 v138, 1.0, v138
	v_add_f32_e32 v139, 1.0, v139
	v_add_f32_e32 v140, 1.0, v140
	v_add_f32_e32 v141, 1.0, v141
	v_add_f32_e32 v142, 1.0, v142
	v_add_f32_e32 v143, 1.0, v143
	v_add_f32_e32 v144, 1.0, v144
	v_add_f32_e32 v145, 1.0, v145
	v_pk_mul_f32 v[42:43], v[42:43], v[94:95] op_sel_hi:[1,0]
	v_pk_mul_f32 v[44:45], v[44:45], v[94:95] op_sel_hi:[1,0]
; DI unsigned pk2(float lo, float hi) { f32x2 v = {lo, hi}; bf16x2_t b = __builtin_convertvector(v, bf16x2_t); return __builtin_bit_cast(unsigned, b); }
; DI void ln_row_v(const Frame& F, f32x4 (&v)[4], float* xout, const float* g, const float* b, const float* sh, const float* sc, bf16_t* hout, const float* slab, const float* gres, float* stat = nullptr) {
;     ...
;         float s = 0.f, s2 = 0.f;
; #pragma unroll
;         for (int j = 0; j < 4; ++j) { s += (v[j][0] + v[j][1]) + (v[j][2] + v[j][3]); s2 += (v[j][0] * v[j][0] + v[j][1] * v[j][1]) + (v[j][2] * v[j][2] + v[j][3] * v[j][3]); }
;         wave_sum2(s, s2, F.lane);
;         const float mean = s * (1.f / D); const float rstd = 1.f / sqrtf(fmaxf(s2 * (1.f / D) - mean * mean, 0.f) + EPS);
;         if (stat && F.lane == 0) { f32x2 sv = {mean, rstd}; *(f32x2*)stat = sv; }
; #pragma unroll
;         for (int j = 0; j < 4; ++j) { const f32x4 gg = ((const f32x4*)g)[F.lane + 64 * j], bb = ((const f32x4*)b)[F.lane + 64 * j];
;             v[j] = (v[j] - mean) * rstd * gg + bb; if (xout) ((f32x4*)xout)[F.lane + 64 * j] = v[j]; }
;     ...
;         const float mean = s * (1.f / D); const float rstd = 1.f / sqrtf(fmaxf(s2 * (1.f / D) - mean * mean, 0.f) + EPS);
; #pragma unroll
;         for (int j = 0; j < 4; ++j) { const f32x4 hh = ((const f32x4*)sh)[F.lane + 64 * j], cc = ((const f32x4*)sc)[F.lane + 64 * j];
;             const f32x4 o = (v[j] - mean) * rstd * (cc + 1.f) + hh; u32x2 wv; wv.x = pk2(o[0], o[1]); wv.y = pk2(o[2], o[3]);
;             ((u32x2*)hout)[F.lane + 64 * j] = wv; }
	v_pk_mul_f32 v[46:47], v[46:47], v[94:95] op_sel_hi:[1,0]
	v_pk_mul_f32 v[48:49], v[48:49], v[94:95] op_sel_hi:[1,0]
	v_pk_mul_f32 v[50:51], v[50:51], v[94:95] op_sel_hi:[1,0]
	v_pk_mul_f32 v[52:53], v[52:53], v[94:95] op_sel_hi:[1,0]
	v_pk_mul_f32 v[54:55], v[54:55], v[94:95] op_sel_hi:[1,0]
	v_pk_mul_f32 v[56:57], v[56:57], v[94:95] op_sel_hi:[1,0]
	v_pk_fma_f32 v[42:43], v[42:43], v[130:131], v[114:115]
	v_pk_fma_f32 v[44:45], v[44:45], v[132:133], v[116:117]
	v_pk_fma_f32 v[46:47], v[46:47], v[134:135], v[118:119]
	v_pk_fma_f32 v[48:49], v[48:49], v[136:137], v[120:121]
	v_pk_fma_f32 v[50:51], v[50:51], v[138:139], v[122:123]
	v_pk_fma_f32 v[52:53], v[52:53], v[140:141], v[124:125]
	v_pk_fma_f32 v[54:55], v[54:55], v[142:143], v[126:127]
	v_pk_fma_f32 v[56:57], v[56:57], v[144:145], v[128:129]
	v_cvt_pk_bf16_f32 v190, v42, v43
	v_cvt_pk_bf16_f32 v191, v44, v45
	v_cvt_pk_bf16_f32 v192, v46, v47
	v_cvt_pk_bf16_f32 v193, v48, v49
	v_cvt_pk_bf16_f32 v194, v50, v51
	v_cvt_pk_bf16_f32 v195, v52, v53
	v_cvt_pk_bf16_f32 v196, v54, v55
	v_cvt_pk_bf16_f32 v197, v56, v57
	s_add_u32 s2, s10, 0x0
	s_addc_u32 s3, s11, 0
	global_store_dwordx2 v1, v[190:191], s[2:3]
	global_store_dwordx2 v1, v[192:193], s[2:3] offset:512
	global_store_dwordx2 v1, v[194:195], s[2:3] offset:1024
	global_store_dwordx2 v1, v[196:197], s[2:3] offset:1536
	s_add_u32 s2, s8, 0x4000
	s_addc_u32 s3, s9, 0
	global_load_dwordx4 v[42:45], v0, s[2:3]
	global_load_dwordx4 v[46:49], v0, s[2:3] offset:1024
	global_load_dwordx4 v[50:53], v0, s[2:3] offset:2048
	global_load_dwordx4 v[54:57], v0, s[2:3] offset:3072
	s_waitcnt vmcnt(17)
	v_pk_add_f32 v[198:199], v[58:59], v[60:61]
	v_pk_mul_f32 v[200:201], v[58:59], v[58:59]
	v_pk_fma_f32 v[200:201], v[60:61], v[60:61], v[200:201]
	v_pk_add_f32 v[198:199], v[198:199], v[62:63]
	v_pk_fma_f32 v[200:201], v[62:63], v[62:63], v[200:201]
	v_pk_add_f32 v[198:199], v[198:199], v[64:65]
	v_pk_fma_f32 v[200:201], v[64:65], v[64:65], v[200:201]
	v_pk_add_f32 v[198:199], v[198:199], v[66:67]
	v_pk_fma_f32 v[200:201], v[66:67], v[66:67], v[200:201]
	v_pk_add_f32 v[198:199], v[198:199], v[68:69]
	v_pk_fma_f32 v[200:201], v[68:69], v[68:69], v[200:201]
	v_pk_add_f32 v[198:199], v[198:199], v[70:71]
	v_pk_fma_f32 v[200:201], v[70:71], v[70:71], v[200:201]
	v_pk_add_f32 v[198:199], v[198:199], v[72:73]
	v_pk_fma_f32 v[200:201], v[72:73], v[72:73], v[200:201]
	v_add_f32_e32 v9, v198, v199
	v_add_f32_e32 v90, v200, v201
	s_nop 1
	v_add_f32_dpp v9, v9, v9 quad_perm:[1,0,3,2] row_mask:0xf bank_mask:0xf
	v_add_f32_dpp v90, v90, v90 quad_perm:[1,0,3,2] row_mask:0xf bank_mask:0xf
	s_nop 0
	v_add_f32_dpp v9, v9, v9 quad_perm:[2,3,0,1] row_mask:0xf bank_mask:0xf
	v_add_f32_dpp v90, v90, v90 quad_perm:[2,3,0,1] row_mask:0xf bank_mask:0xf
	s_nop 0
	v_add_f32_dpp v9, v9, v9 row_half_mirror row_mask:0xf bank_mask:0xf
	v_add_f32_dpp v90, v90, v90 row_half_mirror row_mask:0xf bank_mask:0xf
	s_nop 0
	v_add_f32_dpp v9, v9, v9 row_mirror row_mask:0xf bank_mask:0xf
	v_add_f32_dpp v90, v90, v90 row_mirror row_mask:0xf bank_mask:0xf
	s_nop 0
	v_add_f32_dpp v9, v9, v9 row_bcast:15 row_mask:0xa bank_mask:0xf
	v_add_f32_dpp v90, v90, v90 row_bcast:15 row_mask:0xa bank_mask:0xf
	s_nop 0
	v_add_f32_dpp v9, v9, v9 row_bcast:31 row_mask:0xc bank_mask:0xf
	v_add_f32_dpp v90, v90, v90 row_bcast:31 row_mask:0xc bank_mask:0xf
	s_nop 0
	v_readlane_b32 s2, v9, 63
	v_readlane_b32 s3, v90, 63
	s_nop 1
	v_mov_b32_e32 v9, s2
	v_mov_b32_e32 v90, s3
	v_mul_f32_e32 v93, 0x3a800000, v9
	v_mul_f32_e32 v91, 0x3a800000, v90
	v_fma_f32 v91, -v93, v93, v91
	v_max_f32_e32 v91, 0, v91
	v_add_f32_e32 v91, 0x358637bd, v91
	v_rsq_f32_e32 v94, v91
	v_mul_f32_e32 v91, 0.5, v91
	v_mul_f32_e32 v92, v94, v94
	v_fma_f32 v92, -v91, v92, 0.5
	v_fma_f32 v94, v94, v92, v94
	s_add_u32 s2, s12, 0x8
	s_addc_u32 s3, s13, 0
	v_mov_b32_e32 v188, v93
	v_mov_b32_e32 v189, v94
	s_mov_b64 exec, 1
	global_store_dwordx2 v97, v[188:189], s[2:3]
	s_mov_b64 exec, -1
	v_pk_add_f32 v[58:59], v[58:59], v[92:93] op_sel:[0,1] op_sel_hi:[1,1] neg_lo:[0,1] neg_hi:[0,1]
	v_pk_add_f32 v[60:61], v[60:61], v[92:93] op_sel:[0,1] op_sel_hi:[1,1] neg_lo:[0,1] neg_hi:[0,1]
	v_pk_add_f32 v[62:63], v[62:63], v[92:93] op_sel:[0,1] op_sel_hi:[1,1] neg_lo:[0,1] neg_hi:[0,1]
	v_pk_add_f32 v[64:65], v[64:65], v[92:93] op_sel:[0,1] op_sel_hi:[1,1] neg_lo:[0,1] neg_hi:[0,1]
	v_pk_add_f32 v[66:67], v[66:67], v[92:93] op_sel:[0,1] op_sel_hi:[1,1] neg_lo:[0,1] neg_hi:[0,1]
	v_pk_add_f32 v[68:69], v[68:69], v[92:93] op_sel:[0,1] op_sel_hi:[1,1] neg_lo:[0,1] neg_hi:[0,1]
	v_pk_add_f32 v[70:71], v[70:71], v[92:93] op_sel:[0,1] op_sel_hi:[1,1] neg_lo:[0,1] neg_hi:[0,1]
	v_pk_add_f32 v[72:73], v[72:73], v[92:93] op_sel:[0,1] op_sel_hi:[1,1] neg_lo:[0,1] neg_hi:[0,1]
	v_pk_mul_f32 v[58:59], v[58:59], v[94:95] op_sel_hi:[1,0]
	v_pk_mul_f32 v[60:61], v[60:61], v[94:95] op_sel_hi:[1,0]
	v_pk_mul_f32 v[62:63], v[62:63], v[94:95] op_sel_hi:[1,0]
	v_pk_mul_f32 v[64:65], v[64:65], v[94:95] op_sel_hi:[1,0]
	v_pk_mul_f32 v[66:67], v[66:67], v[94:95] op_sel_hi:[1,0]
	v_pk_mul_f32 v[68:69], v[68:69], v[94:95] op_sel_hi:[1,0]
	v_pk_mul_f32 v[70:71], v[70:71], v[94:95] op_sel_hi:[1,0]
	v_pk_mul_f32 v[72:73], v[72:73], v[94:95] op_sel_hi:[1,0]
	v_pk_fma_f32 v[58:59], v[58:59], v[10:11], v[26:27]
	v_pk_fma_f32 v[60:61], v[60:61], v[12:13], v[28:29]
	v_pk_fma_f32 v[62:63], v[62:63], v[14:15], v[30:31]
	v_pk_fma_f32 v[64:65], v[64:65], v[16:17], v[32:33]
	v_pk_fma_f32 v[66:67], v[66:67], v[18:19], v[34:35]
	v_pk_fma_f32 v[68:69], v[68:69], v[20:21], v[36:37]
	v_pk_fma_f32 v[70:71], v[70:71], v[22:23], v[38:39]
	v_pk_fma_f32 v[72:73], v[72:73], v[24:25], v[40:41]
; DI unsigned pk2(float lo, float hi) { f32x2 v = {lo, hi}; bf16x2_t b = __builtin_convertvector(v, bf16x2_t); return __builtin_bit_cast(unsigned, b); }
; DI void ln_row_v(const Frame& F, f32x4 (&v)[4], float* xout, const float* g, const float* b, const float* sh, const float* sc, bf16_t* hout, const float* slab, const float* gres, float* stat = nullptr) {
;     ...
;         const float mean = s * (1.f / D); const float rstd = 1.f / sqrtf(fmaxf(s2 * (1.f / D) - mean * mean, 0.f) + EPS);
; #pragma unroll
;         for (int j = 0; j < 4; ++j) { const f32x4 hh = ((const f32x4*)sh)[F.lane + 64 * j], cc = ((const f32x4*)sc)[F.lane + 64 * j];
;             const f32x4 o = (v[j] - mean) * rstd * (cc + 1.f) + hh; u32x2 wv; wv.x = pk2(o[0], o[1]); wv.y = pk2(o[2], o[3]);
;             ((u32x2*)hout)[F.lane + 64 * j] = wv; }
	v_pk_add_f32 v[198:199], v[58:59], v[60:61]
	v_pk_mul_f32 v[200:201], v[58:59], v[58:59]
	v_pk_fma_f32 v[200:201], v[60:61], v[60:61], v[200:201]
	v_pk_add_f32 v[198:199], v[198:199], v[62:63]
	v_pk_fma_f32 v[200:201], v[62:63], v[62:63], v[200:201]
	v_pk_add_f32 v[198:199], v[198:199], v[64:65]
	v_pk_fma_f32 v[200:201], v[64:65], v[64:65], v[200:201]
	v_pk_add_f32 v[198:199], v[198:199], v[66:67]
	v_pk_fma_f32 v[200:201], v[66:67], v[66:67], v[200:201]
	v_pk_add_f32 v[198:199], v[198:199], v[68:69]
	v_pk_fma_f32 v[200:201], v[68:69], v[68:69], v[200:201]
	v_pk_add_f32 v[198:199], v[198:199], v[70:71]
	v_pk_fma_f32 v[200:201], v[70:71], v[70:71], v[200:201]
	v_pk_add_f32 v[198:199], v[198:199], v[72:73]
	v_pk_fma_f32 v[200:201], v[72:73], v[72:73], v[200:201]
	v_add_f32_e32 v9, v198, v199
	v_add_f32_e32 v90, v200, v201
	s_nop 1
	v_add_f32_dpp v9, v9, v9 quad_perm:[1,0,3,2] row_mask:0xf bank_mask:0xf
	v_add_f32_dpp v90, v90, v90 quad_perm:[1,0,3,2] row_mask:0xf bank_mask:0xf
	s_nop 0
	v_add_f32_dpp v9, v9, v9 quad_perm:[2,3,0,1] row_mask:0xf bank_mask:0xf
	v_add_f32_dpp v90, v90, v90 quad_perm:[2,3,0,1] row_mask:0xf bank_mask:0xf
	s_nop 0
	v_add_f32_dpp v9, v9, v9 row_half_mirror row_mask:0xf bank_mask:0xf
	v_add_f32_dpp v90, v90, v90 row_half_mirror row_mask:0xf bank_mask:0xf
	s_nop 0
	v_add_f32_dpp v9, v9, v9 row_mirror row_mask:0xf bank_mask:0xf
	v_add_f32_dpp v90, v90, v90 row_mirror row_mask:0xf bank_mask:0xf
	s_nop 0
	v_add_f32_dpp v9, v9, v9 row_bcast:15 row_mask:0xa bank_mask:0xf
	v_add_f32_dpp v90, v90, v90 row_bcast:15 row_mask:0xa bank_mask:0xf
	s_nop 0
	v_add_f32_dpp v9, v9, v9 row_bcast:31 row_mask:0xc bank_mask:0xf
	v_add_f32_dpp v90, v90, v90 row_bcast:31 row_mask:0xc bank_mask:0xf
	s_nop 0
	v_readlane_b32 s2, v9, 63
	v_readlane_b32 s3, v90, 63
	s_nop 1
	v_mov_b32_e32 v9, s2
	v_mov_b32_e32 v90, s3
	v_mul_f32_e32 v93, 0x3a800000, v9
	v_mul_f32_e32 v91, 0x3a800000, v90
	v_fma_f32 v91, -v93, v93, v91
	v_max_f32_e32 v91, 0, v91
	v_add_f32_e32 v91, 0x358637bd, v91
	v_rsq_f32_e32 v94, v91
	v_mul_f32_e32 v91, 0.5, v91
	v_mul_f32_e32 v92, v94, v94
	v_fma_f32 v92, -v91, v92, 0.5
	v_fma_f32 v94, v94, v92, v94
	v_pk_add_f32 v[58:59], v[58:59], v[92:93] op_sel:[0,1] op_sel_hi:[1,1] neg_lo:[0,1] neg_hi:[0,1]
	v_pk_add_f32 v[60:61], v[60:61], v[92:93] op_sel:[0,1] op_sel_hi:[1,1] neg_lo:[0,1] neg_hi:[0,1]
	v_pk_add_f32 v[62:63], v[62:63], v[92:93] op_sel:[0,1] op_sel_hi:[1,1] neg_lo:[0,1] neg_hi:[0,1]
	v_pk_add_f32 v[64:65], v[64:65], v[92:93] op_sel:[0,1] op_sel_hi:[1,1] neg_lo:[0,1] neg_hi:[0,1]
	v_pk_add_f32 v[66:67], v[66:67], v[92:93] op_sel:[0,1] op_sel_hi:[1,1] neg_lo:[0,1] neg_hi:[0,1]
	v_pk_add_f32 v[68:69], v[68:69], v[92:93] op_sel:[0,1] op_sel_hi:[1,1] neg_lo:[0,1] neg_hi:[0,1]
	v_pk_add_f32 v[70:71], v[70:71], v[92:93] op_sel:[0,1] op_sel_hi:[1,1] neg_lo:[0,1] neg_hi:[0,1]
	v_pk_add_f32 v[72:73], v[72:73], v[92:93] op_sel:[0,1] op_sel_hi:[1,1] neg_lo:[0,1] neg_hi:[0,1]
	v_pk_mul_f32 v[58:59], v[58:59], v[94:95] op_sel_hi:[1,0]
	v_pk_mul_f32 v[60:61], v[60:61], v[94:95] op_sel_hi:[1,0]
	v_pk_mul_f32 v[62:63], v[62:63], v[94:95] op_sel_hi:[1,0]
	v_pk_mul_f32 v[64:65], v[64:65], v[94:95] op_sel_hi:[1,0]
	v_pk_mul_f32 v[66:67], v[66:67], v[94:95] op_sel_hi:[1,0]
	v_pk_mul_f32 v[68:69], v[68:69], v[94:95] op_sel_hi:[1,0]
	v_pk_mul_f32 v[70:71], v[70:71], v[94:95] op_sel_hi:[1,0]
	v_pk_mul_f32 v[72:73], v[72:73], v[94:95] op_sel_hi:[1,0]
	v_pk_fma_f32 v[58:59], v[58:59], v[130:131], v[114:115]
	v_pk_fma_f32 v[60:61], v[60:61], v[132:133], v[116:117]
	v_pk_fma_f32 v[62:63], v[62:63], v[134:135], v[118:119]
	v_pk_fma_f32 v[64:65], v[64:65], v[136:137], v[120:121]
	v_pk_fma_f32 v[66:67], v[66:67], v[138:139], v[122:123]
	v_pk_fma_f32 v[68:69], v[68:69], v[140:141], v[124:125]
	v_pk_fma_f32 v[70:71], v[70:71], v[142:143], v[126:127]
	v_pk_fma_f32 v[72:73], v[72:73], v[144:145], v[128:129]
	v_cvt_pk_bf16_f32 v190, v58, v59
	v_cvt_pk_bf16_f32 v191, v60, v61
	v_cvt_pk_bf16_f32 v192, v62, v63
	v_cvt_pk_bf16_f32 v193, v64, v65
	v_cvt_pk_bf16_f32 v194, v66, v67
	v_cvt_pk_bf16_f32 v195, v68, v69
	v_cvt_pk_bf16_f32 v196, v70, v71
	v_cvt_pk_bf16_f32 v197, v72, v73
	s_add_u32 s2, s10, 0x800
	s_addc_u32 s3, s11, 0
	global_store_dwordx2 v1, v[190:191], s[2:3]
	global_store_dwordx2 v1, v[192:193], s[2:3] offset:512
	global_store_dwordx2 v1, v[194:195], s[2:3] offset:1024
	global_store_dwordx2 v1, v[196:197], s[2:3] offset:1536
	s_add_u32 s2, s8, 0x5000
	s_addc_u32 s3, s9, 0
	global_load_dwordx4 v[58:61], v0, s[2:3]
	global_load_dwordx4 v[62:65], v0, s[2:3] offset:1024
	global_load_dwordx4 v[66:69], v0, s[2:3] offset:2048
	global_load_dwordx4 v[70:73], v0, s[2:3] offset:3072
	s_waitcnt vmcnt(22)
; DI void ln_row_v(const Frame& F, f32x4 (&v)[4], float* xout, const float* g, const float* b, const float* sh, const float* sc, bf16_t* hout, const float* slab, const float* gres, float* stat = nullptr) {
;     ...
;         float s = 0.f, s2 = 0.f;
; #pragma unroll
;         for (int j = 0; j < 4; ++j) { s += (v[j][0] + v[j][1]) + (v[j][2] + v[j][3]); s2 += (v[j][0] * v[j][0] + v[j][1] * v[j][1]) + (v[j][2] * v[j][2] + v[j][3] * v[j][3]); }
;         wave_sum2(s, s2, F.lane);
;         const float mean = s * (1.f / D); const float rstd = 1.f / sqrtf(fmaxf(s2 * (1.f / D) - mean * mean, 0.f) + EPS);
;         if (stat && F.lane == 0) { f32x2 sv = {mean, rstd}; *(f32x2*)stat = sv; }
; #pragma unroll
;         for (int j = 0; j < 4; ++j) { const f32x4 gg = ((const f32x4*)g)[F.lane + 64 * j], bb = ((const f32x4*)b)[F.lane + 64 * j];
;             v[j] = (v[j] - mean) * rstd * gg + bb; if (xout) ((f32x4*)xout)[F.lane + 64 * j] = v[j]; }
;     }
;     if (hout) {
;         float s = 0.f, s2 = 0.f;
; #pragma unroll
;         for (int j = 0; j < 4; ++j) { s += (v[j][0] + v[j][1]) + (v[j][2] + v[j][3]); s2 += (v[j][0] * v[j][0] + v[j][1] * v[j][1]) + (v[j][2] * v[j][2] + v[j][3] * v[j][3]); }
;         wave_sum2(s, s2, F.lane);
;         const float mean = s * (1.f / D); const float rstd = 1.f / sqrtf(fmaxf(s2 * (1.f / D) - mean * mean, 0.f) + EPS);
	v_pk_add_f32 v[198:199], v[74:75], v[76:77]
	v_pk_mul_f32 v[200:201], v[74:75], v[74:75]
	v_pk_fma_f32 v[200:201], v[76:77], v[76:77], v[200:201]
	v_pk_add_f32 v[198:199], v[198:199], v[78:79]
	v_pk_fma_f32 v[200:201], v[78:79], v[78:79], v[200:201]
	v_pk_add_f32 v[198:199], v[198:199], v[80:81]
	v_pk_fma_f32 v[200:201], v[80:81], v[80:81], v[200:201]
	v_pk_add_f32 v[198:199], v[198:199], v[82:83]
	v_pk_fma_f32 v[200:201], v[82:83], v[82:83], v[200:201]
	v_pk_add_f32 v[198:199], v[198:199], v[84:85]
	v_pk_fma_f32 v[200:201], v[84:85], v[84:85], v[200:201]
	v_pk_add_f32 v[198:199], v[198:199], v[86:87]
	v_pk_fma_f32 v[200:201], v[86:87], v[86:87], v[200:201]
	v_pk_add_f32 v[198:199], v[198:199], v[88:89]
	v_pk_fma_f32 v[200:201], v[88:89], v[88:89], v[200:201]
	v_add_f32_e32 v9, v198, v199
	v_add_f32_e32 v90, v200, v201
	s_nop 1
	v_add_f32_dpp v9, v9, v9 quad_perm:[1,0,3,2] row_mask:0xf bank_mask:0xf
	v_add_f32_dpp v90, v90, v90 quad_perm:[1,0,3,2] row_mask:0xf bank_mask:0xf
	s_nop 0
	v_add_f32_dpp v9, v9, v9 quad_perm:[2,3,0,1] row_mask:0xf bank_mask:0xf
	v_add_f32_dpp v90, v90, v90 quad_perm:[2,3,0,1] row_mask:0xf bank_mask:0xf
	s_nop 0
	v_add_f32_dpp v9, v9, v9 row_half_mirror row_mask:0xf bank_mask:0xf
	v_add_f32_dpp v90, v90, v90 row_half_mirror row_mask:0xf bank_mask:0xf
	s_nop 0
	v_add_f32_dpp v9, v9, v9 row_mirror row_mask:0xf bank_mask:0xf
	v_add_f32_dpp v90, v90, v90 row_mirror row_mask:0xf bank_mask:0xf
	s_nop 0
	v_add_f32_dpp v9, v9, v9 row_bcast:15 row_mask:0xa bank_mask:0xf
	v_add_f32_dpp v90, v90, v90 row_bcast:15 row_mask:0xa bank_mask:0xf
	s_nop 0
	v_add_f32_dpp v9, v9, v9 row_bcast:31 row_mask:0xc bank_mask:0xf
	v_add_f32_dpp v90, v90, v90 row_bcast:31 row_mask:0xc bank_mask:0xf
	s_nop 0
	v_readlane_b32 s2, v9, 63
	v_readlane_b32 s3, v90, 63
	s_nop 1
	v_mov_b32_e32 v9, s2
	v_mov_b32_e32 v90, s3
	v_mul_f32_e32 v93, 0x3a800000, v9
	v_mul_f32_e32 v91, 0x3a800000, v90
	v_fma_f32 v91, -v93, v93, v91
	v_max_f32_e32 v91, 0, v91
	v_add_f32_e32 v91, 0x358637bd, v91
	v_rsq_f32_e32 v94, v91
	v_mul_f32_e32 v91, 0.5, v91
	v_mul_f32_e32 v92, v94, v94
	v_fma_f32 v92, -v91, v92, 0.5
	v_fma_f32 v94, v94, v92, v94
	s_add_u32 s2, s12, 0x10
	s_addc_u32 s3, s13, 0
	v_mov_b32_e32 v188, v93
	v_mov_b32_e32 v189, v94
	s_mov_b64 exec, 1
	global_store_dwordx2 v97, v[188:189], s[2:3]
	s_mov_b64 exec, -1
	v_pk_add_f32 v[74:75], v[74:75], v[92:93] op_sel:[0,1] op_sel_hi:[1,1] neg_lo:[0,1] neg_hi:[0,1]
	v_pk_add_f32 v[76:77], v[76:77], v[92:93] op_sel:[0,1] op_sel_hi:[1,1] neg_lo:[0,1] neg_hi:[0,1]
	v_pk_add_f32 v[78:79], v[78:79], v[92:93] op_sel:[0,1] op_sel_hi:[1,1] neg_lo:[0,1] neg_hi:[0,1]
	v_pk_add_f32 v[80:81], v[80:81], v[92:93] op_sel:[0,1] op_sel_hi:[1,1] neg_lo:[0,1] neg_hi:[0,1]
	v_pk_add_f32 v[82:83], v[82:83], v[92:93] op_sel:[0,1] op_sel_hi:[1,1] neg_lo:[0,1] neg_hi:[0,1]
	v_pk_add_f32 v[84:85], v[84:85], v[92:93] op_sel:[0,1] op_sel_hi:[1,1] neg_lo:[0,1] neg_hi:[0,1]
	v_pk_add_f32 v[86:87], v[86:87], v[92:93] op_sel:[0,1] op_sel_hi:[1,1] neg_lo:[0,1] neg_hi:[0,1]
	v_pk_add_f32 v[88:89], v[88:89], v[92:93] op_sel:[0,1] op_sel_hi:[1,1] neg_lo:[0,1] neg_hi:[0,1]
	v_pk_mul_f32 v[74:75], v[74:75], v[94:95] op_sel_hi:[1,0]
	v_pk_mul_f32 v[76:77], v[76:77], v[94:95] op_sel_hi:[1,0]
	v_pk_mul_f32 v[78:79], v[78:79], v[94:95] op_sel_hi:[1,0]
	v_pk_mul_f32 v[80:81], v[80:81], v[94:95] op_sel_hi:[1,0]
	v_pk_mul_f32 v[82:83], v[82:83], v[94:95] op_sel_hi:[1,0]
	v_pk_mul_f32 v[84:85], v[84:85], v[94:95] op_sel_hi:[1,0]
	v_pk_mul_f32 v[86:87], v[86:87], v[94:95] op_sel_hi:[1,0]
	v_pk_mul_f32 v[88:89], v[88:89], v[94:95] op_sel_hi:[1,0]
	v_pk_fma_f32 v[74:75], v[74:75], v[10:11], v[26:27]
	v_pk_fma_f32 v[76:77], v[76:77], v[12:13], v[28:29]
	v_pk_fma_f32 v[78:79], v[78:79], v[14:15], v[30:31]
	v_pk_fma_f32 v[80:81], v[80:81], v[16:17], v[32:33]
	v_pk_fma_f32 v[82:83], v[82:83], v[18:19], v[34:35]
	v_pk_fma_f32 v[84:85], v[84:85], v[20:21], v[36:37]
	v_pk_fma_f32 v[86:87], v[86:87], v[22:23], v[38:39]
	v_pk_fma_f32 v[88:89], v[88:89], v[24:25], v[40:41]
	v_pk_add_f32 v[198:199], v[74:75], v[76:77]
	v_pk_mul_f32 v[200:201], v[74:75], v[74:75]
	v_pk_fma_f32 v[200:201], v[76:77], v[76:77], v[200:201]
	v_pk_add_f32 v[198:199], v[198:199], v[78:79]
	v_pk_fma_f32 v[200:201], v[78:79], v[78:79], v[200:201]
	v_pk_add_f32 v[198:199], v[198:199], v[80:81]
	v_pk_fma_f32 v[200:201], v[80:81], v[80:81], v[200:201]
	v_pk_add_f32 v[198:199], v[198:199], v[82:83]
	v_pk_fma_f32 v[200:201], v[82:83], v[82:83], v[200:201]
	v_pk_add_f32 v[198:199], v[198:199], v[84:85]
	v_pk_fma_f32 v[200:201], v[84:85], v[84:85], v[200:201]
	v_pk_add_f32 v[198:199], v[198:199], v[86:87]
	v_pk_fma_f32 v[200:201], v[86:87], v[86:87], v[200:201]
	v_pk_add_f32 v[198:199], v[198:199], v[88:89]
	v_pk_fma_f32 v[200:201], v[88:89], v[88:89], v[200:201]
	v_add_f32_e32 v9, v198, v199
	v_add_f32_e32 v90, v200, v201
	s_nop 1
	v_add_f32_dpp v9, v9, v9 quad_perm:[1,0,3,2] row_mask:0xf bank_mask:0xf
	v_add_f32_dpp v90, v90, v90 quad_perm:[1,0,3,2] row_mask:0xf bank_mask:0xf
	s_nop 0
	v_add_f32_dpp v9, v9, v9 quad_perm:[2,3,0,1] row_mask:0xf bank_mask:0xf
	v_add_f32_dpp v90, v90, v90 quad_perm:[2,3,0,1] row_mask:0xf bank_mask:0xf
	s_nop 0
	v_add_f32_dpp v9, v9, v9 row_half_mirror row_mask:0xf bank_mask:0xf
	v_add_f32_dpp v90, v90, v90 row_half_mirror row_mask:0xf bank_mask:0xf
	s_nop 0
	v_add_f32_dpp v9, v9, v9 row_mirror row_mask:0xf bank_mask:0xf
	v_add_f32_dpp v90, v90, v90 row_mirror row_mask:0xf bank_mask:0xf
	s_nop 0
	v_add_f32_dpp v9, v9, v9 row_bcast:15 row_mask:0xa bank_mask:0xf
	v_add_f32_dpp v90, v90, v90 row_bcast:15 row_mask:0xa bank_mask:0xf
	s_nop 0
	v_add_f32_dpp v9, v9, v9 row_bcast:31 row_mask:0xc bank_mask:0xf
; DI unsigned pk2(float lo, float hi) { f32x2 v = {lo, hi}; bf16x2_t b = __builtin_convertvector(v, bf16x2_t); return __builtin_bit_cast(unsigned, b); }
; DI void ln_row_v(const Frame& F, f32x4 (&v)[4], float* xout, const float* g, const float* b, const float* sh, const float* sc, bf16_t* hout, const float* slab, const float* gres, float* stat = nullptr) {
;     ...
;     if (g) {
;         float s = 0.f, s2 = 0.f;
; #pragma unroll
;         for (int j = 0; j < 4; ++j) { s += (v[j][0] + v[j][1]) + (v[j][2] + v[j][3]); s2 += (v[j][0] * v[j][0] + v[j][1] * v[j][1]) + (v[j][2] * v[j][2] + v[j][3] * v[j][3]); }
;         wave_sum2(s, s2, F.lane);
;         const float mean = s * (1.f / D); const float rstd = 1.f / sqrtf(fmaxf(s2 * (1.f / D) - mean * mean, 0.f) + EPS);
;         if (stat && F.lane == 0) { f32x2 sv = {mean, rstd}; *(f32x2*)stat = sv; }
; #pragma unroll
;         for (int j = 0; j < 4; ++j) { const f32x4 gg = ((const f32x4*)g)[F.lane + 64 * j], bb = ((const f32x4*)b)[F.lane + 64 * j];
;             v[j] = (v[j] - mean) * rstd * gg + bb; if (xout) ((f32x4*)xout)[F.lane + 64 * j] = v[j]; }
;     }
;     if (hout) {
;         float s = 0.f, s2 = 0.f;
; #pragma unroll
;         for (int j = 0; j < 4; ++j) { s += (v[j][0] + v[j][1]) + (v[j][2] + v[j][3]); s2 += (v[j][0] * v[j][0] + v[j][1] * v[j][1]) + (v[j][2] * v[j][2] + v[j][3] * v[j][3]); }
;         wave_sum2(s, s2, F.lane);
;         const float mean = s * (1.f / D); const float rstd = 1.f / sqrtf(fmaxf(s2 * (1.f / D) - mean * mean, 0.f) + EPS);
; #pragma unroll
;         for (int j = 0; j < 4; ++j) { const f32x4 hh = ((const f32x4*)sh)[F.lane + 64 * j], cc = ((const f32x4*)sc)[F.lane + 64 * j];
;             const f32x4 o = (v[j] - mean) * rstd * (cc + 1.f) + hh; u32x2 wv; wv.x = pk2(o[0], o[1]); wv.y = pk2(o[2], o[3]);
;             ((u32x2*)hout)[F.lane + 64 * j] = wv; }
	v_add_f32_dpp v90, v90, v90 row_bcast:31 row_mask:0xc bank_mask:0xf
	s_nop 0
	v_readlane_b32 s2, v9, 63
	v_readlane_b32 s3, v90, 63
	s_nop 1
	v_mov_b32_e32 v9, s2
	v_mov_b32_e32 v90, s3
	v_mul_f32_e32 v93, 0x3a800000, v9
	v_mul_f32_e32 v91, 0x3a800000, v90
	v_fma_f32 v91, -v93, v93, v91
	v_max_f32_e32 v91, 0, v91
	v_add_f32_e32 v91, 0x358637bd, v91
	v_rsq_f32_e32 v94, v91
	v_mul_f32_e32 v91, 0.5, v91
	v_mul_f32_e32 v92, v94, v94
	v_fma_f32 v92, -v91, v92, 0.5
	v_fma_f32 v94, v94, v92, v94
	v_pk_add_f32 v[74:75], v[74:75], v[92:93] op_sel:[0,1] op_sel_hi:[1,1] neg_lo:[0,1] neg_hi:[0,1]
	v_pk_add_f32 v[76:77], v[76:77], v[92:93] op_sel:[0,1] op_sel_hi:[1,1] neg_lo:[0,1] neg_hi:[0,1]
	v_pk_add_f32 v[78:79], v[78:79], v[92:93] op_sel:[0,1] op_sel_hi:[1,1] neg_lo:[0,1] neg_hi:[0,1]
	v_pk_add_f32 v[80:81], v[80:81], v[92:93] op_sel:[0,1] op_sel_hi:[1,1] neg_lo:[0,1] neg_hi:[0,1]
	v_pk_add_f32 v[82:83], v[82:83], v[92:93] op_sel:[0,1] op_sel_hi:[1,1] neg_lo:[0,1] neg_hi:[0,1]
	v_pk_add_f32 v[84:85], v[84:85], v[92:93] op_sel:[0,1] op_sel_hi:[1,1] neg_lo:[0,1] neg_hi:[0,1]
	v_pk_add_f32 v[86:87], v[86:87], v[92:93] op_sel:[0,1] op_sel_hi:[1,1] neg_lo:[0,1] neg_hi:[0,1]
	v_pk_add_f32 v[88:89], v[88:89], v[92:93] op_sel:[0,1] op_sel_hi:[1,1] neg_lo:[0,1] neg_hi:[0,1]
	v_pk_mul_f32 v[74:75], v[74:75], v[94:95] op_sel_hi:[1,0]
	v_pk_mul_f32 v[76:77], v[76:77], v[94:95] op_sel_hi:[1,0]
	v_pk_mul_f32 v[78:79], v[78:79], v[94:95] op_sel_hi:[1,0]
	v_pk_mul_f32 v[80:81], v[80:81], v[94:95] op_sel_hi:[1,0]
	v_pk_mul_f32 v[82:83], v[82:83], v[94:95] op_sel_hi:[1,0]
	v_pk_mul_f32 v[84:85], v[84:85], v[94:95] op_sel_hi:[1,0]
	v_pk_mul_f32 v[86:87], v[86:87], v[94:95] op_sel_hi:[1,0]
	v_pk_mul_f32 v[88:89], v[88:89], v[94:95] op_sel_hi:[1,0]
	v_pk_fma_f32 v[74:75], v[74:75], v[130:131], v[114:115]
	v_pk_fma_f32 v[76:77], v[76:77], v[132:133], v[116:117]
	v_pk_fma_f32 v[78:79], v[78:79], v[134:135], v[118:119]
	v_pk_fma_f32 v[80:81], v[80:81], v[136:137], v[120:121]
	v_pk_fma_f32 v[82:83], v[82:83], v[138:139], v[122:123]
	v_pk_fma_f32 v[84:85], v[84:85], v[140:141], v[124:125]
	v_pk_fma_f32 v[86:87], v[86:87], v[142:143], v[126:127]
	v_pk_fma_f32 v[88:89], v[88:89], v[144:145], v[128:129]
	v_cvt_pk_bf16_f32 v190, v74, v75
	v_cvt_pk_bf16_f32 v191, v76, v77
	v_cvt_pk_bf16_f32 v192, v78, v79
	v_cvt_pk_bf16_f32 v193, v80, v81
	v_cvt_pk_bf16_f32 v194, v82, v83
	v_cvt_pk_bf16_f32 v195, v84, v85
	v_cvt_pk_bf16_f32 v196, v86, v87
	v_cvt_pk_bf16_f32 v197, v88, v89
	s_add_u32 s2, s10, 0x1000
	s_addc_u32 s3, s11, 0
	global_store_dwordx2 v1, v[190:191], s[2:3]
	global_store_dwordx2 v1, v[192:193], s[2:3] offset:512
	global_store_dwordx2 v1, v[194:195], s[2:3] offset:1024
	global_store_dwordx2 v1, v[196:197], s[2:3] offset:1536
	s_add_u32 s2, s8, 0x6000
	s_addc_u32 s3, s9, 0
	global_load_dwordx4 v[74:77], v0, s[2:3]
	global_load_dwordx4 v[78:81], v0, s[2:3] offset:1024
	global_load_dwordx4 v[82:85], v0, s[2:3] offset:2048
	global_load_dwordx4 v[86:89], v0, s[2:3] offset:3072
	s_waitcnt vmcnt(27)
	v_pk_add_f32 v[198:199], v[98:99], v[100:101]
	v_pk_mul_f32 v[200:201], v[98:99], v[98:99]
	v_pk_fma_f32 v[200:201], v[100:101], v[100:101], v[200:201]
	v_pk_add_f32 v[198:199], v[198:199], v[102:103]
	v_pk_fma_f32 v[200:201], v[102:103], v[102:103], v[200:201]
	v_pk_add_f32 v[198:199], v[198:199], v[104:105]
	v_pk_fma_f32 v[200:201], v[104:105], v[104:105], v[200:201]
	v_pk_add_f32 v[198:199], v[198:199], v[106:107]
	v_pk_fma_f32 v[200:201], v[106:107], v[106:107], v[200:201]
	v_pk_add_f32 v[198:199], v[198:199], v[108:109]
	v_pk_fma_f32 v[200:201], v[108:109], v[108:109], v[200:201]
	v_pk_add_f32 v[198:199], v[198:199], v[110:111]
	v_pk_fma_f32 v[200:201], v[110:111], v[110:111], v[200:201]
	v_pk_add_f32 v[198:199], v[198:199], v[112:113]
	v_pk_fma_f32 v[200:201], v[112:113], v[112:113], v[200:201]
	v_add_f32_e32 v9, v198, v199
	v_add_f32_e32 v90, v200, v201
	s_nop 1
	v_add_f32_dpp v9, v9, v9 quad_perm:[1,0,3,2] row_mask:0xf bank_mask:0xf
	v_add_f32_dpp v90, v90, v90 quad_perm:[1,0,3,2] row_mask:0xf bank_mask:0xf
	s_nop 0
	v_add_f32_dpp v9, v9, v9 quad_perm:[2,3,0,1] row_mask:0xf bank_mask:0xf
	v_add_f32_dpp v90, v90, v90 quad_perm:[2,3,0,1] row_mask:0xf bank_mask:0xf
	s_nop 0
	v_add_f32_dpp v9, v9, v9 row_half_mirror row_mask:0xf bank_mask:0xf
	v_add_f32_dpp v90, v90, v90 row_half_mirror row_mask:0xf bank_mask:0xf
	s_nop 0
	v_add_f32_dpp v9, v9, v9 row_mirror row_mask:0xf bank_mask:0xf
	v_add_f32_dpp v90, v90, v90 row_mirror row_mask:0xf bank_mask:0xf
	s_nop 0
	v_add_f32_dpp v9, v9, v9 row_bcast:15 row_mask:0xa bank_mask:0xf
	v_add_f32_dpp v90, v90, v90 row_bcast:15 row_mask:0xa bank_mask:0xf
	s_nop 0
	v_add_f32_dpp v9, v9, v9 row_bcast:31 row_mask:0xc bank_mask:0xf
	v_add_f32_dpp v90, v90, v90 row_bcast:31 row_mask:0xc bank_mask:0xf
	s_nop 0
	v_readlane_b32 s2, v9, 63
	v_readlane_b32 s3, v90, 63
	s_nop 1
	v_mov_b32_e32 v9, s2
	v_mov_b32_e32 v90, s3
	v_mul_f32_e32 v93, 0x3a800000, v9
	v_mul_f32_e32 v91, 0x3a800000, v90
	v_fma_f32 v91, -v93, v93, v91
	v_max_f32_e32 v91, 0, v91
	v_add_f32_e32 v91, 0x358637bd, v91
	v_rsq_f32_e32 v94, v91
	v_mul_f32_e32 v91, 0.5, v91
	v_mul_f32_e32 v92, v94, v94
	v_fma_f32 v92, -v91, v92, 0.5
	v_fma_f32 v94, v94, v92, v94
	s_add_u32 s2, s12, 0x18
	s_addc_u32 s3, s13, 0
	v_mov_b32_e32 v188, v93
	v_mov_b32_e32 v189, v94
	s_mov_b64 exec, 1
	global_store_dwordx2 v97, v[188:189], s[2:3]
	s_mov_b64 exec, -1
	v_pk_add_f32 v[98:99], v[98:99], v[92:93] op_sel:[0,1] op_sel_hi:[1,1] neg_lo:[0,1] neg_hi:[0,1]
	v_pk_add_f32 v[100:101], v[100:101], v[92:93] op_sel:[0,1] op_sel_hi:[1,1] neg_lo:[0,1] neg_hi:[0,1]
; DI unsigned pk2(float lo, float hi) { f32x2 v = {lo, hi}; bf16x2_t b = __builtin_convertvector(v, bf16x2_t); return __builtin_bit_cast(unsigned, b); }
; DI void ln_row_v(const Frame& F, f32x4 (&v)[4], float* xout, const float* g, const float* b, const float* sh, const float* sc, bf16_t* hout, const float* slab, const float* gres, float* stat = nullptr) {
;     ...
;     if (g) {
;         float s = 0.f, s2 = 0.f;
; #pragma unroll
;         for (int j = 0; j < 4; ++j) { s += (v[j][0] + v[j][1]) + (v[j][2] + v[j][3]); s2 += (v[j][0] * v[j][0] + v[j][1] * v[j][1]) + (v[j][2] * v[j][2] + v[j][3] * v[j][3]); }
;         wave_sum2(s, s2, F.lane);
;         const float mean = s * (1.f / D); const float rstd = 1.f / sqrtf(fmaxf(s2 * (1.f / D) - mean * mean, 0.f) + EPS);
;         if (stat && F.lane == 0) { f32x2 sv = {mean, rstd}; *(f32x2*)stat = sv; }
; #pragma unroll
;         for (int j = 0; j < 4; ++j) { const f32x4 gg = ((const f32x4*)g)[F.lane + 64 * j], bb = ((const f32x4*)b)[F.lane + 64 * j];
;             v[j] = (v[j] - mean) * rstd * gg + bb; if (xout) ((f32x4*)xout)[F.lane + 64 * j] = v[j]; }
;     }
;     if (hout) {
;         float s = 0.f, s2 = 0.f;
; #pragma unroll
;         for (int j = 0; j < 4; ++j) { s += (v[j][0] + v[j][1]) + (v[j][2] + v[j][3]); s2 += (v[j][0] * v[j][0] + v[j][1] * v[j][1]) + (v[j][2] * v[j][2] + v[j][3] * v[j][3]); }
;         wave_sum2(s, s2, F.lane);
;         const float mean = s * (1.f / D); const float rstd = 1.f / sqrtf(fmaxf(s2 * (1.f / D) - mean * mean, 0.f) + EPS);
; #pragma unroll
;         for (int j = 0; j < 4; ++j) { const f32x4 hh = ((const f32x4*)sh)[F.lane + 64 * j], cc = ((const f32x4*)sc)[F.lane + 64 * j];
;             const f32x4 o = (v[j] - mean) * rstd * (cc + 1.f) + hh; u32x2 wv; wv.x = pk2(o[0], o[1]); wv.y = pk2(o[2], o[3]);
;             ((u32x2*)hout)[F.lane + 64 * j] = wv; }
	v_pk_add_f32 v[102:103], v[102:103], v[92:93] op_sel:[0,1] op_sel_hi:[1,1] neg_lo:[0,1] neg_hi:[0,1]
	v_pk_add_f32 v[104:105], v[104:105], v[92:93] op_sel:[0,1] op_sel_hi:[1,1] neg_lo:[0,1] neg_hi:[0,1]
	v_pk_add_f32 v[106:107], v[106:107], v[92:93] op_sel:[0,1] op_sel_hi:[1,1] neg_lo:[0,1] neg_hi:[0,1]
	v_pk_add_f32 v[108:109], v[108:109], v[92:93] op_sel:[0,1] op_sel_hi:[1,1] neg_lo:[0,1] neg_hi:[0,1]
	v_pk_add_f32 v[110:111], v[110:111], v[92:93] op_sel:[0,1] op_sel_hi:[1,1] neg_lo:[0,1] neg_hi:[0,1]
	v_pk_add_f32 v[112:113], v[112:113], v[92:93] op_sel:[0,1] op_sel_hi:[1,1] neg_lo:[0,1] neg_hi:[0,1]
	v_pk_mul_f32 v[98:99], v[98:99], v[94:95] op_sel_hi:[1,0]
	v_pk_mul_f32 v[100:101], v[100:101], v[94:95] op_sel_hi:[1,0]
	v_pk_mul_f32 v[102:103], v[102:103], v[94:95] op_sel_hi:[1,0]
	v_pk_mul_f32 v[104:105], v[104:105], v[94:95] op_sel_hi:[1,0]
	v_pk_mul_f32 v[106:107], v[106:107], v[94:95] op_sel_hi:[1,0]
	v_pk_mul_f32 v[108:109], v[108:109], v[94:95] op_sel_hi:[1,0]
	v_pk_mul_f32 v[110:111], v[110:111], v[94:95] op_sel_hi:[1,0]
	v_pk_mul_f32 v[112:113], v[112:113], v[94:95] op_sel_hi:[1,0]
	v_pk_fma_f32 v[98:99], v[98:99], v[10:11], v[26:27]
	v_pk_fma_f32 v[100:101], v[100:101], v[12:13], v[28:29]
	v_pk_fma_f32 v[102:103], v[102:103], v[14:15], v[30:31]
	v_pk_fma_f32 v[104:105], v[104:105], v[16:17], v[32:33]
	v_pk_fma_f32 v[106:107], v[106:107], v[18:19], v[34:35]
	v_pk_fma_f32 v[108:109], v[108:109], v[20:21], v[36:37]
	v_pk_fma_f32 v[110:111], v[110:111], v[22:23], v[38:39]
	v_pk_fma_f32 v[112:113], v[112:113], v[24:25], v[40:41]
	v_pk_add_f32 v[198:199], v[98:99], v[100:101]
	v_pk_mul_f32 v[200:201], v[98:99], v[98:99]
	v_pk_fma_f32 v[200:201], v[100:101], v[100:101], v[200:201]
	v_pk_add_f32 v[198:199], v[198:199], v[102:103]
	v_pk_fma_f32 v[200:201], v[102:103], v[102:103], v[200:201]
	v_pk_add_f32 v[198:199], v[198:199], v[104:105]
	v_pk_fma_f32 v[200:201], v[104:105], v[104:105], v[200:201]
	v_pk_add_f32 v[198:199], v[198:199], v[106:107]
	v_pk_fma_f32 v[200:201], v[106:107], v[106:107], v[200:201]
	v_pk_add_f32 v[198:199], v[198:199], v[108:109]
	v_pk_fma_f32 v[200:201], v[108:109], v[108:109], v[200:201]
	v_pk_add_f32 v[198:199], v[198:199], v[110:111]
	v_pk_fma_f32 v[200:201], v[110:111], v[110:111], v[200:201]
	v_pk_add_f32 v[198:199], v[198:199], v[112:113]
	v_pk_fma_f32 v[200:201], v[112:113], v[112:113], v[200:201]
	v_add_f32_e32 v9, v198, v199
	v_add_f32_e32 v90, v200, v201
	s_nop 1
	v_add_f32_dpp v9, v9, v9 quad_perm:[1,0,3,2] row_mask:0xf bank_mask:0xf
	v_add_f32_dpp v90, v90, v90 quad_perm:[1,0,3,2] row_mask:0xf bank_mask:0xf
	s_nop 0
	v_add_f32_dpp v9, v9, v9 quad_perm:[2,3,0,1] row_mask:0xf bank_mask:0xf
	v_add_f32_dpp v90, v90, v90 quad_perm:[2,3,0,1] row_mask:0xf bank_mask:0xf
	s_nop 0
	v_add_f32_dpp v9, v9, v9 row_half_mirror row_mask:0xf bank_mask:0xf
	v_add_f32_dpp v90, v90, v90 row_half_mirror row_mask:0xf bank_mask:0xf
	s_nop 0
	v_add_f32_dpp v9, v9, v9 row_mirror row_mask:0xf bank_mask:0xf
	v_add_f32_dpp v90, v90, v90 row_mirror row_mask:0xf bank_mask:0xf
	s_nop 0
	v_add_f32_dpp v9, v9, v9 row_bcast:15 row_mask:0xa bank_mask:0xf
	v_add_f32_dpp v90, v90, v90 row_bcast:15 row_mask:0xa bank_mask:0xf
	s_nop 0
	v_add_f32_dpp v9, v9, v9 row_bcast:31 row_mask:0xc bank_mask:0xf
	v_add_f32_dpp v90, v90, v90 row_bcast:31 row_mask:0xc bank_mask:0xf
	s_nop 0
	v_readlane_b32 s2, v9, 63
	v_readlane_b32 s3, v90, 63
	s_nop 1
	v_mov_b32_e32 v9, s2
	v_mov_b32_e32 v90, s3
	v_mul_f32_e32 v93, 0x3a800000, v9
	v_mul_f32_e32 v91, 0x3a800000, v90
	v_fma_f32 v91, -v93, v93, v91
	v_max_f32_e32 v91, 0, v91
	v_add_f32_e32 v91, 0x358637bd, v91
	v_rsq_f32_e32 v94, v91
	v_mul_f32_e32 v91, 0.5, v91
	v_mul_f32_e32 v92, v94, v94
	v_fma_f32 v92, -v91, v92, 0.5
	v_fma_f32 v94, v94, v92, v94
	v_pk_add_f32 v[98:99], v[98:99], v[92:93] op_sel:[0,1] op_sel_hi:[1,1] neg_lo:[0,1] neg_hi:[0,1]
	v_pk_add_f32 v[100:101], v[100:101], v[92:93] op_sel:[0,1] op_sel_hi:[1,1] neg_lo:[0,1] neg_hi:[0,1]
	v_pk_add_f32 v[102:103], v[102:103], v[92:93] op_sel:[0,1] op_sel_hi:[1,1] neg_lo:[0,1] neg_hi:[0,1]
	v_pk_add_f32 v[104:105], v[104:105], v[92:93] op_sel:[0,1] op_sel_hi:[1,1] neg_lo:[0,1] neg_hi:[0,1]
	v_pk_add_f32 v[106:107], v[106:107], v[92:93] op_sel:[0,1] op_sel_hi:[1,1] neg_lo:[0,1] neg_hi:[0,1]
	v_pk_add_f32 v[108:109], v[108:109], v[92:93] op_sel:[0,1] op_sel_hi:[1,1] neg_lo:[0,1] neg_hi:[0,1]
	v_pk_add_f32 v[110:111], v[110:111], v[92:93] op_sel:[0,1] op_sel_hi:[1,1] neg_lo:[0,1] neg_hi:[0,1]
	v_pk_add_f32 v[112:113], v[112:113], v[92:93] op_sel:[0,1] op_sel_hi:[1,1] neg_lo:[0,1] neg_hi:[0,1]
	v_pk_mul_f32 v[98:99], v[98:99], v[94:95] op_sel_hi:[1,0]
	v_pk_mul_f32 v[100:101], v[100:101], v[94:95] op_sel_hi:[1,0]
	v_pk_mul_f32 v[102:103], v[102:103], v[94:95] op_sel_hi:[1,0]
	v_pk_mul_f32 v[104:105], v[104:105], v[94:95] op_sel_hi:[1,0]
	v_pk_mul_f32 v[106:107], v[106:107], v[94:95] op_sel_hi:[1,0]
	v_pk_mul_f32 v[108:109], v[108:109], v[94:95] op_sel_hi:[1,0]
	v_pk_mul_f32 v[110:111], v[110:111], v[94:95] op_sel_hi:[1,0]
	v_pk_mul_f32 v[112:113], v[112:113], v[94:95] op_sel_hi:[1,0]
	v_pk_fma_f32 v[98:99], v[98:99], v[130:131], v[114:115]
	v_pk_fma_f32 v[100:101], v[100:101], v[132:133], v[116:117]
	v_pk_fma_f32 v[102:103], v[102:103], v[134:135], v[118:119]
	v_pk_fma_f32 v[104:105], v[104:105], v[136:137], v[120:121]
	v_pk_fma_f32 v[106:107], v[106:107], v[138:139], v[122:123]
	v_pk_fma_f32 v[108:109], v[108:109], v[140:141], v[124:125]
	v_pk_fma_f32 v[110:111], v[110:111], v[142:143], v[126:127]
	v_pk_fma_f32 v[112:113], v[112:113], v[144:145], v[128:129]
	v_cvt_pk_bf16_f32 v190, v98, v99
	v_cvt_pk_bf16_f32 v191, v100, v101
	v_cvt_pk_bf16_f32 v192, v102, v103
	v_cvt_pk_bf16_f32 v193, v104, v105
	v_cvt_pk_bf16_f32 v194, v106, v107
	v_cvt_pk_bf16_f32 v195, v108, v109
	v_cvt_pk_bf16_f32 v196, v110, v111
	v_cvt_pk_bf16_f32 v197, v112, v113
	s_add_u32 s2, s10, 0x1800
	s_addc_u32 s3, s11, 0
	global_store_dwordx2 v1, v[190:191], s[2:3]
	global_store_dwordx2 v1, v[192:193], s[2:3] offset:512
	global_store_dwordx2 v1, v[194:195], s[2:3] offset:1024
	global_store_dwordx2 v1, v[196:197], s[2:3] offset:1536
	s_add_u32 s2, s8, 0x7000
	s_addc_u32 s3, s9, 0
	global_load_dwordx4 v[98:101], v0, s[2:3]
	global_load_dwordx4 v[102:105], v0, s[2:3] offset:1024
	global_load_dwordx4 v[106:109], v0, s[2:3] offset:2048
	global_load_dwordx4 v[110:113], v0, s[2:3] offset:3072
	s_waitcnt vmcnt(27)
; DI unsigned pk2(float lo, float hi) { f32x2 v = {lo, hi}; bf16x2_t b = __builtin_convertvector(v, bf16x2_t); return __builtin_bit_cast(unsigned, b); }
; DI void ln_row_v(const Frame& F, f32x4 (&v)[4], float* xout, const float* g, const float* b, const float* sh, const float* sc, bf16_t* hout, const float* slab, const float* gres, float* stat = nullptr) {
;     ...
;     if (g) {
;         float s = 0.f, s2 = 0.f;
; #pragma unroll
;         for (int j = 0; j < 4; ++j) { s += (v[j][0] + v[j][1]) + (v[j][2] + v[j][3]); s2 += (v[j][0] * v[j][0] + v[j][1] * v[j][1]) + (v[j][2] * v[j][2] + v[j][3] * v[j][3]); }
;         wave_sum2(s, s2, F.lane);
;         const float mean = s * (1.f / D); const float rstd = 1.f / sqrtf(fmaxf(s2 * (1.f / D) - mean * mean, 0.f) + EPS);
;         if (stat && F.lane == 0) { f32x2 sv = {mean, rstd}; *(f32x2*)stat = sv; }
; #pragma unroll
;         for (int j = 0; j < 4; ++j) { const f32x4 gg = ((const f32x4*)g)[F.lane + 64 * j], bb = ((const f32x4*)b)[F.lane + 64 * j];
;             v[j] = (v[j] - mean) * rstd * gg + bb; if (xout) ((f32x4*)xout)[F.lane + 64 * j] = v[j]; }
;     }
;     if (hout) {
;         float s = 0.f, s2 = 0.f;
; #pragma unroll
;         for (int j = 0; j < 4; ++j) { s += (v[j][0] + v[j][1]) + (v[j][2] + v[j][3]); s2 += (v[j][0] * v[j][0] + v[j][1] * v[j][1]) + (v[j][2] * v[j][2] + v[j][3] * v[j][3]); }
;         wave_sum2(s, s2, F.lane);
;         const float mean = s * (1.f / D); const float rstd = 1.f / sqrtf(fmaxf(s2 * (1.f / D) - mean * mean, 0.f) + EPS);
; #pragma unroll
;         for (int j = 0; j < 4; ++j) { const f32x4 hh = ((const f32x4*)sh)[F.lane + 64 * j], cc = ((const f32x4*)sc)[F.lane + 64 * j];
;             const f32x4 o = (v[j] - mean) * rstd * (cc + 1.f) + hh; u32x2 wv; wv.x = pk2(o[0], o[1]); wv.y = pk2(o[2], o[3]);
;             ((u32x2*)hout)[F.lane + 64 * j] = wv; }
	v_pk_add_f32 v[198:199], v[42:43], v[44:45]
	v_pk_mul_f32 v[200:201], v[42:43], v[42:43]
	v_pk_fma_f32 v[200:201], v[44:45], v[44:45], v[200:201]
	v_pk_add_f32 v[198:199], v[198:199], v[46:47]
	v_pk_fma_f32 v[200:201], v[46:47], v[46:47], v[200:201]
	v_pk_add_f32 v[198:199], v[198:199], v[48:49]
	v_pk_fma_f32 v[200:201], v[48:49], v[48:49], v[200:201]
	v_pk_add_f32 v[198:199], v[198:199], v[50:51]
	v_pk_fma_f32 v[200:201], v[50:51], v[50:51], v[200:201]
	v_pk_add_f32 v[198:199], v[198:199], v[52:53]
	v_pk_fma_f32 v[200:201], v[52:53], v[52:53], v[200:201]
	v_pk_add_f32 v[198:199], v[198:199], v[54:55]
	v_pk_fma_f32 v[200:201], v[54:55], v[54:55], v[200:201]
	v_pk_add_f32 v[198:199], v[198:199], v[56:57]
	v_pk_fma_f32 v[200:201], v[56:57], v[56:57], v[200:201]
	v_add_f32_e32 v9, v198, v199
	v_add_f32_e32 v90, v200, v201
	s_nop 1
	v_add_f32_dpp v9, v9, v9 quad_perm:[1,0,3,2] row_mask:0xf bank_mask:0xf
	v_add_f32_dpp v90, v90, v90 quad_perm:[1,0,3,2] row_mask:0xf bank_mask:0xf
	s_nop 0
	v_add_f32_dpp v9, v9, v9 quad_perm:[2,3,0,1] row_mask:0xf bank_mask:0xf
	v_add_f32_dpp v90, v90, v90 quad_perm:[2,3,0,1] row_mask:0xf bank_mask:0xf
	s_nop 0
	v_add_f32_dpp v9, v9, v9 row_half_mirror row_mask:0xf bank_mask:0xf
	v_add_f32_dpp v90, v90, v90 row_half_mirror row_mask:0xf bank_mask:0xf
	s_nop 0
	v_add_f32_dpp v9, v9, v9 row_mirror row_mask:0xf bank_mask:0xf
	v_add_f32_dpp v90, v90, v90 row_mirror row_mask:0xf bank_mask:0xf
	s_nop 0
	v_add_f32_dpp v9, v9, v9 row_bcast:15 row_mask:0xa bank_mask:0xf
	v_add_f32_dpp v90, v90, v90 row_bcast:15 row_mask:0xa bank_mask:0xf
	s_nop 0
	v_add_f32_dpp v9, v9, v9 row_bcast:31 row_mask:0xc bank_mask:0xf
	v_add_f32_dpp v90, v90, v90 row_bcast:31 row_mask:0xc bank_mask:0xf
	s_nop 0
	v_readlane_b32 s2, v9, 63
	v_readlane_b32 s3, v90, 63
	s_nop 1
	v_mov_b32_e32 v9, s2
	v_mov_b32_e32 v90, s3
	v_mul_f32_e32 v93, 0x3a800000, v9
	v_mul_f32_e32 v91, 0x3a800000, v90
	v_fma_f32 v91, -v93, v93, v91
	v_max_f32_e32 v91, 0, v91
	v_add_f32_e32 v91, 0x358637bd, v91
	v_rsq_f32_e32 v94, v91
	v_mul_f32_e32 v91, 0.5, v91
	v_mul_f32_e32 v92, v94, v94
	v_fma_f32 v92, -v91, v92, 0.5
	v_fma_f32 v94, v94, v92, v94
	s_add_u32 s2, s12, 0x20
	s_addc_u32 s3, s13, 0
	v_mov_b32_e32 v188, v93
	v_mov_b32_e32 v189, v94
	s_mov_b64 exec, 1
	global_store_dwordx2 v97, v[188:189], s[2:3]
	s_mov_b64 exec, -1
	v_pk_add_f32 v[42:43], v[42:43], v[92:93] op_sel:[0,1] op_sel_hi:[1,1] neg_lo:[0,1] neg_hi:[0,1]
	v_pk_add_f32 v[44:45], v[44:45], v[92:93] op_sel:[0,1] op_sel_hi:[1,1] neg_lo:[0,1] neg_hi:[0,1]
	v_pk_add_f32 v[46:47], v[46:47], v[92:93] op_sel:[0,1] op_sel_hi:[1,1] neg_lo:[0,1] neg_hi:[0,1]
	v_pk_add_f32 v[48:49], v[48:49], v[92:93] op_sel:[0,1] op_sel_hi:[1,1] neg_lo:[0,1] neg_hi:[0,1]
	v_pk_add_f32 v[50:51], v[50:51], v[92:93] op_sel:[0,1] op_sel_hi:[1,1] neg_lo:[0,1] neg_hi:[0,1]
	v_pk_add_f32 v[52:53], v[52:53], v[92:93] op_sel:[0,1] op_sel_hi:[1,1] neg_lo:[0,1] neg_hi:[0,1]
	v_pk_add_f32 v[54:55], v[54:55], v[92:93] op_sel:[0,1] op_sel_hi:[1,1] neg_lo:[0,1] neg_hi:[0,1]
	v_pk_add_f32 v[56:57], v[56:57], v[92:93] op_sel:[0,1] op_sel_hi:[1,1] neg_lo:[0,1] neg_hi:[0,1]
	v_pk_mul_f32 v[42:43], v[42:43], v[94:95] op_sel_hi:[1,0]
	v_pk_mul_f32 v[44:45], v[44:45], v[94:95] op_sel_hi:[1,0]
	v_pk_mul_f32 v[46:47], v[46:47], v[94:95] op_sel_hi:[1,0]
	v_pk_mul_f32 v[48:49], v[48:49], v[94:95] op_sel_hi:[1,0]
	v_pk_mul_f32 v[50:51], v[50:51], v[94:95] op_sel_hi:[1,0]
	v_pk_mul_f32 v[52:53], v[52:53], v[94:95] op_sel_hi:[1,0]
	v_pk_mul_f32 v[54:55], v[54:55], v[94:95] op_sel_hi:[1,0]
	v_pk_mul_f32 v[56:57], v[56:57], v[94:95] op_sel_hi:[1,0]
	v_pk_fma_f32 v[42:43], v[42:43], v[10:11], v[26:27]
	v_pk_fma_f32 v[44:45], v[44:45], v[12:13], v[28:29]
	v_pk_fma_f32 v[46:47], v[46:47], v[14:15], v[30:31]
	v_pk_fma_f32 v[48:49], v[48:49], v[16:17], v[32:33]
	v_pk_fma_f32 v[50:51], v[50:51], v[18:19], v[34:35]
	v_pk_fma_f32 v[52:53], v[52:53], v[20:21], v[36:37]
	v_pk_fma_f32 v[54:55], v[54:55], v[22:23], v[38:39]
	v_pk_fma_f32 v[56:57], v[56:57], v[24:25], v[40:41]
	v_pk_add_f32 v[198:199], v[42:43], v[44:45]
	v_pk_mul_f32 v[200:201], v[42:43], v[42:43]
	v_pk_fma_f32 v[200:201], v[44:45], v[44:45], v[200:201]
	v_pk_add_f32 v[198:199], v[198:199], v[46:47]
	v_pk_fma_f32 v[200:201], v[46:47], v[46:47], v[200:201]
	v_pk_add_f32 v[198:199], v[198:199], v[48:49]
	v_pk_fma_f32 v[200:201], v[48:49], v[48:49], v[200:201]
	v_pk_add_f32 v[198:199], v[198:199], v[50:51]
	v_pk_fma_f32 v[200:201], v[50:51], v[50:51], v[200:201]
	v_pk_add_f32 v[198:199], v[198:199], v[52:53]
	v_pk_fma_f32 v[200:201], v[52:53], v[52:53], v[200:201]
	v_pk_add_f32 v[198:199], v[198:199], v[54:55]
	v_pk_fma_f32 v[200:201], v[54:55], v[54:55], v[200:201]
	v_pk_add_f32 v[198:199], v[198:199], v[56:57]
	v_pk_fma_f32 v[200:201], v[56:57], v[56:57], v[200:201]
	v_add_f32_e32 v9, v198, v199
	v_add_f32_e32 v90, v200, v201
	s_nop 1
	v_add_f32_dpp v9, v9, v9 quad_perm:[1,0,3,2] row_mask:0xf bank_mask:0xf
	v_add_f32_dpp v90, v90, v90 quad_perm:[1,0,3,2] row_mask:0xf bank_mask:0xf
	s_nop 0
	v_add_f32_dpp v9, v9, v9 quad_perm:[2,3,0,1] row_mask:0xf bank_mask:0xf
	v_add_f32_dpp v90, v90, v90 quad_perm:[2,3,0,1] row_mask:0xf bank_mask:0xf
	s_nop 0
	v_add_f32_dpp v9, v9, v9 row_half_mirror row_mask:0xf bank_mask:0xf
	v_add_f32_dpp v90, v90, v90 row_half_mirror row_mask:0xf bank_mask:0xf
	s_nop 0
	v_add_f32_dpp v9, v9, v9 row_mirror row_mask:0xf bank_mask:0xf
	v_add_f32_dpp v90, v90, v90 row_mirror row_mask:0xf bank_mask:0xf
	s_nop 0
	v_add_f32_dpp v9, v9, v9 row_bcast:15 row_mask:0xa bank_mask:0xf
	v_add_f32_dpp v90, v90, v90 row_bcast:15 row_mask:0xa bank_mask:0xf
	s_nop 0
	v_add_f32_dpp v9, v9, v9 row_bcast:31 row_mask:0xc bank_mask:0xf
; DI unsigned pk2(float lo, float hi) { f32x2 v = {lo, hi}; bf16x2_t b = __builtin_convertvector(v, bf16x2_t); return __builtin_bit_cast(unsigned, b); }
; DI void ln_row_v(const Frame& F, f32x4 (&v)[4], float* xout, const float* g, const float* b, const float* sh, const float* sc, bf16_t* hout, const float* slab, const float* gres, float* stat = nullptr) {
;     ...
;     if (g) {
;         float s = 0.f, s2 = 0.f;
; #pragma unroll
;         for (int j = 0; j < 4; ++j) { s += (v[j][0] + v[j][1]) + (v[j][2] + v[j][3]); s2 += (v[j][0] * v[j][0] + v[j][1] * v[j][1]) + (v[j][2] * v[j][2] + v[j][3] * v[j][3]); }
;         wave_sum2(s, s2, F.lane);
;         const float mean = s * (1.f / D); const float rstd = 1.f / sqrtf(fmaxf(s2 * (1.f / D) - mean * mean, 0.f) + EPS);
;         if (stat && F.lane == 0) { f32x2 sv = {mean, rstd}; *(f32x2*)stat = sv; }
; #pragma unroll
;         for (int j = 0; j < 4; ++j) { const f32x4 gg = ((const f32x4*)g)[F.lane + 64 * j], bb = ((const f32x4*)b)[F.lane + 64 * j];
;             v[j] = (v[j] - mean) * rstd * gg + bb; if (xout) ((f32x4*)xout)[F.lane + 64 * j] = v[j]; }
;     ...
;     if (hout) {
;         float s = 0.f, s2 = 0.f;
; #pragma unroll
;         for (int j = 0; j < 4; ++j) { s += (v[j][0] + v[j][1]) + (v[j][2] + v[j][3]); s2 += (v[j][0] * v[j][0] + v[j][1] * v[j][1]) + (v[j][2] * v[j][2] + v[j][3] * v[j][3]); }
;         wave_sum2(s, s2, F.lane);
;         const float mean = s * (1.f / D); const float rstd = 1.f / sqrtf(fmaxf(s2 * (1.f / D) - mean * mean, 0.f) + EPS);
; #pragma unroll
;         for (int j = 0; j < 4; ++j) { const f32x4 hh = ((const f32x4*)sh)[F.lane + 64 * j], cc = ((const f32x4*)sc)[F.lane + 64 * j];
;             const f32x4 o = (v[j] - mean) * rstd * (cc + 1.f) + hh; u32x2 wv; wv.x = pk2(o[0], o[1]); wv.y = pk2(o[2], o[3]);
;             ((u32x2*)hout)[F.lane + 64 * j] = wv; }
	v_add_f32_dpp v90, v90, v90 row_bcast:31 row_mask:0xc bank_mask:0xf
	s_nop 0
	v_readlane_b32 s2, v9, 63
	v_readlane_b32 s3, v90, 63
	s_nop 1
	v_mov_b32_e32 v9, s2
	v_mov_b32_e32 v90, s3
	v_mul_f32_e32 v93, 0x3a800000, v9
	v_mul_f32_e32 v91, 0x3a800000, v90
	v_fma_f32 v91, -v93, v93, v91
	v_max_f32_e32 v91, 0, v91
	v_add_f32_e32 v91, 0x358637bd, v91
	v_rsq_f32_e32 v94, v91
	v_mul_f32_e32 v91, 0.5, v91
	v_mul_f32_e32 v92, v94, v94
	v_fma_f32 v92, -v91, v92, 0.5
	v_fma_f32 v94, v94, v92, v94
	v_pk_add_f32 v[42:43], v[42:43], v[92:93] op_sel:[0,1] op_sel_hi:[1,1] neg_lo:[0,1] neg_hi:[0,1]
	v_pk_add_f32 v[44:45], v[44:45], v[92:93] op_sel:[0,1] op_sel_hi:[1,1] neg_lo:[0,1] neg_hi:[0,1]
	v_pk_add_f32 v[46:47], v[46:47], v[92:93] op_sel:[0,1] op_sel_hi:[1,1] neg_lo:[0,1] neg_hi:[0,1]
	v_pk_add_f32 v[48:49], v[48:49], v[92:93] op_sel:[0,1] op_sel_hi:[1,1] neg_lo:[0,1] neg_hi:[0,1]
	v_pk_add_f32 v[50:51], v[50:51], v[92:93] op_sel:[0,1] op_sel_hi:[1,1] neg_lo:[0,1] neg_hi:[0,1]
	v_pk_add_f32 v[52:53], v[52:53], v[92:93] op_sel:[0,1] op_sel_hi:[1,1] neg_lo:[0,1] neg_hi:[0,1]
	v_pk_add_f32 v[54:55], v[54:55], v[92:93] op_sel:[0,1] op_sel_hi:[1,1] neg_lo:[0,1] neg_hi:[0,1]
	v_pk_add_f32 v[56:57], v[56:57], v[92:93] op_sel:[0,1] op_sel_hi:[1,1] neg_lo:[0,1] neg_hi:[0,1]
	v_pk_mul_f32 v[42:43], v[42:43], v[94:95] op_sel_hi:[1,0]
	v_pk_mul_f32 v[44:45], v[44:45], v[94:95] op_sel_hi:[1,0]
	v_pk_mul_f32 v[46:47], v[46:47], v[94:95] op_sel_hi:[1,0]
	v_pk_mul_f32 v[48:49], v[48:49], v[94:95] op_sel_hi:[1,0]
	v_pk_mul_f32 v[50:51], v[50:51], v[94:95] op_sel_hi:[1,0]
	v_pk_mul_f32 v[52:53], v[52:53], v[94:95] op_sel_hi:[1,0]
	v_pk_mul_f32 v[54:55], v[54:55], v[94:95] op_sel_hi:[1,0]
	v_pk_mul_f32 v[56:57], v[56:57], v[94:95] op_sel_hi:[1,0]
	v_pk_fma_f32 v[42:43], v[42:43], v[130:131], v[114:115]
	v_pk_fma_f32 v[44:45], v[44:45], v[132:133], v[116:117]
	v_pk_fma_f32 v[46:47], v[46:47], v[134:135], v[118:119]
	v_pk_fma_f32 v[48:49], v[48:49], v[136:137], v[120:121]
	v_pk_fma_f32 v[50:51], v[50:51], v[138:139], v[122:123]
	v_pk_fma_f32 v[52:53], v[52:53], v[140:141], v[124:125]
	v_pk_fma_f32 v[54:55], v[54:55], v[142:143], v[126:127]
	v_pk_fma_f32 v[56:57], v[56:57], v[144:145], v[128:129]
	v_cvt_pk_bf16_f32 v190, v42, v43
	v_cvt_pk_bf16_f32 v191, v44, v45
	v_cvt_pk_bf16_f32 v192, v46, v47
	v_cvt_pk_bf16_f32 v193, v48, v49
	v_cvt_pk_bf16_f32 v194, v50, v51
	v_cvt_pk_bf16_f32 v195, v52, v53
	v_cvt_pk_bf16_f32 v196, v54, v55
	v_cvt_pk_bf16_f32 v197, v56, v57
	s_add_u32 s2, s10, 0x2000
	s_addc_u32 s3, s11, 0
	global_store_dwordx2 v1, v[190:191], s[2:3]
	global_store_dwordx2 v1, v[192:193], s[2:3] offset:512
	global_store_dwordx2 v1, v[194:195], s[2:3] offset:1024
	global_store_dwordx2 v1, v[196:197], s[2:3] offset:1536
	s_mov_b64 s[2:3], s[20:21]
	global_load_dwordx4 v[42:45], v0, s[2:3]
	global_load_dwordx4 v[46:49], v0, s[2:3] offset:1024
	global_load_dwordx4 v[50:53], v0, s[2:3] offset:2048
	global_load_dwordx4 v[54:57], v0, s[2:3] offset:3072
	s_waitcnt vmcnt(27)
	v_pk_add_f32 v[198:199], v[58:59], v[60:61]
	v_pk_mul_f32 v[200:201], v[58:59], v[58:59]
	v_pk_fma_f32 v[200:201], v[60:61], v[60:61], v[200:201]
	v_pk_add_f32 v[198:199], v[198:199], v[62:63]
	v_pk_fma_f32 v[200:201], v[62:63], v[62:63], v[200:201]
	v_pk_add_f32 v[198:199], v[198:199], v[64:65]
	v_pk_fma_f32 v[200:201], v[64:65], v[64:65], v[200:201]
	v_pk_add_f32 v[198:199], v[198:199], v[66:67]
	v_pk_fma_f32 v[200:201], v[66:67], v[66:67], v[200:201]
	v_pk_add_f32 v[198:199], v[198:199], v[68:69]
	v_pk_fma_f32 v[200:201], v[68:69], v[68:69], v[200:201]
	v_pk_add_f32 v[198:199], v[198:199], v[70:71]
	v_pk_fma_f32 v[200:201], v[70:71], v[70:71], v[200:201]
	v_pk_add_f32 v[198:199], v[198:199], v[72:73]
	v_pk_fma_f32 v[200:201], v[72:73], v[72:73], v[200:201]
	v_add_f32_e32 v9, v198, v199
	v_add_f32_e32 v90, v200, v201
	s_nop 1
	v_add_f32_dpp v9, v9, v9 quad_perm:[1,0,3,2] row_mask:0xf bank_mask:0xf
	v_add_f32_dpp v90, v90, v90 quad_perm:[1,0,3,2] row_mask:0xf bank_mask:0xf
	s_nop 0
	v_add_f32_dpp v9, v9, v9 quad_perm:[2,3,0,1] row_mask:0xf bank_mask:0xf
	v_add_f32_dpp v90, v90, v90 quad_perm:[2,3,0,1] row_mask:0xf bank_mask:0xf
	s_nop 0
	v_add_f32_dpp v9, v9, v9 row_half_mirror row_mask:0xf bank_mask:0xf
	v_add_f32_dpp v90, v90, v90 row_half_mirror row_mask:0xf bank_mask:0xf
	s_nop 0
	v_add_f32_dpp v9, v9, v9 row_mirror row_mask:0xf bank_mask:0xf
	v_add_f32_dpp v90, v90, v90 row_mirror row_mask:0xf bank_mask:0xf
	s_nop 0
	v_add_f32_dpp v9, v9, v9 row_bcast:15 row_mask:0xa bank_mask:0xf
	v_add_f32_dpp v90, v90, v90 row_bcast:15 row_mask:0xa bank_mask:0xf
	s_nop 0
	v_add_f32_dpp v9, v9, v9 row_bcast:31 row_mask:0xc bank_mask:0xf
	v_add_f32_dpp v90, v90, v90 row_bcast:31 row_mask:0xc bank_mask:0xf
	s_nop 0
	v_readlane_b32 s2, v9, 63
	v_readlane_b32 s3, v90, 63
	s_nop 1
	v_mov_b32_e32 v9, s2
	v_mov_b32_e32 v90, s3
	v_mul_f32_e32 v93, 0x3a800000, v9
	v_mul_f32_e32 v91, 0x3a800000, v90
	v_fma_f32 v91, -v93, v93, v91
	v_max_f32_e32 v91, 0, v91
	v_add_f32_e32 v91, 0x358637bd, v91
	v_rsq_f32_e32 v94, v91
	v_mul_f32_e32 v91, 0.5, v91
	v_mul_f32_e32 v92, v94, v94
	v_fma_f32 v92, -v91, v92, 0.5
	v_fma_f32 v94, v94, v92, v94
	s_add_u32 s2, s12, 0x28
	s_addc_u32 s3, s13, 0
	v_mov_b32_e32 v188, v93
	v_mov_b32_e32 v189, v94
	s_mov_b64 exec, 1
	global_store_dwordx2 v97, v[188:189], s[2:3]
	s_mov_b64 exec, -1
	v_pk_add_f32 v[58:59], v[58:59], v[92:93] op_sel:[0,1] op_sel_hi:[1,1] neg_lo:[0,1] neg_hi:[0,1]
	v_pk_add_f32 v[60:61], v[60:61], v[92:93] op_sel:[0,1] op_sel_hi:[1,1] neg_lo:[0,1] neg_hi:[0,1]
	v_pk_add_f32 v[62:63], v[62:63], v[92:93] op_sel:[0,1] op_sel_hi:[1,1] neg_lo:[0,1] neg_hi:[0,1]
; DI unsigned pk2(float lo, float hi) { f32x2 v = {lo, hi}; bf16x2_t b = __builtin_convertvector(v, bf16x2_t); return __builtin_bit_cast(unsigned, b); }
; DI void ln_row_v(const Frame& F, f32x4 (&v)[4], float* xout, const float* g, const float* b, const float* sh, const float* sc, bf16_t* hout, const float* slab, const float* gres, float* stat = nullptr) {
;     ...
;     if (g) {
;         float s = 0.f, s2 = 0.f;
; #pragma unroll
;         for (int j = 0; j < 4; ++j) { s += (v[j][0] + v[j][1]) + (v[j][2] + v[j][3]); s2 += (v[j][0] * v[j][0] + v[j][1] * v[j][1]) + (v[j][2] * v[j][2] + v[j][3] * v[j][3]); }
;         wave_sum2(s, s2, F.lane);
;         const float mean = s * (1.f / D); const float rstd = 1.f / sqrtf(fmaxf(s2 * (1.f / D) - mean * mean, 0.f) + EPS);
;         if (stat && F.lane == 0) { f32x2 sv = {mean, rstd}; *(f32x2*)stat = sv; }
; #pragma unroll
;         for (int j = 0; j < 4; ++j) { const f32x4 gg = ((const f32x4*)g)[F.lane + 64 * j], bb = ((const f32x4*)b)[F.lane + 64 * j];
;             v[j] = (v[j] - mean) * rstd * gg + bb; if (xout) ((f32x4*)xout)[F.lane + 64 * j] = v[j]; }
;     }
;     if (hout) {
;         float s = 0.f, s2 = 0.f;
; #pragma unroll
;         for (int j = 0; j < 4; ++j) { s += (v[j][0] + v[j][1]) + (v[j][2] + v[j][3]); s2 += (v[j][0] * v[j][0] + v[j][1] * v[j][1]) + (v[j][2] * v[j][2] + v[j][3] * v[j][3]); }
;         wave_sum2(s, s2, F.lane);
;         const float mean = s * (1.f / D); const float rstd = 1.f / sqrtf(fmaxf(s2 * (1.f / D) - mean * mean, 0.f) + EPS);
; #pragma unroll
;         for (int j = 0; j < 4; ++j) { const f32x4 hh = ((const f32x4*)sh)[F.lane + 64 * j], cc = ((const f32x4*)sc)[F.lane + 64 * j];
;             const f32x4 o = (v[j] - mean) * rstd * (cc + 1.f) + hh; u32x2 wv; wv.x = pk2(o[0], o[1]); wv.y = pk2(o[2], o[3]);
;             ((u32x2*)hout)[F.lane + 64 * j] = wv; }
	v_pk_add_f32 v[64:65], v[64:65], v[92:93] op_sel:[0,1] op_sel_hi:[1,1] neg_lo:[0,1] neg_hi:[0,1]
	v_pk_add_f32 v[66:67], v[66:67], v[92:93] op_sel:[0,1] op_sel_hi:[1,1] neg_lo:[0,1] neg_hi:[0,1]
	v_pk_add_f32 v[68:69], v[68:69], v[92:93] op_sel:[0,1] op_sel_hi:[1,1] neg_lo:[0,1] neg_hi:[0,1]
	v_pk_add_f32 v[70:71], v[70:71], v[92:93] op_sel:[0,1] op_sel_hi:[1,1] neg_lo:[0,1] neg_hi:[0,1]
	v_pk_add_f32 v[72:73], v[72:73], v[92:93] op_sel:[0,1] op_sel_hi:[1,1] neg_lo:[0,1] neg_hi:[0,1]
	v_pk_mul_f32 v[58:59], v[58:59], v[94:95] op_sel_hi:[1,0]
	v_pk_mul_f32 v[60:61], v[60:61], v[94:95] op_sel_hi:[1,0]
	v_pk_mul_f32 v[62:63], v[62:63], v[94:95] op_sel_hi:[1,0]
	v_pk_mul_f32 v[64:65], v[64:65], v[94:95] op_sel_hi:[1,0]
	v_pk_mul_f32 v[66:67], v[66:67], v[94:95] op_sel_hi:[1,0]
	v_pk_mul_f32 v[68:69], v[68:69], v[94:95] op_sel_hi:[1,0]
	v_pk_mul_f32 v[70:71], v[70:71], v[94:95] op_sel_hi:[1,0]
	v_pk_mul_f32 v[72:73], v[72:73], v[94:95] op_sel_hi:[1,0]
	v_pk_fma_f32 v[58:59], v[58:59], v[10:11], v[26:27]
	v_pk_fma_f32 v[60:61], v[60:61], v[12:13], v[28:29]
	v_pk_fma_f32 v[62:63], v[62:63], v[14:15], v[30:31]
	v_pk_fma_f32 v[64:65], v[64:65], v[16:17], v[32:33]
	v_pk_fma_f32 v[66:67], v[66:67], v[18:19], v[34:35]
	v_pk_fma_f32 v[68:69], v[68:69], v[20:21], v[36:37]
	v_pk_fma_f32 v[70:71], v[70:71], v[22:23], v[38:39]
	v_pk_fma_f32 v[72:73], v[72:73], v[24:25], v[40:41]
	v_pk_add_f32 v[198:199], v[58:59], v[60:61]
	v_pk_mul_f32 v[200:201], v[58:59], v[58:59]
	v_pk_fma_f32 v[200:201], v[60:61], v[60:61], v[200:201]
	v_pk_add_f32 v[198:199], v[198:199], v[62:63]
	v_pk_fma_f32 v[200:201], v[62:63], v[62:63], v[200:201]
	v_pk_add_f32 v[198:199], v[198:199], v[64:65]
	v_pk_fma_f32 v[200:201], v[64:65], v[64:65], v[200:201]
	v_pk_add_f32 v[198:199], v[198:199], v[66:67]
	v_pk_fma_f32 v[200:201], v[66:67], v[66:67], v[200:201]
	v_pk_add_f32 v[198:199], v[198:199], v[68:69]
	v_pk_fma_f32 v[200:201], v[68:69], v[68:69], v[200:201]
	v_pk_add_f32 v[198:199], v[198:199], v[70:71]
	v_pk_fma_f32 v[200:201], v[70:71], v[70:71], v[200:201]
	v_pk_add_f32 v[198:199], v[198:199], v[72:73]
	v_pk_fma_f32 v[200:201], v[72:73], v[72:73], v[200:201]
	v_add_f32_e32 v9, v198, v199
	v_add_f32_e32 v90, v200, v201
	s_nop 1
	v_add_f32_dpp v9, v9, v9 quad_perm:[1,0,3,2] row_mask:0xf bank_mask:0xf
	v_add_f32_dpp v90, v90, v90 quad_perm:[1,0,3,2] row_mask:0xf bank_mask:0xf
	s_nop 0
	v_add_f32_dpp v9, v9, v9 quad_perm:[2,3,0,1] row_mask:0xf bank_mask:0xf
	v_add_f32_dpp v90, v90, v90 quad_perm:[2,3,0,1] row_mask:0xf bank_mask:0xf
	s_nop 0
	v_add_f32_dpp v9, v9, v9 row_half_mirror row_mask:0xf bank_mask:0xf
	v_add_f32_dpp v90, v90, v90 row_half_mirror row_mask:0xf bank_mask:0xf
	s_nop 0
	v_add_f32_dpp v9, v9, v9 row_mirror row_mask:0xf bank_mask:0xf
	v_add_f32_dpp v90, v90, v90 row_mirror row_mask:0xf bank_mask:0xf
	s_nop 0
	v_add_f32_dpp v9, v9, v9 row_bcast:15 row_mask:0xa bank_mask:0xf
	v_add_f32_dpp v90, v90, v90 row_bcast:15 row_mask:0xa bank_mask:0xf
	s_nop 0
	v_add_f32_dpp v9, v9, v9 row_bcast:31 row_mask:0xc bank_mask:0xf
	v_add_f32_dpp v90, v90, v90 row_bcast:31 row_mask:0xc bank_mask:0xf
	s_nop 0
	v_readlane_b32 s2, v9, 63
	v_readlane_b32 s3, v90, 63
	s_nop 1
	v_mov_b32_e32 v9, s2
	v_mov_b32_e32 v90, s3
	v_mul_f32_e32 v93, 0x3a800000, v9
	v_mul_f32_e32 v91, 0x3a800000, v90
	v_fma_f32 v91, -v93, v93, v91
	v_max_f32_e32 v91, 0, v91
	v_add_f32_e32 v91, 0x358637bd, v91
	v_rsq_f32_e32 v94, v91
	v_mul_f32_e32 v91, 0.5, v91
	v_mul_f32_e32 v92, v94, v94
	v_fma_f32 v92, -v91, v92, 0.5
	v_fma_f32 v94, v94, v92, v94
	v_pk_add_f32 v[58:59], v[58:59], v[92:93] op_sel:[0,1] op_sel_hi:[1,1] neg_lo:[0,1] neg_hi:[0,1]
	v_pk_add_f32 v[60:61], v[60:61], v[92:93] op_sel:[0,1] op_sel_hi:[1,1] neg_lo:[0,1] neg_hi:[0,1]
	v_pk_add_f32 v[62:63], v[62:63], v[92:93] op_sel:[0,1] op_sel_hi:[1,1] neg_lo:[0,1] neg_hi:[0,1]
	v_pk_add_f32 v[64:65], v[64:65], v[92:93] op_sel:[0,1] op_sel_hi:[1,1] neg_lo:[0,1] neg_hi:[0,1]
	v_pk_add_f32 v[66:67], v[66:67], v[92:93] op_sel:[0,1] op_sel_hi:[1,1] neg_lo:[0,1] neg_hi:[0,1]
	v_pk_add_f32 v[68:69], v[68:69], v[92:93] op_sel:[0,1] op_sel_hi:[1,1] neg_lo:[0,1] neg_hi:[0,1]
	v_pk_add_f32 v[70:71], v[70:71], v[92:93] op_sel:[0,1] op_sel_hi:[1,1] neg_lo:[0,1] neg_hi:[0,1]
	v_pk_add_f32 v[72:73], v[72:73], v[92:93] op_sel:[0,1] op_sel_hi:[1,1] neg_lo:[0,1] neg_hi:[0,1]
	v_pk_mul_f32 v[58:59], v[58:59], v[94:95] op_sel_hi:[1,0]
	v_pk_mul_f32 v[60:61], v[60:61], v[94:95] op_sel_hi:[1,0]
	v_pk_mul_f32 v[62:63], v[62:63], v[94:95] op_sel_hi:[1,0]
	v_pk_mul_f32 v[64:65], v[64:65], v[94:95] op_sel_hi:[1,0]
	v_pk_mul_f32 v[66:67], v[66:67], v[94:95] op_sel_hi:[1,0]
	v_pk_mul_f32 v[68:69], v[68:69], v[94:95] op_sel_hi:[1,0]
	v_pk_mul_f32 v[70:71], v[70:71], v[94:95] op_sel_hi:[1,0]
	v_pk_mul_f32 v[72:73], v[72:73], v[94:95] op_sel_hi:[1,0]
	v_pk_fma_f32 v[58:59], v[58:59], v[130:131], v[114:115]
	v_pk_fma_f32 v[60:61], v[60:61], v[132:133], v[116:117]
	v_pk_fma_f32 v[62:63], v[62:63], v[134:135], v[118:119]
	v_pk_fma_f32 v[64:65], v[64:65], v[136:137], v[120:121]
	v_pk_fma_f32 v[66:67], v[66:67], v[138:139], v[122:123]
	v_pk_fma_f32 v[68:69], v[68:69], v[140:141], v[124:125]
	v_pk_fma_f32 v[70:71], v[70:71], v[142:143], v[126:127]
	v_pk_fma_f32 v[72:73], v[72:73], v[144:145], v[128:129]
	v_cvt_pk_bf16_f32 v190, v58, v59
	v_cvt_pk_bf16_f32 v191, v60, v61
	v_cvt_pk_bf16_f32 v192, v62, v63
	v_cvt_pk_bf16_f32 v193, v64, v65
	v_cvt_pk_bf16_f32 v194, v66, v67
	v_cvt_pk_bf16_f32 v195, v68, v69
	v_cvt_pk_bf16_f32 v196, v70, v71
	v_cvt_pk_bf16_f32 v197, v72, v73
	s_add_u32 s2, s10, 0x2800
	s_addc_u32 s3, s11, 0
	global_store_dwordx2 v1, v[190:191], s[2:3]
	global_store_dwordx2 v1, v[192:193], s[2:3] offset:512
	global_store_dwordx2 v1, v[194:195], s[2:3] offset:1024
	global_store_dwordx2 v1, v[196:197], s[2:3] offset:1536
	s_waitcnt vmcnt(23)
; DI unsigned pk2(float lo, float hi) { f32x2 v = {lo, hi}; bf16x2_t b = __builtin_convertvector(v, bf16x2_t); return __builtin_bit_cast(unsigned, b); }
; DI void ln_row_v(const Frame& F, f32x4 (&v)[4], float* xout, const float* g, const float* b, const float* sh, const float* sc, bf16_t* hout, const float* slab, const float* gres, float* stat = nullptr) {
;     ...
;     if (g) {
;         float s = 0.f, s2 = 0.f;
; #pragma unroll
;         for (int j = 0; j < 4; ++j) { s += (v[j][0] + v[j][1]) + (v[j][2] + v[j][3]); s2 += (v[j][0] * v[j][0] + v[j][1] * v[j][1]) + (v[j][2] * v[j][2] + v[j][3] * v[j][3]); }
;         wave_sum2(s, s2, F.lane);
;         const float mean = s * (1.f / D); const float rstd = 1.f / sqrtf(fmaxf(s2 * (1.f / D) - mean * mean, 0.f) + EPS);
;         if (stat && F.lane == 0) { f32x2 sv = {mean, rstd}; *(f32x2*)stat = sv; }
; #pragma unroll
;         for (int j = 0; j < 4; ++j) { const f32x4 gg = ((const f32x4*)g)[F.lane + 64 * j], bb = ((const f32x4*)b)[F.lane + 64 * j];
;             v[j] = (v[j] - mean) * rstd * gg + bb; if (xout) ((f32x4*)xout)[F.lane + 64 * j] = v[j]; }
;     }
;     if (hout) {
;         float s = 0.f, s2 = 0.f;
; #pragma unroll
;         for (int j = 0; j < 4; ++j) { s += (v[j][0] + v[j][1]) + (v[j][2] + v[j][3]); s2 += (v[j][0] * v[j][0] + v[j][1] * v[j][1]) + (v[j][2] * v[j][2] + v[j][3] * v[j][3]); }
;         wave_sum2(s, s2, F.lane);
;         const float mean = s * (1.f / D); const float rstd = 1.f / sqrtf(fmaxf(s2 * (1.f / D) - mean * mean, 0.f) + EPS);
; #pragma unroll
;         for (int j = 0; j < 4; ++j) { const f32x4 hh = ((const f32x4*)sh)[F.lane + 64 * j], cc = ((const f32x4*)sc)[F.lane + 64 * j];
;             const f32x4 o = (v[j] - mean) * rstd * (cc + 1.f) + hh; u32x2 wv; wv.x = pk2(o[0], o[1]); wv.y = pk2(o[2], o[3]);
;             ((u32x2*)hout)[F.lane + 64 * j] = wv; }
	v_pk_add_f32 v[198:199], v[74:75], v[76:77]
	v_pk_mul_f32 v[200:201], v[74:75], v[74:75]
	v_pk_fma_f32 v[200:201], v[76:77], v[76:77], v[200:201]
	v_pk_add_f32 v[198:199], v[198:199], v[78:79]
	v_pk_fma_f32 v[200:201], v[78:79], v[78:79], v[200:201]
	v_pk_add_f32 v[198:199], v[198:199], v[80:81]
	v_pk_fma_f32 v[200:201], v[80:81], v[80:81], v[200:201]
	v_pk_add_f32 v[198:199], v[198:199], v[82:83]
	v_pk_fma_f32 v[200:201], v[82:83], v[82:83], v[200:201]
	v_pk_add_f32 v[198:199], v[198:199], v[84:85]
	v_pk_fma_f32 v[200:201], v[84:85], v[84:85], v[200:201]
	v_pk_add_f32 v[198:199], v[198:199], v[86:87]
	v_pk_fma_f32 v[200:201], v[86:87], v[86:87], v[200:201]
	v_pk_add_f32 v[198:199], v[198:199], v[88:89]
	v_pk_fma_f32 v[200:201], v[88:89], v[88:89], v[200:201]
	v_add_f32_e32 v9, v198, v199
	v_add_f32_e32 v90, v200, v201
	s_nop 1
	v_add_f32_dpp v9, v9, v9 quad_perm:[1,0,3,2] row_mask:0xf bank_mask:0xf
	v_add_f32_dpp v90, v90, v90 quad_perm:[1,0,3,2] row_mask:0xf bank_mask:0xf
	s_nop 0
	v_add_f32_dpp v9, v9, v9 quad_perm:[2,3,0,1] row_mask:0xf bank_mask:0xf
	v_add_f32_dpp v90, v90, v90 quad_perm:[2,3,0,1] row_mask:0xf bank_mask:0xf
	s_nop 0
	v_add_f32_dpp v9, v9, v9 row_half_mirror row_mask:0xf bank_mask:0xf
	v_add_f32_dpp v90, v90, v90 row_half_mirror row_mask:0xf bank_mask:0xf
	s_nop 0
	v_add_f32_dpp v9, v9, v9 row_mirror row_mask:0xf bank_mask:0xf
	v_add_f32_dpp v90, v90, v90 row_mirror row_mask:0xf bank_mask:0xf
	s_nop 0
	v_add_f32_dpp v9, v9, v9 row_bcast:15 row_mask:0xa bank_mask:0xf
	v_add_f32_dpp v90, v90, v90 row_bcast:15 row_mask:0xa bank_mask:0xf
	s_nop 0
	v_add_f32_dpp v9, v9, v9 row_bcast:31 row_mask:0xc bank_mask:0xf
	v_add_f32_dpp v90, v90, v90 row_bcast:31 row_mask:0xc bank_mask:0xf
	s_nop 0
	v_readlane_b32 s2, v9, 63
	v_readlane_b32 s3, v90, 63
	s_nop 1
	v_mov_b32_e32 v9, s2
	v_mov_b32_e32 v90, s3
	v_mul_f32_e32 v93, 0x3a800000, v9
	v_mul_f32_e32 v91, 0x3a800000, v90
	v_fma_f32 v91, -v93, v93, v91
	v_max_f32_e32 v91, 0, v91
	v_add_f32_e32 v91, 0x358637bd, v91
	v_rsq_f32_e32 v94, v91
	v_mul_f32_e32 v91, 0.5, v91
	v_mul_f32_e32 v92, v94, v94
	v_fma_f32 v92, -v91, v92, 0.5
	v_fma_f32 v94, v94, v92, v94
	s_add_u32 s2, s12, 0x30
	s_addc_u32 s3, s13, 0
	v_mov_b32_e32 v188, v93
	v_mov_b32_e32 v189, v94
	s_mov_b64 exec, 1
	global_store_dwordx2 v97, v[188:189], s[2:3]
	s_mov_b64 exec, -1
	v_pk_add_f32 v[74:75], v[74:75], v[92:93] op_sel:[0,1] op_sel_hi:[1,1] neg_lo:[0,1] neg_hi:[0,1]
	v_pk_add_f32 v[76:77], v[76:77], v[92:93] op_sel:[0,1] op_sel_hi:[1,1] neg_lo:[0,1] neg_hi:[0,1]
	v_pk_add_f32 v[78:79], v[78:79], v[92:93] op_sel:[0,1] op_sel_hi:[1,1] neg_lo:[0,1] neg_hi:[0,1]
	v_pk_add_f32 v[80:81], v[80:81], v[92:93] op_sel:[0,1] op_sel_hi:[1,1] neg_lo:[0,1] neg_hi:[0,1]
	v_pk_add_f32 v[82:83], v[82:83], v[92:93] op_sel:[0,1] op_sel_hi:[1,1] neg_lo:[0,1] neg_hi:[0,1]
	v_pk_add_f32 v[84:85], v[84:85], v[92:93] op_sel:[0,1] op_sel_hi:[1,1] neg_lo:[0,1] neg_hi:[0,1]
	v_pk_add_f32 v[86:87], v[86:87], v[92:93] op_sel:[0,1] op_sel_hi:[1,1] neg_lo:[0,1] neg_hi:[0,1]
	v_pk_add_f32 v[88:89], v[88:89], v[92:93] op_sel:[0,1] op_sel_hi:[1,1] neg_lo:[0,1] neg_hi:[0,1]
	v_pk_mul_f32 v[74:75], v[74:75], v[94:95] op_sel_hi:[1,0]
	v_pk_mul_f32 v[76:77], v[76:77], v[94:95] op_sel_hi:[1,0]
	v_pk_mul_f32 v[78:79], v[78:79], v[94:95] op_sel_hi:[1,0]
	v_pk_mul_f32 v[80:81], v[80:81], v[94:95] op_sel_hi:[1,0]
	v_pk_mul_f32 v[82:83], v[82:83], v[94:95] op_sel_hi:[1,0]
	v_pk_mul_f32 v[84:85], v[84:85], v[94:95] op_sel_hi:[1,0]
	v_pk_mul_f32 v[86:87], v[86:87], v[94:95] op_sel_hi:[1,0]
	v_pk_mul_f32 v[88:89], v[88:89], v[94:95] op_sel_hi:[1,0]
	v_pk_fma_f32 v[74:75], v[74:75], v[10:11], v[26:27]
	v_pk_fma_f32 v[76:77], v[76:77], v[12:13], v[28:29]
	v_pk_fma_f32 v[78:79], v[78:79], v[14:15], v[30:31]
	v_pk_fma_f32 v[80:81], v[80:81], v[16:17], v[32:33]
	v_pk_fma_f32 v[82:83], v[82:83], v[18:19], v[34:35]
	v_pk_fma_f32 v[84:85], v[84:85], v[20:21], v[36:37]
	v_pk_fma_f32 v[86:87], v[86:87], v[22:23], v[38:39]
	v_pk_fma_f32 v[88:89], v[88:89], v[24:25], v[40:41]
	v_pk_add_f32 v[198:199], v[74:75], v[76:77]
	v_pk_mul_f32 v[200:201], v[74:75], v[74:75]
	v_pk_fma_f32 v[200:201], v[76:77], v[76:77], v[200:201]
	v_pk_add_f32 v[198:199], v[198:199], v[78:79]
	v_pk_fma_f32 v[200:201], v[78:79], v[78:79], v[200:201]
	v_pk_add_f32 v[198:199], v[198:199], v[80:81]
	v_pk_fma_f32 v[200:201], v[80:81], v[80:81], v[200:201]
	v_pk_add_f32 v[198:199], v[198:199], v[82:83]
	v_pk_fma_f32 v[200:201], v[82:83], v[82:83], v[200:201]
	v_pk_add_f32 v[198:199], v[198:199], v[84:85]
	v_pk_fma_f32 v[200:201], v[84:85], v[84:85], v[200:201]
	v_pk_add_f32 v[198:199], v[198:199], v[86:87]
	v_pk_fma_f32 v[200:201], v[86:87], v[86:87], v[200:201]
	v_pk_add_f32 v[198:199], v[198:199], v[88:89]
	v_pk_fma_f32 v[200:201], v[88:89], v[88:89], v[200:201]
	v_add_f32_e32 v9, v198, v199
	v_add_f32_e32 v90, v200, v201
	s_nop 1
	v_add_f32_dpp v9, v9, v9 quad_perm:[1,0,3,2] row_mask:0xf bank_mask:0xf
	v_add_f32_dpp v90, v90, v90 quad_perm:[1,0,3,2] row_mask:0xf bank_mask:0xf
	s_nop 0
	v_add_f32_dpp v9, v9, v9 quad_perm:[2,3,0,1] row_mask:0xf bank_mask:0xf
	v_add_f32_dpp v90, v90, v90 quad_perm:[2,3,0,1] row_mask:0xf bank_mask:0xf
	s_nop 0
	v_add_f32_dpp v9, v9, v9 row_half_mirror row_mask:0xf bank_mask:0xf
	v_add_f32_dpp v90, v90, v90 row_half_mirror row_mask:0xf bank_mask:0xf
	s_nop 0
	v_add_f32_dpp v9, v9, v9 row_mirror row_mask:0xf bank_mask:0xf
	v_add_f32_dpp v90, v90, v90 row_mirror row_mask:0xf bank_mask:0xf
	s_nop 0
	v_add_f32_dpp v9, v9, v9 row_bcast:15 row_mask:0xa bank_mask:0xf
	v_add_f32_dpp v90, v90, v90 row_bcast:15 row_mask:0xa bank_mask:0xf
	s_nop 0
	v_add_f32_dpp v9, v9, v9 row_bcast:31 row_mask:0xc bank_mask:0xf
; DI unsigned pk2(float lo, float hi) { f32x2 v = {lo, hi}; bf16x2_t b = __builtin_convertvector(v, bf16x2_t); return __builtin_bit_cast(unsigned, b); }
; DI void ln_row_v(const Frame& F, f32x4 (&v)[4], float* xout, const float* g, const float* b, const float* sh, const float* sc, bf16_t* hout, const float* slab, const float* gres, float* stat = nullptr) {
;     ...
;     if (g) {
;         float s = 0.f, s2 = 0.f;
; #pragma unroll
;         for (int j = 0; j < 4; ++j) { s += (v[j][0] + v[j][1]) + (v[j][2] + v[j][3]); s2 += (v[j][0] * v[j][0] + v[j][1] * v[j][1]) + (v[j][2] * v[j][2] + v[j][3] * v[j][3]); }
;         wave_sum2(s, s2, F.lane);
;         const float mean = s * (1.f / D); const float rstd = 1.f / sqrtf(fmaxf(s2 * (1.f / D) - mean * mean, 0.f) + EPS);
;         if (stat && F.lane == 0) { f32x2 sv = {mean, rstd}; *(f32x2*)stat = sv; }
; #pragma unroll
;         for (int j = 0; j < 4; ++j) { const f32x4 gg = ((const f32x4*)g)[F.lane + 64 * j], bb = ((const f32x4*)b)[F.lane + 64 * j];
;             v[j] = (v[j] - mean) * rstd * gg + bb; if (xout) ((f32x4*)xout)[F.lane + 64 * j] = v[j]; }
;     ...
;     if (hout) {
;         float s = 0.f, s2 = 0.f;
; #pragma unroll
;         for (int j = 0; j < 4; ++j) { s += (v[j][0] + v[j][1]) + (v[j][2] + v[j][3]); s2 += (v[j][0] * v[j][0] + v[j][1] * v[j][1]) + (v[j][2] * v[j][2] + v[j][3] * v[j][3]); }
;         wave_sum2(s, s2, F.lane);
;         const float mean = s * (1.f / D); const float rstd = 1.f / sqrtf(fmaxf(s2 * (1.f / D) - mean * mean, 0.f) + EPS);
; #pragma unroll
;         for (int j = 0; j < 4; ++j) { const f32x4 hh = ((const f32x4*)sh)[F.lane + 64 * j], cc = ((const f32x4*)sc)[F.lane + 64 * j];
;             const f32x4 o = (v[j] - mean) * rstd * (cc + 1.f) + hh; u32x2 wv; wv.x = pk2(o[0], o[1]); wv.y = pk2(o[2], o[3]);
;             ((u32x2*)hout)[F.lane + 64 * j] = wv; }
	v_add_f32_dpp v90, v90, v90 row_bcast:31 row_mask:0xc bank_mask:0xf
	s_nop 0
	v_readlane_b32 s2, v9, 63
	v_readlane_b32 s3, v90, 63
	s_nop 1
	v_mov_b32_e32 v9, s2
	v_mov_b32_e32 v90, s3
	v_mul_f32_e32 v93, 0x3a800000, v9
	v_mul_f32_e32 v91, 0x3a800000, v90
	v_fma_f32 v91, -v93, v93, v91
	v_max_f32_e32 v91, 0, v91
	v_add_f32_e32 v91, 0x358637bd, v91
	v_rsq_f32_e32 v94, v91
	v_mul_f32_e32 v91, 0.5, v91
	v_mul_f32_e32 v92, v94, v94
	v_fma_f32 v92, -v91, v92, 0.5
	v_fma_f32 v94, v94, v92, v94
	v_pk_add_f32 v[74:75], v[74:75], v[92:93] op_sel:[0,1] op_sel_hi:[1,1] neg_lo:[0,1] neg_hi:[0,1]
	v_pk_add_f32 v[76:77], v[76:77], v[92:93] op_sel:[0,1] op_sel_hi:[1,1] neg_lo:[0,1] neg_hi:[0,1]
	v_pk_add_f32 v[78:79], v[78:79], v[92:93] op_sel:[0,1] op_sel_hi:[1,1] neg_lo:[0,1] neg_hi:[0,1]
	v_pk_add_f32 v[80:81], v[80:81], v[92:93] op_sel:[0,1] op_sel_hi:[1,1] neg_lo:[0,1] neg_hi:[0,1]
	v_pk_add_f32 v[82:83], v[82:83], v[92:93] op_sel:[0,1] op_sel_hi:[1,1] neg_lo:[0,1] neg_hi:[0,1]
	v_pk_add_f32 v[84:85], v[84:85], v[92:93] op_sel:[0,1] op_sel_hi:[1,1] neg_lo:[0,1] neg_hi:[0,1]
	v_pk_add_f32 v[86:87], v[86:87], v[92:93] op_sel:[0,1] op_sel_hi:[1,1] neg_lo:[0,1] neg_hi:[0,1]
	v_pk_add_f32 v[88:89], v[88:89], v[92:93] op_sel:[0,1] op_sel_hi:[1,1] neg_lo:[0,1] neg_hi:[0,1]
	v_pk_mul_f32 v[74:75], v[74:75], v[94:95] op_sel_hi:[1,0]
	v_pk_mul_f32 v[76:77], v[76:77], v[94:95] op_sel_hi:[1,0]
	v_pk_mul_f32 v[78:79], v[78:79], v[94:95] op_sel_hi:[1,0]
	v_pk_mul_f32 v[80:81], v[80:81], v[94:95] op_sel_hi:[1,0]
	v_pk_mul_f32 v[82:83], v[82:83], v[94:95] op_sel_hi:[1,0]
	v_pk_mul_f32 v[84:85], v[84:85], v[94:95] op_sel_hi:[1,0]
	v_pk_mul_f32 v[86:87], v[86:87], v[94:95] op_sel_hi:[1,0]
	v_pk_mul_f32 v[88:89], v[88:89], v[94:95] op_sel_hi:[1,0]
	v_pk_fma_f32 v[74:75], v[74:75], v[130:131], v[114:115]
	v_pk_fma_f32 v[76:77], v[76:77], v[132:133], v[116:117]
	v_pk_fma_f32 v[78:79], v[78:79], v[134:135], v[118:119]
	v_pk_fma_f32 v[80:81], v[80:81], v[136:137], v[120:121]
	v_pk_fma_f32 v[82:83], v[82:83], v[138:139], v[122:123]
	v_pk_fma_f32 v[84:85], v[84:85], v[140:141], v[124:125]
	v_pk_fma_f32 v[86:87], v[86:87], v[142:143], v[126:127]
	v_pk_fma_f32 v[88:89], v[88:89], v[144:145], v[128:129]
	v_cvt_pk_bf16_f32 v190, v74, v75
	v_cvt_pk_bf16_f32 v191, v76, v77
	v_cvt_pk_bf16_f32 v192, v78, v79
	v_cvt_pk_bf16_f32 v193, v80, v81
	v_cvt_pk_bf16_f32 v194, v82, v83
	v_cvt_pk_bf16_f32 v195, v84, v85
	v_cvt_pk_bf16_f32 v196, v86, v87
	v_cvt_pk_bf16_f32 v197, v88, v89
	s_add_u32 s2, s10, 0x3000
	s_addc_u32 s3, s11, 0
	global_store_dwordx2 v1, v[190:191], s[2:3]
	global_store_dwordx2 v1, v[192:193], s[2:3] offset:512
	global_store_dwordx2 v1, v[194:195], s[2:3] offset:1024
	global_store_dwordx2 v1, v[196:197], s[2:3] offset:1536
	s_waitcnt vmcnt(19)
	v_pk_add_f32 v[198:199], v[98:99], v[100:101]
	v_pk_mul_f32 v[200:201], v[98:99], v[98:99]
	v_pk_fma_f32 v[200:201], v[100:101], v[100:101], v[200:201]
	v_pk_add_f32 v[198:199], v[198:199], v[102:103]
	v_pk_fma_f32 v[200:201], v[102:103], v[102:103], v[200:201]
	v_pk_add_f32 v[198:199], v[198:199], v[104:105]
	v_pk_fma_f32 v[200:201], v[104:105], v[104:105], v[200:201]
	v_pk_add_f32 v[198:199], v[198:199], v[106:107]
	v_pk_fma_f32 v[200:201], v[106:107], v[106:107], v[200:201]
	v_pk_add_f32 v[198:199], v[198:199], v[108:109]
	v_pk_fma_f32 v[200:201], v[108:109], v[108:109], v[200:201]
	v_pk_add_f32 v[198:199], v[198:199], v[110:111]
	v_pk_fma_f32 v[200:201], v[110:111], v[110:111], v[200:201]
	v_pk_add_f32 v[198:199], v[198:199], v[112:113]
	v_pk_fma_f32 v[200:201], v[112:113], v[112:113], v[200:201]
	v_add_f32_e32 v9, v198, v199
	v_add_f32_e32 v90, v200, v201
	s_nop 1
	v_add_f32_dpp v9, v9, v9 quad_perm:[1,0,3,2] row_mask:0xf bank_mask:0xf
	v_add_f32_dpp v90, v90, v90 quad_perm:[1,0,3,2] row_mask:0xf bank_mask:0xf
	s_nop 0
	v_add_f32_dpp v9, v9, v9 quad_perm:[2,3,0,1] row_mask:0xf bank_mask:0xf
	v_add_f32_dpp v90, v90, v90 quad_perm:[2,3,0,1] row_mask:0xf bank_mask:0xf
	s_nop 0
	v_add_f32_dpp v9, v9, v9 row_half_mirror row_mask:0xf bank_mask:0xf
	v_add_f32_dpp v90, v90, v90 row_half_mirror row_mask:0xf bank_mask:0xf
	s_nop 0
	v_add_f32_dpp v9, v9, v9 row_mirror row_mask:0xf bank_mask:0xf
	v_add_f32_dpp v90, v90, v90 row_mirror row_mask:0xf bank_mask:0xf
	s_nop 0
	v_add_f32_dpp v9, v9, v9 row_bcast:15 row_mask:0xa bank_mask:0xf
	v_add_f32_dpp v90, v90, v90 row_bcast:15 row_mask:0xa bank_mask:0xf
	s_nop 0
	v_add_f32_dpp v9, v9, v9 row_bcast:31 row_mask:0xc bank_mask:0xf
	v_add_f32_dpp v90, v90, v90 row_bcast:31 row_mask:0xc bank_mask:0xf
	s_nop 0
	v_readlane_b32 s2, v9, 63
	v_readlane_b32 s3, v90, 63
	s_nop 1
	v_mov_b32_e32 v9, s2
	v_mov_b32_e32 v90, s3
	v_mul_f32_e32 v93, 0x3a800000, v9
	v_mul_f32_e32 v91, 0x3a800000, v90
	v_fma_f32 v91, -v93, v93, v91
	v_max_f32_e32 v91, 0, v91
	v_add_f32_e32 v91, 0x358637bd, v91
	v_rsq_f32_e32 v94, v91
	v_mul_f32_e32 v91, 0.5, v91
	v_mul_f32_e32 v92, v94, v94
	v_fma_f32 v92, -v91, v92, 0.5
	v_fma_f32 v94, v94, v92, v94
	s_add_u32 s2, s12, 0x38
	s_addc_u32 s3, s13, 0
	v_mov_b32_e32 v188, v93
	v_mov_b32_e32 v189, v94
	s_mov_b64 exec, 1
	global_store_dwordx2 v97, v[188:189], s[2:3]
	s_mov_b64 exec, -1
	v_pk_add_f32 v[98:99], v[98:99], v[92:93] op_sel:[0,1] op_sel_hi:[1,1] neg_lo:[0,1] neg_hi:[0,1]
	v_pk_add_f32 v[100:101], v[100:101], v[92:93] op_sel:[0,1] op_sel_hi:[1,1] neg_lo:[0,1] neg_hi:[0,1]
	v_pk_add_f32 v[102:103], v[102:103], v[92:93] op_sel:[0,1] op_sel_hi:[1,1] neg_lo:[0,1] neg_hi:[0,1]
	v_pk_add_f32 v[104:105], v[104:105], v[92:93] op_sel:[0,1] op_sel_hi:[1,1] neg_lo:[0,1] neg_hi:[0,1]
	v_pk_add_f32 v[106:107], v[106:107], v[92:93] op_sel:[0,1] op_sel_hi:[1,1] neg_lo:[0,1] neg_hi:[0,1]
; DI unsigned pk2(float lo, float hi) { f32x2 v = {lo, hi}; bf16x2_t b = __builtin_convertvector(v, bf16x2_t); return __builtin_bit_cast(unsigned, b); }
; DI void ln_row_v(const Frame& F, f32x4 (&v)[4], float* xout, const float* g, const float* b, const float* sh, const float* sc, bf16_t* hout, const float* slab, const float* gres, float* stat = nullptr) {
;     ...
;     if (g) {
;         float s = 0.f, s2 = 0.f;
; #pragma unroll
;         for (int j = 0; j < 4; ++j) { s += (v[j][0] + v[j][1]) + (v[j][2] + v[j][3]); s2 += (v[j][0] * v[j][0] + v[j][1] * v[j][1]) + (v[j][2] * v[j][2] + v[j][3] * v[j][3]); }
;         wave_sum2(s, s2, F.lane);
;         const float mean = s * (1.f / D); const float rstd = 1.f / sqrtf(fmaxf(s2 * (1.f / D) - mean * mean, 0.f) + EPS);
;         if (stat && F.lane == 0) { f32x2 sv = {mean, rstd}; *(f32x2*)stat = sv; }
; #pragma unroll
;         for (int j = 0; j < 4; ++j) { const f32x4 gg = ((const f32x4*)g)[F.lane + 64 * j], bb = ((const f32x4*)b)[F.lane + 64 * j];
;             v[j] = (v[j] - mean) * rstd * gg + bb; if (xout) ((f32x4*)xout)[F.lane + 64 * j] = v[j]; }
;     }
;     if (hout) {
;         float s = 0.f, s2 = 0.f;
; #pragma unroll
;         for (int j = 0; j < 4; ++j) { s += (v[j][0] + v[j][1]) + (v[j][2] + v[j][3]); s2 += (v[j][0] * v[j][0] + v[j][1] * v[j][1]) + (v[j][2] * v[j][2] + v[j][3] * v[j][3]); }
;         wave_sum2(s, s2, F.lane);
;         const float mean = s * (1.f / D); const float rstd = 1.f / sqrtf(fmaxf(s2 * (1.f / D) - mean * mean, 0.f) + EPS);
; #pragma unroll
;         for (int j = 0; j < 4; ++j) { const f32x4 hh = ((const f32x4*)sh)[F.lane + 64 * j], cc = ((const f32x4*)sc)[F.lane + 64 * j];
;             const f32x4 o = (v[j] - mean) * rstd * (cc + 1.f) + hh; u32x2 wv; wv.x = pk2(o[0], o[1]); wv.y = pk2(o[2], o[3]);
;             ((u32x2*)hout)[F.lane + 64 * j] = wv; }
	v_pk_add_f32 v[108:109], v[108:109], v[92:93] op_sel:[0,1] op_sel_hi:[1,1] neg_lo:[0,1] neg_hi:[0,1]
	v_pk_add_f32 v[110:111], v[110:111], v[92:93] op_sel:[0,1] op_sel_hi:[1,1] neg_lo:[0,1] neg_hi:[0,1]
	v_pk_add_f32 v[112:113], v[112:113], v[92:93] op_sel:[0,1] op_sel_hi:[1,1] neg_lo:[0,1] neg_hi:[0,1]
	v_pk_mul_f32 v[98:99], v[98:99], v[94:95] op_sel_hi:[1,0]
	v_pk_mul_f32 v[100:101], v[100:101], v[94:95] op_sel_hi:[1,0]
	v_pk_mul_f32 v[102:103], v[102:103], v[94:95] op_sel_hi:[1,0]
	v_pk_mul_f32 v[104:105], v[104:105], v[94:95] op_sel_hi:[1,0]
	v_pk_mul_f32 v[106:107], v[106:107], v[94:95] op_sel_hi:[1,0]
	v_pk_mul_f32 v[108:109], v[108:109], v[94:95] op_sel_hi:[1,0]
	v_pk_mul_f32 v[110:111], v[110:111], v[94:95] op_sel_hi:[1,0]
	v_pk_mul_f32 v[112:113], v[112:113], v[94:95] op_sel_hi:[1,0]
	v_pk_fma_f32 v[98:99], v[98:99], v[10:11], v[26:27]
	v_pk_fma_f32 v[100:101], v[100:101], v[12:13], v[28:29]
	v_pk_fma_f32 v[102:103], v[102:103], v[14:15], v[30:31]
	v_pk_fma_f32 v[104:105], v[104:105], v[16:17], v[32:33]
	v_pk_fma_f32 v[106:107], v[106:107], v[18:19], v[34:35]
	v_pk_fma_f32 v[108:109], v[108:109], v[20:21], v[36:37]
	v_pk_fma_f32 v[110:111], v[110:111], v[22:23], v[38:39]
	v_pk_fma_f32 v[112:113], v[112:113], v[24:25], v[40:41]
	v_pk_add_f32 v[198:199], v[98:99], v[100:101]
	v_pk_mul_f32 v[200:201], v[98:99], v[98:99]
	v_pk_fma_f32 v[200:201], v[100:101], v[100:101], v[200:201]
	v_pk_add_f32 v[198:199], v[198:199], v[102:103]
	v_pk_fma_f32 v[200:201], v[102:103], v[102:103], v[200:201]
	v_pk_add_f32 v[198:199], v[198:199], v[104:105]
	v_pk_fma_f32 v[200:201], v[104:105], v[104:105], v[200:201]
	v_pk_add_f32 v[198:199], v[198:199], v[106:107]
	v_pk_fma_f32 v[200:201], v[106:107], v[106:107], v[200:201]
	v_pk_add_f32 v[198:199], v[198:199], v[108:109]
	v_pk_fma_f32 v[200:201], v[108:109], v[108:109], v[200:201]
	v_pk_add_f32 v[198:199], v[198:199], v[110:111]
	v_pk_fma_f32 v[200:201], v[110:111], v[110:111], v[200:201]
	v_pk_add_f32 v[198:199], v[198:199], v[112:113]
	v_pk_fma_f32 v[200:201], v[112:113], v[112:113], v[200:201]
	v_add_f32_e32 v9, v198, v199
	v_add_f32_e32 v90, v200, v201
	s_nop 1
	v_add_f32_dpp v9, v9, v9 quad_perm:[1,0,3,2] row_mask:0xf bank_mask:0xf
	v_add_f32_dpp v90, v90, v90 quad_perm:[1,0,3,2] row_mask:0xf bank_mask:0xf
	s_nop 0
	v_add_f32_dpp v9, v9, v9 quad_perm:[2,3,0,1] row_mask:0xf bank_mask:0xf
	v_add_f32_dpp v90, v90, v90 quad_perm:[2,3,0,1] row_mask:0xf bank_mask:0xf
	s_nop 0
	v_add_f32_dpp v9, v9, v9 row_half_mirror row_mask:0xf bank_mask:0xf
	v_add_f32_dpp v90, v90, v90 row_half_mirror row_mask:0xf bank_mask:0xf
	s_nop 0
	v_add_f32_dpp v9, v9, v9 row_mirror row_mask:0xf bank_mask:0xf
	v_add_f32_dpp v90, v90, v90 row_mirror row_mask:0xf bank_mask:0xf
	s_nop 0
	v_add_f32_dpp v9, v9, v9 row_bcast:15 row_mask:0xa bank_mask:0xf
	v_add_f32_dpp v90, v90, v90 row_bcast:15 row_mask:0xa bank_mask:0xf
	s_nop 0
	v_add_f32_dpp v9, v9, v9 row_bcast:31 row_mask:0xc bank_mask:0xf
	v_add_f32_dpp v90, v90, v90 row_bcast:31 row_mask:0xc bank_mask:0xf
	s_nop 0
	v_readlane_b32 s2, v9, 63
	v_readlane_b32 s3, v90, 63
	s_nop 1
	v_mov_b32_e32 v9, s2
	v_mov_b32_e32 v90, s3
	v_mul_f32_e32 v93, 0x3a800000, v9
	v_mul_f32_e32 v91, 0x3a800000, v90
	v_fma_f32 v91, -v93, v93, v91
	v_max_f32_e32 v91, 0, v91
	v_add_f32_e32 v91, 0x358637bd, v91
	v_rsq_f32_e32 v94, v91
	v_mul_f32_e32 v91, 0.5, v91
	v_mul_f32_e32 v92, v94, v94
	v_fma_f32 v92, -v91, v92, 0.5
	v_fma_f32 v94, v94, v92, v94
	v_pk_add_f32 v[98:99], v[98:99], v[92:93] op_sel:[0,1] op_sel_hi:[1,1] neg_lo:[0,1] neg_hi:[0,1]
	v_pk_add_f32 v[100:101], v[100:101], v[92:93] op_sel:[0,1] op_sel_hi:[1,1] neg_lo:[0,1] neg_hi:[0,1]
	v_pk_add_f32 v[102:103], v[102:103], v[92:93] op_sel:[0,1] op_sel_hi:[1,1] neg_lo:[0,1] neg_hi:[0,1]
	v_pk_add_f32 v[104:105], v[104:105], v[92:93] op_sel:[0,1] op_sel_hi:[1,1] neg_lo:[0,1] neg_hi:[0,1]
	v_pk_add_f32 v[106:107], v[106:107], v[92:93] op_sel:[0,1] op_sel_hi:[1,1] neg_lo:[0,1] neg_hi:[0,1]
	v_pk_add_f32 v[108:109], v[108:109], v[92:93] op_sel:[0,1] op_sel_hi:[1,1] neg_lo:[0,1] neg_hi:[0,1]
	v_pk_add_f32 v[110:111], v[110:111], v[92:93] op_sel:[0,1] op_sel_hi:[1,1] neg_lo:[0,1] neg_hi:[0,1]
	v_pk_add_f32 v[112:113], v[112:113], v[92:93] op_sel:[0,1] op_sel_hi:[1,1] neg_lo:[0,1] neg_hi:[0,1]
	v_pk_mul_f32 v[98:99], v[98:99], v[94:95] op_sel_hi:[1,0]
	v_pk_mul_f32 v[100:101], v[100:101], v[94:95] op_sel_hi:[1,0]
	v_pk_mul_f32 v[102:103], v[102:103], v[94:95] op_sel_hi:[1,0]
	v_pk_mul_f32 v[104:105], v[104:105], v[94:95] op_sel_hi:[1,0]
	v_pk_mul_f32 v[106:107], v[106:107], v[94:95] op_sel_hi:[1,0]
	v_pk_mul_f32 v[108:109], v[108:109], v[94:95] op_sel_hi:[1,0]
	v_pk_mul_f32 v[110:111], v[110:111], v[94:95] op_sel_hi:[1,0]
	v_pk_mul_f32 v[112:113], v[112:113], v[94:95] op_sel_hi:[1,0]
	v_pk_fma_f32 v[98:99], v[98:99], v[130:131], v[114:115]
	v_pk_fma_f32 v[100:101], v[100:101], v[132:133], v[116:117]
	v_pk_fma_f32 v[102:103], v[102:103], v[134:135], v[118:119]
	v_pk_fma_f32 v[104:105], v[104:105], v[136:137], v[120:121]
	v_pk_fma_f32 v[106:107], v[106:107], v[138:139], v[122:123]
	v_pk_fma_f32 v[108:109], v[108:109], v[140:141], v[124:125]
	v_pk_fma_f32 v[110:111], v[110:111], v[142:143], v[126:127]
	v_pk_fma_f32 v[112:113], v[112:113], v[144:145], v[128:129]
	v_cvt_pk_bf16_f32 v190, v98, v99
	v_cvt_pk_bf16_f32 v191, v100, v101
	v_cvt_pk_bf16_f32 v192, v102, v103
	v_cvt_pk_bf16_f32 v193, v104, v105
	v_cvt_pk_bf16_f32 v194, v106, v107
	v_cvt_pk_bf16_f32 v195, v108, v109
	v_cvt_pk_bf16_f32 v196, v110, v111
	v_cvt_pk_bf16_f32 v197, v112, v113
	s_add_u32 s2, s10, 0x3800
	s_addc_u32 s3, s11, 0
	global_store_dwordx2 v1, v[190:191], s[2:3]
	global_store_dwordx2 v1, v[192:193], s[2:3] offset:512
	global_store_dwordx2 v1, v[194:195], s[2:3] offset:1024
	global_store_dwordx2 v1, v[196:197], s[2:3] offset:1536
	s_cmp_eq_u32 s22, 3
	s_cbranch_scc1 .Lln_b_noctx
; DI void ln_row_v(const Frame& F, f32x4 (&v)[4], float* xout, const float* g, const float* b, const float* sh, const float* sc, bf16_t* hout, const float* slab, const float* gres, float* stat = nullptr) {
;     if (slab) {
; #pragma unroll
;         for (int j = 0; j < 4; ++j) { f32x4 a = ((const f32x4*)slab)[F.lane + 64 * j];
; #pragma unroll
;             for (int z = 1; z < 8; ++z) a += ((const f32x4*)(slab + (size_t)z * MC * 1024))[F.lane + 64 * j];
;             v[j] = v[j] * ALPHA + ((const f32x4*)gres)[F.lane + 64 * j] * a; }
;     }
	s_add_u32 s2, s24, 0x0
	s_addc_u32 s3, s25, 0
	global_load_dwordx4 v[58:61], v0, s[2:3]
	global_load_dwordx4 v[62:65], v0, s[2:3] offset:1024
	global_load_dwordx4 v[66:69], v0, s[2:3] offset:2048
	global_load_dwordx4 v[70:73], v0, s[2:3] offset:3072
	s_add_u32 s2, s24, 0x800000
	s_addc_u32 s3, s25, 0
	global_load_dwordx4 v[74:77], v0, s[2:3]
	global_load_dwordx4 v[78:81], v0, s[2:3] offset:1024
	global_load_dwordx4 v[82:85], v0, s[2:3] offset:2048
	global_load_dwordx4 v[86:89], v0, s[2:3] offset:3072
	s_add_u32 s2, s24, 0x1000000
	s_addc_u32 s3, s25, 0
	global_load_dwordx4 v[98:101], v0, s[2:3]
	global_load_dwordx4 v[102:105], v0, s[2:3] offset:1024
	global_load_dwordx4 v[106:109], v0, s[2:3] offset:2048
	global_load_dwordx4 v[110:113], v0, s[2:3] offset:3072
	s_add_u32 s2, s24, 0x1800000
	s_addc_u32 s3, s25, 0
	global_load_dwordx4 v[146:149], v0, s[2:3]
	global_load_dwordx4 v[150:153], v0, s[2:3] offset:1024
	global_load_dwordx4 v[154:157], v0, s[2:3] offset:2048
	global_load_dwordx4 v[158:161], v0, s[2:3] offset:3072
	s_add_u32 s2, s24, 0x2000000
	s_addc_u32 s3, s25, 0
	global_load_dwordx4 v[162:165], v0, s[2:3]
	global_load_dwordx4 v[166:169], v0, s[2:3] offset:1024
	global_load_dwordx4 v[170:173], v0, s[2:3] offset:2048
	global_load_dwordx4 v[174:177], v0, s[2:3] offset:3072
	s_mov_b64 s[2:3], s[26:27]
	global_load_dwordx4 v[226:229], v0, s[2:3]
	global_load_dwordx4 v[230:233], v0, s[2:3] offset:1024
	global_load_dwordx4 v[234:237], v0, s[2:3] offset:2048
	global_load_dwordx4 v[238:241], v0, s[2:3] offset:3072
	s_waitcnt vmcnt(16)
	v_add_f32_e32 v58, v58, v74
	v_add_f32_e32 v59, v59, v75
	v_add_f32_e32 v60, v60, v76
	v_add_f32_e32 v61, v61, v77
	v_add_f32_e32 v62, v62, v78
	v_add_f32_e32 v63, v63, v79
	v_add_f32_e32 v64, v64, v80
	v_add_f32_e32 v65, v65, v81
	v_add_f32_e32 v66, v66, v82
	v_add_f32_e32 v67, v67, v83
	v_add_f32_e32 v68, v68, v84
	v_add_f32_e32 v69, v69, v85
	v_add_f32_e32 v70, v70, v86
	v_add_f32_e32 v71, v71, v87
	v_add_f32_e32 v72, v72, v88
	v_add_f32_e32 v73, v73, v89
	s_add_u32 s2, s24, 0x2800000
	s_addc_u32 s3, s25, 0
	global_load_dwordx4 v[74:77], v0, s[2:3]
	global_load_dwordx4 v[78:81], v0, s[2:3] offset:1024
	global_load_dwordx4 v[82:85], v0, s[2:3] offset:2048
	global_load_dwordx4 v[86:89], v0, s[2:3] offset:3072
	s_waitcnt vmcnt(16)
	v_add_f32_e32 v58, v58, v98
	v_add_f32_e32 v59, v59, v99
	v_add_f32_e32 v60, v60, v100
	v_add_f32_e32 v61, v61, v101
	v_add_f32_e32 v62, v62, v102
	v_add_f32_e32 v63, v63, v103
	v_add_f32_e32 v64, v64, v104
	v_add_f32_e32 v65, v65, v105
	v_add_f32_e32 v66, v66, v106
	v_add_f32_e32 v67, v67, v107
	v_add_f32_e32 v68, v68, v108
	v_add_f32_e32 v69, v69, v109
	v_add_f32_e32 v70, v70, v110
	v_add_f32_e32 v71, v71, v111
	v_add_f32_e32 v72, v72, v112
	v_add_f32_e32 v73, v73, v113
	s_add_u32 s2, s24, 0x3000000
	s_addc_u32 s3, s25, 0
	global_load_dwordx4 v[98:101], v0, s[2:3]
	global_load_dwordx4 v[102:105], v0, s[2:3] offset:1024
	global_load_dwordx4 v[106:109], v0, s[2:3] offset:2048
	global_load_dwordx4 v[110:113], v0, s[2:3] offset:3072
	s_waitcnt vmcnt(16)
	v_add_f32_e32 v58, v58, v146
	v_add_f32_e32 v59, v59, v147
	v_add_f32_e32 v60, v60, v148
	v_add_f32_e32 v61, v61, v149
	v_add_f32_e32 v62, v62, v150
	v_add_f32_e32 v63, v63, v151
	v_add_f32_e32 v64, v64, v152
	v_add_f32_e32 v65, v65, v153
	v_add_f32_e32 v66, v66, v154
	v_add_f32_e32 v67, v67, v155
	v_add_f32_e32 v68, v68, v156
	v_add_f32_e32 v69, v69, v157
	v_add_f32_e32 v70, v70, v158
	v_add_f32_e32 v71, v71, v159
	v_add_f32_e32 v72, v72, v160
	v_add_f32_e32 v73, v73, v161
	s_add_u32 s2, s24, 0x3800000
	s_addc_u32 s3, s25, 0
	global_load_dwordx4 v[146:149], v0, s[2:3]
	global_load_dwordx4 v[150:153], v0, s[2:3] offset:1024
	global_load_dwordx4 v[154:157], v0, s[2:3] offset:2048
	global_load_dwordx4 v[158:161], v0, s[2:3] offset:3072
	s_waitcnt vmcnt(16)
	v_add_f32_e32 v58, v58, v162
	v_add_f32_e32 v59, v59, v163
	v_add_f32_e32 v60, v60, v164
	v_add_f32_e32 v61, v61, v165
	v_add_f32_e32 v62, v62, v166
	v_add_f32_e32 v63, v63, v167
	v_add_f32_e32 v64, v64, v168
	v_add_f32_e32 v65, v65, v169
	v_add_f32_e32 v66, v66, v170
	v_add_f32_e32 v67, v67, v171
	v_add_f32_e32 v68, v68, v172
	v_add_f32_e32 v69, v69, v173
	v_add_f32_e32 v70, v70, v174
	v_add_f32_e32 v71, v71, v175
	v_add_f32_e32 v72, v72, v176
	v_add_f32_e32 v73, v73, v177
	s_waitcnt vmcnt(8)
	v_add_f32_e32 v58, v58, v74
	v_add_f32_e32 v59, v59, v75
	v_add_f32_e32 v60, v60, v76
	v_add_f32_e32 v61, v61, v77
	v_add_f32_e32 v62, v62, v78
	v_add_f32_e32 v63, v63, v79
	v_add_f32_e32 v64, v64, v80
	v_add_f32_e32 v65, v65, v81
	v_add_f32_e32 v66, v66, v82
	v_add_f32_e32 v67, v67, v83
	v_add_f32_e32 v68, v68, v84
	v_add_f32_e32 v69, v69, v85
	v_add_f32_e32 v70, v70, v86
	v_add_f32_e32 v71, v71, v87
	v_add_f32_e32 v72, v72, v88
	v_add_f32_e32 v73, v73, v89
	s_waitcnt vmcnt(4)
	v_add_f32_e32 v58, v58, v98
	v_add_f32_e32 v59, v59, v99
	v_add_f32_e32 v60, v60, v100
	v_add_f32_e32 v61, v61, v101
	v_add_f32_e32 v62, v62, v102
	v_add_f32_e32 v63, v63, v103
	v_add_f32_e32 v64, v64, v104
	v_add_f32_e32 v65, v65, v105
	v_add_f32_e32 v66, v66, v106
	v_add_f32_e32 v67, v67, v107
	v_add_f32_e32 v68, v68, v108
	v_add_f32_e32 v69, v69, v109
	v_add_f32_e32 v70, v70, v110
	v_add_f32_e32 v71, v71, v111
	v_add_f32_e32 v72, v72, v112
	v_add_f32_e32 v73, v73, v113
	s_waitcnt vmcnt(0)
; DI void ln_row_v(const Frame& F, f32x4 (&v)[4], float* xout, const float* g, const float* b, const float* sh, const float* sc, bf16_t* hout, const float* slab, const float* gres, float* stat = nullptr) {
;     if (slab) {
; #pragma unroll
;         for (int j = 0; j < 4; ++j) { f32x4 a = ((const f32x4*)slab)[F.lane + 64 * j];
; #pragma unroll
;             for (int z = 1; z < 8; ++z) a += ((const f32x4*)(slab + (size_t)z * MC * 1024))[F.lane + 64 * j];
;             v[j] = v[j] * ALPHA + ((const f32x4*)gres)[F.lane + 64 * j] * a; }
;     }
;     if (g) {
;         float s = 0.f, s2 = 0.f;
; #pragma unroll
;         for (int j = 0; j < 4; ++j) { s += (v[j][0] + v[j][1]) + (v[j][2] + v[j][3]); s2 += (v[j][0] * v[j][0] + v[j][1] * v[j][1]) + (v[j][2] * v[j][2] + v[j][3] * v[j][3]); }
;         wave_sum2(s, s2, F.lane);
;         const float mean = s * (1.f / D); const float rstd = 1.f / sqrtf(fmaxf(s2 * (1.f / D) - mean * mean, 0.f) + EPS);
;         if (stat && F.lane == 0) { f32x2 sv = {mean, rstd}; *(f32x2*)stat = sv; }
; #pragma unroll
;         for (int j = 0; j < 4; ++j) { const f32x4 gg = ((const f32x4*)g)[F.lane + 64 * j], bb = ((const f32x4*)b)[F.lane + 64 * j];
;             v[j] = (v[j] - mean) * rstd * gg + bb; if (xout) ((f32x4*)xout)[F.lane + 64 * j] = v[j]; }
	v_add_f32_e32 v58, v58, v146
	v_add_f32_e32 v59, v59, v147
	v_add_f32_e32 v60, v60, v148
	v_add_f32_e32 v61, v61, v149
	v_add_f32_e32 v62, v62, v150
	v_add_f32_e32 v63, v63, v151
	v_add_f32_e32 v64, v64, v152
	v_add_f32_e32 v65, v65, v153
	v_add_f32_e32 v66, v66, v154
	v_add_f32_e32 v67, v67, v155
	v_add_f32_e32 v68, v68, v156
	v_add_f32_e32 v69, v69, v157
	v_add_f32_e32 v70, v70, v158
	v_add_f32_e32 v71, v71, v159
	v_add_f32_e32 v72, v72, v160
	v_add_f32_e32 v73, v73, v161
	s_mov_b32 s23, 0x30000
	s_add_u32 s2, s14, s23
	s_addc_u32 s3, s15, 0
	global_load_dwordx4 v[146:149], v0, s[2:3]
	global_load_dwordx4 v[150:153], v0, s[2:3] offset:1024
	global_load_dwordx4 v[154:157], v0, s[2:3] offset:2048
	global_load_dwordx4 v[158:161], v0, s[2:3] offset:3072
	s_add_u32 s2, s18, s23
	s_addc_u32 s3, s19, 0
	global_load_dwordx4 v[162:165], v0, s[2:3]
	global_load_dwordx4 v[166:169], v0, s[2:3] offset:1024
	global_load_dwordx4 v[170:173], v0, s[2:3] offset:2048
	global_load_dwordx4 v[174:177], v0, s[2:3] offset:3072
	v_mul_f32_e32 v42, 0x3fd744fd, v42
	v_mul_f32_e32 v43, 0x3fd744fd, v43
	v_mul_f32_e32 v44, 0x3fd744fd, v44
	v_mul_f32_e32 v45, 0x3fd744fd, v45
	v_mul_f32_e32 v46, 0x3fd744fd, v46
	v_mul_f32_e32 v47, 0x3fd744fd, v47
	v_mul_f32_e32 v48, 0x3fd744fd, v48
	v_mul_f32_e32 v49, 0x3fd744fd, v49
	v_mul_f32_e32 v50, 0x3fd744fd, v50
	v_mul_f32_e32 v51, 0x3fd744fd, v51
	v_mul_f32_e32 v52, 0x3fd744fd, v52
	v_mul_f32_e32 v53, 0x3fd744fd, v53
	v_mul_f32_e32 v54, 0x3fd744fd, v54
	v_mul_f32_e32 v55, 0x3fd744fd, v55
	v_mul_f32_e32 v56, 0x3fd744fd, v56
	v_mul_f32_e32 v57, 0x3fd744fd, v57
	v_fmac_f32_e32 v42, v226, v58
	v_fmac_f32_e32 v43, v227, v59
	v_fmac_f32_e32 v44, v228, v60
	v_fmac_f32_e32 v45, v229, v61
	v_fmac_f32_e32 v46, v230, v62
	v_fmac_f32_e32 v47, v231, v63
	v_fmac_f32_e32 v48, v232, v64
	v_fmac_f32_e32 v49, v233, v65
	v_fmac_f32_e32 v50, v234, v66
	v_fmac_f32_e32 v51, v235, v67
	v_fmac_f32_e32 v52, v236, v68
	v_fmac_f32_e32 v53, v237, v69
	v_fmac_f32_e32 v54, v238, v70
	v_fmac_f32_e32 v55, v239, v71
	v_fmac_f32_e32 v56, v240, v72
	v_fmac_f32_e32 v57, v241, v73
	v_pk_add_f32 v[198:199], v[42:43], v[44:45]
	v_pk_mul_f32 v[200:201], v[42:43], v[42:43]
	v_pk_fma_f32 v[200:201], v[44:45], v[44:45], v[200:201]
	v_pk_add_f32 v[198:199], v[198:199], v[46:47]
	v_pk_fma_f32 v[200:201], v[46:47], v[46:47], v[200:201]
	v_pk_add_f32 v[198:199], v[198:199], v[48:49]
	v_pk_fma_f32 v[200:201], v[48:49], v[48:49], v[200:201]
	v_pk_add_f32 v[198:199], v[198:199], v[50:51]
	v_pk_fma_f32 v[200:201], v[50:51], v[50:51], v[200:201]
	v_pk_add_f32 v[198:199], v[198:199], v[52:53]
	v_pk_fma_f32 v[200:201], v[52:53], v[52:53], v[200:201]
	v_pk_add_f32 v[198:199], v[198:199], v[54:55]
	v_pk_fma_f32 v[200:201], v[54:55], v[54:55], v[200:201]
	v_pk_add_f32 v[198:199], v[198:199], v[56:57]
	v_pk_fma_f32 v[200:201], v[56:57], v[56:57], v[200:201]
	v_add_f32_e32 v9, v198, v199
	v_add_f32_e32 v90, v200, v201
	s_nop 1
	v_add_f32_dpp v9, v9, v9 quad_perm:[1,0,3,2] row_mask:0xf bank_mask:0xf
	v_add_f32_dpp v90, v90, v90 quad_perm:[1,0,3,2] row_mask:0xf bank_mask:0xf
	s_nop 0
	v_add_f32_dpp v9, v9, v9 quad_perm:[2,3,0,1] row_mask:0xf bank_mask:0xf
	v_add_f32_dpp v90, v90, v90 quad_perm:[2,3,0,1] row_mask:0xf bank_mask:0xf
	s_nop 0
	v_add_f32_dpp v9, v9, v9 row_half_mirror row_mask:0xf bank_mask:0xf
	v_add_f32_dpp v90, v90, v90 row_half_mirror row_mask:0xf bank_mask:0xf
	s_nop 0
	v_add_f32_dpp v9, v9, v9 row_mirror row_mask:0xf bank_mask:0xf
	v_add_f32_dpp v90, v90, v90 row_mirror row_mask:0xf bank_mask:0xf
	s_nop 0
	v_add_f32_dpp v9, v9, v9 row_bcast:15 row_mask:0xa bank_mask:0xf
	v_add_f32_dpp v90, v90, v90 row_bcast:15 row_mask:0xa bank_mask:0xf
	s_nop 0
	v_add_f32_dpp v9, v9, v9 row_bcast:31 row_mask:0xc bank_mask:0xf
	v_add_f32_dpp v90, v90, v90 row_bcast:31 row_mask:0xc bank_mask:0xf
	s_nop 0
	v_readlane_b32 s2, v9, 63
	v_readlane_b32 s3, v90, 63
	s_nop 1
	v_mov_b32_e32 v9, s2
	v_mov_b32_e32 v90, s3
	v_mul_f32_e32 v93, 0x3a800000, v9
	v_mul_f32_e32 v91, 0x3a800000, v90
	v_fma_f32 v91, -v93, v93, v91
	v_max_f32_e32 v91, 0, v91
	v_add_f32_e32 v91, 0x358637bd, v91
	v_rsq_f32_e32 v94, v91
	v_mul_f32_e32 v91, 0.5, v91
	v_mul_f32_e32 v92, v94, v94
	v_fma_f32 v92, -v91, v92, 0.5
	v_fma_f32 v94, v94, v92, v94
	v_pk_add_f32 v[42:43], v[42:43], v[92:93] op_sel:[0,1] op_sel_hi:[1,1] neg_lo:[0,1] neg_hi:[0,1]
	v_pk_add_f32 v[44:45], v[44:45], v[92:93] op_sel:[0,1] op_sel_hi:[1,1] neg_lo:[0,1] neg_hi:[0,1]
	v_pk_add_f32 v[46:47], v[46:47], v[92:93] op_sel:[0,1] op_sel_hi:[1,1] neg_lo:[0,1] neg_hi:[0,1]
	v_pk_add_f32 v[48:49], v[48:49], v[92:93] op_sel:[0,1] op_sel_hi:[1,1] neg_lo:[0,1] neg_hi:[0,1]
	v_pk_add_f32 v[50:51], v[50:51], v[92:93] op_sel:[0,1] op_sel_hi:[1,1] neg_lo:[0,1] neg_hi:[0,1]
	v_pk_add_f32 v[52:53], v[52:53], v[92:93] op_sel:[0,1] op_sel_hi:[1,1] neg_lo:[0,1] neg_hi:[0,1]
	v_pk_add_f32 v[54:55], v[54:55], v[92:93] op_sel:[0,1] op_sel_hi:[1,1] neg_lo:[0,1] neg_hi:[0,1]
	v_pk_add_f32 v[56:57], v[56:57], v[92:93] op_sel:[0,1] op_sel_hi:[1,1] neg_lo:[0,1] neg_hi:[0,1]
	v_pk_mul_f32 v[42:43], v[42:43], v[94:95] op_sel_hi:[1,0]
	v_pk_mul_f32 v[44:45], v[44:45], v[94:95] op_sel_hi:[1,0]
	v_pk_mul_f32 v[46:47], v[46:47], v[94:95] op_sel_hi:[1,0]
	v_pk_mul_f32 v[48:49], v[48:49], v[94:95] op_sel_hi:[1,0]
	v_pk_mul_f32 v[50:51], v[50:51], v[94:95] op_sel_hi:[1,0]
	v_pk_mul_f32 v[52:53], v[52:53], v[94:95] op_sel_hi:[1,0]
	v_pk_mul_f32 v[54:55], v[54:55], v[94:95] op_sel_hi:[1,0]
	v_pk_mul_f32 v[56:57], v[56:57], v[94:95] op_sel_hi:[1,0]
	v_pk_fma_f32 v[42:43], v[42:43], v[10:11], v[26:27]
; DI unsigned pk2(float lo, float hi) { f32x2 v = {lo, hi}; bf16x2_t b = __builtin_convertvector(v, bf16x2_t); return __builtin_bit_cast(unsigned, b); }
; DI void ln_row_v(const Frame& F, f32x4 (&v)[4], float* xout, const float* g, const float* b, const float* sh, const float* sc, bf16_t* hout, const float* slab, const float* gres, float* stat = nullptr) {
;     ...
;         for (int j = 0; j < 4; ++j) { const f32x4 gg = ((const f32x4*)g)[F.lane + 64 * j], bb = ((const f32x4*)b)[F.lane + 64 * j];
;             v[j] = (v[j] - mean) * rstd * gg + bb; if (xout) ((f32x4*)xout)[F.lane + 64 * j] = v[j]; }
;     }
;     if (hout) {
;         float s = 0.f, s2 = 0.f;
; #pragma unroll
;         for (int j = 0; j < 4; ++j) { s += (v[j][0] + v[j][1]) + (v[j][2] + v[j][3]); s2 += (v[j][0] * v[j][0] + v[j][1] * v[j][1]) + (v[j][2] * v[j][2] + v[j][3] * v[j][3]); }
;         wave_sum2(s, s2, F.lane);
;         const float mean = s * (1.f / D); const float rstd = 1.f / sqrtf(fmaxf(s2 * (1.f / D) - mean * mean, 0.f) + EPS);
; #pragma unroll
;         for (int j = 0; j < 4; ++j) { const f32x4 hh = ((const f32x4*)sh)[F.lane + 64 * j], cc = ((const f32x4*)sc)[F.lane + 64 * j];
;             const f32x4 o = (v[j] - mean) * rstd * (cc + 1.f) + hh; u32x2 wv; wv.x = pk2(o[0], o[1]); wv.y = pk2(o[2], o[3]);
;             ((u32x2*)hout)[F.lane + 64 * j] = wv; }
	v_pk_fma_f32 v[44:45], v[44:45], v[12:13], v[28:29]
	v_pk_fma_f32 v[46:47], v[46:47], v[14:15], v[30:31]
	v_pk_fma_f32 v[48:49], v[48:49], v[16:17], v[32:33]
	v_pk_fma_f32 v[50:51], v[50:51], v[18:19], v[34:35]
	v_pk_fma_f32 v[52:53], v[52:53], v[20:21], v[36:37]
	v_pk_fma_f32 v[54:55], v[54:55], v[22:23], v[38:39]
	v_pk_fma_f32 v[56:57], v[56:57], v[24:25], v[40:41]
	s_mov_b64 s[2:3], s[20:21]
	global_store_dwordx4 v0, v[42:45], s[2:3]
	global_store_dwordx4 v0, v[46:49], s[2:3] offset:1024
	global_store_dwordx4 v0, v[50:53], s[2:3] offset:2048
	global_store_dwordx4 v0, v[54:57], s[2:3] offset:3072
	v_pk_add_f32 v[198:199], v[42:43], v[44:45]
	v_pk_mul_f32 v[200:201], v[42:43], v[42:43]
	v_pk_fma_f32 v[200:201], v[44:45], v[44:45], v[200:201]
	v_pk_add_f32 v[198:199], v[198:199], v[46:47]
	v_pk_fma_f32 v[200:201], v[46:47], v[46:47], v[200:201]
	v_pk_add_f32 v[198:199], v[198:199], v[48:49]
	v_pk_fma_f32 v[200:201], v[48:49], v[48:49], v[200:201]
	v_pk_add_f32 v[198:199], v[198:199], v[50:51]
	v_pk_fma_f32 v[200:201], v[50:51], v[50:51], v[200:201]
	v_pk_add_f32 v[198:199], v[198:199], v[52:53]
	v_pk_fma_f32 v[200:201], v[52:53], v[52:53], v[200:201]
	v_pk_add_f32 v[198:199], v[198:199], v[54:55]
	v_pk_fma_f32 v[200:201], v[54:55], v[54:55], v[200:201]
	v_pk_add_f32 v[198:199], v[198:199], v[56:57]
	v_pk_fma_f32 v[200:201], v[56:57], v[56:57], v[200:201]
	v_add_f32_e32 v9, v198, v199
	v_add_f32_e32 v90, v200, v201
	s_nop 1
	v_add_f32_dpp v9, v9, v9 quad_perm:[1,0,3,2] row_mask:0xf bank_mask:0xf
	v_add_f32_dpp v90, v90, v90 quad_perm:[1,0,3,2] row_mask:0xf bank_mask:0xf
	s_nop 0
	v_add_f32_dpp v9, v9, v9 quad_perm:[2,3,0,1] row_mask:0xf bank_mask:0xf
	v_add_f32_dpp v90, v90, v90 quad_perm:[2,3,0,1] row_mask:0xf bank_mask:0xf
	s_nop 0
	v_add_f32_dpp v9, v9, v9 row_half_mirror row_mask:0xf bank_mask:0xf
	v_add_f32_dpp v90, v90, v90 row_half_mirror row_mask:0xf bank_mask:0xf
	s_nop 0
	v_add_f32_dpp v9, v9, v9 row_mirror row_mask:0xf bank_mask:0xf
	v_add_f32_dpp v90, v90, v90 row_mirror row_mask:0xf bank_mask:0xf
	s_nop 0
	v_add_f32_dpp v9, v9, v9 row_bcast:15 row_mask:0xa bank_mask:0xf
	v_add_f32_dpp v90, v90, v90 row_bcast:15 row_mask:0xa bank_mask:0xf
	s_nop 0
	v_add_f32_dpp v9, v9, v9 row_bcast:31 row_mask:0xc bank_mask:0xf
	v_add_f32_dpp v90, v90, v90 row_bcast:31 row_mask:0xc bank_mask:0xf
	s_nop 0
	v_readlane_b32 s2, v9, 63
	v_readlane_b32 s3, v90, 63
	s_nop 1
	v_mov_b32_e32 v9, s2
	v_mov_b32_e32 v90, s3
	v_mul_f32_e32 v93, 0x3a800000, v9
	v_mul_f32_e32 v91, 0x3a800000, v90
	v_fma_f32 v91, -v93, v93, v91
	v_max_f32_e32 v91, 0, v91
	v_add_f32_e32 v91, 0x358637bd, v91
	v_rsq_f32_e32 v94, v91
	v_mul_f32_e32 v91, 0.5, v91
	v_mul_f32_e32 v92, v94, v94
	v_fma_f32 v92, -v91, v92, 0.5
	v_fma_f32 v94, v94, v92, v94
	s_waitcnt vmcnt(4)
	v_pk_add_f32 v[42:43], v[42:43], v[92:93] op_sel:[0,1] op_sel_hi:[1,1] neg_lo:[0,1] neg_hi:[0,1]
	v_pk_add_f32 v[44:45], v[44:45], v[92:93] op_sel:[0,1] op_sel_hi:[1,1] neg_lo:[0,1] neg_hi:[0,1]
	v_pk_add_f32 v[46:47], v[46:47], v[92:93] op_sel:[0,1] op_sel_hi:[1,1] neg_lo:[0,1] neg_hi:[0,1]
	v_pk_add_f32 v[48:49], v[48:49], v[92:93] op_sel:[0,1] op_sel_hi:[1,1] neg_lo:[0,1] neg_hi:[0,1]
	v_pk_add_f32 v[50:51], v[50:51], v[92:93] op_sel:[0,1] op_sel_hi:[1,1] neg_lo:[0,1] neg_hi:[0,1]
	v_pk_add_f32 v[52:53], v[52:53], v[92:93] op_sel:[0,1] op_sel_hi:[1,1] neg_lo:[0,1] neg_hi:[0,1]
	v_pk_add_f32 v[54:55], v[54:55], v[92:93] op_sel:[0,1] op_sel_hi:[1,1] neg_lo:[0,1] neg_hi:[0,1]
	v_pk_add_f32 v[56:57], v[56:57], v[92:93] op_sel:[0,1] op_sel_hi:[1,1] neg_lo:[0,1] neg_hi:[0,1]
	v_add_f32_e32 v162, 1.0, v162
	v_add_f32_e32 v163, 1.0, v163
	v_add_f32_e32 v164, 1.0, v164
	v_add_f32_e32 v165, 1.0, v165
	v_add_f32_e32 v166, 1.0, v166
	v_add_f32_e32 v167, 1.0, v167
	v_add_f32_e32 v168, 1.0, v168
	v_add_f32_e32 v169, 1.0, v169
	v_add_f32_e32 v170, 1.0, v170
	v_add_f32_e32 v171, 1.0, v171
	v_add_f32_e32 v172, 1.0, v172
	v_add_f32_e32 v173, 1.0, v173
	v_add_f32_e32 v174, 1.0, v174
	v_add_f32_e32 v175, 1.0, v175
	v_add_f32_e32 v176, 1.0, v176
	v_add_f32_e32 v177, 1.0, v177
	v_pk_mul_f32 v[42:43], v[42:43], v[94:95] op_sel_hi:[1,0]
	v_pk_mul_f32 v[44:45], v[44:45], v[94:95] op_sel_hi:[1,0]
	v_pk_mul_f32 v[46:47], v[46:47], v[94:95] op_sel_hi:[1,0]
	v_pk_mul_f32 v[48:49], v[48:49], v[94:95] op_sel_hi:[1,0]
	v_pk_mul_f32 v[50:51], v[50:51], v[94:95] op_sel_hi:[1,0]
	v_pk_mul_f32 v[52:53], v[52:53], v[94:95] op_sel_hi:[1,0]
	v_pk_mul_f32 v[54:55], v[54:55], v[94:95] op_sel_hi:[1,0]
	v_pk_mul_f32 v[56:57], v[56:57], v[94:95] op_sel_hi:[1,0]
	v_pk_fma_f32 v[42:43], v[42:43], v[162:163], v[146:147]
	v_pk_fma_f32 v[44:45], v[44:45], v[164:165], v[148:149]
	v_pk_fma_f32 v[46:47], v[46:47], v[166:167], v[150:151]
	v_pk_fma_f32 v[48:49], v[48:49], v[168:169], v[152:153]
	v_pk_fma_f32 v[50:51], v[50:51], v[170:171], v[154:155]
	v_pk_fma_f32 v[52:53], v[52:53], v[172:173], v[156:157]
	v_pk_fma_f32 v[54:55], v[54:55], v[174:175], v[158:159]
	v_pk_fma_f32 v[56:57], v[56:57], v[176:177], v[160:161]
	v_cvt_pk_bf16_f32 v190, v42, v43
	v_cvt_pk_bf16_f32 v191, v44, v45
	v_cvt_pk_bf16_f32 v192, v46, v47
	v_cvt_pk_bf16_f32 v193, v48, v49
	v_cvt_pk_bf16_f32 v194, v50, v51
	v_cvt_pk_bf16_f32 v195, v52, v53
	v_cvt_pk_bf16_f32 v196, v54, v55
	v_cvt_pk_bf16_f32 v197, v56, v57
	s_lshl_b32 s2, s16, 11
	s_add_u32 s2, s94, s2
	s_addc_u32 s3, s95, 0
	s_add_u32 s2, s2, 0x5e00000
	s_addc_u32 s3, s3, 0
	global_store_dwordx2 v1, v[190:191], s[2:3]
	global_store_dwordx2 v1, v[192:193], s[2:3] offset:512
	global_store_dwordx2 v1, v[194:195], s[2:3] offset:1024
	global_store_dwordx2 v1, v[196:197], s[2:3] offset:1536

; DI void ln_row_v(const Frame& F, f32x4 (&v)[4], float* xout, const float* g, const float* b, const float* sh, const float* sc, bf16_t* hout, const float* slab, const float* gres, float* stat = nullptr) {
;     ...
;         float s = 0.f, s2 = 0.f;
; #pragma unroll
;         for (int j = 0; j < 4; ++j) { s += (v[j][0] + v[j][1]) + (v[j][2] + v[j][3]); s2 += (v[j][0] * v[j][0] + v[j][1] * v[j][1]) + (v[j][2] * v[j][2] + v[j][3] * v[j][3]); }
;         wave_sum2(s, s2, F.lane);
;         const float mean = s * (1.f / D); const float rstd = 1.f / sqrtf(fmaxf(s2 * (1.f / D) - mean * mean, 0.f) + EPS);
;         if (stat && F.lane == 0) { f32x2 sv = {mean, rstd}; *(f32x2*)stat = sv; }
; #pragma unroll
;         for (int j = 0; j < 4; ++j) { const f32x4 gg = ((const f32x4*)g)[F.lane + 64 * j], bb = ((const f32x4*)b)[F.lane + 64 * j];
;             v[j] = (v[j] - mean) * rstd * gg + bb; if (xout) ((f32x4*)xout)[F.lane + 64 * j] = v[j]; }
.Lln_b_final:
	global_load_dwordx4 v[10:13], v0, s[4:5]
	global_load_dwordx4 v[14:17], v0, s[4:5] offset:1024
	global_load_dwordx4 v[18:21], v0, s[4:5] offset:2048
	global_load_dwordx4 v[22:25], v0, s[4:5] offset:3072
	global_load_dwordx4 v[26:29], v0, s[6:7]
	global_load_dwordx4 v[30:33], v0, s[6:7] offset:1024
	global_load_dwordx4 v[34:37], v0, s[6:7] offset:2048
	global_load_dwordx4 v[38:41], v0, s[6:7] offset:3072
	s_add_u32 s2, s8, 0x0
	s_addc_u32 s3, s9, 0
	global_load_dwordx4 v[42:45], v0, s[2:3]
	global_load_dwordx4 v[46:49], v0, s[2:3] offset:1024
	global_load_dwordx4 v[50:53], v0, s[2:3] offset:2048
	global_load_dwordx4 v[54:57], v0, s[2:3] offset:3072
	s_add_u32 s2, s8, 0x1000
	s_addc_u32 s3, s9, 0
	global_load_dwordx4 v[58:61], v0, s[2:3]
	global_load_dwordx4 v[62:65], v0, s[2:3] offset:1024
	global_load_dwordx4 v[66:69], v0, s[2:3] offset:2048
	global_load_dwordx4 v[70:73], v0, s[2:3] offset:3072
	s_add_u32 s2, s8, 0x2000
	s_addc_u32 s3, s9, 0
	global_load_dwordx4 v[74:77], v0, s[2:3]
	global_load_dwordx4 v[78:81], v0, s[2:3] offset:1024
	global_load_dwordx4 v[82:85], v0, s[2:3] offset:2048
	global_load_dwordx4 v[86:89], v0, s[2:3] offset:3072
	s_add_u32 s2, s8, 0x3000
	s_addc_u32 s3, s9, 0
	global_load_dwordx4 v[98:101], v0, s[2:3]
	global_load_dwordx4 v[102:105], v0, s[2:3] offset:1024
	global_load_dwordx4 v[106:109], v0, s[2:3] offset:2048
	global_load_dwordx4 v[110:113], v0, s[2:3] offset:3072
	s_waitcnt vmcnt(12)
	v_pk_add_f32 v[198:199], v[42:43], v[44:45]
	v_pk_mul_f32 v[200:201], v[42:43], v[42:43]
	v_pk_fma_f32 v[200:201], v[44:45], v[44:45], v[200:201]
	v_pk_add_f32 v[198:199], v[198:199], v[46:47]
	v_pk_fma_f32 v[200:201], v[46:47], v[46:47], v[200:201]
	v_pk_add_f32 v[198:199], v[198:199], v[48:49]
	v_pk_fma_f32 v[200:201], v[48:49], v[48:49], v[200:201]
	v_pk_add_f32 v[198:199], v[198:199], v[50:51]
	v_pk_fma_f32 v[200:201], v[50:51], v[50:51], v[200:201]
	v_pk_add_f32 v[198:199], v[198:199], v[52:53]
	v_pk_fma_f32 v[200:201], v[52:53], v[52:53], v[200:201]
	v_pk_add_f32 v[198:199], v[198:199], v[54:55]
	v_pk_fma_f32 v[200:201], v[54:55], v[54:55], v[200:201]
	v_pk_add_f32 v[198:199], v[198:199], v[56:57]
	v_pk_fma_f32 v[200:201], v[56:57], v[56:57], v[200:201]
	v_add_f32_e32 v9, v198, v199
	v_add_f32_e32 v90, v200, v201
	s_nop 1
	v_add_f32_dpp v9, v9, v9 quad_perm:[1,0,3,2] row_mask:0xf bank_mask:0xf
	v_add_f32_dpp v90, v90, v90 quad_perm:[1,0,3,2] row_mask:0xf bank_mask:0xf
	s_nop 0
	v_add_f32_dpp v9, v9, v9 quad_perm:[2,3,0,1] row_mask:0xf bank_mask:0xf
	v_add_f32_dpp v90, v90, v90 quad_perm:[2,3,0,1] row_mask:0xf bank_mask:0xf
	s_nop 0
	v_add_f32_dpp v9, v9, v9 row_half_mirror row_mask:0xf bank_mask:0xf
	v_add_f32_dpp v90, v90, v90 row_half_mirror row_mask:0xf bank_mask:0xf
	s_nop 0
	v_add_f32_dpp v9, v9, v9 row_mirror row_mask:0xf bank_mask:0xf
	v_add_f32_dpp v90, v90, v90 row_mirror row_mask:0xf bank_mask:0xf
	s_nop 0
	v_add_f32_dpp v9, v9, v9 row_bcast:15 row_mask:0xa bank_mask:0xf
	v_add_f32_dpp v90, v90, v90 row_bcast:15 row_mask:0xa bank_mask:0xf
	s_nop 0
	v_add_f32_dpp v9, v9, v9 row_bcast:31 row_mask:0xc bank_mask:0xf
	v_add_f32_dpp v90, v90, v90 row_bcast:31 row_mask:0xc bank_mask:0xf
	s_nop 0
	v_readlane_b32 s2, v9, 63
	v_readlane_b32 s3, v90, 63
	s_nop 1
	v_mov_b32_e32 v9, s2
	v_mov_b32_e32 v90, s3
	v_mul_f32_e32 v93, 0x3a800000, v9
	v_mul_f32_e32 v91, 0x3a800000, v90
	v_fma_f32 v91, -v93, v93, v91
	v_max_f32_e32 v91, 0, v91
	v_add_f32_e32 v91, 0x358637bd, v91
	v_rsq_f32_e32 v94, v91
	v_mul_f32_e32 v91, 0.5, v91
	v_mul_f32_e32 v92, v94, v94
	v_fma_f32 v92, -v91, v92, 0.5
	v_fma_f32 v94, v94, v92, v94
	v_pk_add_f32 v[42:43], v[42:43], v[92:93] op_sel:[0,1] op_sel_hi:[1,1] neg_lo:[0,1] neg_hi:[0,1]
	v_pk_add_f32 v[44:45], v[44:45], v[92:93] op_sel:[0,1] op_sel_hi:[1,1] neg_lo:[0,1] neg_hi:[0,1]
	v_pk_add_f32 v[46:47], v[46:47], v[92:93] op_sel:[0,1] op_sel_hi:[1,1] neg_lo:[0,1] neg_hi:[0,1]
	v_pk_add_f32 v[48:49], v[48:49], v[92:93] op_sel:[0,1] op_sel_hi:[1,1] neg_lo:[0,1] neg_hi:[0,1]
	v_pk_add_f32 v[50:51], v[50:51], v[92:93] op_sel:[0,1] op_sel_hi:[1,1] neg_lo:[0,1] neg_hi:[0,1]
	v_pk_add_f32 v[52:53], v[52:53], v[92:93] op_sel:[0,1] op_sel_hi:[1,1] neg_lo:[0,1] neg_hi:[0,1]
	v_pk_add_f32 v[54:55], v[54:55], v[92:93] op_sel:[0,1] op_sel_hi:[1,1] neg_lo:[0,1] neg_hi:[0,1]
	v_pk_add_f32 v[56:57], v[56:57], v[92:93] op_sel:[0,1] op_sel_hi:[1,1] neg_lo:[0,1] neg_hi:[0,1]
	v_pk_mul_f32 v[42:43], v[42:43], v[94:95] op_sel_hi:[1,0]
	v_pk_mul_f32 v[44:45], v[44:45], v[94:95] op_sel_hi:[1,0]
	v_pk_mul_f32 v[46:47], v[46:47], v[94:95] op_sel_hi:[1,0]
	v_pk_mul_f32 v[48:49], v[48:49], v[94:95] op_sel_hi:[1,0]
	v_pk_mul_f32 v[50:51], v[50:51], v[94:95] op_sel_hi:[1,0]
	v_pk_mul_f32 v[52:53], v[52:53], v[94:95] op_sel_hi:[1,0]
	v_pk_mul_f32 v[54:55], v[54:55], v[94:95] op_sel_hi:[1,0]
	v_pk_mul_f32 v[56:57], v[56:57], v[94:95] op_sel_hi:[1,0]
	v_pk_fma_f32 v[42:43], v[42:43], v[10:11], v[26:27]
	v_pk_fma_f32 v[44:45], v[44:45], v[12:13], v[28:29]
	v_pk_fma_f32 v[46:47], v[46:47], v[14:15], v[30:31]
	v_pk_fma_f32 v[48:49], v[48:49], v[16:17], v[32:33]
	v_pk_fma_f32 v[50:51], v[50:51], v[18:19], v[34:35]
	v_pk_fma_f32 v[52:53], v[52:53], v[20:21], v[36:37]
	v_pk_fma_f32 v[54:55], v[54:55], v[22:23], v[38:39]
	v_pk_fma_f32 v[56:57], v[56:57], v[24:25], v[40:41]
	s_add_u32 s2, s8, 0x0
	s_addc_u32 s3, s9, 0
	global_store_dwordx4 v0, v[42:45], s[2:3]
	global_store_dwordx4 v0, v[46:49], s[2:3] offset:1024
	global_store_dwordx4 v0, v[50:53], s[2:3] offset:2048
	global_store_dwordx4 v0, v[54:57], s[2:3] offset:3072
	s_add_u32 s2, s8, 0x4000
	s_addc_u32 s3, s9, 0
	global_load_dwordx4 v[42:45], v0, s[2:3]
	global_load_dwordx4 v[46:49], v0, s[2:3] offset:1024
	global_load_dwordx4 v[50:53], v0, s[2:3] offset:2048
	global_load_dwordx4 v[54:57], v0, s[2:3] offset:3072
	s_waitcnt vmcnt(16)
; DI void ln_row_v(const Frame& F, f32x4 (&v)[4], float* xout, const float* g, const float* b, const float* sh, const float* sc, bf16_t* hout, const float* slab, const float* gres, float* stat = nullptr) {
;     ...
;         float s = 0.f, s2 = 0.f;
; #pragma unroll
;         for (int j = 0; j < 4; ++j) { s += (v[j][0] + v[j][1]) + (v[j][2] + v[j][3]); s2 += (v[j][0] * v[j][0] + v[j][1] * v[j][1]) + (v[j][2] * v[j][2] + v[j][3] * v[j][3]); }
;         wave_sum2(s, s2, F.lane);
;         const float mean = s * (1.f / D); const float rstd = 1.f / sqrtf(fmaxf(s2 * (1.f / D) - mean * mean, 0.f) + EPS);
;         if (stat && F.lane == 0) { f32x2 sv = {mean, rstd}; *(f32x2*)stat = sv; }
; #pragma unroll
;         for (int j = 0; j < 4; ++j) { const f32x4 gg = ((const f32x4*)g)[F.lane + 64 * j], bb = ((const f32x4*)b)[F.lane + 64 * j];
;             v[j] = (v[j] - mean) * rstd * gg + bb; if (xout) ((f32x4*)xout)[F.lane + 64 * j] = v[j]; }
	v_pk_add_f32 v[198:199], v[58:59], v[60:61]
	v_pk_mul_f32 v[200:201], v[58:59], v[58:59]
	v_pk_fma_f32 v[200:201], v[60:61], v[60:61], v[200:201]
	v_pk_add_f32 v[198:199], v[198:199], v[62:63]
	v_pk_fma_f32 v[200:201], v[62:63], v[62:63], v[200:201]
	v_pk_add_f32 v[198:199], v[198:199], v[64:65]
	v_pk_fma_f32 v[200:201], v[64:65], v[64:65], v[200:201]
	v_pk_add_f32 v[198:199], v[198:199], v[66:67]
	v_pk_fma_f32 v[200:201], v[66:67], v[66:67], v[200:201]
	v_pk_add_f32 v[198:199], v[198:199], v[68:69]
	v_pk_fma_f32 v[200:201], v[68:69], v[68:69], v[200:201]
	v_pk_add_f32 v[198:199], v[198:199], v[70:71]
	v_pk_fma_f32 v[200:201], v[70:71], v[70:71], v[200:201]
	v_pk_add_f32 v[198:199], v[198:199], v[72:73]
	v_pk_fma_f32 v[200:201], v[72:73], v[72:73], v[200:201]
	v_add_f32_e32 v9, v198, v199
	v_add_f32_e32 v90, v200, v201
	s_nop 1
	v_add_f32_dpp v9, v9, v9 quad_perm:[1,0,3,2] row_mask:0xf bank_mask:0xf
	v_add_f32_dpp v90, v90, v90 quad_perm:[1,0,3,2] row_mask:0xf bank_mask:0xf
	s_nop 0
	v_add_f32_dpp v9, v9, v9 quad_perm:[2,3,0,1] row_mask:0xf bank_mask:0xf
	v_add_f32_dpp v90, v90, v90 quad_perm:[2,3,0,1] row_mask:0xf bank_mask:0xf
	s_nop 0
	v_add_f32_dpp v9, v9, v9 row_half_mirror row_mask:0xf bank_mask:0xf
	v_add_f32_dpp v90, v90, v90 row_half_mirror row_mask:0xf bank_mask:0xf
	s_nop 0
	v_add_f32_dpp v9, v9, v9 row_mirror row_mask:0xf bank_mask:0xf
	v_add_f32_dpp v90, v90, v90 row_mirror row_mask:0xf bank_mask:0xf
	s_nop 0
	v_add_f32_dpp v9, v9, v9 row_bcast:15 row_mask:0xa bank_mask:0xf
	v_add_f32_dpp v90, v90, v90 row_bcast:15 row_mask:0xa bank_mask:0xf
	s_nop 0
	v_add_f32_dpp v9, v9, v9 row_bcast:31 row_mask:0xc bank_mask:0xf
	v_add_f32_dpp v90, v90, v90 row_bcast:31 row_mask:0xc bank_mask:0xf
	s_nop 0
	v_readlane_b32 s2, v9, 63
	v_readlane_b32 s3, v90, 63
	s_nop 1
	v_mov_b32_e32 v9, s2
	v_mov_b32_e32 v90, s3
	v_mul_f32_e32 v93, 0x3a800000, v9
	v_mul_f32_e32 v91, 0x3a800000, v90
	v_fma_f32 v91, -v93, v93, v91
	v_max_f32_e32 v91, 0, v91
	v_add_f32_e32 v91, 0x358637bd, v91
	v_rsq_f32_e32 v94, v91
	v_mul_f32_e32 v91, 0.5, v91
	v_mul_f32_e32 v92, v94, v94
	v_fma_f32 v92, -v91, v92, 0.5
	v_fma_f32 v94, v94, v92, v94
	v_pk_add_f32 v[58:59], v[58:59], v[92:93] op_sel:[0,1] op_sel_hi:[1,1] neg_lo:[0,1] neg_hi:[0,1]
	v_pk_add_f32 v[60:61], v[60:61], v[92:93] op_sel:[0,1] op_sel_hi:[1,1] neg_lo:[0,1] neg_hi:[0,1]
	v_pk_add_f32 v[62:63], v[62:63], v[92:93] op_sel:[0,1] op_sel_hi:[1,1] neg_lo:[0,1] neg_hi:[0,1]
	v_pk_add_f32 v[64:65], v[64:65], v[92:93] op_sel:[0,1] op_sel_hi:[1,1] neg_lo:[0,1] neg_hi:[0,1]
	v_pk_add_f32 v[66:67], v[66:67], v[92:93] op_sel:[0,1] op_sel_hi:[1,1] neg_lo:[0,1] neg_hi:[0,1]
	v_pk_add_f32 v[68:69], v[68:69], v[92:93] op_sel:[0,1] op_sel_hi:[1,1] neg_lo:[0,1] neg_hi:[0,1]
	v_pk_add_f32 v[70:71], v[70:71], v[92:93] op_sel:[0,1] op_sel_hi:[1,1] neg_lo:[0,1] neg_hi:[0,1]
	v_pk_add_f32 v[72:73], v[72:73], v[92:93] op_sel:[0,1] op_sel_hi:[1,1] neg_lo:[0,1] neg_hi:[0,1]
	v_pk_mul_f32 v[58:59], v[58:59], v[94:95] op_sel_hi:[1,0]
	v_pk_mul_f32 v[60:61], v[60:61], v[94:95] op_sel_hi:[1,0]
	v_pk_mul_f32 v[62:63], v[62:63], v[94:95] op_sel_hi:[1,0]
	v_pk_mul_f32 v[64:65], v[64:65], v[94:95] op_sel_hi:[1,0]
	v_pk_mul_f32 v[66:67], v[66:67], v[94:95] op_sel_hi:[1,0]
	v_pk_mul_f32 v[68:69], v[68:69], v[94:95] op_sel_hi:[1,0]
	v_pk_mul_f32 v[70:71], v[70:71], v[94:95] op_sel_hi:[1,0]
	v_pk_mul_f32 v[72:73], v[72:73], v[94:95] op_sel_hi:[1,0]
	v_pk_fma_f32 v[58:59], v[58:59], v[10:11], v[26:27]
	v_pk_fma_f32 v[60:61], v[60:61], v[12:13], v[28:29]
	v_pk_fma_f32 v[62:63], v[62:63], v[14:15], v[30:31]
	v_pk_fma_f32 v[64:65], v[64:65], v[16:17], v[32:33]
	v_pk_fma_f32 v[66:67], v[66:67], v[18:19], v[34:35]
	v_pk_fma_f32 v[68:69], v[68:69], v[20:21], v[36:37]
	v_pk_fma_f32 v[70:71], v[70:71], v[22:23], v[38:39]
	v_pk_fma_f32 v[72:73], v[72:73], v[24:25], v[40:41]
	s_add_u32 s2, s8, 0x1000
	s_addc_u32 s3, s9, 0
	global_store_dwordx4 v0, v[58:61], s[2:3]
	global_store_dwordx4 v0, v[62:65], s[2:3] offset:1024
	global_store_dwordx4 v0, v[66:69], s[2:3] offset:2048
	global_store_dwordx4 v0, v[70:73], s[2:3] offset:3072
	s_add_u32 s2, s8, 0x5000
	s_addc_u32 s3, s9, 0
	global_load_dwordx4 v[58:61], v0, s[2:3]
	global_load_dwordx4 v[62:65], v0, s[2:3] offset:1024
	global_load_dwordx4 v[66:69], v0, s[2:3] offset:2048
	global_load_dwordx4 v[70:73], v0, s[2:3] offset:3072
	s_waitcnt vmcnt(20)
; DI void ln_row_v(const Frame& F, f32x4 (&v)[4], float* xout, const float* g, const float* b, const float* sh, const float* sc, bf16_t* hout, const float* slab, const float* gres, float* stat = nullptr) {
;     ...
;         float s = 0.f, s2 = 0.f;
; #pragma unroll
;         for (int j = 0; j < 4; ++j) { s += (v[j][0] + v[j][1]) + (v[j][2] + v[j][3]); s2 += (v[j][0] * v[j][0] + v[j][1] * v[j][1]) + (v[j][2] * v[j][2] + v[j][3] * v[j][3]); }
;         wave_sum2(s, s2, F.lane);
;         const float mean = s * (1.f / D); const float rstd = 1.f / sqrtf(fmaxf(s2 * (1.f / D) - mean * mean, 0.f) + EPS);
;         if (stat && F.lane == 0) { f32x2 sv = {mean, rstd}; *(f32x2*)stat = sv; }
; #pragma unroll
;         for (int j = 0; j < 4; ++j) { const f32x4 gg = ((const f32x4*)g)[F.lane + 64 * j], bb = ((const f32x4*)b)[F.lane + 64 * j];
;             v[j] = (v[j] - mean) * rstd * gg + bb; if (xout) ((f32x4*)xout)[F.lane + 64 * j] = v[j]; }
	v_pk_add_f32 v[198:199], v[74:75], v[76:77]
	v_pk_mul_f32 v[200:201], v[74:75], v[74:75]
	v_pk_fma_f32 v[200:201], v[76:77], v[76:77], v[200:201]
	v_pk_add_f32 v[198:199], v[198:199], v[78:79]
	v_pk_fma_f32 v[200:201], v[78:79], v[78:79], v[200:201]
	v_pk_add_f32 v[198:199], v[198:199], v[80:81]
	v_pk_fma_f32 v[200:201], v[80:81], v[80:81], v[200:201]
	v_pk_add_f32 v[198:199], v[198:199], v[82:83]
	v_pk_fma_f32 v[200:201], v[82:83], v[82:83], v[200:201]
	v_pk_add_f32 v[198:199], v[198:199], v[84:85]
	v_pk_fma_f32 v[200:201], v[84:85], v[84:85], v[200:201]
	v_pk_add_f32 v[198:199], v[198:199], v[86:87]
	v_pk_fma_f32 v[200:201], v[86:87], v[86:87], v[200:201]
	v_pk_add_f32 v[198:199], v[198:199], v[88:89]
	v_pk_fma_f32 v[200:201], v[88:89], v[88:89], v[200:201]
	v_add_f32_e32 v9, v198, v199
	v_add_f32_e32 v90, v200, v201
	s_nop 1
	v_add_f32_dpp v9, v9, v9 quad_perm:[1,0,3,2] row_mask:0xf bank_mask:0xf
	v_add_f32_dpp v90, v90, v90 quad_perm:[1,0,3,2] row_mask:0xf bank_mask:0xf
	s_nop 0
	v_add_f32_dpp v9, v9, v9 quad_perm:[2,3,0,1] row_mask:0xf bank_mask:0xf
	v_add_f32_dpp v90, v90, v90 quad_perm:[2,3,0,1] row_mask:0xf bank_mask:0xf
	s_nop 0
	v_add_f32_dpp v9, v9, v9 row_half_mirror row_mask:0xf bank_mask:0xf
	v_add_f32_dpp v90, v90, v90 row_half_mirror row_mask:0xf bank_mask:0xf
	s_nop 0
	v_add_f32_dpp v9, v9, v9 row_mirror row_mask:0xf bank_mask:0xf
	v_add_f32_dpp v90, v90, v90 row_mirror row_mask:0xf bank_mask:0xf
	s_nop 0
	v_add_f32_dpp v9, v9, v9 row_bcast:15 row_mask:0xa bank_mask:0xf
	v_add_f32_dpp v90, v90, v90 row_bcast:15 row_mask:0xa bank_mask:0xf
	s_nop 0
	v_add_f32_dpp v9, v9, v9 row_bcast:31 row_mask:0xc bank_mask:0xf
	v_add_f32_dpp v90, v90, v90 row_bcast:31 row_mask:0xc bank_mask:0xf
	s_nop 0
	v_readlane_b32 s2, v9, 63
	v_readlane_b32 s3, v90, 63
	s_nop 1
	v_mov_b32_e32 v9, s2
	v_mov_b32_e32 v90, s3
	v_mul_f32_e32 v93, 0x3a800000, v9
	v_mul_f32_e32 v91, 0x3a800000, v90
	v_fma_f32 v91, -v93, v93, v91
	v_max_f32_e32 v91, 0, v91
	v_add_f32_e32 v91, 0x358637bd, v91
	v_rsq_f32_e32 v94, v91
	v_mul_f32_e32 v91, 0.5, v91
	v_mul_f32_e32 v92, v94, v94
	v_fma_f32 v92, -v91, v92, 0.5
	v_fma_f32 v94, v94, v92, v94
	v_pk_add_f32 v[74:75], v[74:75], v[92:93] op_sel:[0,1] op_sel_hi:[1,1] neg_lo:[0,1] neg_hi:[0,1]
	v_pk_add_f32 v[76:77], v[76:77], v[92:93] op_sel:[0,1] op_sel_hi:[1,1] neg_lo:[0,1] neg_hi:[0,1]
	v_pk_add_f32 v[78:79], v[78:79], v[92:93] op_sel:[0,1] op_sel_hi:[1,1] neg_lo:[0,1] neg_hi:[0,1]
	v_pk_add_f32 v[80:81], v[80:81], v[92:93] op_sel:[0,1] op_sel_hi:[1,1] neg_lo:[0,1] neg_hi:[0,1]
	v_pk_add_f32 v[82:83], v[82:83], v[92:93] op_sel:[0,1] op_sel_hi:[1,1] neg_lo:[0,1] neg_hi:[0,1]
	v_pk_add_f32 v[84:85], v[84:85], v[92:93] op_sel:[0,1] op_sel_hi:[1,1] neg_lo:[0,1] neg_hi:[0,1]
	v_pk_add_f32 v[86:87], v[86:87], v[92:93] op_sel:[0,1] op_sel_hi:[1,1] neg_lo:[0,1] neg_hi:[0,1]
	v_pk_add_f32 v[88:89], v[88:89], v[92:93] op_sel:[0,1] op_sel_hi:[1,1] neg_lo:[0,1] neg_hi:[0,1]
	v_pk_mul_f32 v[74:75], v[74:75], v[94:95] op_sel_hi:[1,0]
	v_pk_mul_f32 v[76:77], v[76:77], v[94:95] op_sel_hi:[1,0]
	v_pk_mul_f32 v[78:79], v[78:79], v[94:95] op_sel_hi:[1,0]
	v_pk_mul_f32 v[80:81], v[80:81], v[94:95] op_sel_hi:[1,0]
	v_pk_mul_f32 v[82:83], v[82:83], v[94:95] op_sel_hi:[1,0]
	v_pk_mul_f32 v[84:85], v[84:85], v[94:95] op_sel_hi:[1,0]
	v_pk_mul_f32 v[86:87], v[86:87], v[94:95] op_sel_hi:[1,0]
	v_pk_mul_f32 v[88:89], v[88:89], v[94:95] op_sel_hi:[1,0]
	v_pk_fma_f32 v[74:75], v[74:75], v[10:11], v[26:27]
	v_pk_fma_f32 v[76:77], v[76:77], v[12:13], v[28:29]
	v_pk_fma_f32 v[78:79], v[78:79], v[14:15], v[30:31]
	v_pk_fma_f32 v[80:81], v[80:81], v[16:17], v[32:33]
	v_pk_fma_f32 v[82:83], v[82:83], v[18:19], v[34:35]
	v_pk_fma_f32 v[84:85], v[84:85], v[20:21], v[36:37]
	v_pk_fma_f32 v[86:87], v[86:87], v[22:23], v[38:39]
	v_pk_fma_f32 v[88:89], v[88:89], v[24:25], v[40:41]
	s_add_u32 s2, s8, 0x2000
	s_addc_u32 s3, s9, 0
	global_store_dwordx4 v0, v[74:77], s[2:3]
	global_store_dwordx4 v0, v[78:81], s[2:3] offset:1024
	global_store_dwordx4 v0, v[82:85], s[2:3] offset:2048
	global_store_dwordx4 v0, v[86:89], s[2:3] offset:3072
	s_add_u32 s2, s8, 0x6000
	s_addc_u32 s3, s9, 0
	global_load_dwordx4 v[74:77], v0, s[2:3]
	global_load_dwordx4 v[78:81], v0, s[2:3] offset:1024
	global_load_dwordx4 v[82:85], v0, s[2:3] offset:2048
	global_load_dwordx4 v[86:89], v0, s[2:3] offset:3072
	s_waitcnt vmcnt(24)
; DI void ln_row_v(const Frame& F, f32x4 (&v)[4], float* xout, const float* g, const float* b, const float* sh, const float* sc, bf16_t* hout, const float* slab, const float* gres, float* stat = nullptr) {
;     ...
;         float s = 0.f, s2 = 0.f;
; #pragma unroll
;         for (int j = 0; j < 4; ++j) { s += (v[j][0] + v[j][1]) + (v[j][2] + v[j][3]); s2 += (v[j][0] * v[j][0] + v[j][1] * v[j][1]) + (v[j][2] * v[j][2] + v[j][3] * v[j][3]); }
;         wave_sum2(s, s2, F.lane);
;         const float mean = s * (1.f / D); const float rstd = 1.f / sqrtf(fmaxf(s2 * (1.f / D) - mean * mean, 0.f) + EPS);
;         if (stat && F.lane == 0) { f32x2 sv = {mean, rstd}; *(f32x2*)stat = sv; }
; #pragma unroll
;         for (int j = 0; j < 4; ++j) { const f32x4 gg = ((const f32x4*)g)[F.lane + 64 * j], bb = ((const f32x4*)b)[F.lane + 64 * j];
;             v[j] = (v[j] - mean) * rstd * gg + bb; if (xout) ((f32x4*)xout)[F.lane + 64 * j] = v[j]; }
	v_pk_add_f32 v[198:199], v[98:99], v[100:101]
	v_pk_mul_f32 v[200:201], v[98:99], v[98:99]
	v_pk_fma_f32 v[200:201], v[100:101], v[100:101], v[200:201]
	v_pk_add_f32 v[198:199], v[198:199], v[102:103]
	v_pk_fma_f32 v[200:201], v[102:103], v[102:103], v[200:201]
	v_pk_add_f32 v[198:199], v[198:199], v[104:105]
	v_pk_fma_f32 v[200:201], v[104:105], v[104:105], v[200:201]
	v_pk_add_f32 v[198:199], v[198:199], v[106:107]
	v_pk_fma_f32 v[200:201], v[106:107], v[106:107], v[200:201]
	v_pk_add_f32 v[198:199], v[198:199], v[108:109]
	v_pk_fma_f32 v[200:201], v[108:109], v[108:109], v[200:201]
	v_pk_add_f32 v[198:199], v[198:199], v[110:111]
	v_pk_fma_f32 v[200:201], v[110:111], v[110:111], v[200:201]
	v_pk_add_f32 v[198:199], v[198:199], v[112:113]
	v_pk_fma_f32 v[200:201], v[112:113], v[112:113], v[200:201]
	v_add_f32_e32 v9, v198, v199
	v_add_f32_e32 v90, v200, v201
	s_nop 1
	v_add_f32_dpp v9, v9, v9 quad_perm:[1,0,3,2] row_mask:0xf bank_mask:0xf
	v_add_f32_dpp v90, v90, v90 quad_perm:[1,0,3,2] row_mask:0xf bank_mask:0xf
	s_nop 0
	v_add_f32_dpp v9, v9, v9 quad_perm:[2,3,0,1] row_mask:0xf bank_mask:0xf
	v_add_f32_dpp v90, v90, v90 quad_perm:[2,3,0,1] row_mask:0xf bank_mask:0xf
	s_nop 0
	v_add_f32_dpp v9, v9, v9 row_half_mirror row_mask:0xf bank_mask:0xf
	v_add_f32_dpp v90, v90, v90 row_half_mirror row_mask:0xf bank_mask:0xf
	s_nop 0
	v_add_f32_dpp v9, v9, v9 row_mirror row_mask:0xf bank_mask:0xf
	v_add_f32_dpp v90, v90, v90 row_mirror row_mask:0xf bank_mask:0xf
	s_nop 0
	v_add_f32_dpp v9, v9, v9 row_bcast:15 row_mask:0xa bank_mask:0xf
	v_add_f32_dpp v90, v90, v90 row_bcast:15 row_mask:0xa bank_mask:0xf
	s_nop 0
	v_add_f32_dpp v9, v9, v9 row_bcast:31 row_mask:0xc bank_mask:0xf
	v_add_f32_dpp v90, v90, v90 row_bcast:31 row_mask:0xc bank_mask:0xf
	s_nop 0
	v_readlane_b32 s2, v9, 63
	v_readlane_b32 s3, v90, 63
	s_nop 1
	v_mov_b32_e32 v9, s2
	v_mov_b32_e32 v90, s3
	v_mul_f32_e32 v93, 0x3a800000, v9
	v_mul_f32_e32 v91, 0x3a800000, v90
	v_fma_f32 v91, -v93, v93, v91
	v_max_f32_e32 v91, 0, v91
	v_add_f32_e32 v91, 0x358637bd, v91
	v_rsq_f32_e32 v94, v91
	v_mul_f32_e32 v91, 0.5, v91
	v_mul_f32_e32 v92, v94, v94
	v_fma_f32 v92, -v91, v92, 0.5
	v_fma_f32 v94, v94, v92, v94
	v_pk_add_f32 v[98:99], v[98:99], v[92:93] op_sel:[0,1] op_sel_hi:[1,1] neg_lo:[0,1] neg_hi:[0,1]
	v_pk_add_f32 v[100:101], v[100:101], v[92:93] op_sel:[0,1] op_sel_hi:[1,1] neg_lo:[0,1] neg_hi:[0,1]
	v_pk_add_f32 v[102:103], v[102:103], v[92:93] op_sel:[0,1] op_sel_hi:[1,1] neg_lo:[0,1] neg_hi:[0,1]
	v_pk_add_f32 v[104:105], v[104:105], v[92:93] op_sel:[0,1] op_sel_hi:[1,1] neg_lo:[0,1] neg_hi:[0,1]
	v_pk_add_f32 v[106:107], v[106:107], v[92:93] op_sel:[0,1] op_sel_hi:[1,1] neg_lo:[0,1] neg_hi:[0,1]
	v_pk_add_f32 v[108:109], v[108:109], v[92:93] op_sel:[0,1] op_sel_hi:[1,1] neg_lo:[0,1] neg_hi:[0,1]
	v_pk_add_f32 v[110:111], v[110:111], v[92:93] op_sel:[0,1] op_sel_hi:[1,1] neg_lo:[0,1] neg_hi:[0,1]
	v_pk_add_f32 v[112:113], v[112:113], v[92:93] op_sel:[0,1] op_sel_hi:[1,1] neg_lo:[0,1] neg_hi:[0,1]
	v_pk_mul_f32 v[98:99], v[98:99], v[94:95] op_sel_hi:[1,0]
	v_pk_mul_f32 v[100:101], v[100:101], v[94:95] op_sel_hi:[1,0]
	v_pk_mul_f32 v[102:103], v[102:103], v[94:95] op_sel_hi:[1,0]
	v_pk_mul_f32 v[104:105], v[104:105], v[94:95] op_sel_hi:[1,0]
	v_pk_mul_f32 v[106:107], v[106:107], v[94:95] op_sel_hi:[1,0]
	v_pk_mul_f32 v[108:109], v[108:109], v[94:95] op_sel_hi:[1,0]
	v_pk_mul_f32 v[110:111], v[110:111], v[94:95] op_sel_hi:[1,0]
	v_pk_mul_f32 v[112:113], v[112:113], v[94:95] op_sel_hi:[1,0]
	v_pk_fma_f32 v[98:99], v[98:99], v[10:11], v[26:27]
	v_pk_fma_f32 v[100:101], v[100:101], v[12:13], v[28:29]
	v_pk_fma_f32 v[102:103], v[102:103], v[14:15], v[30:31]
	v_pk_fma_f32 v[104:105], v[104:105], v[16:17], v[32:33]
	v_pk_fma_f32 v[106:107], v[106:107], v[18:19], v[34:35]
	v_pk_fma_f32 v[108:109], v[108:109], v[20:21], v[36:37]
	v_pk_fma_f32 v[110:111], v[110:111], v[22:23], v[38:39]
	v_pk_fma_f32 v[112:113], v[112:113], v[24:25], v[40:41]
	s_add_u32 s2, s8, 0x3000
	s_addc_u32 s3, s9, 0
	global_store_dwordx4 v0, v[98:101], s[2:3]
	global_store_dwordx4 v0, v[102:105], s[2:3] offset:1024
	global_store_dwordx4 v0, v[106:109], s[2:3] offset:2048
	global_store_dwordx4 v0, v[110:113], s[2:3] offset:3072
	s_add_u32 s2, s8, 0x7000
	s_addc_u32 s3, s9, 0
	global_load_dwordx4 v[98:101], v0, s[2:3]
	global_load_dwordx4 v[102:105], v0, s[2:3] offset:1024
	global_load_dwordx4 v[106:109], v0, s[2:3] offset:2048
	global_load_dwordx4 v[110:113], v0, s[2:3] offset:3072
	s_waitcnt vmcnt(24)
; DI void ln_row_v(const Frame& F, f32x4 (&v)[4], float* xout, const float* g, const float* b, const float* sh, const float* sc, bf16_t* hout, const float* slab, const float* gres, float* stat = nullptr) {
;     ...
;         float s = 0.f, s2 = 0.f;
; #pragma unroll
;         for (int j = 0; j < 4; ++j) { s += (v[j][0] + v[j][1]) + (v[j][2] + v[j][3]); s2 += (v[j][0] * v[j][0] + v[j][1] * v[j][1]) + (v[j][2] * v[j][2] + v[j][3] * v[j][3]); }
;         wave_sum2(s, s2, F.lane);
;         const float mean = s * (1.f / D); const float rstd = 1.f / sqrtf(fmaxf(s2 * (1.f / D) - mean * mean, 0.f) + EPS);
;         if (stat && F.lane == 0) { f32x2 sv = {mean, rstd}; *(f32x2*)stat = sv; }
; #pragma unroll
;         for (int j = 0; j < 4; ++j) { const f32x4 gg = ((const f32x4*)g)[F.lane + 64 * j], bb = ((const f32x4*)b)[F.lane + 64 * j];
;             v[j] = (v[j] - mean) * rstd * gg + bb; if (xout) ((f32x4*)xout)[F.lane + 64 * j] = v[j]; }
	v_pk_add_f32 v[198:199], v[42:43], v[44:45]
	v_pk_mul_f32 v[200:201], v[42:43], v[42:43]
	v_pk_fma_f32 v[200:201], v[44:45], v[44:45], v[200:201]
	v_pk_add_f32 v[198:199], v[198:199], v[46:47]
	v_pk_fma_f32 v[200:201], v[46:47], v[46:47], v[200:201]
	v_pk_add_f32 v[198:199], v[198:199], v[48:49]
	v_pk_fma_f32 v[200:201], v[48:49], v[48:49], v[200:201]
	v_pk_add_f32 v[198:199], v[198:199], v[50:51]
	v_pk_fma_f32 v[200:201], v[50:51], v[50:51], v[200:201]
	v_pk_add_f32 v[198:199], v[198:199], v[52:53]
	v_pk_fma_f32 v[200:201], v[52:53], v[52:53], v[200:201]
	v_pk_add_f32 v[198:199], v[198:199], v[54:55]
	v_pk_fma_f32 v[200:201], v[54:55], v[54:55], v[200:201]
	v_pk_add_f32 v[198:199], v[198:199], v[56:57]
	v_pk_fma_f32 v[200:201], v[56:57], v[56:57], v[200:201]
	v_add_f32_e32 v9, v198, v199
	v_add_f32_e32 v90, v200, v201
	s_nop 1
	v_add_f32_dpp v9, v9, v9 quad_perm:[1,0,3,2] row_mask:0xf bank_mask:0xf
	v_add_f32_dpp v90, v90, v90 quad_perm:[1,0,3,2] row_mask:0xf bank_mask:0xf
	s_nop 0
	v_add_f32_dpp v9, v9, v9 quad_perm:[2,3,0,1] row_mask:0xf bank_mask:0xf
	v_add_f32_dpp v90, v90, v90 quad_perm:[2,3,0,1] row_mask:0xf bank_mask:0xf
	s_nop 0
	v_add_f32_dpp v9, v9, v9 row_half_mirror row_mask:0xf bank_mask:0xf
	v_add_f32_dpp v90, v90, v90 row_half_mirror row_mask:0xf bank_mask:0xf
	s_nop 0
	v_add_f32_dpp v9, v9, v9 row_mirror row_mask:0xf bank_mask:0xf
	v_add_f32_dpp v90, v90, v90 row_mirror row_mask:0xf bank_mask:0xf
	s_nop 0
	v_add_f32_dpp v9, v9, v9 row_bcast:15 row_mask:0xa bank_mask:0xf
	v_add_f32_dpp v90, v90, v90 row_bcast:15 row_mask:0xa bank_mask:0xf
	s_nop 0
	v_add_f32_dpp v9, v9, v9 row_bcast:31 row_mask:0xc bank_mask:0xf
	v_add_f32_dpp v90, v90, v90 row_bcast:31 row_mask:0xc bank_mask:0xf
	s_nop 0
	v_readlane_b32 s2, v9, 63
	v_readlane_b32 s3, v90, 63
	s_nop 1
	v_mov_b32_e32 v9, s2
	v_mov_b32_e32 v90, s3
	v_mul_f32_e32 v93, 0x3a800000, v9
	v_mul_f32_e32 v91, 0x3a800000, v90
	v_fma_f32 v91, -v93, v93, v91
	v_max_f32_e32 v91, 0, v91
	v_add_f32_e32 v91, 0x358637bd, v91
	v_rsq_f32_e32 v94, v91
	v_mul_f32_e32 v91, 0.5, v91
	v_mul_f32_e32 v92, v94, v94
	v_fma_f32 v92, -v91, v92, 0.5
	v_fma_f32 v94, v94, v92, v94
	v_pk_add_f32 v[42:43], v[42:43], v[92:93] op_sel:[0,1] op_sel_hi:[1,1] neg_lo:[0,1] neg_hi:[0,1]
	v_pk_add_f32 v[44:45], v[44:45], v[92:93] op_sel:[0,1] op_sel_hi:[1,1] neg_lo:[0,1] neg_hi:[0,1]
	v_pk_add_f32 v[46:47], v[46:47], v[92:93] op_sel:[0,1] op_sel_hi:[1,1] neg_lo:[0,1] neg_hi:[0,1]
	v_pk_add_f32 v[48:49], v[48:49], v[92:93] op_sel:[0,1] op_sel_hi:[1,1] neg_lo:[0,1] neg_hi:[0,1]
	v_pk_add_f32 v[50:51], v[50:51], v[92:93] op_sel:[0,1] op_sel_hi:[1,1] neg_lo:[0,1] neg_hi:[0,1]
	v_pk_add_f32 v[52:53], v[52:53], v[92:93] op_sel:[0,1] op_sel_hi:[1,1] neg_lo:[0,1] neg_hi:[0,1]
	v_pk_add_f32 v[54:55], v[54:55], v[92:93] op_sel:[0,1] op_sel_hi:[1,1] neg_lo:[0,1] neg_hi:[0,1]
	v_pk_add_f32 v[56:57], v[56:57], v[92:93] op_sel:[0,1] op_sel_hi:[1,1] neg_lo:[0,1] neg_hi:[0,1]
	v_pk_mul_f32 v[42:43], v[42:43], v[94:95] op_sel_hi:[1,0]
	v_pk_mul_f32 v[44:45], v[44:45], v[94:95] op_sel_hi:[1,0]
	v_pk_mul_f32 v[46:47], v[46:47], v[94:95] op_sel_hi:[1,0]
	v_pk_mul_f32 v[48:49], v[48:49], v[94:95] op_sel_hi:[1,0]
	v_pk_mul_f32 v[50:51], v[50:51], v[94:95] op_sel_hi:[1,0]
	v_pk_mul_f32 v[52:53], v[52:53], v[94:95] op_sel_hi:[1,0]
	v_pk_mul_f32 v[54:55], v[54:55], v[94:95] op_sel_hi:[1,0]
	v_pk_mul_f32 v[56:57], v[56:57], v[94:95] op_sel_hi:[1,0]
	v_pk_fma_f32 v[42:43], v[42:43], v[10:11], v[26:27]
	v_pk_fma_f32 v[44:45], v[44:45], v[12:13], v[28:29]
	v_pk_fma_f32 v[46:47], v[46:47], v[14:15], v[30:31]
	v_pk_fma_f32 v[48:49], v[48:49], v[16:17], v[32:33]
	v_pk_fma_f32 v[50:51], v[50:51], v[18:19], v[34:35]
	v_pk_fma_f32 v[52:53], v[52:53], v[20:21], v[36:37]
	v_pk_fma_f32 v[54:55], v[54:55], v[22:23], v[38:39]
	v_pk_fma_f32 v[56:57], v[56:57], v[24:25], v[40:41]
	s_add_u32 s2, s8, 0x4000
	s_addc_u32 s3, s9, 0
	global_store_dwordx4 v0, v[42:45], s[2:3]
	global_store_dwordx4 v0, v[46:49], s[2:3] offset:1024
	global_store_dwordx4 v0, v[50:53], s[2:3] offset:2048
	global_store_dwordx4 v0, v[54:57], s[2:3] offset:3072
	s_waitcnt vmcnt(20)
	v_pk_add_f32 v[198:199], v[58:59], v[60:61]
	v_pk_mul_f32 v[200:201], v[58:59], v[58:59]
	v_pk_fma_f32 v[200:201], v[60:61], v[60:61], v[200:201]
	v_pk_add_f32 v[198:199], v[198:199], v[62:63]
	v_pk_fma_f32 v[200:201], v[62:63], v[62:63], v[200:201]
	v_pk_add_f32 v[198:199], v[198:199], v[64:65]
	v_pk_fma_f32 v[200:201], v[64:65], v[64:65], v[200:201]
	v_pk_add_f32 v[198:199], v[198:199], v[66:67]
	v_pk_fma_f32 v[200:201], v[66:67], v[66:67], v[200:201]
	v_pk_add_f32 v[198:199], v[198:199], v[68:69]
	v_pk_fma_f32 v[200:201], v[68:69], v[68:69], v[200:201]
	v_pk_add_f32 v[198:199], v[198:199], v[70:71]
	v_pk_fma_f32 v[200:201], v[70:71], v[70:71], v[200:201]
	v_pk_add_f32 v[198:199], v[198:199], v[72:73]
	v_pk_fma_f32 v[200:201], v[72:73], v[72:73], v[200:201]
	v_add_f32_e32 v9, v198, v199
	v_add_f32_e32 v90, v200, v201
	s_nop 1
	v_add_f32_dpp v9, v9, v9 quad_perm:[1,0,3,2] row_mask:0xf bank_mask:0xf
	v_add_f32_dpp v90, v90, v90 quad_perm:[1,0,3,2] row_mask:0xf bank_mask:0xf
	s_nop 0
	v_add_f32_dpp v9, v9, v9 quad_perm:[2,3,0,1] row_mask:0xf bank_mask:0xf
	v_add_f32_dpp v90, v90, v90 quad_perm:[2,3,0,1] row_mask:0xf bank_mask:0xf
	s_nop 0
	v_add_f32_dpp v9, v9, v9 row_half_mirror row_mask:0xf bank_mask:0xf
	v_add_f32_dpp v90, v90, v90 row_half_mirror row_mask:0xf bank_mask:0xf
	s_nop 0
	v_add_f32_dpp v9, v9, v9 row_mirror row_mask:0xf bank_mask:0xf
	v_add_f32_dpp v90, v90, v90 row_mirror row_mask:0xf bank_mask:0xf
	s_nop 0
	v_add_f32_dpp v9, v9, v9 row_bcast:15 row_mask:0xa bank_mask:0xf
; DI void ln_row_v(const Frame& F, f32x4 (&v)[4], float* xout, const float* g, const float* b, const float* sh, const float* sc, bf16_t* hout, const float* slab, const float* gres, float* stat = nullptr) {
;     ...
;         float s = 0.f, s2 = 0.f;
; #pragma unroll
;         for (int j = 0; j < 4; ++j) { s += (v[j][0] + v[j][1]) + (v[j][2] + v[j][3]); s2 += (v[j][0] * v[j][0] + v[j][1] * v[j][1]) + (v[j][2] * v[j][2] + v[j][3] * v[j][3]); }
;         wave_sum2(s, s2, F.lane);
;         const float mean = s * (1.f / D); const float rstd = 1.f / sqrtf(fmaxf(s2 * (1.f / D) - mean * mean, 0.f) + EPS);
;         if (stat && F.lane == 0) { f32x2 sv = {mean, rstd}; *(f32x2*)stat = sv; }
; #pragma unroll
;         for (int j = 0; j < 4; ++j) { const f32x4 gg = ((const f32x4*)g)[F.lane + 64 * j], bb = ((const f32x4*)b)[F.lane + 64 * j];
;             v[j] = (v[j] - mean) * rstd * gg + bb; if (xout) ((f32x4*)xout)[F.lane + 64 * j] = v[j]; }
	v_add_f32_dpp v90, v90, v90 row_bcast:15 row_mask:0xa bank_mask:0xf
	s_nop 0
	v_add_f32_dpp v9, v9, v9 row_bcast:31 row_mask:0xc bank_mask:0xf
	v_add_f32_dpp v90, v90, v90 row_bcast:31 row_mask:0xc bank_mask:0xf
	s_nop 0
	v_readlane_b32 s2, v9, 63
	v_readlane_b32 s3, v90, 63
	s_nop 1
	v_mov_b32_e32 v9, s2
	v_mov_b32_e32 v90, s3
	v_mul_f32_e32 v93, 0x3a800000, v9
	v_mul_f32_e32 v91, 0x3a800000, v90
	v_fma_f32 v91, -v93, v93, v91
	v_max_f32_e32 v91, 0, v91
	v_add_f32_e32 v91, 0x358637bd, v91
	v_rsq_f32_e32 v94, v91
	v_mul_f32_e32 v91, 0.5, v91
	v_mul_f32_e32 v92, v94, v94
	v_fma_f32 v92, -v91, v92, 0.5
	v_fma_f32 v94, v94, v92, v94
	v_pk_add_f32 v[58:59], v[58:59], v[92:93] op_sel:[0,1] op_sel_hi:[1,1] neg_lo:[0,1] neg_hi:[0,1]
	v_pk_add_f32 v[60:61], v[60:61], v[92:93] op_sel:[0,1] op_sel_hi:[1,1] neg_lo:[0,1] neg_hi:[0,1]
	v_pk_add_f32 v[62:63], v[62:63], v[92:93] op_sel:[0,1] op_sel_hi:[1,1] neg_lo:[0,1] neg_hi:[0,1]
	v_pk_add_f32 v[64:65], v[64:65], v[92:93] op_sel:[0,1] op_sel_hi:[1,1] neg_lo:[0,1] neg_hi:[0,1]
	v_pk_add_f32 v[66:67], v[66:67], v[92:93] op_sel:[0,1] op_sel_hi:[1,1] neg_lo:[0,1] neg_hi:[0,1]
	v_pk_add_f32 v[68:69], v[68:69], v[92:93] op_sel:[0,1] op_sel_hi:[1,1] neg_lo:[0,1] neg_hi:[0,1]
	v_pk_add_f32 v[70:71], v[70:71], v[92:93] op_sel:[0,1] op_sel_hi:[1,1] neg_lo:[0,1] neg_hi:[0,1]
	v_pk_add_f32 v[72:73], v[72:73], v[92:93] op_sel:[0,1] op_sel_hi:[1,1] neg_lo:[0,1] neg_hi:[0,1]
	v_pk_mul_f32 v[58:59], v[58:59], v[94:95] op_sel_hi:[1,0]
	v_pk_mul_f32 v[60:61], v[60:61], v[94:95] op_sel_hi:[1,0]
	v_pk_mul_f32 v[62:63], v[62:63], v[94:95] op_sel_hi:[1,0]
	v_pk_mul_f32 v[64:65], v[64:65], v[94:95] op_sel_hi:[1,0]
	v_pk_mul_f32 v[66:67], v[66:67], v[94:95] op_sel_hi:[1,0]
	v_pk_mul_f32 v[68:69], v[68:69], v[94:95] op_sel_hi:[1,0]
	v_pk_mul_f32 v[70:71], v[70:71], v[94:95] op_sel_hi:[1,0]
	v_pk_mul_f32 v[72:73], v[72:73], v[94:95] op_sel_hi:[1,0]
	v_pk_fma_f32 v[58:59], v[58:59], v[10:11], v[26:27]
	v_pk_fma_f32 v[60:61], v[60:61], v[12:13], v[28:29]
	v_pk_fma_f32 v[62:63], v[62:63], v[14:15], v[30:31]
	v_pk_fma_f32 v[64:65], v[64:65], v[16:17], v[32:33]
	v_pk_fma_f32 v[66:67], v[66:67], v[18:19], v[34:35]
	v_pk_fma_f32 v[68:69], v[68:69], v[20:21], v[36:37]
	v_pk_fma_f32 v[70:71], v[70:71], v[22:23], v[38:39]
	v_pk_fma_f32 v[72:73], v[72:73], v[24:25], v[40:41]
	s_add_u32 s2, s8, 0x5000
	s_addc_u32 s3, s9, 0
	global_store_dwordx4 v0, v[58:61], s[2:3]
	global_store_dwordx4 v0, v[62:65], s[2:3] offset:1024
	global_store_dwordx4 v0, v[66:69], s[2:3] offset:2048
	global_store_dwordx4 v0, v[70:73], s[2:3] offset:3072
	s_waitcnt vmcnt(16)
	v_pk_add_f32 v[198:199], v[74:75], v[76:77]
	v_pk_mul_f32 v[200:201], v[74:75], v[74:75]
	v_pk_fma_f32 v[200:201], v[76:77], v[76:77], v[200:201]
	v_pk_add_f32 v[198:199], v[198:199], v[78:79]
	v_pk_fma_f32 v[200:201], v[78:79], v[78:79], v[200:201]
	v_pk_add_f32 v[198:199], v[198:199], v[80:81]
	v_pk_fma_f32 v[200:201], v[80:81], v[80:81], v[200:201]
	v_pk_add_f32 v[198:199], v[198:199], v[82:83]
	v_pk_fma_f32 v[200:201], v[82:83], v[82:83], v[200:201]
	v_pk_add_f32 v[198:199], v[198:199], v[84:85]
	v_pk_fma_f32 v[200:201], v[84:85], v[84:85], v[200:201]
	v_pk_add_f32 v[198:199], v[198:199], v[86:87]
	v_pk_fma_f32 v[200:201], v[86:87], v[86:87], v[200:201]
	v_pk_add_f32 v[198:199], v[198:199], v[88:89]
	v_pk_fma_f32 v[200:201], v[88:89], v[88:89], v[200:201]
	v_add_f32_e32 v9, v198, v199
	v_add_f32_e32 v90, v200, v201
	s_nop 1
	v_add_f32_dpp v9, v9, v9 quad_perm:[1,0,3,2] row_mask:0xf bank_mask:0xf
	v_add_f32_dpp v90, v90, v90 quad_perm:[1,0,3,2] row_mask:0xf bank_mask:0xf
	s_nop 0
	v_add_f32_dpp v9, v9, v9 quad_perm:[2,3,0,1] row_mask:0xf bank_mask:0xf
	v_add_f32_dpp v90, v90, v90 quad_perm:[2,3,0,1] row_mask:0xf bank_mask:0xf
	s_nop 0
	v_add_f32_dpp v9, v9, v9 row_half_mirror row_mask:0xf bank_mask:0xf
	v_add_f32_dpp v90, v90, v90 row_half_mirror row_mask:0xf bank_mask:0xf
	s_nop 0
	v_add_f32_dpp v9, v9, v9 row_mirror row_mask:0xf bank_mask:0xf
	v_add_f32_dpp v90, v90, v90 row_mirror row_mask:0xf bank_mask:0xf
	s_nop 0
	v_add_f32_dpp v9, v9, v9 row_bcast:15 row_mask:0xa bank_mask:0xf
	v_add_f32_dpp v90, v90, v90 row_bcast:15 row_mask:0xa bank_mask:0xf
	s_nop 0
	v_add_f32_dpp v9, v9, v9 row_bcast:31 row_mask:0xc bank_mask:0xf
	v_add_f32_dpp v90, v90, v90 row_bcast:31 row_mask:0xc bank_mask:0xf
	s_nop 0
	v_readlane_b32 s2, v9, 63
	v_readlane_b32 s3, v90, 63
	s_nop 1
	v_mov_b32_e32 v9, s2
	v_mov_b32_e32 v90, s3
	v_mul_f32_e32 v93, 0x3a800000, v9
	v_mul_f32_e32 v91, 0x3a800000, v90
	v_fma_f32 v91, -v93, v93, v91
	v_max_f32_e32 v91, 0, v91
	v_add_f32_e32 v91, 0x358637bd, v91
	v_rsq_f32_e32 v94, v91
	v_mul_f32_e32 v91, 0.5, v91
	v_mul_f32_e32 v92, v94, v94
	v_fma_f32 v92, -v91, v92, 0.5
	v_fma_f32 v94, v94, v92, v94
	v_pk_add_f32 v[74:75], v[74:75], v[92:93] op_sel:[0,1] op_sel_hi:[1,1] neg_lo:[0,1] neg_hi:[0,1]
	v_pk_add_f32 v[76:77], v[76:77], v[92:93] op_sel:[0,1] op_sel_hi:[1,1] neg_lo:[0,1] neg_hi:[0,1]
	v_pk_add_f32 v[78:79], v[78:79], v[92:93] op_sel:[0,1] op_sel_hi:[1,1] neg_lo:[0,1] neg_hi:[0,1]
	v_pk_add_f32 v[80:81], v[80:81], v[92:93] op_sel:[0,1] op_sel_hi:[1,1] neg_lo:[0,1] neg_hi:[0,1]
	v_pk_add_f32 v[82:83], v[82:83], v[92:93] op_sel:[0,1] op_sel_hi:[1,1] neg_lo:[0,1] neg_hi:[0,1]
	v_pk_add_f32 v[84:85], v[84:85], v[92:93] op_sel:[0,1] op_sel_hi:[1,1] neg_lo:[0,1] neg_hi:[0,1]
	v_pk_add_f32 v[86:87], v[86:87], v[92:93] op_sel:[0,1] op_sel_hi:[1,1] neg_lo:[0,1] neg_hi:[0,1]
	v_pk_add_f32 v[88:89], v[88:89], v[92:93] op_sel:[0,1] op_sel_hi:[1,1] neg_lo:[0,1] neg_hi:[0,1]
	v_pk_mul_f32 v[74:75], v[74:75], v[94:95] op_sel_hi:[1,0]
	v_pk_mul_f32 v[76:77], v[76:77], v[94:95] op_sel_hi:[1,0]
	v_pk_mul_f32 v[78:79], v[78:79], v[94:95] op_sel_hi:[1,0]
	v_pk_mul_f32 v[80:81], v[80:81], v[94:95] op_sel_hi:[1,0]
	v_pk_mul_f32 v[82:83], v[82:83], v[94:95] op_sel_hi:[1,0]
	v_pk_mul_f32 v[84:85], v[84:85], v[94:95] op_sel_hi:[1,0]
	v_pk_mul_f32 v[86:87], v[86:87], v[94:95] op_sel_hi:[1,0]
	v_pk_mul_f32 v[88:89], v[88:89], v[94:95] op_sel_hi:[1,0]
	v_pk_fma_f32 v[74:75], v[74:75], v[10:11], v[26:27]
	v_pk_fma_f32 v[76:77], v[76:77], v[12:13], v[28:29]
	v_pk_fma_f32 v[78:79], v[78:79], v[14:15], v[30:31]
	v_pk_fma_f32 v[80:81], v[80:81], v[16:17], v[32:33]
	v_pk_fma_f32 v[82:83], v[82:83], v[18:19], v[34:35]
	v_pk_fma_f32 v[84:85], v[84:85], v[20:21], v[36:37]
	v_pk_fma_f32 v[86:87], v[86:87], v[22:23], v[38:39]
	v_pk_fma_f32 v[88:89], v[88:89], v[24:25], v[40:41]
	s_add_u32 s2, s8, 0x6000
	s_addc_u32 s3, s9, 0
	global_store_dwordx4 v0, v[74:77], s[2:3]
	global_store_dwordx4 v0, v[78:81], s[2:3] offset:1024
	global_store_dwordx4 v0, v[82:85], s[2:3] offset:2048
	global_store_dwordx4 v0, v[86:89], s[2:3] offset:3072
	s_waitcnt vmcnt(12)
; DI void ln_row_v(const Frame& F, f32x4 (&v)[4], float* xout, const float* g, const float* b, const float* sh, const float* sc, bf16_t* hout, const float* slab, const float* gres, float* stat = nullptr) {
;     ...
;         float s = 0.f, s2 = 0.f;
; #pragma unroll
;         for (int j = 0; j < 4; ++j) { s += (v[j][0] + v[j][1]) + (v[j][2] + v[j][3]); s2 += (v[j][0] * v[j][0] + v[j][1] * v[j][1]) + (v[j][2] * v[j][2] + v[j][3] * v[j][3]); }
;         wave_sum2(s, s2, F.lane);
;         const float mean = s * (1.f / D); const float rstd = 1.f / sqrtf(fmaxf(s2 * (1.f / D) - mean * mean, 0.f) + EPS);
;         if (stat && F.lane == 0) { f32x2 sv = {mean, rstd}; *(f32x2*)stat = sv; }
; #pragma unroll
;         for (int j = 0; j < 4; ++j) { const f32x4 gg = ((const f32x4*)g)[F.lane + 64 * j], bb = ((const f32x4*)b)[F.lane + 64 * j];
;             v[j] = (v[j] - mean) * rstd * gg + bb; if (xout) ((f32x4*)xout)[F.lane + 64 * j] = v[j]; }
	v_pk_add_f32 v[198:199], v[98:99], v[100:101]
	v_pk_mul_f32 v[200:201], v[98:99], v[98:99]
	v_pk_fma_f32 v[200:201], v[100:101], v[100:101], v[200:201]
	v_pk_add_f32 v[198:199], v[198:199], v[102:103]
	v_pk_fma_f32 v[200:201], v[102:103], v[102:103], v[200:201]
	v_pk_add_f32 v[198:199], v[198:199], v[104:105]
	v_pk_fma_f32 v[200:201], v[104:105], v[104:105], v[200:201]
	v_pk_add_f32 v[198:199], v[198:199], v[106:107]
	v_pk_fma_f32 v[200:201], v[106:107], v[106:107], v[200:201]
	v_pk_add_f32 v[198:199], v[198:199], v[108:109]
	v_pk_fma_f32 v[200:201], v[108:109], v[108:109], v[200:201]
	v_pk_add_f32 v[198:199], v[198:199], v[110:111]
	v_pk_fma_f32 v[200:201], v[110:111], v[110:111], v[200:201]
	v_pk_add_f32 v[198:199], v[198:199], v[112:113]
	v_pk_fma_f32 v[200:201], v[112:113], v[112:113], v[200:201]
	v_add_f32_e32 v9, v198, v199
	v_add_f32_e32 v90, v200, v201
	s_nop 1
	v_add_f32_dpp v9, v9, v9 quad_perm:[1,0,3,2] row_mask:0xf bank_mask:0xf
	v_add_f32_dpp v90, v90, v90 quad_perm:[1,0,3,2] row_mask:0xf bank_mask:0xf
	s_nop 0
	v_add_f32_dpp v9, v9, v9 quad_perm:[2,3,0,1] row_mask:0xf bank_mask:0xf
	v_add_f32_dpp v90, v90, v90 quad_perm:[2,3,0,1] row_mask:0xf bank_mask:0xf
	s_nop 0
	v_add_f32_dpp v9, v9, v9 row_half_mirror row_mask:0xf bank_mask:0xf
	v_add_f32_dpp v90, v90, v90 row_half_mirror row_mask:0xf bank_mask:0xf
	s_nop 0
	v_add_f32_dpp v9, v9, v9 row_mirror row_mask:0xf bank_mask:0xf
	v_add_f32_dpp v90, v90, v90 row_mirror row_mask:0xf bank_mask:0xf
	s_nop 0
	v_add_f32_dpp v9, v9, v9 row_bcast:15 row_mask:0xa bank_mask:0xf
	v_add_f32_dpp v90, v90, v90 row_bcast:15 row_mask:0xa bank_mask:0xf
	s_nop 0
	v_add_f32_dpp v9, v9, v9 row_bcast:31 row_mask:0xc bank_mask:0xf
	v_add_f32_dpp v90, v90, v90 row_bcast:31 row_mask:0xc bank_mask:0xf
	s_nop 0
	v_readlane_b32 s2, v9, 63
	v_readlane_b32 s3, v90, 63
	s_nop 1
	v_mov_b32_e32 v9, s2
	v_mov_b32_e32 v90, s3
	v_mul_f32_e32 v93, 0x3a800000, v9
	v_mul_f32_e32 v91, 0x3a800000, v90
	v_fma_f32 v91, -v93, v93, v91
	v_max_f32_e32 v91, 0, v91
	v_add_f32_e32 v91, 0x358637bd, v91
	v_rsq_f32_e32 v94, v91
	v_mul_f32_e32 v91, 0.5, v91
	v_mul_f32_e32 v92, v94, v94
	v_fma_f32 v92, -v91, v92, 0.5
	v_fma_f32 v94, v94, v92, v94
	v_pk_add_f32 v[98:99], v[98:99], v[92:93] op_sel:[0,1] op_sel_hi:[1,1] neg_lo:[0,1] neg_hi:[0,1]
	v_pk_add_f32 v[100:101], v[100:101], v[92:93] op_sel:[0,1] op_sel_hi:[1,1] neg_lo:[0,1] neg_hi:[0,1]
	v_pk_add_f32 v[102:103], v[102:103], v[92:93] op_sel:[0,1] op_sel_hi:[1,1] neg_lo:[0,1] neg_hi:[0,1]
	v_pk_add_f32 v[104:105], v[104:105], v[92:93] op_sel:[0,1] op_sel_hi:[1,1] neg_lo:[0,1] neg_hi:[0,1]
	v_pk_add_f32 v[106:107], v[106:107], v[92:93] op_sel:[0,1] op_sel_hi:[1,1] neg_lo:[0,1] neg_hi:[0,1]
	v_pk_add_f32 v[108:109], v[108:109], v[92:93] op_sel:[0,1] op_sel_hi:[1,1] neg_lo:[0,1] neg_hi:[0,1]
	v_pk_add_f32 v[110:111], v[110:111], v[92:93] op_sel:[0,1] op_sel_hi:[1,1] neg_lo:[0,1] neg_hi:[0,1]
	v_pk_add_f32 v[112:113], v[112:113], v[92:93] op_sel:[0,1] op_sel_hi:[1,1] neg_lo:[0,1] neg_hi:[0,1]
	v_pk_mul_f32 v[98:99], v[98:99], v[94:95] op_sel_hi:[1,0]
	v_pk_mul_f32 v[100:101], v[100:101], v[94:95] op_sel_hi:[1,0]
	v_pk_mul_f32 v[102:103], v[102:103], v[94:95] op_sel_hi:[1,0]
	v_pk_mul_f32 v[104:105], v[104:105], v[94:95] op_sel_hi:[1,0]
	v_pk_mul_f32 v[106:107], v[106:107], v[94:95] op_sel_hi:[1,0]
	v_pk_mul_f32 v[108:109], v[108:109], v[94:95] op_sel_hi:[1,0]
	v_pk_mul_f32 v[110:111], v[110:111], v[94:95] op_sel_hi:[1,0]
	v_pk_mul_f32 v[112:113], v[112:113], v[94:95] op_sel_hi:[1,0]
	v_pk_fma_f32 v[98:99], v[98:99], v[10:11], v[26:27]
	v_pk_fma_f32 v[100:101], v[100:101], v[12:13], v[28:29]
	v_pk_fma_f32 v[102:103], v[102:103], v[14:15], v[30:31]
	v_pk_fma_f32 v[104:105], v[104:105], v[16:17], v[32:33]
	v_pk_fma_f32 v[106:107], v[106:107], v[18:19], v[34:35]
	v_pk_fma_f32 v[108:109], v[108:109], v[20:21], v[36:37]
	v_pk_fma_f32 v[110:111], v[110:111], v[22:23], v[38:39]
	v_pk_fma_f32 v[112:113], v[112:113], v[24:25], v[40:41]
	s_add_u32 s2, s8, 0x7000
	s_addc_u32 s3, s9, 0
	global_store_dwordx4 v0, v[98:101], s[2:3]
	global_store_dwordx4 v0, v[102:105], s[2:3] offset:1024
	global_store_dwordx4 v0, v[106:109], s[2:3] offset:2048
	global_store_dwordx4 v0, v[110:113], s[2:3] offset:3072
	s_waitcnt vmcnt(0)

; DI const float* modp(const Frame& F, int l, int mr, int which) { return (const float*)(F.ws + WS_MOD) + ((size_t)(l * 9 + mr) * 6 + which) * 1024; }
; DI void ln_row_v(const Frame& F, f32x4 (&v)[4], float* xout, const float* g, const float* b, const float* sh, const float* sc, bf16_t* hout, const float* slab, const float* gres, float* stat = nullptr) {
;     ...
;     if (hout) {
;         float s = 0.f, s2 = 0.f;
; #pragma unroll
;         for (int j = 0; j < 4; ++j) { s += (v[j][0] + v[j][1]) + (v[j][2] + v[j][3]); s2 += (v[j][0] * v[j][0] + v[j][1] * v[j][1]) + (v[j][2] * v[j][2] + v[j][3] * v[j][3]); }
;         wave_sum2(s, s2, F.lane);
;         const float mean = s * (1.f / D); const float rstd = 1.f / sqrtf(fmaxf(s2 * (1.f / D) - mean * mean, 0.f) + EPS);
; DI void prologue_b(const Frame& F) {
;     const int gw = F.vcu * 8 + F.wave, NGW = F.G * 8;
;     bf16_t* H = (bf16_t*)(F.ws + WS_HB);
;     for (int row = gw; row < MT; row += NGW) {
;         const int mr = row < ML ? (row >> 11) : 8;
;         const float* xi = row < ML ? pin(F, I_X) + (size_t)row * D : pin(F, I_CTX) + (size_t)(row - ML) * D;
;         ln_row(F, xi, nullptr, nullptr, nullptr, modp(F, 0, mr, 0), modp(F, 0, mr, 1), H + (size_t)row * D);
;     }
.LBB0_663:
	s_and_b64 vcc, exec, s[2:3]
	s_cbranch_vccz .LBB0_671
	v_readlane_b32 s2, v255, 29
	s_lshl_b32 s2, s2, 3
	v_readlane_b32 s3, v255, 31
	s_add_i32 s16, s3, s2
	v_lshlrev_b32_e32 v0, 4, v186
	v_lshlrev_b32_e32 v1, 3, v186
	v_lshlrev_b32_e32 v96, 2, v186
	v_xor_b32_e32 v3, 4, v96
	v_xor_b32_e32 v4, 8, v96
	v_xor_b32_e32 v5, 16, v96
	v_xor_b32_e32 v6, 32, v96
	v_xor_b32_e32 v7, 64, v96
	v_xor_b32_e32 v8, 128, v96
	s_load_dwordx2 s[8:9], s[62:63], 0x0
	s_load_dwordx2 s[20:21], s[62:63], 0x10
	s_mov_b32 s22, 0
	s_lshl_b32 s2, s16, 12
	s_lshl_b32 s3, s16, 15
	s_waitcnt lgkmcnt(0)
	s_add_u32 s8, s8, s3
	s_addc_u32 s9, s9, 0
	s_add_u32 s20, s20, s2
	s_addc_u32 s21, s21, 0
	s_lshl_b32 s2, s16, 14
	s_add_u32 s10, s94, s2
	s_addc_u32 s11, s95, 0
	s_add_u32 s10, s10, 0x3e00000
	s_addc_u32 s11, s11, 0
	s_lshl_b32 s2, s16, 6
	s_add_u32 s12, s94, s2
	s_addc_u32 s13, s95, 0
	s_add_u32 s12, s12, 0x4c0000
	s_addc_u32 s13, s13, 0
	s_mov_b32 s3, 0
	s_mul_i32 s3, s3, 0x36000
	s_add_u32 s14, s94, s3
	s_addc_u32 s15, s95, 0
	s_add_u32 s14, s14, 0x100000
	s_addc_u32 s15, s15, 0
	s_add_u32 s18, s14, 0x1000
	s_addc_u32 s19, s15, 0
	s_add_u32 s2, s8, 0x0
	s_addc_u32 s3, s9, 0
	global_load_dwordx4 v[42:45], v0, s[2:3]
	global_load_dwordx4 v[46:49], v0, s[2:3] offset:1024
	global_load_dwordx4 v[50:53], v0, s[2:3] offset:2048
	global_load_dwordx4 v[54:57], v0, s[2:3] offset:3072
	s_lshr_b32 s23, s16, 8
	s_mul_i32 s23, s23, 0x6000
	s_add_u32 s2, s14, s23
	s_addc_u32 s3, s15, 0
	global_load_dwordx4 v[114:117], v0, s[2:3]
	global_load_dwordx4 v[118:121], v0, s[2:3] offset:1024
	global_load_dwordx4 v[122:125], v0, s[2:3] offset:2048
	global_load_dwordx4 v[126:129], v0, s[2:3] offset:3072
	s_add_u32 s2, s18, s23
	s_addc_u32 s3, s19, 0
	global_load_dwordx4 v[130:133], v0, s[2:3]
	global_load_dwordx4 v[134:137], v0, s[2:3] offset:1024
	global_load_dwordx4 v[138:141], v0, s[2:3] offset:2048
	global_load_dwordx4 v[142:145], v0, s[2:3] offset:3072
	s_add_u32 s2, s8, 0x1000
	s_addc_u32 s3, s9, 0
	global_load_dwordx4 v[58:61], v0, s[2:3]
	global_load_dwordx4 v[62:65], v0, s[2:3] offset:1024
	global_load_dwordx4 v[66:69], v0, s[2:3] offset:2048
	global_load_dwordx4 v[70:73], v0, s[2:3] offset:3072
	s_mov_b32 s23, 0x30000
	s_add_u32 s2, s14, s23
	s_addc_u32 s3, s15, 0
	global_load_dwordx4 v[146:149], v0, s[2:3]
	global_load_dwordx4 v[150:153], v0, s[2:3] offset:1024
	global_load_dwordx4 v[154:157], v0, s[2:3] offset:2048
	global_load_dwordx4 v[158:161], v0, s[2:3] offset:3072
	s_add_u32 s2, s18, s23
	s_addc_u32 s3, s19, 0
	global_load_dwordx4 v[162:165], v0, s[2:3]
	global_load_dwordx4 v[166:169], v0, s[2:3] offset:1024
	global_load_dwordx4 v[170:173], v0, s[2:3] offset:2048
	global_load_dwordx4 v[174:177], v0, s[2:3] offset:3072
	s_add_u32 s2, s8, 0x2000
	s_addc_u32 s3, s9, 0
	global_load_dwordx4 v[74:77], v0, s[2:3]
	global_load_dwordx4 v[78:81], v0, s[2:3] offset:1024
	global_load_dwordx4 v[82:85], v0, s[2:3] offset:2048
	global_load_dwordx4 v[86:89], v0, s[2:3] offset:3072
	s_add_u32 s2, s8, 0x3000
	s_addc_u32 s3, s9, 0
	global_load_dwordx4 v[98:101], v0, s[2:3]
	global_load_dwordx4 v[102:105], v0, s[2:3] offset:1024
	global_load_dwordx4 v[106:109], v0, s[2:3] offset:2048
	global_load_dwordx4 v[110:113], v0, s[2:3] offset:3072
	s_waitcnt vmcnt(28)
	v_pk_add_f32 v[198:199], v[42:43], v[44:45]
	v_pk_mul_f32 v[200:201], v[42:43], v[42:43]
	v_pk_fma_f32 v[200:201], v[44:45], v[44:45], v[200:201]
	v_pk_add_f32 v[198:199], v[198:199], v[46:47]
	v_pk_fma_f32 v[200:201], v[46:47], v[46:47], v[200:201]
	v_pk_add_f32 v[198:199], v[198:199], v[48:49]
	v_pk_fma_f32 v[200:201], v[48:49], v[48:49], v[200:201]
	v_pk_add_f32 v[198:199], v[198:199], v[50:51]
	v_pk_fma_f32 v[200:201], v[50:51], v[50:51], v[200:201]
	v_pk_add_f32 v[198:199], v[198:199], v[52:53]
	v_pk_fma_f32 v[200:201], v[52:53], v[52:53], v[200:201]
	v_pk_add_f32 v[198:199], v[198:199], v[54:55]
	v_pk_fma_f32 v[200:201], v[54:55], v[54:55], v[200:201]
	v_pk_add_f32 v[198:199], v[198:199], v[56:57]
	v_pk_fma_f32 v[200:201], v[56:57], v[56:57], v[200:201]
	v_add_f32_e32 v9, v198, v199
	v_add_f32_e32 v90, v200, v201
	s_nop 1
	v_add_f32_dpp v9, v9, v9 quad_perm:[1,0,3,2] row_mask:0xf bank_mask:0xf
	v_add_f32_dpp v90, v90, v90 quad_perm:[1,0,3,2] row_mask:0xf bank_mask:0xf
	s_nop 0
	v_add_f32_dpp v9, v9, v9 quad_perm:[2,3,0,1] row_mask:0xf bank_mask:0xf
	v_add_f32_dpp v90, v90, v90 quad_perm:[2,3,0,1] row_mask:0xf bank_mask:0xf
	s_nop 0
	v_add_f32_dpp v9, v9, v9 row_half_mirror row_mask:0xf bank_mask:0xf
	v_add_f32_dpp v90, v90, v90 row_half_mirror row_mask:0xf bank_mask:0xf
	s_nop 0
	v_add_f32_dpp v9, v9, v9 row_mirror row_mask:0xf bank_mask:0xf
	v_add_f32_dpp v90, v90, v90 row_mirror row_mask:0xf bank_mask:0xf
	s_nop 0
	v_add_f32_dpp v9, v9, v9 row_bcast:15 row_mask:0xa bank_mask:0xf
	v_add_f32_dpp v90, v90, v90 row_bcast:15 row_mask:0xa bank_mask:0xf
	s_nop 0
	v_add_f32_dpp v9, v9, v9 row_bcast:31 row_mask:0xc bank_mask:0xf
	v_add_f32_dpp v90, v90, v90 row_bcast:31 row_mask:0xc bank_mask:0xf
	s_nop 0
	v_readlane_b32 s2, v9, 63
	v_readlane_b32 s3, v90, 63
	s_nop 1
	v_mov_b32_e32 v9, s2
	v_mov_b32_e32 v90, s3
	v_mul_f32_e32 v93, 0x3a800000, v9
	v_mul_f32_e32 v91, 0x3a800000, v90
	v_fma_f32 v91, -v93, v93, v91
	v_max_f32_e32 v91, 0, v91
	v_add_f32_e32 v91, 0x358637bd, v91
	v_rsq_f32_e32 v94, v91
	v_mul_f32_e32 v91, 0.5, v91
	v_mul_f32_e32 v92, v94, v94
	v_fma_f32 v92, -v91, v92, 0.5
	v_fma_f32 v94, v94, v92, v94
	s_waitcnt vmcnt(20)
; DI unsigned pk2(float lo, float hi) { f32x2 v = {lo, hi}; bf16x2_t b = __builtin_convertvector(v, bf16x2_t); return __builtin_bit_cast(unsigned, b); }
; DI void ln_row_v(const Frame& F, f32x4 (&v)[4], float* xout, const float* g, const float* b, const float* sh, const float* sc, bf16_t* hout, const float* slab, const float* gres, float* stat = nullptr) {
;     ...
;         float s = 0.f, s2 = 0.f;
; #pragma unroll
;         for (int j = 0; j < 4; ++j) { s += (v[j][0] + v[j][1]) + (v[j][2] + v[j][3]); s2 += (v[j][0] * v[j][0] + v[j][1] * v[j][1]) + (v[j][2] * v[j][2] + v[j][3] * v[j][3]); }
;         wave_sum2(s, s2, F.lane);
;         const float mean = s * (1.f / D); const float rstd = 1.f / sqrtf(fmaxf(s2 * (1.f / D) - mean * mean, 0.f) + EPS);
; #pragma unroll
;         for (int j = 0; j < 4; ++j) { const f32x4 hh = ((const f32x4*)sh)[F.lane + 64 * j], cc = ((const f32x4*)sc)[F.lane + 64 * j];
;             const f32x4 o = (v[j] - mean) * rstd * (cc + 1.f) + hh; u32x2 wv; wv.x = pk2(o[0], o[1]); wv.y = pk2(o[2], o[3]);
;             ((u32x2*)hout)[F.lane + 64 * j] = wv; }
	v_pk_add_f32 v[42:43], v[42:43], v[92:93] op_sel:[0,1] op_sel_hi:[1,1] neg_lo:[0,1] neg_hi:[0,1]
	v_pk_add_f32 v[44:45], v[44:45], v[92:93] op_sel:[0,1] op_sel_hi:[1,1] neg_lo:[0,1] neg_hi:[0,1]
	v_pk_add_f32 v[46:47], v[46:47], v[92:93] op_sel:[0,1] op_sel_hi:[1,1] neg_lo:[0,1] neg_hi:[0,1]
	v_pk_add_f32 v[48:49], v[48:49], v[92:93] op_sel:[0,1] op_sel_hi:[1,1] neg_lo:[0,1] neg_hi:[0,1]
	v_pk_add_f32 v[50:51], v[50:51], v[92:93] op_sel:[0,1] op_sel_hi:[1,1] neg_lo:[0,1] neg_hi:[0,1]
	v_pk_add_f32 v[52:53], v[52:53], v[92:93] op_sel:[0,1] op_sel_hi:[1,1] neg_lo:[0,1] neg_hi:[0,1]
	v_pk_add_f32 v[54:55], v[54:55], v[92:93] op_sel:[0,1] op_sel_hi:[1,1] neg_lo:[0,1] neg_hi:[0,1]
	v_pk_add_f32 v[56:57], v[56:57], v[92:93] op_sel:[0,1] op_sel_hi:[1,1] neg_lo:[0,1] neg_hi:[0,1]
	v_add_f32_e32 v130, 1.0, v130
	v_add_f32_e32 v131, 1.0, v131
	v_add_f32_e32 v132, 1.0, v132
	v_add_f32_e32 v133, 1.0, v133
	v_add_f32_e32 v134, 1.0, v134
	v_add_f32_e32 v135, 1.0, v135
	v_add_f32_e32 v136, 1.0, v136
	v_add_f32_e32 v137, 1.0, v137
	v_add_f32_e32 v138, 1.0, v138
	v_add_f32_e32 v139, 1.0, v139
	v_add_f32_e32 v140, 1.0, v140
	v_add_f32_e32 v141, 1.0, v141
	v_add_f32_e32 v142, 1.0, v142
	v_add_f32_e32 v143, 1.0, v143
	v_add_f32_e32 v144, 1.0, v144
	v_add_f32_e32 v145, 1.0, v145
	v_pk_mul_f32 v[42:43], v[42:43], v[94:95] op_sel_hi:[1,0]
	v_pk_mul_f32 v[44:45], v[44:45], v[94:95] op_sel_hi:[1,0]
	v_pk_mul_f32 v[46:47], v[46:47], v[94:95] op_sel_hi:[1,0]
	v_pk_mul_f32 v[48:49], v[48:49], v[94:95] op_sel_hi:[1,0]
	v_pk_mul_f32 v[50:51], v[50:51], v[94:95] op_sel_hi:[1,0]
	v_pk_mul_f32 v[52:53], v[52:53], v[94:95] op_sel_hi:[1,0]
	v_pk_mul_f32 v[54:55], v[54:55], v[94:95] op_sel_hi:[1,0]
	v_pk_mul_f32 v[56:57], v[56:57], v[94:95] op_sel_hi:[1,0]
	v_pk_fma_f32 v[42:43], v[42:43], v[130:131], v[114:115]
	v_pk_fma_f32 v[44:45], v[44:45], v[132:133], v[116:117]
	v_pk_fma_f32 v[46:47], v[46:47], v[134:135], v[118:119]
	v_pk_fma_f32 v[48:49], v[48:49], v[136:137], v[120:121]
	v_pk_fma_f32 v[50:51], v[50:51], v[138:139], v[122:123]
	v_pk_fma_f32 v[52:53], v[52:53], v[140:141], v[124:125]
	v_pk_fma_f32 v[54:55], v[54:55], v[142:143], v[126:127]
	v_pk_fma_f32 v[56:57], v[56:57], v[144:145], v[128:129]
	v_cvt_pk_bf16_f32 v190, v42, v43
	v_cvt_pk_bf16_f32 v191, v44, v45
	v_cvt_pk_bf16_f32 v192, v46, v47
	v_cvt_pk_bf16_f32 v193, v48, v49
	v_cvt_pk_bf16_f32 v194, v50, v51
	v_cvt_pk_bf16_f32 v195, v52, v53
	v_cvt_pk_bf16_f32 v196, v54, v55
	v_cvt_pk_bf16_f32 v197, v56, v57
	s_add_u32 s2, s10, 0x0
	s_addc_u32 s3, s11, 0
	global_store_dwordx2 v1, v[190:191], s[2:3]
	global_store_dwordx2 v1, v[192:193], s[2:3] offset:512
	global_store_dwordx2 v1, v[194:195], s[2:3] offset:1024
	global_store_dwordx2 v1, v[196:197], s[2:3] offset:1536
	s_add_u32 s2, s8, 0x4000
	s_addc_u32 s3, s9, 0
	global_load_dwordx4 v[42:45], v0, s[2:3]
	global_load_dwordx4 v[46:49], v0, s[2:3] offset:1024
	global_load_dwordx4 v[50:53], v0, s[2:3] offset:2048
	global_load_dwordx4 v[54:57], v0, s[2:3] offset:3072
	s_waitcnt vmcnt(24)
	v_pk_add_f32 v[198:199], v[58:59], v[60:61]
	v_pk_mul_f32 v[200:201], v[58:59], v[58:59]
	v_pk_fma_f32 v[200:201], v[60:61], v[60:61], v[200:201]
	v_pk_add_f32 v[198:199], v[198:199], v[62:63]
	v_pk_fma_f32 v[200:201], v[62:63], v[62:63], v[200:201]
	v_pk_add_f32 v[198:199], v[198:199], v[64:65]
	v_pk_fma_f32 v[200:201], v[64:65], v[64:65], v[200:201]
	v_pk_add_f32 v[198:199], v[198:199], v[66:67]
	v_pk_fma_f32 v[200:201], v[66:67], v[66:67], v[200:201]
	v_pk_add_f32 v[198:199], v[198:199], v[68:69]
	v_pk_fma_f32 v[200:201], v[68:69], v[68:69], v[200:201]
	v_pk_add_f32 v[198:199], v[198:199], v[70:71]
	v_pk_fma_f32 v[200:201], v[70:71], v[70:71], v[200:201]
	v_pk_add_f32 v[198:199], v[198:199], v[72:73]
	v_pk_fma_f32 v[200:201], v[72:73], v[72:73], v[200:201]
	v_add_f32_e32 v9, v198, v199
	v_add_f32_e32 v90, v200, v201
	s_nop 1
	v_add_f32_dpp v9, v9, v9 quad_perm:[1,0,3,2] row_mask:0xf bank_mask:0xf
	v_add_f32_dpp v90, v90, v90 quad_perm:[1,0,3,2] row_mask:0xf bank_mask:0xf
	s_nop 0
	v_add_f32_dpp v9, v9, v9 quad_perm:[2,3,0,1] row_mask:0xf bank_mask:0xf
	v_add_f32_dpp v90, v90, v90 quad_perm:[2,3,0,1] row_mask:0xf bank_mask:0xf
	s_nop 0
	v_add_f32_dpp v9, v9, v9 row_half_mirror row_mask:0xf bank_mask:0xf
	v_add_f32_dpp v90, v90, v90 row_half_mirror row_mask:0xf bank_mask:0xf
	s_nop 0
	v_add_f32_dpp v9, v9, v9 row_mirror row_mask:0xf bank_mask:0xf
	v_add_f32_dpp v90, v90, v90 row_mirror row_mask:0xf bank_mask:0xf
	s_nop 0
	v_add_f32_dpp v9, v9, v9 row_bcast:15 row_mask:0xa bank_mask:0xf
	v_add_f32_dpp v90, v90, v90 row_bcast:15 row_mask:0xa bank_mask:0xf
	s_nop 0
	v_add_f32_dpp v9, v9, v9 row_bcast:31 row_mask:0xc bank_mask:0xf
	v_add_f32_dpp v90, v90, v90 row_bcast:31 row_mask:0xc bank_mask:0xf
	s_nop 0
	v_readlane_b32 s2, v9, 63
	v_readlane_b32 s3, v90, 63
	s_nop 1
	v_mov_b32_e32 v9, s2
	v_mov_b32_e32 v90, s3
	v_mul_f32_e32 v93, 0x3a800000, v9
	v_mul_f32_e32 v91, 0x3a800000, v90
	v_fma_f32 v91, -v93, v93, v91
	v_max_f32_e32 v91, 0, v91
	v_add_f32_e32 v91, 0x358637bd, v91
	v_rsq_f32_e32 v94, v91
	v_mul_f32_e32 v91, 0.5, v91
	v_mul_f32_e32 v92, v94, v94
	v_fma_f32 v92, -v91, v92, 0.5
	v_fma_f32 v94, v94, v92, v94
	v_pk_add_f32 v[58:59], v[58:59], v[92:93] op_sel:[0,1] op_sel_hi:[1,1] neg_lo:[0,1] neg_hi:[0,1]
	v_pk_add_f32 v[60:61], v[60:61], v[92:93] op_sel:[0,1] op_sel_hi:[1,1] neg_lo:[0,1] neg_hi:[0,1]
	v_pk_add_f32 v[62:63], v[62:63], v[92:93] op_sel:[0,1] op_sel_hi:[1,1] neg_lo:[0,1] neg_hi:[0,1]
	v_pk_add_f32 v[64:65], v[64:65], v[92:93] op_sel:[0,1] op_sel_hi:[1,1] neg_lo:[0,1] neg_hi:[0,1]
	v_pk_add_f32 v[66:67], v[66:67], v[92:93] op_sel:[0,1] op_sel_hi:[1,1] neg_lo:[0,1] neg_hi:[0,1]
; DI unsigned pk2(float lo, float hi) { f32x2 v = {lo, hi}; bf16x2_t b = __builtin_convertvector(v, bf16x2_t); return __builtin_bit_cast(unsigned, b); }
; DI void ln_row_v(const Frame& F, f32x4 (&v)[4], float* xout, const float* g, const float* b, const float* sh, const float* sc, bf16_t* hout, const float* slab, const float* gres, float* stat = nullptr) {
;     ...
;         float s = 0.f, s2 = 0.f;
; #pragma unroll
;         for (int j = 0; j < 4; ++j) { s += (v[j][0] + v[j][1]) + (v[j][2] + v[j][3]); s2 += (v[j][0] * v[j][0] + v[j][1] * v[j][1]) + (v[j][2] * v[j][2] + v[j][3] * v[j][3]); }
;         wave_sum2(s, s2, F.lane);
;         const float mean = s * (1.f / D); const float rstd = 1.f / sqrtf(fmaxf(s2 * (1.f / D) - mean * mean, 0.f) + EPS);
; #pragma unroll
;         for (int j = 0; j < 4; ++j) { const f32x4 hh = ((const f32x4*)sh)[F.lane + 64 * j], cc = ((const f32x4*)sc)[F.lane + 64 * j];
;             const f32x4 o = (v[j] - mean) * rstd * (cc + 1.f) + hh; u32x2 wv; wv.x = pk2(o[0], o[1]); wv.y = pk2(o[2], o[3]);
;             ((u32x2*)hout)[F.lane + 64 * j] = wv; }
	v_pk_add_f32 v[68:69], v[68:69], v[92:93] op_sel:[0,1] op_sel_hi:[1,1] neg_lo:[0,1] neg_hi:[0,1]
	v_pk_add_f32 v[70:71], v[70:71], v[92:93] op_sel:[0,1] op_sel_hi:[1,1] neg_lo:[0,1] neg_hi:[0,1]
	v_pk_add_f32 v[72:73], v[72:73], v[92:93] op_sel:[0,1] op_sel_hi:[1,1] neg_lo:[0,1] neg_hi:[0,1]
	v_pk_mul_f32 v[58:59], v[58:59], v[94:95] op_sel_hi:[1,0]
	v_pk_mul_f32 v[60:61], v[60:61], v[94:95] op_sel_hi:[1,0]
	v_pk_mul_f32 v[62:63], v[62:63], v[94:95] op_sel_hi:[1,0]
	v_pk_mul_f32 v[64:65], v[64:65], v[94:95] op_sel_hi:[1,0]
	v_pk_mul_f32 v[66:67], v[66:67], v[94:95] op_sel_hi:[1,0]
	v_pk_mul_f32 v[68:69], v[68:69], v[94:95] op_sel_hi:[1,0]
	v_pk_mul_f32 v[70:71], v[70:71], v[94:95] op_sel_hi:[1,0]
	v_pk_mul_f32 v[72:73], v[72:73], v[94:95] op_sel_hi:[1,0]
	v_pk_fma_f32 v[58:59], v[58:59], v[130:131], v[114:115]
	v_pk_fma_f32 v[60:61], v[60:61], v[132:133], v[116:117]
	v_pk_fma_f32 v[62:63], v[62:63], v[134:135], v[118:119]
	v_pk_fma_f32 v[64:65], v[64:65], v[136:137], v[120:121]
	v_pk_fma_f32 v[66:67], v[66:67], v[138:139], v[122:123]
	v_pk_fma_f32 v[68:69], v[68:69], v[140:141], v[124:125]
	v_pk_fma_f32 v[70:71], v[70:71], v[142:143], v[126:127]
	v_pk_fma_f32 v[72:73], v[72:73], v[144:145], v[128:129]
	v_cvt_pk_bf16_f32 v190, v58, v59
	v_cvt_pk_bf16_f32 v191, v60, v61
	v_cvt_pk_bf16_f32 v192, v62, v63
	v_cvt_pk_bf16_f32 v193, v64, v65
	v_cvt_pk_bf16_f32 v194, v66, v67
	v_cvt_pk_bf16_f32 v195, v68, v69
	v_cvt_pk_bf16_f32 v196, v70, v71
	v_cvt_pk_bf16_f32 v197, v72, v73
	s_add_u32 s2, s10, 0x800
	s_addc_u32 s3, s11, 0
	global_store_dwordx2 v1, v[190:191], s[2:3]
	global_store_dwordx2 v1, v[192:193], s[2:3] offset:512
	global_store_dwordx2 v1, v[194:195], s[2:3] offset:1024
	global_store_dwordx2 v1, v[196:197], s[2:3] offset:1536
	s_add_u32 s2, s8, 0x5000
	s_addc_u32 s3, s9, 0
	global_load_dwordx4 v[58:61], v0, s[2:3]
	global_load_dwordx4 v[62:65], v0, s[2:3] offset:1024
	global_load_dwordx4 v[66:69], v0, s[2:3] offset:2048
	global_load_dwordx4 v[70:73], v0, s[2:3] offset:3072
	s_waitcnt vmcnt(20)
	v_pk_add_f32 v[198:199], v[74:75], v[76:77]
	v_pk_mul_f32 v[200:201], v[74:75], v[74:75]
	v_pk_fma_f32 v[200:201], v[76:77], v[76:77], v[200:201]
	v_pk_add_f32 v[198:199], v[198:199], v[78:79]
	v_pk_fma_f32 v[200:201], v[78:79], v[78:79], v[200:201]
	v_pk_add_f32 v[198:199], v[198:199], v[80:81]
	v_pk_fma_f32 v[200:201], v[80:81], v[80:81], v[200:201]
	v_pk_add_f32 v[198:199], v[198:199], v[82:83]
	v_pk_fma_f32 v[200:201], v[82:83], v[82:83], v[200:201]
	v_pk_add_f32 v[198:199], v[198:199], v[84:85]
	v_pk_fma_f32 v[200:201], v[84:85], v[84:85], v[200:201]
	v_pk_add_f32 v[198:199], v[198:199], v[86:87]
	v_pk_fma_f32 v[200:201], v[86:87], v[86:87], v[200:201]
	v_pk_add_f32 v[198:199], v[198:199], v[88:89]
	v_pk_fma_f32 v[200:201], v[88:89], v[88:89], v[200:201]
	v_add_f32_e32 v9, v198, v199
	v_add_f32_e32 v90, v200, v201
	s_nop 1
	v_add_f32_dpp v9, v9, v9 quad_perm:[1,0,3,2] row_mask:0xf bank_mask:0xf
	v_add_f32_dpp v90, v90, v90 quad_perm:[1,0,3,2] row_mask:0xf bank_mask:0xf
	s_nop 0
	v_add_f32_dpp v9, v9, v9 quad_perm:[2,3,0,1] row_mask:0xf bank_mask:0xf
	v_add_f32_dpp v90, v90, v90 quad_perm:[2,3,0,1] row_mask:0xf bank_mask:0xf
	s_nop 0
	v_add_f32_dpp v9, v9, v9 row_half_mirror row_mask:0xf bank_mask:0xf
	v_add_f32_dpp v90, v90, v90 row_half_mirror row_mask:0xf bank_mask:0xf
	s_nop 0
	v_add_f32_dpp v9, v9, v9 row_mirror row_mask:0xf bank_mask:0xf
	v_add_f32_dpp v90, v90, v90 row_mirror row_mask:0xf bank_mask:0xf
	s_nop 0
	v_add_f32_dpp v9, v9, v9 row_bcast:15 row_mask:0xa bank_mask:0xf
	v_add_f32_dpp v90, v90, v90 row_bcast:15 row_mask:0xa bank_mask:0xf
	s_nop 0
	v_add_f32_dpp v9, v9, v9 row_bcast:31 row_mask:0xc bank_mask:0xf
	v_add_f32_dpp v90, v90, v90 row_bcast:31 row_mask:0xc bank_mask:0xf
	s_nop 0
	v_readlane_b32 s2, v9, 63
	v_readlane_b32 s3, v90, 63
	s_nop 1
	v_mov_b32_e32 v9, s2
	v_mov_b32_e32 v90, s3
	v_mul_f32_e32 v93, 0x3a800000, v9
	v_mul_f32_e32 v91, 0x3a800000, v90
	v_fma_f32 v91, -v93, v93, v91
	v_max_f32_e32 v91, 0, v91
	v_add_f32_e32 v91, 0x358637bd, v91
	v_rsq_f32_e32 v94, v91
	v_mul_f32_e32 v91, 0.5, v91
	v_mul_f32_e32 v92, v94, v94
	v_fma_f32 v92, -v91, v92, 0.5
	v_fma_f32 v94, v94, v92, v94
	v_pk_add_f32 v[74:75], v[74:75], v[92:93] op_sel:[0,1] op_sel_hi:[1,1] neg_lo:[0,1] neg_hi:[0,1]
	v_pk_add_f32 v[76:77], v[76:77], v[92:93] op_sel:[0,1] op_sel_hi:[1,1] neg_lo:[0,1] neg_hi:[0,1]
	v_pk_add_f32 v[78:79], v[78:79], v[92:93] op_sel:[0,1] op_sel_hi:[1,1] neg_lo:[0,1] neg_hi:[0,1]
	v_pk_add_f32 v[80:81], v[80:81], v[92:93] op_sel:[0,1] op_sel_hi:[1,1] neg_lo:[0,1] neg_hi:[0,1]
	v_pk_add_f32 v[82:83], v[82:83], v[92:93] op_sel:[0,1] op_sel_hi:[1,1] neg_lo:[0,1] neg_hi:[0,1]
	v_pk_add_f32 v[84:85], v[84:85], v[92:93] op_sel:[0,1] op_sel_hi:[1,1] neg_lo:[0,1] neg_hi:[0,1]
	v_pk_add_f32 v[86:87], v[86:87], v[92:93] op_sel:[0,1] op_sel_hi:[1,1] neg_lo:[0,1] neg_hi:[0,1]
	v_pk_add_f32 v[88:89], v[88:89], v[92:93] op_sel:[0,1] op_sel_hi:[1,1] neg_lo:[0,1] neg_hi:[0,1]
	v_pk_mul_f32 v[74:75], v[74:75], v[94:95] op_sel_hi:[1,0]
	v_pk_mul_f32 v[76:77], v[76:77], v[94:95] op_sel_hi:[1,0]
	v_pk_mul_f32 v[78:79], v[78:79], v[94:95] op_sel_hi:[1,0]
	v_pk_mul_f32 v[80:81], v[80:81], v[94:95] op_sel_hi:[1,0]
	v_pk_mul_f32 v[82:83], v[82:83], v[94:95] op_sel_hi:[1,0]
	v_pk_mul_f32 v[84:85], v[84:85], v[94:95] op_sel_hi:[1,0]
	v_pk_mul_f32 v[86:87], v[86:87], v[94:95] op_sel_hi:[1,0]
	v_pk_mul_f32 v[88:89], v[88:89], v[94:95] op_sel_hi:[1,0]
	v_pk_fma_f32 v[74:75], v[74:75], v[130:131], v[114:115]
	v_pk_fma_f32 v[76:77], v[76:77], v[132:133], v[116:117]
	v_pk_fma_f32 v[78:79], v[78:79], v[134:135], v[118:119]
	v_pk_fma_f32 v[80:81], v[80:81], v[136:137], v[120:121]
	v_pk_fma_f32 v[82:83], v[82:83], v[138:139], v[122:123]
	v_pk_fma_f32 v[84:85], v[84:85], v[140:141], v[124:125]
	v_pk_fma_f32 v[86:87], v[86:87], v[142:143], v[126:127]
	v_pk_fma_f32 v[88:89], v[88:89], v[144:145], v[128:129]
	v_cvt_pk_bf16_f32 v190, v74, v75
	v_cvt_pk_bf16_f32 v191, v76, v77
	v_cvt_pk_bf16_f32 v192, v78, v79
	v_cvt_pk_bf16_f32 v193, v80, v81
	v_cvt_pk_bf16_f32 v194, v82, v83
	v_cvt_pk_bf16_f32 v195, v84, v85
	v_cvt_pk_bf16_f32 v196, v86, v87
	v_cvt_pk_bf16_f32 v197, v88, v89
	s_add_u32 s2, s10, 0x1000
	s_addc_u32 s3, s11, 0
	global_store_dwordx2 v1, v[190:191], s[2:3]
	global_store_dwordx2 v1, v[192:193], s[2:3] offset:512
	global_store_dwordx2 v1, v[194:195], s[2:3] offset:1024
	global_store_dwordx2 v1, v[196:197], s[2:3] offset:1536
	s_add_u32 s2, s8, 0x6000
	s_addc_u32 s3, s9, 0
	global_load_dwordx4 v[74:77], v0, s[2:3]
	global_load_dwordx4 v[78:81], v0, s[2:3] offset:1024
	global_load_dwordx4 v[82:85], v0, s[2:3] offset:2048
	global_load_dwordx4 v[86:89], v0, s[2:3] offset:3072
	s_waitcnt vmcnt(24)
; DI unsigned pk2(float lo, float hi) { f32x2 v = {lo, hi}; bf16x2_t b = __builtin_convertvector(v, bf16x2_t); return __builtin_bit_cast(unsigned, b); }
; DI void ln_row_v(const Frame& F, f32x4 (&v)[4], float* xout, const float* g, const float* b, const float* sh, const float* sc, bf16_t* hout, const float* slab, const float* gres, float* stat = nullptr) {
;     ...
;         float s = 0.f, s2 = 0.f;
; #pragma unroll
;         for (int j = 0; j < 4; ++j) { s += (v[j][0] + v[j][1]) + (v[j][2] + v[j][3]); s2 += (v[j][0] * v[j][0] + v[j][1] * v[j][1]) + (v[j][2] * v[j][2] + v[j][3] * v[j][3]); }
;         wave_sum2(s, s2, F.lane);
;         const float mean = s * (1.f / D); const float rstd = 1.f / sqrtf(fmaxf(s2 * (1.f / D) - mean * mean, 0.f) + EPS);
; #pragma unroll
;         for (int j = 0; j < 4; ++j) { const f32x4 hh = ((const f32x4*)sh)[F.lane + 64 * j], cc = ((const f32x4*)sc)[F.lane + 64 * j];
;             const f32x4 o = (v[j] - mean) * rstd * (cc + 1.f) + hh; u32x2 wv; wv.x = pk2(o[0], o[1]); wv.y = pk2(o[2], o[3]);
;             ((u32x2*)hout)[F.lane + 64 * j] = wv; }
	v_pk_add_f32 v[198:199], v[98:99], v[100:101]
	v_pk_mul_f32 v[200:201], v[98:99], v[98:99]
	v_pk_fma_f32 v[200:201], v[100:101], v[100:101], v[200:201]
	v_pk_add_f32 v[198:199], v[198:199], v[102:103]
	v_pk_fma_f32 v[200:201], v[102:103], v[102:103], v[200:201]
	v_pk_add_f32 v[198:199], v[198:199], v[104:105]
	v_pk_fma_f32 v[200:201], v[104:105], v[104:105], v[200:201]
	v_pk_add_f32 v[198:199], v[198:199], v[106:107]
	v_pk_fma_f32 v[200:201], v[106:107], v[106:107], v[200:201]
	v_pk_add_f32 v[198:199], v[198:199], v[108:109]
	v_pk_fma_f32 v[200:201], v[108:109], v[108:109], v[200:201]
	v_pk_add_f32 v[198:199], v[198:199], v[110:111]
	v_pk_fma_f32 v[200:201], v[110:111], v[110:111], v[200:201]
	v_pk_add_f32 v[198:199], v[198:199], v[112:113]
	v_pk_fma_f32 v[200:201], v[112:113], v[112:113], v[200:201]
	v_add_f32_e32 v9, v198, v199
	v_add_f32_e32 v90, v200, v201
	s_nop 1
	v_add_f32_dpp v9, v9, v9 quad_perm:[1,0,3,2] row_mask:0xf bank_mask:0xf
	v_add_f32_dpp v90, v90, v90 quad_perm:[1,0,3,2] row_mask:0xf bank_mask:0xf
	s_nop 0
	v_add_f32_dpp v9, v9, v9 quad_perm:[2,3,0,1] row_mask:0xf bank_mask:0xf
	v_add_f32_dpp v90, v90, v90 quad_perm:[2,3,0,1] row_mask:0xf bank_mask:0xf
	s_nop 0
	v_add_f32_dpp v9, v9, v9 row_half_mirror row_mask:0xf bank_mask:0xf
	v_add_f32_dpp v90, v90, v90 row_half_mirror row_mask:0xf bank_mask:0xf
	s_nop 0
	v_add_f32_dpp v9, v9, v9 row_mirror row_mask:0xf bank_mask:0xf
	v_add_f32_dpp v90, v90, v90 row_mirror row_mask:0xf bank_mask:0xf
	s_nop 0
	v_add_f32_dpp v9, v9, v9 row_bcast:15 row_mask:0xa bank_mask:0xf
	v_add_f32_dpp v90, v90, v90 row_bcast:15 row_mask:0xa bank_mask:0xf
	s_nop 0
	v_add_f32_dpp v9, v9, v9 row_bcast:31 row_mask:0xc bank_mask:0xf
	v_add_f32_dpp v90, v90, v90 row_bcast:31 row_mask:0xc bank_mask:0xf
	s_nop 0
	v_readlane_b32 s2, v9, 63
	v_readlane_b32 s3, v90, 63
	s_nop 1
	v_mov_b32_e32 v9, s2
	v_mov_b32_e32 v90, s3
	v_mul_f32_e32 v93, 0x3a800000, v9
	v_mul_f32_e32 v91, 0x3a800000, v90
	v_fma_f32 v91, -v93, v93, v91
	v_max_f32_e32 v91, 0, v91
	v_add_f32_e32 v91, 0x358637bd, v91
	v_rsq_f32_e32 v94, v91
	v_mul_f32_e32 v91, 0.5, v91
	v_mul_f32_e32 v92, v94, v94
	v_fma_f32 v92, -v91, v92, 0.5
	v_fma_f32 v94, v94, v92, v94
	v_pk_add_f32 v[98:99], v[98:99], v[92:93] op_sel:[0,1] op_sel_hi:[1,1] neg_lo:[0,1] neg_hi:[0,1]
	v_pk_add_f32 v[100:101], v[100:101], v[92:93] op_sel:[0,1] op_sel_hi:[1,1] neg_lo:[0,1] neg_hi:[0,1]
	v_pk_add_f32 v[102:103], v[102:103], v[92:93] op_sel:[0,1] op_sel_hi:[1,1] neg_lo:[0,1] neg_hi:[0,1]
	v_pk_add_f32 v[104:105], v[104:105], v[92:93] op_sel:[0,1] op_sel_hi:[1,1] neg_lo:[0,1] neg_hi:[0,1]
	v_pk_add_f32 v[106:107], v[106:107], v[92:93] op_sel:[0,1] op_sel_hi:[1,1] neg_lo:[0,1] neg_hi:[0,1]
	v_pk_add_f32 v[108:109], v[108:109], v[92:93] op_sel:[0,1] op_sel_hi:[1,1] neg_lo:[0,1] neg_hi:[0,1]
	v_pk_add_f32 v[110:111], v[110:111], v[92:93] op_sel:[0,1] op_sel_hi:[1,1] neg_lo:[0,1] neg_hi:[0,1]
	v_pk_add_f32 v[112:113], v[112:113], v[92:93] op_sel:[0,1] op_sel_hi:[1,1] neg_lo:[0,1] neg_hi:[0,1]
	v_pk_mul_f32 v[98:99], v[98:99], v[94:95] op_sel_hi:[1,0]
	v_pk_mul_f32 v[100:101], v[100:101], v[94:95] op_sel_hi:[1,0]
	v_pk_mul_f32 v[102:103], v[102:103], v[94:95] op_sel_hi:[1,0]
	v_pk_mul_f32 v[104:105], v[104:105], v[94:95] op_sel_hi:[1,0]
	v_pk_mul_f32 v[106:107], v[106:107], v[94:95] op_sel_hi:[1,0]
	v_pk_mul_f32 v[108:109], v[108:109], v[94:95] op_sel_hi:[1,0]
	v_pk_mul_f32 v[110:111], v[110:111], v[94:95] op_sel_hi:[1,0]
	v_pk_mul_f32 v[112:113], v[112:113], v[94:95] op_sel_hi:[1,0]
	v_pk_fma_f32 v[98:99], v[98:99], v[130:131], v[114:115]
	v_pk_fma_f32 v[100:101], v[100:101], v[132:133], v[116:117]
	v_pk_fma_f32 v[102:103], v[102:103], v[134:135], v[118:119]
	v_pk_fma_f32 v[104:105], v[104:105], v[136:137], v[120:121]
	v_pk_fma_f32 v[106:107], v[106:107], v[138:139], v[122:123]
	v_pk_fma_f32 v[108:109], v[108:109], v[140:141], v[124:125]
	v_pk_fma_f32 v[110:111], v[110:111], v[142:143], v[126:127]
	v_pk_fma_f32 v[112:113], v[112:113], v[144:145], v[128:129]
	v_cvt_pk_bf16_f32 v190, v98, v99
	v_cvt_pk_bf16_f32 v191, v100, v101
	v_cvt_pk_bf16_f32 v192, v102, v103
	v_cvt_pk_bf16_f32 v193, v104, v105
	v_cvt_pk_bf16_f32 v194, v106, v107
	v_cvt_pk_bf16_f32 v195, v108, v109
	v_cvt_pk_bf16_f32 v196, v110, v111
	v_cvt_pk_bf16_f32 v197, v112, v113
	s_add_u32 s2, s10, 0x1800
	s_addc_u32 s3, s11, 0
	global_store_dwordx2 v1, v[190:191], s[2:3]
	global_store_dwordx2 v1, v[192:193], s[2:3] offset:512
	global_store_dwordx2 v1, v[194:195], s[2:3] offset:1024
	global_store_dwordx2 v1, v[196:197], s[2:3] offset:1536
	s_add_u32 s2, s8, 0x7000
	s_addc_u32 s3, s9, 0
	global_load_dwordx4 v[98:101], v0, s[2:3]
	global_load_dwordx4 v[102:105], v0, s[2:3] offset:1024
	global_load_dwordx4 v[106:109], v0, s[2:3] offset:2048
	global_load_dwordx4 v[110:113], v0, s[2:3] offset:3072
	s_waitcnt vmcnt(24)
; DI unsigned pk2(float lo, float hi) { f32x2 v = {lo, hi}; bf16x2_t b = __builtin_convertvector(v, bf16x2_t); return __builtin_bit_cast(unsigned, b); }
; DI void ln_row_v(const Frame& F, f32x4 (&v)[4], float* xout, const float* g, const float* b, const float* sh, const float* sc, bf16_t* hout, const float* slab, const float* gres, float* stat = nullptr) {
;     ...
;         float s = 0.f, s2 = 0.f;
; #pragma unroll
;         for (int j = 0; j < 4; ++j) { s += (v[j][0] + v[j][1]) + (v[j][2] + v[j][3]); s2 += (v[j][0] * v[j][0] + v[j][1] * v[j][1]) + (v[j][2] * v[j][2] + v[j][3] * v[j][3]); }
;         wave_sum2(s, s2, F.lane);
;         const float mean = s * (1.f / D); const float rstd = 1.f / sqrtf(fmaxf(s2 * (1.f / D) - mean * mean, 0.f) + EPS);
; #pragma unroll
;         for (int j = 0; j < 4; ++j) { const f32x4 hh = ((const f32x4*)sh)[F.lane + 64 * j], cc = ((const f32x4*)sc)[F.lane + 64 * j];
;             const f32x4 o = (v[j] - mean) * rstd * (cc + 1.f) + hh; u32x2 wv; wv.x = pk2(o[0], o[1]); wv.y = pk2(o[2], o[3]);
;             ((u32x2*)hout)[F.lane + 64 * j] = wv; }
	v_pk_add_f32 v[198:199], v[42:43], v[44:45]
	v_pk_mul_f32 v[200:201], v[42:43], v[42:43]
	v_pk_fma_f32 v[200:201], v[44:45], v[44:45], v[200:201]
	v_pk_add_f32 v[198:199], v[198:199], v[46:47]
	v_pk_fma_f32 v[200:201], v[46:47], v[46:47], v[200:201]
	v_pk_add_f32 v[198:199], v[198:199], v[48:49]
	v_pk_fma_f32 v[200:201], v[48:49], v[48:49], v[200:201]
	v_pk_add_f32 v[198:199], v[198:199], v[50:51]
	v_pk_fma_f32 v[200:201], v[50:51], v[50:51], v[200:201]
	v_pk_add_f32 v[198:199], v[198:199], v[52:53]
	v_pk_fma_f32 v[200:201], v[52:53], v[52:53], v[200:201]
	v_pk_add_f32 v[198:199], v[198:199], v[54:55]
	v_pk_fma_f32 v[200:201], v[54:55], v[54:55], v[200:201]
	v_pk_add_f32 v[198:199], v[198:199], v[56:57]
	v_pk_fma_f32 v[200:201], v[56:57], v[56:57], v[200:201]
	v_add_f32_e32 v9, v198, v199
	v_add_f32_e32 v90, v200, v201
	s_nop 1
	v_add_f32_dpp v9, v9, v9 quad_perm:[1,0,3,2] row_mask:0xf bank_mask:0xf
	v_add_f32_dpp v90, v90, v90 quad_perm:[1,0,3,2] row_mask:0xf bank_mask:0xf
	s_nop 0
	v_add_f32_dpp v9, v9, v9 quad_perm:[2,3,0,1] row_mask:0xf bank_mask:0xf
	v_add_f32_dpp v90, v90, v90 quad_perm:[2,3,0,1] row_mask:0xf bank_mask:0xf
	s_nop 0
	v_add_f32_dpp v9, v9, v9 row_half_mirror row_mask:0xf bank_mask:0xf
	v_add_f32_dpp v90, v90, v90 row_half_mirror row_mask:0xf bank_mask:0xf
	s_nop 0
	v_add_f32_dpp v9, v9, v9 row_mirror row_mask:0xf bank_mask:0xf
	v_add_f32_dpp v90, v90, v90 row_mirror row_mask:0xf bank_mask:0xf
	s_nop 0
	v_add_f32_dpp v9, v9, v9 row_bcast:15 row_mask:0xa bank_mask:0xf
	v_add_f32_dpp v90, v90, v90 row_bcast:15 row_mask:0xa bank_mask:0xf
	s_nop 0
	v_add_f32_dpp v9, v9, v9 row_bcast:31 row_mask:0xc bank_mask:0xf
	v_add_f32_dpp v90, v90, v90 row_bcast:31 row_mask:0xc bank_mask:0xf
	s_nop 0
	v_readlane_b32 s2, v9, 63
	v_readlane_b32 s3, v90, 63
	s_nop 1
	v_mov_b32_e32 v9, s2
	v_mov_b32_e32 v90, s3
	v_mul_f32_e32 v93, 0x3a800000, v9
	v_mul_f32_e32 v91, 0x3a800000, v90
	v_fma_f32 v91, -v93, v93, v91
	v_max_f32_e32 v91, 0, v91
	v_add_f32_e32 v91, 0x358637bd, v91
	v_rsq_f32_e32 v94, v91
	v_mul_f32_e32 v91, 0.5, v91
	v_mul_f32_e32 v92, v94, v94
	v_fma_f32 v92, -v91, v92, 0.5
	v_fma_f32 v94, v94, v92, v94
	v_pk_add_f32 v[42:43], v[42:43], v[92:93] op_sel:[0,1] op_sel_hi:[1,1] neg_lo:[0,1] neg_hi:[0,1]
	v_pk_add_f32 v[44:45], v[44:45], v[92:93] op_sel:[0,1] op_sel_hi:[1,1] neg_lo:[0,1] neg_hi:[0,1]
	v_pk_add_f32 v[46:47], v[46:47], v[92:93] op_sel:[0,1] op_sel_hi:[1,1] neg_lo:[0,1] neg_hi:[0,1]
	v_pk_add_f32 v[48:49], v[48:49], v[92:93] op_sel:[0,1] op_sel_hi:[1,1] neg_lo:[0,1] neg_hi:[0,1]
	v_pk_add_f32 v[50:51], v[50:51], v[92:93] op_sel:[0,1] op_sel_hi:[1,1] neg_lo:[0,1] neg_hi:[0,1]
	v_pk_add_f32 v[52:53], v[52:53], v[92:93] op_sel:[0,1] op_sel_hi:[1,1] neg_lo:[0,1] neg_hi:[0,1]
	v_pk_add_f32 v[54:55], v[54:55], v[92:93] op_sel:[0,1] op_sel_hi:[1,1] neg_lo:[0,1] neg_hi:[0,1]
	v_pk_add_f32 v[56:57], v[56:57], v[92:93] op_sel:[0,1] op_sel_hi:[1,1] neg_lo:[0,1] neg_hi:[0,1]
	v_pk_mul_f32 v[42:43], v[42:43], v[94:95] op_sel_hi:[1,0]
	v_pk_mul_f32 v[44:45], v[44:45], v[94:95] op_sel_hi:[1,0]
	v_pk_mul_f32 v[46:47], v[46:47], v[94:95] op_sel_hi:[1,0]
	v_pk_mul_f32 v[48:49], v[48:49], v[94:95] op_sel_hi:[1,0]
	v_pk_mul_f32 v[50:51], v[50:51], v[94:95] op_sel_hi:[1,0]
	v_pk_mul_f32 v[52:53], v[52:53], v[94:95] op_sel_hi:[1,0]
	v_pk_mul_f32 v[54:55], v[54:55], v[94:95] op_sel_hi:[1,0]
	v_pk_mul_f32 v[56:57], v[56:57], v[94:95] op_sel_hi:[1,0]
	v_pk_fma_f32 v[42:43], v[42:43], v[130:131], v[114:115]
	v_pk_fma_f32 v[44:45], v[44:45], v[132:133], v[116:117]
	v_pk_fma_f32 v[46:47], v[46:47], v[134:135], v[118:119]
	v_pk_fma_f32 v[48:49], v[48:49], v[136:137], v[120:121]
	v_pk_fma_f32 v[50:51], v[50:51], v[138:139], v[122:123]
	v_pk_fma_f32 v[52:53], v[52:53], v[140:141], v[124:125]
	v_pk_fma_f32 v[54:55], v[54:55], v[142:143], v[126:127]
	v_pk_fma_f32 v[56:57], v[56:57], v[144:145], v[128:129]
	v_cvt_pk_bf16_f32 v190, v42, v43
	v_cvt_pk_bf16_f32 v191, v44, v45
	v_cvt_pk_bf16_f32 v192, v46, v47
	v_cvt_pk_bf16_f32 v193, v48, v49
	v_cvt_pk_bf16_f32 v194, v50, v51
	v_cvt_pk_bf16_f32 v195, v52, v53
	v_cvt_pk_bf16_f32 v196, v54, v55
	v_cvt_pk_bf16_f32 v197, v56, v57
	s_add_u32 s2, s10, 0x2000
	s_addc_u32 s3, s11, 0
	global_store_dwordx2 v1, v[190:191], s[2:3]
	global_store_dwordx2 v1, v[192:193], s[2:3] offset:512
	global_store_dwordx2 v1, v[194:195], s[2:3] offset:1024
	global_store_dwordx2 v1, v[196:197], s[2:3] offset:1536
	s_mov_b64 s[2:3], s[20:21]
	global_load_dwordx4 v[42:45], v0, s[2:3]
	global_load_dwordx4 v[46:49], v0, s[2:3] offset:1024
	global_load_dwordx4 v[50:53], v0, s[2:3] offset:2048
	global_load_dwordx4 v[54:57], v0, s[2:3] offset:3072
	s_waitcnt vmcnt(24)
; DI unsigned pk2(float lo, float hi) { f32x2 v = {lo, hi}; bf16x2_t b = __builtin_convertvector(v, bf16x2_t); return __builtin_bit_cast(unsigned, b); }
; DI void ln_row_v(const Frame& F, f32x4 (&v)[4], float* xout, const float* g, const float* b, const float* sh, const float* sc, bf16_t* hout, const float* slab, const float* gres, float* stat = nullptr) {
;     ...
;         float s = 0.f, s2 = 0.f;
; #pragma unroll
;         for (int j = 0; j < 4; ++j) { s += (v[j][0] + v[j][1]) + (v[j][2] + v[j][3]); s2 += (v[j][0] * v[j][0] + v[j][1] * v[j][1]) + (v[j][2] * v[j][2] + v[j][3] * v[j][3]); }
;         wave_sum2(s, s2, F.lane);
;         const float mean = s * (1.f / D); const float rstd = 1.f / sqrtf(fmaxf(s2 * (1.f / D) - mean * mean, 0.f) + EPS);
; #pragma unroll
;         for (int j = 0; j < 4; ++j) { const f32x4 hh = ((const f32x4*)sh)[F.lane + 64 * j], cc = ((const f32x4*)sc)[F.lane + 64 * j];
;             const f32x4 o = (v[j] - mean) * rstd * (cc + 1.f) + hh; u32x2 wv; wv.x = pk2(o[0], o[1]); wv.y = pk2(o[2], o[3]);
;             ((u32x2*)hout)[F.lane + 64 * j] = wv; }
	v_pk_add_f32 v[198:199], v[58:59], v[60:61]
	v_pk_mul_f32 v[200:201], v[58:59], v[58:59]
	v_pk_fma_f32 v[200:201], v[60:61], v[60:61], v[200:201]
	v_pk_add_f32 v[198:199], v[198:199], v[62:63]
	v_pk_fma_f32 v[200:201], v[62:63], v[62:63], v[200:201]
	v_pk_add_f32 v[198:199], v[198:199], v[64:65]
	v_pk_fma_f32 v[200:201], v[64:65], v[64:65], v[200:201]
	v_pk_add_f32 v[198:199], v[198:199], v[66:67]
	v_pk_fma_f32 v[200:201], v[66:67], v[66:67], v[200:201]
	v_pk_add_f32 v[198:199], v[198:199], v[68:69]
	v_pk_fma_f32 v[200:201], v[68:69], v[68:69], v[200:201]
	v_pk_add_f32 v[198:199], v[198:199], v[70:71]
	v_pk_fma_f32 v[200:201], v[70:71], v[70:71], v[200:201]
	v_pk_add_f32 v[198:199], v[198:199], v[72:73]
	v_pk_fma_f32 v[200:201], v[72:73], v[72:73], v[200:201]
	v_add_f32_e32 v9, v198, v199
	v_add_f32_e32 v90, v200, v201
	s_nop 1
	v_add_f32_dpp v9, v9, v9 quad_perm:[1,0,3,2] row_mask:0xf bank_mask:0xf
	v_add_f32_dpp v90, v90, v90 quad_perm:[1,0,3,2] row_mask:0xf bank_mask:0xf
	s_nop 0
	v_add_f32_dpp v9, v9, v9 quad_perm:[2,3,0,1] row_mask:0xf bank_mask:0xf
	v_add_f32_dpp v90, v90, v90 quad_perm:[2,3,0,1] row_mask:0xf bank_mask:0xf
	s_nop 0
	v_add_f32_dpp v9, v9, v9 row_half_mirror row_mask:0xf bank_mask:0xf
	v_add_f32_dpp v90, v90, v90 row_half_mirror row_mask:0xf bank_mask:0xf
	s_nop 0
	v_add_f32_dpp v9, v9, v9 row_mirror row_mask:0xf bank_mask:0xf
	v_add_f32_dpp v90, v90, v90 row_mirror row_mask:0xf bank_mask:0xf
	s_nop 0
	v_add_f32_dpp v9, v9, v9 row_bcast:15 row_mask:0xa bank_mask:0xf
	v_add_f32_dpp v90, v90, v90 row_bcast:15 row_mask:0xa bank_mask:0xf
	s_nop 0
	v_add_f32_dpp v9, v9, v9 row_bcast:31 row_mask:0xc bank_mask:0xf
	v_add_f32_dpp v90, v90, v90 row_bcast:31 row_mask:0xc bank_mask:0xf
	s_nop 0
	v_readlane_b32 s2, v9, 63
	v_readlane_b32 s3, v90, 63
	s_nop 1
	v_mov_b32_e32 v9, s2
	v_mov_b32_e32 v90, s3
	v_mul_f32_e32 v93, 0x3a800000, v9
	v_mul_f32_e32 v91, 0x3a800000, v90
	v_fma_f32 v91, -v93, v93, v91
	v_max_f32_e32 v91, 0, v91
	v_add_f32_e32 v91, 0x358637bd, v91
	v_rsq_f32_e32 v94, v91
	v_mul_f32_e32 v91, 0.5, v91
	v_mul_f32_e32 v92, v94, v94
	v_fma_f32 v92, -v91, v92, 0.5
	v_fma_f32 v94, v94, v92, v94
	v_pk_add_f32 v[58:59], v[58:59], v[92:93] op_sel:[0,1] op_sel_hi:[1,1] neg_lo:[0,1] neg_hi:[0,1]
	v_pk_add_f32 v[60:61], v[60:61], v[92:93] op_sel:[0,1] op_sel_hi:[1,1] neg_lo:[0,1] neg_hi:[0,1]
	v_pk_add_f32 v[62:63], v[62:63], v[92:93] op_sel:[0,1] op_sel_hi:[1,1] neg_lo:[0,1] neg_hi:[0,1]
	v_pk_add_f32 v[64:65], v[64:65], v[92:93] op_sel:[0,1] op_sel_hi:[1,1] neg_lo:[0,1] neg_hi:[0,1]
	v_pk_add_f32 v[66:67], v[66:67], v[92:93] op_sel:[0,1] op_sel_hi:[1,1] neg_lo:[0,1] neg_hi:[0,1]
	v_pk_add_f32 v[68:69], v[68:69], v[92:93] op_sel:[0,1] op_sel_hi:[1,1] neg_lo:[0,1] neg_hi:[0,1]
	v_pk_add_f32 v[70:71], v[70:71], v[92:93] op_sel:[0,1] op_sel_hi:[1,1] neg_lo:[0,1] neg_hi:[0,1]
	v_pk_add_f32 v[72:73], v[72:73], v[92:93] op_sel:[0,1] op_sel_hi:[1,1] neg_lo:[0,1] neg_hi:[0,1]
	v_pk_mul_f32 v[58:59], v[58:59], v[94:95] op_sel_hi:[1,0]
	v_pk_mul_f32 v[60:61], v[60:61], v[94:95] op_sel_hi:[1,0]
	v_pk_mul_f32 v[62:63], v[62:63], v[94:95] op_sel_hi:[1,0]
	v_pk_mul_f32 v[64:65], v[64:65], v[94:95] op_sel_hi:[1,0]
	v_pk_mul_f32 v[66:67], v[66:67], v[94:95] op_sel_hi:[1,0]
	v_pk_mul_f32 v[68:69], v[68:69], v[94:95] op_sel_hi:[1,0]
	v_pk_mul_f32 v[70:71], v[70:71], v[94:95] op_sel_hi:[1,0]
	v_pk_mul_f32 v[72:73], v[72:73], v[94:95] op_sel_hi:[1,0]
	v_pk_fma_f32 v[58:59], v[58:59], v[130:131], v[114:115]
	v_pk_fma_f32 v[60:61], v[60:61], v[132:133], v[116:117]
	v_pk_fma_f32 v[62:63], v[62:63], v[134:135], v[118:119]
	v_pk_fma_f32 v[64:65], v[64:65], v[136:137], v[120:121]
	v_pk_fma_f32 v[66:67], v[66:67], v[138:139], v[122:123]
	v_pk_fma_f32 v[68:69], v[68:69], v[140:141], v[124:125]
	v_pk_fma_f32 v[70:71], v[70:71], v[142:143], v[126:127]
	v_pk_fma_f32 v[72:73], v[72:73], v[144:145], v[128:129]
	v_cvt_pk_bf16_f32 v190, v58, v59
	v_cvt_pk_bf16_f32 v191, v60, v61
	v_cvt_pk_bf16_f32 v192, v62, v63
	v_cvt_pk_bf16_f32 v193, v64, v65
	v_cvt_pk_bf16_f32 v194, v66, v67
	v_cvt_pk_bf16_f32 v195, v68, v69
	v_cvt_pk_bf16_f32 v196, v70, v71
	v_cvt_pk_bf16_f32 v197, v72, v73
	s_add_u32 s2, s10, 0x2800
	s_addc_u32 s3, s11, 0
	global_store_dwordx2 v1, v[190:191], s[2:3]
	global_store_dwordx2 v1, v[192:193], s[2:3] offset:512
	global_store_dwordx2 v1, v[194:195], s[2:3] offset:1024
	global_store_dwordx2 v1, v[196:197], s[2:3] offset:1536
	s_waitcnt vmcnt(20)
; DI unsigned pk2(float lo, float hi) { f32x2 v = {lo, hi}; bf16x2_t b = __builtin_convertvector(v, bf16x2_t); return __builtin_bit_cast(unsigned, b); }
; DI void ln_row_v(const Frame& F, f32x4 (&v)[4], float* xout, const float* g, const float* b, const float* sh, const float* sc, bf16_t* hout, const float* slab, const float* gres, float* stat = nullptr) {
;     ...
;         float s = 0.f, s2 = 0.f;
; #pragma unroll
;         for (int j = 0; j < 4; ++j) { s += (v[j][0] + v[j][1]) + (v[j][2] + v[j][3]); s2 += (v[j][0] * v[j][0] + v[j][1] * v[j][1]) + (v[j][2] * v[j][2] + v[j][3] * v[j][3]); }
;         wave_sum2(s, s2, F.lane);
;         const float mean = s * (1.f / D); const float rstd = 1.f / sqrtf(fmaxf(s2 * (1.f / D) - mean * mean, 0.f) + EPS);
; #pragma unroll
;         for (int j = 0; j < 4; ++j) { const f32x4 hh = ((const f32x4*)sh)[F.lane + 64 * j], cc = ((const f32x4*)sc)[F.lane + 64 * j];
;             const f32x4 o = (v[j] - mean) * rstd * (cc + 1.f) + hh; u32x2 wv; wv.x = pk2(o[0], o[1]); wv.y = pk2(o[2], o[3]);
;             ((u32x2*)hout)[F.lane + 64 * j] = wv; }
	v_pk_add_f32 v[198:199], v[74:75], v[76:77]
	v_pk_mul_f32 v[200:201], v[74:75], v[74:75]
	v_pk_fma_f32 v[200:201], v[76:77], v[76:77], v[200:201]
	v_pk_add_f32 v[198:199], v[198:199], v[78:79]
	v_pk_fma_f32 v[200:201], v[78:79], v[78:79], v[200:201]
	v_pk_add_f32 v[198:199], v[198:199], v[80:81]
	v_pk_fma_f32 v[200:201], v[80:81], v[80:81], v[200:201]
	v_pk_add_f32 v[198:199], v[198:199], v[82:83]
	v_pk_fma_f32 v[200:201], v[82:83], v[82:83], v[200:201]
	v_pk_add_f32 v[198:199], v[198:199], v[84:85]
	v_pk_fma_f32 v[200:201], v[84:85], v[84:85], v[200:201]
	v_pk_add_f32 v[198:199], v[198:199], v[86:87]
	v_pk_fma_f32 v[200:201], v[86:87], v[86:87], v[200:201]
	v_pk_add_f32 v[198:199], v[198:199], v[88:89]
	v_pk_fma_f32 v[200:201], v[88:89], v[88:89], v[200:201]
	v_add_f32_e32 v9, v198, v199
	v_add_f32_e32 v90, v200, v201
	s_nop 1
	v_add_f32_dpp v9, v9, v9 quad_perm:[1,0,3,2] row_mask:0xf bank_mask:0xf
	v_add_f32_dpp v90, v90, v90 quad_perm:[1,0,3,2] row_mask:0xf bank_mask:0xf
	s_nop 0
	v_add_f32_dpp v9, v9, v9 quad_perm:[2,3,0,1] row_mask:0xf bank_mask:0xf
	v_add_f32_dpp v90, v90, v90 quad_perm:[2,3,0,1] row_mask:0xf bank_mask:0xf
	s_nop 0
	v_add_f32_dpp v9, v9, v9 row_half_mirror row_mask:0xf bank_mask:0xf
	v_add_f32_dpp v90, v90, v90 row_half_mirror row_mask:0xf bank_mask:0xf
	s_nop 0
	v_add_f32_dpp v9, v9, v9 row_mirror row_mask:0xf bank_mask:0xf
	v_add_f32_dpp v90, v90, v90 row_mirror row_mask:0xf bank_mask:0xf
	s_nop 0
	v_add_f32_dpp v9, v9, v9 row_bcast:15 row_mask:0xa bank_mask:0xf
	v_add_f32_dpp v90, v90, v90 row_bcast:15 row_mask:0xa bank_mask:0xf
	s_nop 0
	v_add_f32_dpp v9, v9, v9 row_bcast:31 row_mask:0xc bank_mask:0xf
	v_add_f32_dpp v90, v90, v90 row_bcast:31 row_mask:0xc bank_mask:0xf
	s_nop 0
	v_readlane_b32 s2, v9, 63
	v_readlane_b32 s3, v90, 63
	s_nop 1
	v_mov_b32_e32 v9, s2
	v_mov_b32_e32 v90, s3
	v_mul_f32_e32 v93, 0x3a800000, v9
	v_mul_f32_e32 v91, 0x3a800000, v90
	v_fma_f32 v91, -v93, v93, v91
	v_max_f32_e32 v91, 0, v91
	v_add_f32_e32 v91, 0x358637bd, v91
	v_rsq_f32_e32 v94, v91
	v_mul_f32_e32 v91, 0.5, v91
	v_mul_f32_e32 v92, v94, v94
	v_fma_f32 v92, -v91, v92, 0.5
	v_fma_f32 v94, v94, v92, v94
	v_pk_add_f32 v[74:75], v[74:75], v[92:93] op_sel:[0,1] op_sel_hi:[1,1] neg_lo:[0,1] neg_hi:[0,1]
	v_pk_add_f32 v[76:77], v[76:77], v[92:93] op_sel:[0,1] op_sel_hi:[1,1] neg_lo:[0,1] neg_hi:[0,1]
	v_pk_add_f32 v[78:79], v[78:79], v[92:93] op_sel:[0,1] op_sel_hi:[1,1] neg_lo:[0,1] neg_hi:[0,1]
	v_pk_add_f32 v[80:81], v[80:81], v[92:93] op_sel:[0,1] op_sel_hi:[1,1] neg_lo:[0,1] neg_hi:[0,1]
	v_pk_add_f32 v[82:83], v[82:83], v[92:93] op_sel:[0,1] op_sel_hi:[1,1] neg_lo:[0,1] neg_hi:[0,1]
	v_pk_add_f32 v[84:85], v[84:85], v[92:93] op_sel:[0,1] op_sel_hi:[1,1] neg_lo:[0,1] neg_hi:[0,1]
	v_pk_add_f32 v[86:87], v[86:87], v[92:93] op_sel:[0,1] op_sel_hi:[1,1] neg_lo:[0,1] neg_hi:[0,1]
	v_pk_add_f32 v[88:89], v[88:89], v[92:93] op_sel:[0,1] op_sel_hi:[1,1] neg_lo:[0,1] neg_hi:[0,1]
	v_pk_mul_f32 v[74:75], v[74:75], v[94:95] op_sel_hi:[1,0]
	v_pk_mul_f32 v[76:77], v[76:77], v[94:95] op_sel_hi:[1,0]
	v_pk_mul_f32 v[78:79], v[78:79], v[94:95] op_sel_hi:[1,0]
	v_pk_mul_f32 v[80:81], v[80:81], v[94:95] op_sel_hi:[1,0]
	v_pk_mul_f32 v[82:83], v[82:83], v[94:95] op_sel_hi:[1,0]
	v_pk_mul_f32 v[84:85], v[84:85], v[94:95] op_sel_hi:[1,0]
	v_pk_mul_f32 v[86:87], v[86:87], v[94:95] op_sel_hi:[1,0]
	v_pk_mul_f32 v[88:89], v[88:89], v[94:95] op_sel_hi:[1,0]
	v_pk_fma_f32 v[74:75], v[74:75], v[130:131], v[114:115]
	v_pk_fma_f32 v[76:77], v[76:77], v[132:133], v[116:117]
	v_pk_fma_f32 v[78:79], v[78:79], v[134:135], v[118:119]
	v_pk_fma_f32 v[80:81], v[80:81], v[136:137], v[120:121]
	v_pk_fma_f32 v[82:83], v[82:83], v[138:139], v[122:123]
	v_pk_fma_f32 v[84:85], v[84:85], v[140:141], v[124:125]
	v_pk_fma_f32 v[86:87], v[86:87], v[142:143], v[126:127]
	v_pk_fma_f32 v[88:89], v[88:89], v[144:145], v[128:129]
	v_cvt_pk_bf16_f32 v190, v74, v75
	v_cvt_pk_bf16_f32 v191, v76, v77
	v_cvt_pk_bf16_f32 v192, v78, v79
	v_cvt_pk_bf16_f32 v193, v80, v81
	v_cvt_pk_bf16_f32 v194, v82, v83
	v_cvt_pk_bf16_f32 v195, v84, v85
	v_cvt_pk_bf16_f32 v196, v86, v87
	v_cvt_pk_bf16_f32 v197, v88, v89
	s_add_u32 s2, s10, 0x3000
	s_addc_u32 s3, s11, 0
	global_store_dwordx2 v1, v[190:191], s[2:3]
	global_store_dwordx2 v1, v[192:193], s[2:3] offset:512
	global_store_dwordx2 v1, v[194:195], s[2:3] offset:1024
	global_store_dwordx2 v1, v[196:197], s[2:3] offset:1536
	s_waitcnt vmcnt(16)
; DI unsigned pk2(float lo, float hi) { f32x2 v = {lo, hi}; bf16x2_t b = __builtin_convertvector(v, bf16x2_t); return __builtin_bit_cast(unsigned, b); }
; DI void ln_row_v(const Frame& F, f32x4 (&v)[4], float* xout, const float* g, const float* b, const float* sh, const float* sc, bf16_t* hout, const float* slab, const float* gres, float* stat = nullptr) {
;     ...
;         float s = 0.f, s2 = 0.f;
; #pragma unroll
;         for (int j = 0; j < 4; ++j) { s += (v[j][0] + v[j][1]) + (v[j][2] + v[j][3]); s2 += (v[j][0] * v[j][0] + v[j][1] * v[j][1]) + (v[j][2] * v[j][2] + v[j][3] * v[j][3]); }
;         wave_sum2(s, s2, F.lane);
;         const float mean = s * (1.f / D); const float rstd = 1.f / sqrtf(fmaxf(s2 * (1.f / D) - mean * mean, 0.f) + EPS);
; #pragma unroll
;         for (int j = 0; j < 4; ++j) { const f32x4 hh = ((const f32x4*)sh)[F.lane + 64 * j], cc = ((const f32x4*)sc)[F.lane + 64 * j];
;             const f32x4 o = (v[j] - mean) * rstd * (cc + 1.f) + hh; u32x2 wv; wv.x = pk2(o[0], o[1]); wv.y = pk2(o[2], o[3]);
;             ((u32x2*)hout)[F.lane + 64 * j] = wv; }
	v_pk_add_f32 v[198:199], v[98:99], v[100:101]
	v_pk_mul_f32 v[200:201], v[98:99], v[98:99]
	v_pk_fma_f32 v[200:201], v[100:101], v[100:101], v[200:201]
	v_pk_add_f32 v[198:199], v[198:199], v[102:103]
	v_pk_fma_f32 v[200:201], v[102:103], v[102:103], v[200:201]
	v_pk_add_f32 v[198:199], v[198:199], v[104:105]
	v_pk_fma_f32 v[200:201], v[104:105], v[104:105], v[200:201]
	v_pk_add_f32 v[198:199], v[198:199], v[106:107]
	v_pk_fma_f32 v[200:201], v[106:107], v[106:107], v[200:201]
	v_pk_add_f32 v[198:199], v[198:199], v[108:109]
	v_pk_fma_f32 v[200:201], v[108:109], v[108:109], v[200:201]
	v_pk_add_f32 v[198:199], v[198:199], v[110:111]
	v_pk_fma_f32 v[200:201], v[110:111], v[110:111], v[200:201]
	v_pk_add_f32 v[198:199], v[198:199], v[112:113]
	v_pk_fma_f32 v[200:201], v[112:113], v[112:113], v[200:201]
	v_add_f32_e32 v9, v198, v199
	v_add_f32_e32 v90, v200, v201
	s_nop 1
	v_add_f32_dpp v9, v9, v9 quad_perm:[1,0,3,2] row_mask:0xf bank_mask:0xf
	v_add_f32_dpp v90, v90, v90 quad_perm:[1,0,3,2] row_mask:0xf bank_mask:0xf
	s_nop 0
	v_add_f32_dpp v9, v9, v9 quad_perm:[2,3,0,1] row_mask:0xf bank_mask:0xf
	v_add_f32_dpp v90, v90, v90 quad_perm:[2,3,0,1] row_mask:0xf bank_mask:0xf
	s_nop 0
	v_add_f32_dpp v9, v9, v9 row_half_mirror row_mask:0xf bank_mask:0xf
	v_add_f32_dpp v90, v90, v90 row_half_mirror row_mask:0xf bank_mask:0xf
	s_nop 0
	v_add_f32_dpp v9, v9, v9 row_mirror row_mask:0xf bank_mask:0xf
	v_add_f32_dpp v90, v90, v90 row_mirror row_mask:0xf bank_mask:0xf
	s_nop 0
	v_add_f32_dpp v9, v9, v9 row_bcast:15 row_mask:0xa bank_mask:0xf
	v_add_f32_dpp v90, v90, v90 row_bcast:15 row_mask:0xa bank_mask:0xf
	s_nop 0
	v_add_f32_dpp v9, v9, v9 row_bcast:31 row_mask:0xc bank_mask:0xf
	v_add_f32_dpp v90, v90, v90 row_bcast:31 row_mask:0xc bank_mask:0xf
	s_nop 0
	v_readlane_b32 s2, v9, 63
	v_readlane_b32 s3, v90, 63
	s_nop 1
	v_mov_b32_e32 v9, s2
	v_mov_b32_e32 v90, s3
	v_mul_f32_e32 v93, 0x3a800000, v9
	v_mul_f32_e32 v91, 0x3a800000, v90
	v_fma_f32 v91, -v93, v93, v91
	v_max_f32_e32 v91, 0, v91
	v_add_f32_e32 v91, 0x358637bd, v91
	v_rsq_f32_e32 v94, v91
	v_mul_f32_e32 v91, 0.5, v91
	v_mul_f32_e32 v92, v94, v94
	v_fma_f32 v92, -v91, v92, 0.5
	v_fma_f32 v94, v94, v92, v94
	v_pk_add_f32 v[98:99], v[98:99], v[92:93] op_sel:[0,1] op_sel_hi:[1,1] neg_lo:[0,1] neg_hi:[0,1]
	v_pk_add_f32 v[100:101], v[100:101], v[92:93] op_sel:[0,1] op_sel_hi:[1,1] neg_lo:[0,1] neg_hi:[0,1]
	v_pk_add_f32 v[102:103], v[102:103], v[92:93] op_sel:[0,1] op_sel_hi:[1,1] neg_lo:[0,1] neg_hi:[0,1]
	v_pk_add_f32 v[104:105], v[104:105], v[92:93] op_sel:[0,1] op_sel_hi:[1,1] neg_lo:[0,1] neg_hi:[0,1]
	v_pk_add_f32 v[106:107], v[106:107], v[92:93] op_sel:[0,1] op_sel_hi:[1,1] neg_lo:[0,1] neg_hi:[0,1]
	v_pk_add_f32 v[108:109], v[108:109], v[92:93] op_sel:[0,1] op_sel_hi:[1,1] neg_lo:[0,1] neg_hi:[0,1]
	v_pk_add_f32 v[110:111], v[110:111], v[92:93] op_sel:[0,1] op_sel_hi:[1,1] neg_lo:[0,1] neg_hi:[0,1]
	v_pk_add_f32 v[112:113], v[112:113], v[92:93] op_sel:[0,1] op_sel_hi:[1,1] neg_lo:[0,1] neg_hi:[0,1]
	v_pk_mul_f32 v[98:99], v[98:99], v[94:95] op_sel_hi:[1,0]
	v_pk_mul_f32 v[100:101], v[100:101], v[94:95] op_sel_hi:[1,0]
	v_pk_mul_f32 v[102:103], v[102:103], v[94:95] op_sel_hi:[1,0]
	v_pk_mul_f32 v[104:105], v[104:105], v[94:95] op_sel_hi:[1,0]
	v_pk_mul_f32 v[106:107], v[106:107], v[94:95] op_sel_hi:[1,0]
	v_pk_mul_f32 v[108:109], v[108:109], v[94:95] op_sel_hi:[1,0]
	v_pk_mul_f32 v[110:111], v[110:111], v[94:95] op_sel_hi:[1,0]
	v_pk_mul_f32 v[112:113], v[112:113], v[94:95] op_sel_hi:[1,0]
	v_pk_fma_f32 v[98:99], v[98:99], v[130:131], v[114:115]
	v_pk_fma_f32 v[100:101], v[100:101], v[132:133], v[116:117]
	v_pk_fma_f32 v[102:103], v[102:103], v[134:135], v[118:119]
	v_pk_fma_f32 v[104:105], v[104:105], v[136:137], v[120:121]
	v_pk_fma_f32 v[106:107], v[106:107], v[138:139], v[122:123]
	v_pk_fma_f32 v[108:109], v[108:109], v[140:141], v[124:125]
	v_pk_fma_f32 v[110:111], v[110:111], v[142:143], v[126:127]
	v_pk_fma_f32 v[112:113], v[112:113], v[144:145], v[128:129]
	v_cvt_pk_bf16_f32 v190, v98, v99
	v_cvt_pk_bf16_f32 v191, v100, v101
	v_cvt_pk_bf16_f32 v192, v102, v103
	v_cvt_pk_bf16_f32 v193, v104, v105
	v_cvt_pk_bf16_f32 v194, v106, v107
	v_cvt_pk_bf16_f32 v195, v108, v109
	v_cvt_pk_bf16_f32 v196, v110, v111
	v_cvt_pk_bf16_f32 v197, v112, v113
	s_add_u32 s2, s10, 0x3800
	s_addc_u32 s3, s11, 0
	global_store_dwordx2 v1, v[190:191], s[2:3]
	global_store_dwordx2 v1, v[192:193], s[2:3] offset:512
	global_store_dwordx2 v1, v[194:195], s[2:3] offset:1024
	global_store_dwordx2 v1, v[196:197], s[2:3] offset:1536
	s_waitcnt vmcnt(12)
; DI unsigned pk2(float lo, float hi) { f32x2 v = {lo, hi}; bf16x2_t b = __builtin_convertvector(v, bf16x2_t); return __builtin_bit_cast(unsigned, b); }
; DI const float* modp(const Frame& F, int l, int mr, int which) { return (const float*)(F.ws + WS_MOD) + ((size_t)(l * 9 + mr) * 6 + which) * 1024; }
; DI void ln_row_v(const Frame& F, f32x4 (&v)[4], float* xout, const float* g, const float* b, const float* sh, const float* sc, bf16_t* hout, const float* slab, const float* gres, float* stat = nullptr) {
;     ...
;         float s = 0.f, s2 = 0.f;
; #pragma unroll
;         for (int j = 0; j < 4; ++j) { s += (v[j][0] + v[j][1]) + (v[j][2] + v[j][3]); s2 += (v[j][0] * v[j][0] + v[j][1] * v[j][1]) + (v[j][2] * v[j][2] + v[j][3] * v[j][3]); }
;         wave_sum2(s, s2, F.lane);
;         const float mean = s * (1.f / D); const float rstd = 1.f / sqrtf(fmaxf(s2 * (1.f / D) - mean * mean, 0.f) + EPS);
; #pragma unroll
;         for (int j = 0; j < 4; ++j) { const f32x4 hh = ((const f32x4*)sh)[F.lane + 64 * j], cc = ((const f32x4*)sc)[F.lane + 64 * j];
;             const f32x4 o = (v[j] - mean) * rstd * (cc + 1.f) + hh; u32x2 wv; wv.x = pk2(o[0], o[1]); wv.y = pk2(o[2], o[3]);
;             ((u32x2*)hout)[F.lane + 64 * j] = wv; }
; DI void prologue_b(const Frame& F) {
;     ...
;     for (int row = gw; row < MT; row += NGW) {
;         const int mr = row < ML ? (row >> 11) : 8;
;         const float* xi = row < ML ? pin(F, I_X) + (size_t)row * D : pin(F, I_CTX) + (size_t)(row - ML) * D;
;         ln_row(F, xi, nullptr, nullptr, nullptr, modp(F, 0, mr, 0), modp(F, 0, mr, 1), H + (size_t)row * D);
;     }
	v_pk_add_f32 v[198:199], v[42:43], v[44:45]
	v_pk_mul_f32 v[200:201], v[42:43], v[42:43]
	v_pk_fma_f32 v[200:201], v[44:45], v[44:45], v[200:201]
	v_pk_add_f32 v[198:199], v[198:199], v[46:47]
	v_pk_fma_f32 v[200:201], v[46:47], v[46:47], v[200:201]
	v_pk_add_f32 v[198:199], v[198:199], v[48:49]
	v_pk_fma_f32 v[200:201], v[48:49], v[48:49], v[200:201]
	v_pk_add_f32 v[198:199], v[198:199], v[50:51]
	v_pk_fma_f32 v[200:201], v[50:51], v[50:51], v[200:201]
	v_pk_add_f32 v[198:199], v[198:199], v[52:53]
	v_pk_fma_f32 v[200:201], v[52:53], v[52:53], v[200:201]
	v_pk_add_f32 v[198:199], v[198:199], v[54:55]
	v_pk_fma_f32 v[200:201], v[54:55], v[54:55], v[200:201]
	v_pk_add_f32 v[198:199], v[198:199], v[56:57]
	v_pk_fma_f32 v[200:201], v[56:57], v[56:57], v[200:201]
	v_add_f32_e32 v9, v198, v199
	v_add_f32_e32 v90, v200, v201
	s_nop 1
	v_add_f32_dpp v9, v9, v9 quad_perm:[1,0,3,2] row_mask:0xf bank_mask:0xf
	v_add_f32_dpp v90, v90, v90 quad_perm:[1,0,3,2] row_mask:0xf bank_mask:0xf
	s_nop 0
	v_add_f32_dpp v9, v9, v9 quad_perm:[2,3,0,1] row_mask:0xf bank_mask:0xf
	v_add_f32_dpp v90, v90, v90 quad_perm:[2,3,0,1] row_mask:0xf bank_mask:0xf
	s_nop 0
	v_add_f32_dpp v9, v9, v9 row_half_mirror row_mask:0xf bank_mask:0xf
	v_add_f32_dpp v90, v90, v90 row_half_mirror row_mask:0xf bank_mask:0xf
	s_nop 0
	v_add_f32_dpp v9, v9, v9 row_mirror row_mask:0xf bank_mask:0xf
	v_add_f32_dpp v90, v90, v90 row_mirror row_mask:0xf bank_mask:0xf
	s_nop 0
	v_add_f32_dpp v9, v9, v9 row_bcast:15 row_mask:0xa bank_mask:0xf
	v_add_f32_dpp v90, v90, v90 row_bcast:15 row_mask:0xa bank_mask:0xf
	s_nop 0
	v_add_f32_dpp v9, v9, v9 row_bcast:31 row_mask:0xc bank_mask:0xf
	v_add_f32_dpp v90, v90, v90 row_bcast:31 row_mask:0xc bank_mask:0xf
	s_nop 0
	v_readlane_b32 s2, v9, 63
	v_readlane_b32 s3, v90, 63
	s_nop 1
	v_mov_b32_e32 v9, s2
	v_mov_b32_e32 v90, s3
	v_mul_f32_e32 v93, 0x3a800000, v9
	v_mul_f32_e32 v91, 0x3a800000, v90
	v_fma_f32 v91, -v93, v93, v91
	v_max_f32_e32 v91, 0, v91
	v_add_f32_e32 v91, 0x358637bd, v91
	v_rsq_f32_e32 v94, v91
	v_mul_f32_e32 v91, 0.5, v91
	v_mul_f32_e32 v92, v94, v94
	v_fma_f32 v92, -v91, v92, 0.5
	v_fma_f32 v94, v94, v92, v94
	v_pk_add_f32 v[42:43], v[42:43], v[92:93] op_sel:[0,1] op_sel_hi:[1,1] neg_lo:[0,1] neg_hi:[0,1]
	v_pk_add_f32 v[44:45], v[44:45], v[92:93] op_sel:[0,1] op_sel_hi:[1,1] neg_lo:[0,1] neg_hi:[0,1]
	v_pk_add_f32 v[46:47], v[46:47], v[92:93] op_sel:[0,1] op_sel_hi:[1,1] neg_lo:[0,1] neg_hi:[0,1]
	v_pk_add_f32 v[48:49], v[48:49], v[92:93] op_sel:[0,1] op_sel_hi:[1,1] neg_lo:[0,1] neg_hi:[0,1]
	v_pk_add_f32 v[50:51], v[50:51], v[92:93] op_sel:[0,1] op_sel_hi:[1,1] neg_lo:[0,1] neg_hi:[0,1]
	v_pk_add_f32 v[52:53], v[52:53], v[92:93] op_sel:[0,1] op_sel_hi:[1,1] neg_lo:[0,1] neg_hi:[0,1]
	v_pk_add_f32 v[54:55], v[54:55], v[92:93] op_sel:[0,1] op_sel_hi:[1,1] neg_lo:[0,1] neg_hi:[0,1]
	v_pk_add_f32 v[56:57], v[56:57], v[92:93] op_sel:[0,1] op_sel_hi:[1,1] neg_lo:[0,1] neg_hi:[0,1]
	v_add_f32_e32 v162, 1.0, v162
	v_add_f32_e32 v163, 1.0, v163
	v_add_f32_e32 v164, 1.0, v164
	v_add_f32_e32 v165, 1.0, v165
	v_add_f32_e32 v166, 1.0, v166
	v_add_f32_e32 v167, 1.0, v167
	v_add_f32_e32 v168, 1.0, v168
	v_add_f32_e32 v169, 1.0, v169
	v_add_f32_e32 v170, 1.0, v170
	v_add_f32_e32 v171, 1.0, v171
	v_add_f32_e32 v172, 1.0, v172
	v_add_f32_e32 v173, 1.0, v173
	v_add_f32_e32 v174, 1.0, v174
	v_add_f32_e32 v175, 1.0, v175
	v_add_f32_e32 v176, 1.0, v176
	v_add_f32_e32 v177, 1.0, v177
	v_pk_mul_f32 v[42:43], v[42:43], v[94:95] op_sel_hi:[1,0]
	v_pk_mul_f32 v[44:45], v[44:45], v[94:95] op_sel_hi:[1,0]
	v_pk_mul_f32 v[46:47], v[46:47], v[94:95] op_sel_hi:[1,0]
	v_pk_mul_f32 v[48:49], v[48:49], v[94:95] op_sel_hi:[1,0]
	v_pk_mul_f32 v[50:51], v[50:51], v[94:95] op_sel_hi:[1,0]
	v_pk_mul_f32 v[52:53], v[52:53], v[94:95] op_sel_hi:[1,0]
	v_pk_mul_f32 v[54:55], v[54:55], v[94:95] op_sel_hi:[1,0]
	v_pk_mul_f32 v[56:57], v[56:57], v[94:95] op_sel_hi:[1,0]
	v_pk_fma_f32 v[42:43], v[42:43], v[162:163], v[146:147]
	v_pk_fma_f32 v[44:45], v[44:45], v[164:165], v[148:149]
	v_pk_fma_f32 v[46:47], v[46:47], v[166:167], v[150:151]
	v_pk_fma_f32 v[48:49], v[48:49], v[168:169], v[152:153]
	v_pk_fma_f32 v[50:51], v[50:51], v[170:171], v[154:155]
	v_pk_fma_f32 v[52:53], v[52:53], v[172:173], v[156:157]
	v_pk_fma_f32 v[54:55], v[54:55], v[174:175], v[158:159]
	v_pk_fma_f32 v[56:57], v[56:57], v[176:177], v[160:161]
	v_cvt_pk_bf16_f32 v190, v42, v43
	v_cvt_pk_bf16_f32 v191, v44, v45
	v_cvt_pk_bf16_f32 v192, v46, v47
	v_cvt_pk_bf16_f32 v193, v48, v49
	v_cvt_pk_bf16_f32 v194, v50, v51
	v_cvt_pk_bf16_f32 v195, v52, v53
	v_cvt_pk_bf16_f32 v196, v54, v55
	v_cvt_pk_bf16_f32 v197, v56, v57
	s_lshl_b32 s2, s16, 11
	s_add_u32 s2, s94, s2
	s_addc_u32 s3, s95, 0
	s_add_u32 s2, s2, 0x5e00000
	s_addc_u32 s3, s3, 0
	global_store_dwordx2 v1, v[190:191], s[2:3]
	global_store_dwordx2 v1, v[192:193], s[2:3] offset:512
	global_store_dwordx2 v1, v[194:195], s[2:3] offset:1024
	global_store_dwordx2 v1, v[196:197], s[2:3] offset:1536
	s_waitcnt vmcnt(0)
	s_add_i32 s16, s16, 0x4800
	s_cmpk_gt_u32 s16, 0x47ff
	s_cbranch_scc1 .LBB0_671
	s_lshl_b64 s[2:3], s[44:45], 3
	s_add_u32 s4, s62, s2
	s_addc_u32 s5, s63, s3
	v_lshlrev_b32_e32 v0, 2, v186
	v_lshlrev_b32_e32 v96, 3, v186
	s_add_u32 s18, s94, 0x100000
	v_xor_b32_e32 v18, 4, v0
	v_xor_b32_e32 v19, 8, v0
	v_xor_b32_e32 v20, 16, v0
	v_xor_b32_e32 v21, 32, v0
	v_xor_b32_e32 v22, 64, v0
	v_xor_b32_e32 v23, 0x80, v0
	v_or_b32_e32 v0, 64, v186
	v_or_b32_e32 v2, 0x80, v186
	v_or_b32_e32 v4, 0xc0, v186
	v_lshl_add_u64 v[6:7], s[94:95], 0, v[96:97]
	s_mov_b64 s[2:3], 0x3e00000
	s_addc_u32 s19, s95, 0
	v_lshl_add_u64 v[16:17], v[6:7], 0, s[2:3]
	s_lshl_b32 s20, s93, 3
	s_lshl_b64 s[6:7], s[16:17], 12
	s_lshl_b32 s21, s93, 15
	v_lshlrev_b32_e32 v24, 4, v186
	v_lshlrev_b32_e32 v25, 4, v0
	v_lshlrev_b32_e32 v26, 4, v2
	v_lshlrev_b32_e32 v27, 4, v4
	s_mov_b64 s[8:9], s[16:17]
	s_branch .LBB0_668
